# all 18 GEMM K-loop heads pinned to a 64-byte boundary (.p2align 6)
# speedup vs baseline: 1.0088x; 1.0048x over previous
; #define PG8_STAGE(bufoff, gbase, voff) do { _Pragma("unroll") for (int _i = 0; _i < 2; ++_i) \
;         __builtin_amdgcn_global_load_lds((const unsigned*)((const char*)(gbase) + (voff)[_i]), (PG8_LAS unsigned*)(lds + (bufoff) + ldsw + _i * 8192), 16, 0, 0); } while (0)
; #define PG8_LDA(dst, b, h) do { _Pragma("unroll") for (int m = 0; m < 4; ++m) _Pragma("unroll") for (int k = 0; k < 2; ++k) dst[m][k] = *(const PG8_LAS bf16x8*)(lds + PG8_SA(b, h) + aoff + m * 2048 + k * 1024); } while (0)
; template <class Epi, class Sched, bool ALIGN_EPI = false, bool SP2 = false>
; __device__ __forceinline__ void gemm_phase(PG8_LAS unsigned char* lds, const Gemm g, const Sched& S, const Epi& E) {
;     ...
;     for (;;) {
;         const bool has_next = S.next(ui + 1, nxt);
;         const char* nA = has_next ? (const char*)g.A + (size_t)nxt.pm * tstep : cA; const char* nB = has_next ? (const char*)g.Bt + (size_t)nxt.pn * tstep : cB;
;         for (int t = 0; t < nt; t += 2) {
;             const bool last = (t == nt - 2);
;             const char* a1 = cA + (size_t)(t + 1) * kstep;
;             const char* a2 = last ? nA : cA + (size_t)(t + 2) * kstep; const char* b2 = last ? nB : cB + (size_t)(t + 2) * kstep;
;             const char* a3 = a2 + kstep; const char* b3 = b2 + kstep;
;             if (last && has_next) S.a_ready(nxt);
;             if constexpr (SP2) {
;             PG8_LDB(B0, 0, 0); PG8_LDB(B1, 0, 1); PG8_SCHED; PG8_LDA(At, 0, 0); PG8_STAGE(PG8_SA(1, 1), a1 + hstep, voffA);
;             PG8_WAIT_V(8); PG8_WAIT_L(0); PG8_BAR; PG8_MMA(0, 0, At, B0); PG8_MMA(0, 1, At, B1); PG8_BAR; PG8_SCHED;
;             PG8_LDA(At, 0, 1); PG8_STAGE(PG8_SB(0, 0), b2, voffB); PG8_STAGE(PG8_SB(0, 1), b2 + hstep, voffB); PG8_STAGE(PG8_SA(0, 0), a2, voffA);
;             PG8_WAIT_V(8); PG8_WAIT_L(0); PG8_BAR; PG8_MMA(1, 0, At, B0); PG8_MMA(1, 1, At, B1); PG8_BAR; PG8_SCHED;
;             PG8_LDB(B0, 1, 0); PG8_LDB(B1, 1, 1); PG8_SCHED; PG8_LDA(At, 1, 0); PG8_STAGE(PG8_SA(0, 1), a2 + hstep, voffA);
;             PG8_WAIT_V(8); PG8_WAIT_L(0); PG8_BAR; PG8_MMA(0, 0, At, B0); PG8_MMA(0, 1, At, B1); PG8_BAR; PG8_SCHED;
;             PG8_LDA(At, 1, 1); PG8_STAGE(PG8_SB(1, 0), b3, voffB); PG8_STAGE(PG8_SB(1, 1), b3 + hstep, voffB); PG8_STAGE(PG8_SA(1, 0), a3, voffA);
;             PG8_WAIT_V(8); PG8_WAIT_L(0); PG8_BAR; PG8_MMA(1, 0, At, B0); PG8_MMA(1, 1, At, B1); PG8_BAR; PG8_SCHED;
.LBB0_190:
	s_ashr_i32 s27, s26, 31
	s_lshl_b64 s[14:15], s[26:27], 19
	s_add_u32 s28, s22, s14
	s_addc_u32 s29, s23, s15
	s_and_b64 s[14:15], s[0:1], exec
	s_cselect_b32 s27, s29, s49
	s_cselect_b32 s67, s28, s48
	s_ashr_i32 s25, s24, 31
	s_lshl_b64 s[14:15], s[24:25], 19
	s_add_u32 s40, s94, s14
	s_addc_u32 s41, s96, s15
	s_and_b64 s[14:15], s[0:1], exec
	s_cselect_b32 s25, s41, s51
	s_cselect_b32 s86, s40, s50
	s_add_u32 s48, s48, 0x40080
	s_addc_u32 s49, s49, 0
	s_add_u32 s87, s50, 0x100
	s_addc_u32 s88, s51, 0
	s_mov_b32 s89, -2
	ds_read_b128 v[144:147], v155
	ds_read_b128 v[148:151], v155 offset:1024
	ds_read_b128 v[160:163], v155 offset:2048
	ds_read_b128 v[168:171], v155 offset:3072
	ds_read_b128 v[172:175], v156
	ds_read_b128 v[176:179], v156 offset:1024
	ds_read_b128 v[182:185], v156 offset:2048
	ds_read_b128 v[186:189], v156 offset:3072
	s_add_u32 s3, s48, 0xfffc0080
	s_addc_u32 s14, s49, -1
	s_cmp_eq_u32 s89, 12
	s_cselect_b32 s55, s27, s14
	s_cselect_b32 s54, s67, s3
	s_cselect_b32 s51, s25, s88
	s_cselect_b32 s50, s86, s87
	v_lshl_add_u64 v[164:165], s[48:49], 0, v[136:137]
	s_add_i32 m0, s45, 0xc000
	ds_read_b128 v[190:193], v157
	ds_read_b128 v[194:197], v157 offset:1024
	ds_read_b128 v[198:201], v157 offset:2048
	ds_read_b128 v[208:211], v157 offset:3072
	ds_read_b128 v[212:215], v157 offset:4096
	ds_read_b128 v[216:219], v157 offset:5120
	ds_read_b128 v[220:223], v157 offset:6144
	ds_read_b128 v[224:227], v157 offset:7168
	global_load_lds_dwordx4 v[164:165], off
	v_lshl_add_u64 v[164:165], s[48:49], 0, v[138:139]
	s_add_i32 m0, s45, 0xe000
	s_nop 0
	global_load_lds_dwordx4 v[164:165], off
	s_waitcnt vmcnt(8)
	s_waitcnt lgkmcnt(0)
	s_barrier
	s_setprio 1
	s_waitcnt lgkmcnt(0)
	v_mfma_f32_16x16x32_bf16 v[124:127], v[144:147], v[190:193], 0
	v_mfma_f32_16x16x32_bf16 v[120:123], v[160:163], v[190:193], 0
	v_mfma_f32_16x16x32_bf16 v[108:111], v[144:147], v[198:201], 0
	v_mfma_f32_16x16x32_bf16 v[104:107], v[160:163], v[198:201], 0
	v_mfma_f32_16x16x32_bf16 v[92:95], v[144:147], v[212:215], 0
	v_mfma_f32_16x16x32_bf16 v[88:91], v[160:163], v[212:215], 0
	v_mfma_f32_16x16x32_bf16 v[76:79], v[144:147], v[220:223], 0
	v_mfma_f32_16x16x32_bf16 v[72:75], v[160:163], v[220:223], 0
	v_mfma_f32_16x16x32_bf16 v[124:127], v[148:151], v[194:197], v[124:127]
	v_mfma_f32_16x16x32_bf16 v[120:123], v[168:171], v[194:197], v[120:123]
	v_mfma_f32_16x16x32_bf16 v[108:111], v[148:151], v[208:211], v[108:111]
	v_mfma_f32_16x16x32_bf16 v[104:107], v[168:171], v[208:211], v[104:107]
	v_mfma_f32_16x16x32_bf16 v[92:95], v[148:151], v[216:219], v[92:95]
	v_mfma_f32_16x16x32_bf16 v[88:91], v[168:171], v[216:219], v[88:91]
	v_mfma_f32_16x16x32_bf16 v[76:79], v[148:151], v[224:227], v[76:79]
	v_mfma_f32_16x16x32_bf16 v[72:75], v[168:171], v[224:227], v[72:75]
	s_setprio 0
	s_setprio 1
	v_mfma_f32_16x16x32_bf16 v[116:119], v[172:175], v[190:193], 0
	v_mfma_f32_16x16x32_bf16 v[112:115], v[182:185], v[190:193], 0
	v_mfma_f32_16x16x32_bf16 v[100:103], v[172:175], v[198:201], 0
	v_mfma_f32_16x16x32_bf16 v[96:99], v[182:185], v[198:201], 0
	v_mfma_f32_16x16x32_bf16 v[84:87], v[172:175], v[212:215], 0
	v_mfma_f32_16x16x32_bf16 v[80:83], v[182:185], v[212:215], 0
	v_mfma_f32_16x16x32_bf16 v[68:71], v[172:175], v[220:223], 0
	v_mfma_f32_16x16x32_bf16 v[64:67], v[182:185], v[220:223], 0
	v_mfma_f32_16x16x32_bf16 v[116:119], v[176:179], v[194:197], v[116:119]
	v_mfma_f32_16x16x32_bf16 v[112:115], v[186:189], v[194:197], v[112:115]
	v_mfma_f32_16x16x32_bf16 v[100:103], v[176:179], v[208:211], v[100:103]
	v_mfma_f32_16x16x32_bf16 v[96:99], v[186:189], v[208:211], v[96:99]
	v_mfma_f32_16x16x32_bf16 v[84:87], v[176:179], v[216:219], v[84:87]
	v_mfma_f32_16x16x32_bf16 v[80:83], v[186:189], v[216:219], v[80:83]
	v_mfma_f32_16x16x32_bf16 v[68:71], v[176:179], v[224:227], v[68:71]
	v_mfma_f32_16x16x32_bf16 v[64:67], v[186:189], v[224:227], v[64:67]
	s_setprio 0
	s_barrier
	s_add_i32 s3, s63, s43
	v_lshl_add_u64 v[164:165], s[50:51], 0, v[132:133]
	s_mov_b32 m0, s3
	ds_read_b128 v[190:193], v157 offset:16384
	ds_read_b128 v[194:197], v157 offset:17408
	ds_read_b128 v[198:201], v157 offset:18432
	ds_read_b128 v[208:211], v157 offset:19456
	ds_read_b128 v[212:215], v157 offset:20480
	ds_read_b128 v[216:219], v157 offset:21504
	ds_read_b128 v[220:223], v157 offset:22528
	ds_read_b128 v[224:227], v157 offset:23552
	global_load_lds_dwordx4 v[164:165], off
	s_add_i32 m0, s3, 0x2000
	s_add_u32 s14, s50, 0x40000
	v_lshl_add_u64 v[202:203], s[50:51], 0, v[128:129]
	s_addc_u32 s15, s51, 0
	s_add_i32 s3, s64, s43
	global_load_lds_dwordx4 v[202:203], off
	v_lshl_add_u64 v[228:229], s[14:15], 0, v[132:133]
	s_mov_b32 m0, s3
	global_load_lds_dwordx4 v[228:229], off
	v_lshl_add_u64 v[228:229], s[14:15], 0, v[128:129]
	s_add_i32 m0, s3, 0x2000
	s_nop 0
	global_load_lds_dwordx4 v[228:229], off
	s_waitcnt vmcnt(6)
	s_waitcnt lgkmcnt(0)
	s_barrier
; #define PG8_STAGE(bufoff, gbase, voff) do { _Pragma("unroll") for (int _i = 0; _i < 2; ++_i) \
;         __builtin_amdgcn_global_load_lds((const unsigned*)((const char*)(gbase) + (voff)[_i]), (PG8_LAS unsigned*)(lds + (bufoff) + ldsw + _i * 8192), 16, 0, 0); } while (0)
; #define PG8_LDA(dst, b, h) do { _Pragma("unroll") for (int m = 0; m < 4; ++m) _Pragma("unroll") for (int k = 0; k < 2; ++k) dst[m][k] = *(const PG8_LAS bf16x8*)(lds + PG8_SA(b, h) + aoff + m * 2048 + k * 1024); } while (0)
; #define PG8_LDB(dst, b, h) do { _Pragma("unroll") for (int n = 0; n < 2; ++n) _Pragma("unroll") for (int k = 0; k < 2; ++k) dst[n][k] = *(const PG8_LAS bf16x8*)(lds + PG8_SB(b, h) + boff + n * 2048 + k * 1024); } while (0)
; #define PG8_MMA(ai, bj, At, Bt) do { __builtin_amdgcn_s_setprio(1); _Pragma("unroll") for (int m = 0; m < 4; ++m) _Pragma("unroll") for (int n = 0; n < 2; ++n) _Pragma("unroll") for (int k = 0; k < 2; ++k) \
;         acc[ai][bj][m][n] = __builtin_amdgcn_mfma_f32_16x16x32_bf16(Bt[n][k], At[m][k], acc[ai][bj][m][n], 0, 0, 0); __builtin_amdgcn_s_setprio(0); } while (0)
; #define PG8_WAIT_V(n) asm volatile("s_waitcnt vmcnt(" #n ")" ::: "memory")
; #define PG8_WAIT_L(n) asm volatile("s_waitcnt lgkmcnt(" #n ")" ::: "memory")
; #define PG8_BAR __builtin_amdgcn_s_barrier()
; #define PG8_SCHED __builtin_amdgcn_sched_barrier(0)
; template <class Epi, class Sched, bool ALIGN_EPI = false, bool SP2 = false>
; __device__ __forceinline__ void gemm_phase(PG8_LAS unsigned char* lds, const Gemm g, const Sched& S, const Epi& E) {
;     ...
;             PG8_WAIT_V(8); PG8_WAIT_L(0); PG8_BAR; PG8_MMA(0, 0, At, B0); PG8_MMA(0, 1, At, B1); PG8_BAR; PG8_SCHED;
;             PG8_LDA(At, 0, 1); PG8_STAGE(PG8_SB(0, 0), b2, voffB); PG8_STAGE(PG8_SB(0, 1), b2 + hstep, voffB); PG8_STAGE(PG8_SA(0, 0), a2, voffA);
;             PG8_WAIT_V(8); PG8_WAIT_L(0); PG8_BAR; PG8_MMA(1, 0, At, B0); PG8_MMA(1, 1, At, B1); PG8_BAR; PG8_SCHED;
;             PG8_LDB(B0, 1, 0); PG8_LDB(B1, 1, 1); PG8_SCHED; PG8_LDA(At, 1, 0); PG8_STAGE(PG8_SA(0, 1), a2 + hstep, voffA);
;             PG8_WAIT_V(8); PG8_WAIT_L(0); PG8_BAR; PG8_MMA(0, 0, At, B0); PG8_MMA(0, 1, At, B1); PG8_BAR; PG8_SCHED;
;             PG8_LDA(At, 1, 1); PG8_STAGE(PG8_SB(1, 0), b3, voffB); PG8_STAGE(PG8_SB(1, 1), b3 + hstep, voffB); PG8_STAGE(PG8_SA(1, 0), a3, voffA);
	s_setprio 1
	s_waitcnt lgkmcnt(0)
	v_mfma_f32_16x16x32_bf16 v[60:63], v[144:147], v[190:193], 0
	v_mfma_f32_16x16x32_bf16 v[56:59], v[160:163], v[190:193], 0
	v_mfma_f32_16x16x32_bf16 v[44:47], v[144:147], v[198:201], 0
	v_mfma_f32_16x16x32_bf16 v[40:43], v[160:163], v[198:201], 0
	v_mfma_f32_16x16x32_bf16 v[28:31], v[144:147], v[212:215], 0
	v_mfma_f32_16x16x32_bf16 v[24:27], v[160:163], v[212:215], 0
	v_mfma_f32_16x16x32_bf16 v[12:15], v[144:147], v[220:223], 0
	v_mfma_f32_16x16x32_bf16 v[8:11], v[160:163], v[220:223], 0
	v_mfma_f32_16x16x32_bf16 v[60:63], v[148:151], v[194:197], v[60:63]
	v_mfma_f32_16x16x32_bf16 v[56:59], v[168:171], v[194:197], v[56:59]
	v_mfma_f32_16x16x32_bf16 v[44:47], v[148:151], v[208:211], v[44:47]
	v_mfma_f32_16x16x32_bf16 v[40:43], v[168:171], v[208:211], v[40:43]
	v_mfma_f32_16x16x32_bf16 v[28:31], v[148:151], v[216:219], v[28:31]
	v_mfma_f32_16x16x32_bf16 v[24:27], v[168:171], v[216:219], v[24:27]
	v_lshl_add_u64 v[228:229], s[54:55], 0, v[134:135]
	s_mov_b32 m0, s45
	s_nop 0
	global_load_lds_dwordx4 v[228:229], off
	v_mfma_f32_16x16x32_bf16 v[12:15], v[148:151], v[224:227], v[12:15]
	v_mfma_f32_16x16x32_bf16 v[8:11], v[168:171], v[224:227], v[8:11]
	s_setprio 0
	s_setprio 1
	v_mfma_f32_16x16x32_bf16 v[52:55], v[172:175], v[190:193], 0
	v_mfma_f32_16x16x32_bf16 v[48:51], v[182:185], v[190:193], 0
	v_mfma_f32_16x16x32_bf16 v[36:39], v[172:175], v[198:201], 0
	v_mfma_f32_16x16x32_bf16 v[32:35], v[182:185], v[198:201], 0
	v_mfma_f32_16x16x32_bf16 v[20:23], v[172:175], v[212:215], 0
	v_mfma_f32_16x16x32_bf16 v[16:19], v[182:185], v[212:215], 0
	v_mfma_f32_16x16x32_bf16 v[4:7], v[172:175], v[220:223], 0
	v_mfma_f32_16x16x32_bf16 v[0:3], v[182:185], v[220:223], 0
	v_mfma_f32_16x16x32_bf16 v[52:55], v[176:179], v[194:197], v[52:55]
	v_mfma_f32_16x16x32_bf16 v[48:51], v[186:189], v[194:197], v[48:51]
	v_mfma_f32_16x16x32_bf16 v[36:39], v[176:179], v[208:211], v[36:39]
	v_mfma_f32_16x16x32_bf16 v[32:35], v[186:189], v[208:211], v[32:35]
	v_mfma_f32_16x16x32_bf16 v[20:23], v[176:179], v[216:219], v[20:23]
	v_mfma_f32_16x16x32_bf16 v[16:19], v[186:189], v[216:219], v[16:19]
	v_lshl_add_u64 v[230:231], s[54:55], 0, v[130:131]
	s_mov_b32 m0, s57
	s_nop 0
	global_load_lds_dwordx4 v[230:231], off
	v_mfma_f32_16x16x32_bf16 v[4:7], v[176:179], v[224:227], v[4:7]
	v_mfma_f32_16x16x32_bf16 v[0:3], v[186:189], v[224:227], v[0:3]
	s_setprio 0
	s_barrier
	s_add_i32 s3, 0, 0x18000
	v_add_u32_e32 v159, s3, v153
	s_add_i32 s33, 0, 0x1c000
	ds_read_b128 v[144:147], v159
	ds_read_b128 v[148:151], v159 offset:1024
	ds_read_b128 v[160:163], v159 offset:2048
	ds_read_b128 v[168:171], v159 offset:3072
	v_add_u32_e32 v159, s33, v153
	ds_read_b128 v[172:175], v159
	ds_read_b128 v[176:179], v159 offset:1024
	ds_read_b128 v[182:185], v159 offset:2048
	ds_read_b128 v[186:189], v159 offset:3072
	s_add_u32 s14, s54, 0x40000
	s_addc_u32 s15, s55, 0
	s_mov_b32 m0, s58
	v_lshl_add_u64 v[232:233], s[14:15], 0, v[134:135]
	ds_read_b128 v[190:193], v157 offset:32768
	ds_read_b128 v[194:197], v157 offset:33792
	ds_read_b128 v[198:201], v157 offset:34816
	ds_read_b128 v[208:211], v157 offset:35840
	ds_read_b128 v[212:215], v157 offset:36864
	ds_read_b128 v[216:219], v157 offset:37888
	ds_read_b128 v[220:223], v157 offset:38912
	ds_read_b128 v[224:227], v157 offset:39936
	global_load_lds_dwordx4 v[232:233], off
	v_lshl_add_u64 v[232:233], s[14:15], 0, v[130:131]
	s_mov_b32 m0, s59
	s_nop 0
	global_load_lds_dwordx4 v[232:233], off
	s_waitcnt vmcnt(8)
	s_waitcnt lgkmcnt(0)
	s_barrier
	s_setprio 1
	s_waitcnt lgkmcnt(0)
	v_mfma_f32_16x16x32_bf16 v[124:127], v[144:147], v[190:193], v[124:127]
	v_mfma_f32_16x16x32_bf16 v[120:123], v[160:163], v[190:193], v[120:123]
	v_mfma_f32_16x16x32_bf16 v[108:111], v[144:147], v[198:201], v[108:111]
	v_mfma_f32_16x16x32_bf16 v[104:107], v[160:163], v[198:201], v[104:107]
	v_mfma_f32_16x16x32_bf16 v[92:95], v[144:147], v[212:215], v[92:95]
	v_mfma_f32_16x16x32_bf16 v[88:91], v[160:163], v[212:215], v[88:91]
	v_mfma_f32_16x16x32_bf16 v[76:79], v[144:147], v[220:223], v[76:79]
	v_mfma_f32_16x16x32_bf16 v[72:75], v[160:163], v[220:223], v[72:75]
	v_mfma_f32_16x16x32_bf16 v[124:127], v[148:151], v[194:197], v[124:127]
	v_mfma_f32_16x16x32_bf16 v[120:123], v[168:171], v[194:197], v[120:123]
	v_mfma_f32_16x16x32_bf16 v[108:111], v[148:151], v[208:211], v[108:111]
	v_mfma_f32_16x16x32_bf16 v[104:107], v[168:171], v[208:211], v[104:107]
	v_mfma_f32_16x16x32_bf16 v[92:95], v[148:151], v[216:219], v[92:95]
	v_mfma_f32_16x16x32_bf16 v[88:91], v[168:171], v[216:219], v[88:91]
	v_mfma_f32_16x16x32_bf16 v[76:79], v[148:151], v[224:227], v[76:79]
	v_mfma_f32_16x16x32_bf16 v[72:75], v[168:171], v[224:227], v[72:75]
	s_setprio 0
	s_setprio 1
	v_mfma_f32_16x16x32_bf16 v[116:119], v[172:175], v[190:193], v[116:119]
	v_mfma_f32_16x16x32_bf16 v[112:115], v[182:185], v[190:193], v[112:115]
	v_mfma_f32_16x16x32_bf16 v[100:103], v[172:175], v[198:201], v[100:103]
	v_mfma_f32_16x16x32_bf16 v[96:99], v[182:185], v[198:201], v[96:99]
	v_mfma_f32_16x16x32_bf16 v[84:87], v[172:175], v[212:215], v[84:87]
	v_mfma_f32_16x16x32_bf16 v[80:83], v[182:185], v[212:215], v[80:83]
	v_mfma_f32_16x16x32_bf16 v[68:71], v[172:175], v[220:223], v[68:71]
	v_mfma_f32_16x16x32_bf16 v[64:67], v[182:185], v[220:223], v[64:67]
	v_mfma_f32_16x16x32_bf16 v[116:119], v[176:179], v[194:197], v[116:119]
	v_mfma_f32_16x16x32_bf16 v[112:115], v[186:189], v[194:197], v[112:115]
	v_mfma_f32_16x16x32_bf16 v[100:103], v[176:179], v[208:211], v[100:103]
	v_mfma_f32_16x16x32_bf16 v[96:99], v[186:189], v[208:211], v[96:99]
	v_mfma_f32_16x16x32_bf16 v[84:87], v[176:179], v[216:219], v[84:87]
	v_mfma_f32_16x16x32_bf16 v[80:83], v[186:189], v[216:219], v[80:83]
	v_mfma_f32_16x16x32_bf16 v[68:71], v[176:179], v[224:227], v[68:71]
	v_mfma_f32_16x16x32_bf16 v[64:67], v[186:189], v[224:227], v[64:67]
	s_setprio 0
	s_barrier
; #define PG8_STAGE(bufoff, gbase, voff) do { _Pragma("unroll") for (int _i = 0; _i < 2; ++_i) \
;         __builtin_amdgcn_global_load_lds((const unsigned*)((const char*)(gbase) + (voff)[_i]), (PG8_LAS unsigned*)(lds + (bufoff) + ldsw + _i * 8192), 16, 0, 0); } while (0)
; #define PG8_LDA(dst, b, h) do { _Pragma("unroll") for (int m = 0; m < 4; ++m) _Pragma("unroll") for (int k = 0; k < 2; ++k) dst[m][k] = *(const PG8_LAS bf16x8*)(lds + PG8_SA(b, h) + aoff + m * 2048 + k * 1024); } while (0)
; #define PG8_MMA(ai, bj, At, Bt) do { __builtin_amdgcn_s_setprio(1); _Pragma("unroll") for (int m = 0; m < 4; ++m) _Pragma("unroll") for (int n = 0; n < 2; ++n) _Pragma("unroll") for (int k = 0; k < 2; ++k) \
;         acc[ai][bj][m][n] = __builtin_amdgcn_mfma_f32_16x16x32_bf16(Bt[n][k], At[m][k], acc[ai][bj][m][n], 0, 0, 0); __builtin_amdgcn_s_setprio(0); } while (0)
; #define PG8_WAIT_V(n) asm volatile("s_waitcnt vmcnt(" #n ")" ::: "memory")
; #define PG8_WAIT_L(n) asm volatile("s_waitcnt lgkmcnt(" #n ")" ::: "memory")
; #define PG8_BAR __builtin_amdgcn_s_barrier()
; #define PG8_SCHED __builtin_amdgcn_sched_barrier(0)
; template <class Epi, class Sched, bool ALIGN_EPI = false, bool SP2 = false>
; __device__ __forceinline__ void gemm_phase(PG8_LAS unsigned char* lds, const Gemm g, const Sched& S, const Epi& E) {
;     ...
;         for (int t = 0; t < nt; t += 2) {
;     ...
;             PG8_LDA(At, 1, 1); PG8_STAGE(PG8_SB(1, 0), b3, voffB); PG8_STAGE(PG8_SB(1, 1), b3 + hstep, voffB); PG8_STAGE(PG8_SA(1, 0), a3, voffA);
;             PG8_WAIT_V(8); PG8_WAIT_L(0); PG8_BAR; PG8_MMA(1, 0, At, B0); PG8_MMA(1, 1, At, B1); PG8_BAR; PG8_SCHED;
	s_add_i32 s3, s3, s43
	v_lshl_add_u64 v[164:165], v[164:165], 0, s[10:11]
	s_mov_b32 m0, s3
	ds_read_b128 v[190:193], v157 offset:49152
	ds_read_b128 v[194:197], v157 offset:50176
	ds_read_b128 v[198:201], v157 offset:51200
	ds_read_b128 v[208:211], v157 offset:52224
	ds_read_b128 v[212:215], v157 offset:53248
	ds_read_b128 v[216:219], v157 offset:54272
	ds_read_b128 v[220:223], v157 offset:55296
	ds_read_b128 v[224:227], v157 offset:56320
	global_load_lds_dwordx4 v[164:165], off
	s_add_i32 m0, s3, 0x2000
	s_add_u32 s14, s50, 0x40080
	v_lshl_add_u64 v[164:165], v[202:203], 0, s[10:11]
	s_addc_u32 s15, s51, 0
	s_add_i32 s3, s33, s43
	global_load_lds_dwordx4 v[164:165], off
	v_lshl_add_u64 v[164:165], s[14:15], 0, v[132:133]
	s_mov_b32 m0, s3
	s_nop 0
	global_load_lds_dwordx4 v[164:165], off
	v_lshl_add_u64 v[164:165], s[14:15], 0, v[128:129]
	s_add_i32 m0, s3, 0x2000
	s_nop 0
	global_load_lds_dwordx4 v[164:165], off
	s_waitcnt vmcnt(6)
	s_waitcnt lgkmcnt(0)
	s_barrier
	s_setprio 1
	s_waitcnt lgkmcnt(0)
	v_mfma_f32_16x16x32_bf16 v[60:63], v[144:147], v[190:193], v[60:63]
	v_mfma_f32_16x16x32_bf16 v[56:59], v[160:163], v[190:193], v[56:59]
	v_mfma_f32_16x16x32_bf16 v[44:47], v[144:147], v[198:201], v[44:47]
	v_mfma_f32_16x16x32_bf16 v[40:43], v[160:163], v[198:201], v[40:43]
	v_mfma_f32_16x16x32_bf16 v[28:31], v[144:147], v[212:215], v[28:31]
	v_mfma_f32_16x16x32_bf16 v[24:27], v[160:163], v[212:215], v[24:27]
	v_mfma_f32_16x16x32_bf16 v[12:15], v[144:147], v[220:223], v[12:15]
	v_mfma_f32_16x16x32_bf16 v[8:11], v[160:163], v[220:223], v[8:11]
	v_mfma_f32_16x16x32_bf16 v[60:63], v[148:151], v[194:197], v[60:63]
	v_mfma_f32_16x16x32_bf16 v[56:59], v[168:171], v[194:197], v[56:59]
	v_mfma_f32_16x16x32_bf16 v[44:47], v[148:151], v[208:211], v[44:47]
	v_mfma_f32_16x16x32_bf16 v[40:43], v[168:171], v[208:211], v[40:43]
	v_mfma_f32_16x16x32_bf16 v[28:31], v[148:151], v[216:219], v[28:31]
	v_mfma_f32_16x16x32_bf16 v[24:27], v[168:171], v[216:219], v[24:27]
	v_lshl_add_u64 v[164:165], v[228:229], 0, s[10:11]
	s_mov_b32 m0, s61
	s_nop 0
	global_load_lds_dwordx4 v[164:165], off
	v_mfma_f32_16x16x32_bf16 v[12:15], v[148:151], v[224:227], v[12:15]
	v_mfma_f32_16x16x32_bf16 v[8:11], v[168:171], v[224:227], v[8:11]
	s_setprio 0
	s_setprio 1
	v_mfma_f32_16x16x32_bf16 v[52:55], v[172:175], v[190:193], v[52:55]
	v_mfma_f32_16x16x32_bf16 v[48:51], v[182:185], v[190:193], v[48:51]
	v_mfma_f32_16x16x32_bf16 v[36:39], v[172:175], v[198:201], v[36:39]
	v_mfma_f32_16x16x32_bf16 v[32:35], v[182:185], v[198:201], v[32:35]
	v_mfma_f32_16x16x32_bf16 v[20:23], v[172:175], v[212:215], v[20:23]
	v_mfma_f32_16x16x32_bf16 v[16:19], v[182:185], v[212:215], v[16:19]
	v_mfma_f32_16x16x32_bf16 v[4:7], v[172:175], v[220:223], v[4:7]
	v_mfma_f32_16x16x32_bf16 v[0:3], v[182:185], v[220:223], v[0:3]
	v_mfma_f32_16x16x32_bf16 v[52:55], v[176:179], v[194:197], v[52:55]
	v_mfma_f32_16x16x32_bf16 v[48:51], v[186:189], v[194:197], v[48:51]
	v_mfma_f32_16x16x32_bf16 v[36:39], v[176:179], v[208:211], v[36:39]
	v_mfma_f32_16x16x32_bf16 v[32:35], v[186:189], v[208:211], v[32:35]
	v_mfma_f32_16x16x32_bf16 v[20:23], v[176:179], v[216:219], v[20:23]
	v_mfma_f32_16x16x32_bf16 v[16:19], v[186:189], v[216:219], v[16:19]
	v_lshl_add_u64 v[164:165], v[230:231], 0, s[10:11]
	s_mov_b32 m0, s62
	s_nop 0
	global_load_lds_dwordx4 v[164:165], off
	v_mfma_f32_16x16x32_bf16 v[4:7], v[176:179], v[224:227], v[4:7]
	v_mfma_f32_16x16x32_bf16 v[0:3], v[186:189], v[224:227], v[0:3]
	s_setprio 0
	s_barrier
	s_add_i32 s89, s89, 2
	s_add_u32 s48, s48, 0x100
	s_addc_u32 s49, s49, 0
	s_add_u32 s87, s87, 0x100
	s_addc_u32 s88, s88, 0
	.p2align 6

; #define PG8_STAGE(bufoff, gbase, voff) do { _Pragma("unroll") for (int _i = 0; _i < 2; ++_i) \
;         __builtin_amdgcn_global_load_lds((const unsigned*)((const char*)(gbase) + (voff)[_i]), (PG8_LAS unsigned*)(lds + (bufoff) + ldsw + _i * 8192), 16, 0, 0); } while (0)
; #define PG8_LDA(dst, b, h) do { _Pragma("unroll") for (int m = 0; m < 4; ++m) _Pragma("unroll") for (int k = 0; k < 2; ++k) dst[m][k] = *(const PG8_LAS bf16x8*)(lds + PG8_SA(b, h) + aoff + m * 2048 + k * 1024); } while (0)
; template <class Epi, class Sched, bool ALIGN_EPI = false, bool SP2 = false>
; __device__ __forceinline__ void gemm_phase(PG8_LAS unsigned char* lds, const Gemm g, const Sched& S, const Epi& E) {
;     ...
;     for (;;) {
;         const bool has_next = S.next(ui + 1, nxt);
;         const char* nA = has_next ? (const char*)g.A + (size_t)nxt.pm * tstep : cA; const char* nB = has_next ? (const char*)g.Bt + (size_t)nxt.pn * tstep : cB;
;         for (int t = 0; t < nt; t += 2) {
;             const bool last = (t == nt - 2);
;             const char* a1 = cA + (size_t)(t + 1) * kstep;
;             const char* a2 = last ? nA : cA + (size_t)(t + 2) * kstep; const char* b2 = last ? nB : cB + (size_t)(t + 2) * kstep;
;             const char* a3 = a2 + kstep; const char* b3 = b2 + kstep;
;             if (last && has_next) S.a_ready(nxt);
;             if constexpr (SP2) {
;             PG8_LDB(B0, 0, 0); PG8_LDB(B1, 0, 1); PG8_SCHED; PG8_LDA(At, 0, 0); PG8_STAGE(PG8_SA(1, 1), a1 + hstep, voffA);
;             PG8_WAIT_V(8); PG8_WAIT_L(0); PG8_BAR; PG8_MMA(0, 0, At, B0); PG8_MMA(0, 1, At, B1); PG8_BAR; PG8_SCHED;
;             PG8_LDA(At, 0, 1); PG8_STAGE(PG8_SB(0, 0), b2, voffB); PG8_STAGE(PG8_SB(0, 1), b2 + hstep, voffB); PG8_STAGE(PG8_SA(0, 0), a2, voffA);
;             PG8_WAIT_V(8); PG8_WAIT_L(0); PG8_BAR; PG8_MMA(1, 0, At, B0); PG8_MMA(1, 1, At, B1); PG8_BAR; PG8_SCHED;
;             PG8_LDB(B0, 1, 0); PG8_LDB(B1, 1, 1); PG8_SCHED; PG8_LDA(At, 1, 0); PG8_STAGE(PG8_SA(0, 1), a2 + hstep, voffA);
;             PG8_WAIT_V(8); PG8_WAIT_L(0); PG8_BAR; PG8_MMA(0, 0, At, B0); PG8_MMA(0, 1, At, B1); PG8_BAR; PG8_SCHED;
;             PG8_LDA(At, 1, 1); PG8_STAGE(PG8_SB(1, 0), b3, voffB); PG8_STAGE(PG8_SB(1, 1), b3 + hstep, voffB); PG8_STAGE(PG8_SA(1, 0), a3, voffA);
;             PG8_WAIT_V(8); PG8_WAIT_L(0); PG8_BAR; PG8_MMA(1, 0, At, B0); PG8_MMA(1, 1, At, B1); PG8_BAR; PG8_SCHED;
.LBB0_268:
	s_add_u32 s91, s50, 0x100
	s_addc_u32 s92, s51, 0
	s_mov_b32 s93, -2
	s_waitcnt lgkmcnt(0)
	ds_read_b128 v[128:131], v165
	ds_read_b128 v[132:135], v165 offset:1024
	ds_read_b128 v[152:155], v165 offset:2048
	ds_read_b128 v[156:159], v165 offset:3072
	ds_read_b128 v[172:175], v168
	ds_read_b128 v[176:179], v168 offset:1024
	ds_read_b128 v[182:185], v168 offset:2048
	ds_read_b128 v[186:189], v168 offset:3072
	s_add_u32 s50, s10, 0x100
	s_addc_u32 s51, s11, 0
	s_cmp_eq_u32 s93, 40
	s_cselect_b32 s57, s1, s51
	s_cselect_b32 s56, s0, s50
	s_cselect_b32 s55, s49, s92
	s_cselect_b32 s54, s48, s91
	v_lshl_add_u64 v[160:161], s[10:11], 0, v[144:145]
	s_add_i32 m0, s58, 0xc000
	ds_read_b128 v[190:193], v169
	ds_read_b128 v[194:197], v169 offset:1024
	ds_read_b128 v[198:201], v169 offset:2048
	ds_read_b128 v[208:211], v169 offset:3072
	ds_read_b128 v[212:215], v169 offset:4096
	ds_read_b128 v[216:219], v169 offset:5120
	ds_read_b128 v[220:223], v169 offset:6144
	ds_read_b128 v[224:227], v169 offset:7168
	global_load_lds_dwordx4 v[160:161], off
	v_lshl_add_u64 v[160:161], s[10:11], 0, v[146:147]
	s_add_i32 m0, s58, 0xe000
	s_nop 0
	global_load_lds_dwordx4 v[160:161], off
	s_waitcnt vmcnt(8)
	s_waitcnt lgkmcnt(0)
	s_barrier
	s_setprio 1
	s_waitcnt lgkmcnt(0)
	v_mfma_f32_16x16x32_bf16 v[124:127], v[128:131], v[190:193], 0
	v_mfma_f32_16x16x32_bf16 v[120:123], v[152:155], v[190:193], 0
	v_mfma_f32_16x16x32_bf16 v[108:111], v[128:131], v[198:201], 0
	v_mfma_f32_16x16x32_bf16 v[104:107], v[152:155], v[198:201], 0
	v_mfma_f32_16x16x32_bf16 v[92:95], v[128:131], v[212:215], 0
	v_mfma_f32_16x16x32_bf16 v[88:91], v[152:155], v[212:215], 0
	v_mfma_f32_16x16x32_bf16 v[76:79], v[128:131], v[220:223], 0
	v_mfma_f32_16x16x32_bf16 v[72:75], v[152:155], v[220:223], 0
	v_mfma_f32_16x16x32_bf16 v[124:127], v[132:135], v[194:197], v[124:127]
	v_mfma_f32_16x16x32_bf16 v[120:123], v[156:159], v[194:197], v[120:123]
	v_mfma_f32_16x16x32_bf16 v[108:111], v[132:135], v[208:211], v[108:111]
	v_mfma_f32_16x16x32_bf16 v[104:107], v[156:159], v[208:211], v[104:107]
	v_mfma_f32_16x16x32_bf16 v[92:95], v[132:135], v[216:219], v[92:95]
	v_mfma_f32_16x16x32_bf16 v[88:91], v[156:159], v[216:219], v[88:91]
	v_mfma_f32_16x16x32_bf16 v[76:79], v[132:135], v[224:227], v[76:79]
	v_mfma_f32_16x16x32_bf16 v[72:75], v[156:159], v[224:227], v[72:75]
	s_setprio 0
	s_setprio 1
	v_mfma_f32_16x16x32_bf16 v[116:119], v[172:175], v[190:193], 0
	v_mfma_f32_16x16x32_bf16 v[112:115], v[182:185], v[190:193], 0
	v_mfma_f32_16x16x32_bf16 v[100:103], v[172:175], v[198:201], 0
	v_mfma_f32_16x16x32_bf16 v[96:99], v[182:185], v[198:201], 0
	v_mfma_f32_16x16x32_bf16 v[84:87], v[172:175], v[212:215], 0
	v_mfma_f32_16x16x32_bf16 v[80:83], v[182:185], v[212:215], 0
	v_mfma_f32_16x16x32_bf16 v[68:71], v[172:175], v[220:223], 0
	v_mfma_f32_16x16x32_bf16 v[64:67], v[182:185], v[220:223], 0
	v_mfma_f32_16x16x32_bf16 v[116:119], v[176:179], v[194:197], v[116:119]
	v_mfma_f32_16x16x32_bf16 v[112:115], v[186:189], v[194:197], v[112:115]
	v_mfma_f32_16x16x32_bf16 v[100:103], v[176:179], v[208:211], v[100:103]
	v_mfma_f32_16x16x32_bf16 v[96:99], v[186:189], v[208:211], v[96:99]
	v_mfma_f32_16x16x32_bf16 v[84:87], v[176:179], v[216:219], v[84:87]
	v_mfma_f32_16x16x32_bf16 v[80:83], v[186:189], v[216:219], v[80:83]
	v_mfma_f32_16x16x32_bf16 v[68:71], v[176:179], v[224:227], v[68:71]
	v_mfma_f32_16x16x32_bf16 v[64:67], v[186:189], v[224:227], v[64:67]
	s_setprio 0
	s_barrier
	s_add_i32 s3, s65, s43
	v_lshl_add_u64 v[160:161], s[54:55], 0, v[138:139]
	s_mov_b32 m0, s3
	ds_read_b128 v[190:193], v169 offset:16384
	ds_read_b128 v[194:197], v169 offset:17408
	ds_read_b128 v[198:201], v169 offset:18432
	ds_read_b128 v[208:211], v169 offset:19456
	ds_read_b128 v[212:215], v169 offset:20480
	ds_read_b128 v[216:219], v169 offset:21504
	ds_read_b128 v[220:223], v169 offset:22528
	ds_read_b128 v[224:227], v169 offset:23552
	global_load_lds_dwordx4 v[160:161], off
	s_add_i32 m0, s3, 0x2000
	s_add_u32 s10, s54, 0xb0000
	v_lshl_add_u64 v[202:203], s[54:55], 0, v[142:143]
	s_addc_u32 s11, s55, 0
	s_add_i32 s3, s66, s43
	global_load_lds_dwordx4 v[202:203], off
	v_lshl_add_u64 v[228:229], s[10:11], 0, v[138:139]
	s_mov_b32 m0, s3
	global_load_lds_dwordx4 v[228:229], off
	v_lshl_add_u64 v[228:229], s[10:11], 0, v[142:143]
	s_add_i32 m0, s3, 0x2000
	s_nop 0
	global_load_lds_dwordx4 v[228:229], off
	s_waitcnt vmcnt(6)
	s_waitcnt lgkmcnt(0)
	s_barrier
; #define PG8_STAGE(bufoff, gbase, voff) do { _Pragma("unroll") for (int _i = 0; _i < 2; ++_i) \
;         __builtin_amdgcn_global_load_lds((const unsigned*)((const char*)(gbase) + (voff)[_i]), (PG8_LAS unsigned*)(lds + (bufoff) + ldsw + _i * 8192), 16, 0, 0); } while (0)
; #define PG8_LDA(dst, b, h) do { _Pragma("unroll") for (int m = 0; m < 4; ++m) _Pragma("unroll") for (int k = 0; k < 2; ++k) dst[m][k] = *(const PG8_LAS bf16x8*)(lds + PG8_SA(b, h) + aoff + m * 2048 + k * 1024); } while (0)
; #define PG8_LDB(dst, b, h) do { _Pragma("unroll") for (int n = 0; n < 2; ++n) _Pragma("unroll") for (int k = 0; k < 2; ++k) dst[n][k] = *(const PG8_LAS bf16x8*)(lds + PG8_SB(b, h) + boff + n * 2048 + k * 1024); } while (0)
; #define PG8_MMA(ai, bj, At, Bt) do { __builtin_amdgcn_s_setprio(1); _Pragma("unroll") for (int m = 0; m < 4; ++m) _Pragma("unroll") for (int n = 0; n < 2; ++n) _Pragma("unroll") for (int k = 0; k < 2; ++k) \
;         acc[ai][bj][m][n] = __builtin_amdgcn_mfma_f32_16x16x32_bf16(Bt[n][k], At[m][k], acc[ai][bj][m][n], 0, 0, 0); __builtin_amdgcn_s_setprio(0); } while (0)
; #define PG8_WAIT_V(n) asm volatile("s_waitcnt vmcnt(" #n ")" ::: "memory")
; #define PG8_WAIT_L(n) asm volatile("s_waitcnt lgkmcnt(" #n ")" ::: "memory")
; #define PG8_BAR __builtin_amdgcn_s_barrier()
; #define PG8_SCHED __builtin_amdgcn_sched_barrier(0)
; template <class Epi, class Sched, bool ALIGN_EPI = false, bool SP2 = false>
; __device__ __forceinline__ void gemm_phase(PG8_LAS unsigned char* lds, const Gemm g, const Sched& S, const Epi& E) {
;     ...
;             PG8_WAIT_V(8); PG8_WAIT_L(0); PG8_BAR; PG8_MMA(0, 0, At, B0); PG8_MMA(0, 1, At, B1); PG8_BAR; PG8_SCHED;
;             PG8_LDA(At, 0, 1); PG8_STAGE(PG8_SB(0, 0), b2, voffB); PG8_STAGE(PG8_SB(0, 1), b2 + hstep, voffB); PG8_STAGE(PG8_SA(0, 0), a2, voffA);
;             PG8_WAIT_V(8); PG8_WAIT_L(0); PG8_BAR; PG8_MMA(1, 0, At, B0); PG8_MMA(1, 1, At, B1); PG8_BAR; PG8_SCHED;
;             PG8_LDB(B0, 1, 0); PG8_LDB(B1, 1, 1); PG8_SCHED; PG8_LDA(At, 1, 0); PG8_STAGE(PG8_SA(0, 1), a2 + hstep, voffA);
;             PG8_WAIT_V(8); PG8_WAIT_L(0); PG8_BAR; PG8_MMA(0, 0, At, B0); PG8_MMA(0, 1, At, B1); PG8_BAR; PG8_SCHED;
;             PG8_LDA(At, 1, 1); PG8_STAGE(PG8_SB(1, 0), b3, voffB); PG8_STAGE(PG8_SB(1, 1), b3 + hstep, voffB); PG8_STAGE(PG8_SA(1, 0), a3, voffA);
	s_setprio 1
	s_waitcnt lgkmcnt(0)
	v_mfma_f32_16x16x32_bf16 v[60:63], v[128:131], v[190:193], 0
	v_mfma_f32_16x16x32_bf16 v[56:59], v[152:155], v[190:193], 0
	v_mfma_f32_16x16x32_bf16 v[44:47], v[128:131], v[198:201], 0
	v_mfma_f32_16x16x32_bf16 v[40:43], v[152:155], v[198:201], 0
	v_mfma_f32_16x16x32_bf16 v[28:31], v[128:131], v[212:215], 0
	v_mfma_f32_16x16x32_bf16 v[24:27], v[152:155], v[212:215], 0
	v_mfma_f32_16x16x32_bf16 v[12:15], v[128:131], v[220:223], 0
	v_mfma_f32_16x16x32_bf16 v[8:11], v[152:155], v[220:223], 0
	v_mfma_f32_16x16x32_bf16 v[60:63], v[132:135], v[194:197], v[60:63]
	v_mfma_f32_16x16x32_bf16 v[56:59], v[156:159], v[194:197], v[56:59]
	v_mfma_f32_16x16x32_bf16 v[44:47], v[132:135], v[208:211], v[44:47]
	v_mfma_f32_16x16x32_bf16 v[40:43], v[156:159], v[208:211], v[40:43]
	v_mfma_f32_16x16x32_bf16 v[28:31], v[132:135], v[216:219], v[28:31]
	v_mfma_f32_16x16x32_bf16 v[24:27], v[156:159], v[216:219], v[24:27]
	v_lshl_add_u64 v[228:229], s[56:57], 0, v[136:137]
	s_mov_b32 m0, s58
	s_nop 0
	global_load_lds_dwordx4 v[228:229], off
	v_mfma_f32_16x16x32_bf16 v[12:15], v[132:135], v[224:227], v[12:15]
	v_mfma_f32_16x16x32_bf16 v[8:11], v[156:159], v[224:227], v[8:11]
	s_setprio 0
	s_setprio 1
	v_mfma_f32_16x16x32_bf16 v[52:55], v[172:175], v[190:193], 0
	v_mfma_f32_16x16x32_bf16 v[48:51], v[182:185], v[190:193], 0
	v_mfma_f32_16x16x32_bf16 v[36:39], v[172:175], v[198:201], 0
	v_mfma_f32_16x16x32_bf16 v[32:35], v[182:185], v[198:201], 0
	v_mfma_f32_16x16x32_bf16 v[20:23], v[172:175], v[212:215], 0
	v_mfma_f32_16x16x32_bf16 v[16:19], v[182:185], v[212:215], 0
	v_mfma_f32_16x16x32_bf16 v[4:7], v[172:175], v[220:223], 0
	v_mfma_f32_16x16x32_bf16 v[0:3], v[182:185], v[220:223], 0
	v_mfma_f32_16x16x32_bf16 v[52:55], v[176:179], v[194:197], v[52:55]
	v_mfma_f32_16x16x32_bf16 v[48:51], v[186:189], v[194:197], v[48:51]
	v_mfma_f32_16x16x32_bf16 v[36:39], v[176:179], v[208:211], v[36:39]
	v_mfma_f32_16x16x32_bf16 v[32:35], v[186:189], v[208:211], v[32:35]
	v_mfma_f32_16x16x32_bf16 v[20:23], v[176:179], v[216:219], v[20:23]
	v_mfma_f32_16x16x32_bf16 v[16:19], v[186:189], v[216:219], v[16:19]
	v_lshl_add_u64 v[230:231], s[56:57], 0, v[140:141]
	s_mov_b32 m0, s59
	s_nop 0
	global_load_lds_dwordx4 v[230:231], off
	v_mfma_f32_16x16x32_bf16 v[4:7], v[176:179], v[224:227], v[4:7]
	v_mfma_f32_16x16x32_bf16 v[0:3], v[186:189], v[224:227], v[0:3]
	s_setprio 0
	s_barrier
	s_add_i32 s3, 0, 0x18000
	s_add_i32 s14, 0, 0x1c000
	v_add_u32_e32 v156, s3, v163
	v_add_u32_e32 v171, s14, v163
	ds_read_b128 v[128:131], v156
	ds_read_b128 v[132:135], v156 offset:1024
	ds_read_b128 v[152:155], v156 offset:2048
	ds_read_b128 v[156:159], v156 offset:3072
	ds_read_b128 v[172:175], v171
	ds_read_b128 v[176:179], v171 offset:1024
	ds_read_b128 v[182:185], v171 offset:2048
	ds_read_b128 v[186:189], v171 offset:3072
	s_add_u32 s10, s56, 0xb0000
	s_addc_u32 s11, s57, 0
	s_mov_b32 m0, s60
	v_lshl_add_u64 v[232:233], s[10:11], 0, v[136:137]
	ds_read_b128 v[190:193], v169 offset:32768
	ds_read_b128 v[194:197], v169 offset:33792
	ds_read_b128 v[198:201], v169 offset:34816
	ds_read_b128 v[208:211], v169 offset:35840
	ds_read_b128 v[212:215], v169 offset:36864
	ds_read_b128 v[216:219], v169 offset:37888
	ds_read_b128 v[220:223], v169 offset:38912
	ds_read_b128 v[224:227], v169 offset:39936
	global_load_lds_dwordx4 v[232:233], off
	v_lshl_add_u64 v[232:233], s[10:11], 0, v[140:141]
	s_mov_b32 m0, s61
	s_nop 0
	global_load_lds_dwordx4 v[232:233], off
	s_waitcnt vmcnt(8)
	s_waitcnt lgkmcnt(0)
	s_barrier
	s_setprio 1
	s_waitcnt lgkmcnt(0)
	v_mfma_f32_16x16x32_bf16 v[124:127], v[128:131], v[190:193], v[124:127]
	v_mfma_f32_16x16x32_bf16 v[120:123], v[152:155], v[190:193], v[120:123]
	v_mfma_f32_16x16x32_bf16 v[108:111], v[128:131], v[198:201], v[108:111]
	v_mfma_f32_16x16x32_bf16 v[104:107], v[152:155], v[198:201], v[104:107]
	v_mfma_f32_16x16x32_bf16 v[92:95], v[128:131], v[212:215], v[92:95]
	v_mfma_f32_16x16x32_bf16 v[88:91], v[152:155], v[212:215], v[88:91]
	v_mfma_f32_16x16x32_bf16 v[76:79], v[128:131], v[220:223], v[76:79]
	v_mfma_f32_16x16x32_bf16 v[72:75], v[152:155], v[220:223], v[72:75]
	v_mfma_f32_16x16x32_bf16 v[124:127], v[132:135], v[194:197], v[124:127]
	v_mfma_f32_16x16x32_bf16 v[120:123], v[156:159], v[194:197], v[120:123]
	v_mfma_f32_16x16x32_bf16 v[108:111], v[132:135], v[208:211], v[108:111]
	v_mfma_f32_16x16x32_bf16 v[104:107], v[156:159], v[208:211], v[104:107]
	v_mfma_f32_16x16x32_bf16 v[92:95], v[132:135], v[216:219], v[92:95]
	v_mfma_f32_16x16x32_bf16 v[88:91], v[156:159], v[216:219], v[88:91]
	v_mfma_f32_16x16x32_bf16 v[76:79], v[132:135], v[224:227], v[76:79]
	v_mfma_f32_16x16x32_bf16 v[72:75], v[156:159], v[224:227], v[72:75]
	s_setprio 0
	s_setprio 1
	v_mfma_f32_16x16x32_bf16 v[116:119], v[172:175], v[190:193], v[116:119]
	v_mfma_f32_16x16x32_bf16 v[112:115], v[182:185], v[190:193], v[112:115]
	v_mfma_f32_16x16x32_bf16 v[100:103], v[172:175], v[198:201], v[100:103]
	v_mfma_f32_16x16x32_bf16 v[96:99], v[182:185], v[198:201], v[96:99]
	v_mfma_f32_16x16x32_bf16 v[84:87], v[172:175], v[212:215], v[84:87]
	v_mfma_f32_16x16x32_bf16 v[80:83], v[182:185], v[212:215], v[80:83]
	v_mfma_f32_16x16x32_bf16 v[68:71], v[172:175], v[220:223], v[68:71]
	v_mfma_f32_16x16x32_bf16 v[64:67], v[182:185], v[220:223], v[64:67]
	v_mfma_f32_16x16x32_bf16 v[116:119], v[176:179], v[194:197], v[116:119]
	v_mfma_f32_16x16x32_bf16 v[112:115], v[186:189], v[194:197], v[112:115]
	v_mfma_f32_16x16x32_bf16 v[100:103], v[176:179], v[208:211], v[100:103]
	v_mfma_f32_16x16x32_bf16 v[96:99], v[186:189], v[208:211], v[96:99]
	v_mfma_f32_16x16x32_bf16 v[84:87], v[176:179], v[216:219], v[84:87]
	v_mfma_f32_16x16x32_bf16 v[80:83], v[186:189], v[216:219], v[80:83]
	v_mfma_f32_16x16x32_bf16 v[68:71], v[176:179], v[224:227], v[68:71]
	v_mfma_f32_16x16x32_bf16 v[64:67], v[186:189], v[224:227], v[64:67]
	s_setprio 0
	s_barrier
; #define PG8_STAGE(bufoff, gbase, voff) do { _Pragma("unroll") for (int _i = 0; _i < 2; ++_i) \
;         __builtin_amdgcn_global_load_lds((const unsigned*)((const char*)(gbase) + (voff)[_i]), (PG8_LAS unsigned*)(lds + (bufoff) + ldsw + _i * 8192), 16, 0, 0); } while (0)
; #define PG8_LDA(dst, b, h) do { _Pragma("unroll") for (int m = 0; m < 4; ++m) _Pragma("unroll") for (int k = 0; k < 2; ++k) dst[m][k] = *(const PG8_LAS bf16x8*)(lds + PG8_SA(b, h) + aoff + m * 2048 + k * 1024); } while (0)
; #define PG8_MMA(ai, bj, At, Bt) do { __builtin_amdgcn_s_setprio(1); _Pragma("unroll") for (int m = 0; m < 4; ++m) _Pragma("unroll") for (int n = 0; n < 2; ++n) _Pragma("unroll") for (int k = 0; k < 2; ++k) \
;         acc[ai][bj][m][n] = __builtin_amdgcn_mfma_f32_16x16x32_bf16(Bt[n][k], At[m][k], acc[ai][bj][m][n], 0, 0, 0); __builtin_amdgcn_s_setprio(0); } while (0)
; #define PG8_WAIT_V(n) asm volatile("s_waitcnt vmcnt(" #n ")" ::: "memory")
; #define PG8_WAIT_L(n) asm volatile("s_waitcnt lgkmcnt(" #n ")" ::: "memory")
; #define PG8_BAR __builtin_amdgcn_s_barrier()
; #define PG8_SCHED __builtin_amdgcn_sched_barrier(0)
; template <class Epi, class Sched, bool ALIGN_EPI = false, bool SP2 = false>
; __device__ __forceinline__ void gemm_phase(PG8_LAS unsigned char* lds, const Gemm g, const Sched& S, const Epi& E) {
;     ...
;         for (int t = 0; t < nt; t += 2) {
;     ...
;             PG8_LDA(At, 1, 1); PG8_STAGE(PG8_SB(1, 0), b3, voffB); PG8_STAGE(PG8_SB(1, 1), b3 + hstep, voffB); PG8_STAGE(PG8_SA(1, 0), a3, voffA);
;             PG8_WAIT_V(8); PG8_WAIT_L(0); PG8_BAR; PG8_MMA(1, 0, At, B0); PG8_MMA(1, 1, At, B1); PG8_BAR; PG8_SCHED;
	s_add_i32 s3, s3, s43
	v_lshl_add_u64 v[160:161], v[160:161], 0, s[40:41]
	s_mov_b32 m0, s3
	ds_read_b128 v[190:193], v169 offset:49152
	ds_read_b128 v[194:197], v169 offset:50176
	ds_read_b128 v[198:201], v169 offset:51200
	ds_read_b128 v[208:211], v169 offset:52224
	ds_read_b128 v[212:215], v169 offset:53248
	ds_read_b128 v[216:219], v169 offset:54272
	ds_read_b128 v[220:223], v169 offset:55296
	ds_read_b128 v[224:227], v169 offset:56320
	global_load_lds_dwordx4 v[160:161], off
	s_add_i32 m0, s3, 0x2000
	s_add_u32 s10, s54, 0xb0080
	v_lshl_add_u64 v[160:161], v[202:203], 0, s[40:41]
	s_addc_u32 s11, s55, 0
	s_add_i32 s3, s14, s43
	global_load_lds_dwordx4 v[160:161], off
	v_lshl_add_u64 v[160:161], s[10:11], 0, v[138:139]
	s_mov_b32 m0, s3
	s_nop 0
	global_load_lds_dwordx4 v[160:161], off
	v_lshl_add_u64 v[160:161], s[10:11], 0, v[142:143]
	s_add_i32 m0, s3, 0x2000
	s_nop 0
	global_load_lds_dwordx4 v[160:161], off
	s_waitcnt vmcnt(6)
	s_waitcnt lgkmcnt(0)
	s_barrier
	s_setprio 1
	s_waitcnt lgkmcnt(0)
	v_mfma_f32_16x16x32_bf16 v[60:63], v[128:131], v[190:193], v[60:63]
	v_mfma_f32_16x16x32_bf16 v[56:59], v[152:155], v[190:193], v[56:59]
	v_mfma_f32_16x16x32_bf16 v[44:47], v[128:131], v[198:201], v[44:47]
	v_mfma_f32_16x16x32_bf16 v[40:43], v[152:155], v[198:201], v[40:43]
	v_mfma_f32_16x16x32_bf16 v[28:31], v[128:131], v[212:215], v[28:31]
	v_mfma_f32_16x16x32_bf16 v[24:27], v[152:155], v[212:215], v[24:27]
	v_mfma_f32_16x16x32_bf16 v[12:15], v[128:131], v[220:223], v[12:15]
	v_mfma_f32_16x16x32_bf16 v[8:11], v[152:155], v[220:223], v[8:11]
	v_mfma_f32_16x16x32_bf16 v[60:63], v[132:135], v[194:197], v[60:63]
	v_mfma_f32_16x16x32_bf16 v[56:59], v[156:159], v[194:197], v[56:59]
	v_mfma_f32_16x16x32_bf16 v[44:47], v[132:135], v[208:211], v[44:47]
	v_mfma_f32_16x16x32_bf16 v[40:43], v[156:159], v[208:211], v[40:43]
	v_mfma_f32_16x16x32_bf16 v[28:31], v[132:135], v[216:219], v[28:31]
	v_mfma_f32_16x16x32_bf16 v[24:27], v[156:159], v[216:219], v[24:27]
	v_lshl_add_u64 v[160:161], v[228:229], 0, s[40:41]
	s_mov_b32 m0, s63
	s_nop 0
	global_load_lds_dwordx4 v[160:161], off
	v_mfma_f32_16x16x32_bf16 v[12:15], v[132:135], v[224:227], v[12:15]
	v_mfma_f32_16x16x32_bf16 v[8:11], v[156:159], v[224:227], v[8:11]
	s_setprio 0
	s_setprio 1
	v_mfma_f32_16x16x32_bf16 v[52:55], v[172:175], v[190:193], v[52:55]
	v_mfma_f32_16x16x32_bf16 v[48:51], v[182:185], v[190:193], v[48:51]
	v_mfma_f32_16x16x32_bf16 v[36:39], v[172:175], v[198:201], v[36:39]
	v_mfma_f32_16x16x32_bf16 v[32:35], v[182:185], v[198:201], v[32:35]
	v_mfma_f32_16x16x32_bf16 v[20:23], v[172:175], v[212:215], v[20:23]
	v_mfma_f32_16x16x32_bf16 v[16:19], v[182:185], v[212:215], v[16:19]
	v_mfma_f32_16x16x32_bf16 v[4:7], v[172:175], v[220:223], v[4:7]
	v_mfma_f32_16x16x32_bf16 v[0:3], v[182:185], v[220:223], v[0:3]
	v_mfma_f32_16x16x32_bf16 v[52:55], v[176:179], v[194:197], v[52:55]
	v_mfma_f32_16x16x32_bf16 v[48:51], v[186:189], v[194:197], v[48:51]
	v_mfma_f32_16x16x32_bf16 v[36:39], v[176:179], v[208:211], v[36:39]
	v_mfma_f32_16x16x32_bf16 v[32:35], v[186:189], v[208:211], v[32:35]
	v_mfma_f32_16x16x32_bf16 v[20:23], v[176:179], v[216:219], v[20:23]
	v_mfma_f32_16x16x32_bf16 v[16:19], v[186:189], v[216:219], v[16:19]
	v_lshl_add_u64 v[160:161], v[230:231], 0, s[40:41]
	s_mov_b32 m0, s64
	s_nop 0
	global_load_lds_dwordx4 v[160:161], off
	v_mfma_f32_16x16x32_bf16 v[4:7], v[176:179], v[224:227], v[4:7]
	v_mfma_f32_16x16x32_bf16 v[0:3], v[186:189], v[224:227], v[0:3]
	s_setprio 0
	s_barrier
	s_add_i32 s93, s93, 2
	s_add_u32 s91, s91, 0x100
	s_addc_u32 s92, s92, 0
	s_mov_b64 s[10:11], s[50:51]
	.p2align 6

; #define PG8_STAGE(bufoff, gbase, voff) do { _Pragma("unroll") for (int _i = 0; _i < 2; ++_i) \
;         __builtin_amdgcn_global_load_lds((const unsigned*)((const char*)(gbase) + (voff)[_i]), (PG8_LAS unsigned*)(lds + (bufoff) + ldsw + _i * 8192), 16, 0, 0); } while (0)
; #define PG8_LDA(dst, b, h) do { _Pragma("unroll") for (int m = 0; m < 4; ++m) _Pragma("unroll") for (int k = 0; k < 2; ++k) dst[m][k] = *(const PG8_LAS bf16x8*)(lds + PG8_SA(b, h) + aoff + m * 2048 + k * 1024); } while (0)
; template <class Epi, class Sched, bool ALIGN_EPI = false, bool SP2 = false>
; __device__ __forceinline__ void gemm_phase(PG8_LAS unsigned char* lds, const Gemm g, const Sched& S, const Epi& E) {
;     ...
;     for (;;) {
;         const bool has_next = S.next(ui + 1, nxt);
;         const char* nA = has_next ? (const char*)g.A + (size_t)nxt.pm * tstep : cA; const char* nB = has_next ? (const char*)g.Bt + (size_t)nxt.pn * tstep : cB;
;         for (int t = 0; t < nt; t += 2) {
;             const bool last = (t == nt - 2);
;             const char* a1 = cA + (size_t)(t + 1) * kstep;
;             const char* a2 = last ? nA : cA + (size_t)(t + 2) * kstep; const char* b2 = last ? nB : cB + (size_t)(t + 2) * kstep;
;             const char* a3 = a2 + kstep; const char* b3 = b2 + kstep;
;             if (last && has_next) S.a_ready(nxt);
;             if constexpr (SP2) {
;             PG8_LDB(B0, 0, 0); PG8_LDB(B1, 0, 1); PG8_SCHED; PG8_LDA(At, 0, 0); PG8_STAGE(PG8_SA(1, 1), a1 + hstep, voffA);
;             PG8_WAIT_V(8); PG8_WAIT_L(0); PG8_BAR; PG8_MMA(0, 0, At, B0); PG8_MMA(0, 1, At, B1); PG8_BAR; PG8_SCHED;
;             PG8_LDA(At, 0, 1); PG8_STAGE(PG8_SB(0, 0), b2, voffB); PG8_STAGE(PG8_SB(0, 1), b2 + hstep, voffB); PG8_STAGE(PG8_SA(0, 0), a2, voffA);
;             PG8_WAIT_V(8); PG8_WAIT_L(0); PG8_BAR; PG8_MMA(1, 0, At, B0); PG8_MMA(1, 1, At, B1); PG8_BAR; PG8_SCHED;
;             PG8_LDB(B0, 1, 0); PG8_LDB(B1, 1, 1); PG8_SCHED; PG8_LDA(At, 1, 0); PG8_STAGE(PG8_SA(0, 1), a2 + hstep, voffA);
;             PG8_WAIT_V(8); PG8_WAIT_L(0); PG8_BAR; PG8_MMA(0, 0, At, B0); PG8_MMA(0, 1, At, B1); PG8_BAR; PG8_SCHED;
;             PG8_LDA(At, 1, 1); PG8_STAGE(PG8_SB(1, 0), b3, voffB); PG8_STAGE(PG8_SB(1, 1), b3 + hstep, voffB); PG8_STAGE(PG8_SA(1, 0), a3, voffA);
;             PG8_WAIT_V(8); PG8_WAIT_L(0); PG8_BAR; PG8_MMA(1, 0, At, B0); PG8_MMA(1, 1, At, B1); PG8_BAR; PG8_SCHED;
.LBB0_416:
	s_ashr_i32 s45, s44, 31
	s_lshl_b64 s[14:15], s[44:45], 19
	s_add_u32 s48, s22, s14
	s_addc_u32 s49, s23, s15
	s_and_b64 s[14:15], s[6:7], exec
	s_cselect_b32 s45, s49, s55
	s_cselect_b32 s89, s48, s54
	s_ashr_i32 s41, s40, 31
	s_lshl_b64 s[14:15], s[40:41], 19
	s_add_u32 s50, s84, s14
	s_addc_u32 s51, s85, s15
	s_and_b64 s[14:15], s[6:7], exec
	s_cselect_b32 s41, s51, s57
	s_cselect_b32 s90, s50, s56
	s_add_u32 s54, s54, 0x40080
	s_addc_u32 s55, s55, 0
	s_add_u32 s91, s56, 0x100
	s_addc_u32 s92, s57, 0
	s_mov_b32 s93, -2
	ds_read_b128 v[154:157], v169
	ds_read_b128 v[158:161], v169 offset:1024
	ds_read_b128 v[162:165], v169 offset:2048
	ds_read_b128 v[174:177], v169 offset:3072
	ds_read_b128 v[182:185], v170
	ds_read_b128 v[186:189], v170 offset:1024
	ds_read_b128 v[190:193], v170 offset:2048
	ds_read_b128 v[194:197], v170 offset:3072
	s_add_u32 s3, s54, 0xfffc0080
	s_addc_u32 s14, s55, -1
	s_cmp_eq_u32 s93, 12
	s_cselect_b32 s59, s45, s14
	s_cselect_b32 s58, s89, s3
	s_cselect_b32 s57, s41, s92
	s_cselect_b32 s56, s90, s91
	v_lshl_add_u64 v[178:179], s[54:55], 0, v[146:147]
	s_add_i32 m0, s60, 0xc000
	ds_read_b128 v[198:201], v171
	ds_read_b128 v[208:211], v171 offset:1024
	ds_read_b128 v[212:215], v171 offset:2048
	ds_read_b128 v[216:219], v171 offset:3072
	ds_read_b128 v[220:223], v171 offset:4096
	ds_read_b128 v[224:227], v171 offset:5120
	ds_read_b128 v[228:231], v171 offset:6144
	ds_read_b128 v[232:235], v171 offset:7168
	global_load_lds_dwordx4 v[178:179], off
	v_lshl_add_u64 v[178:179], s[54:55], 0, v[148:149]
	s_add_i32 m0, s60, 0xe000
	s_nop 0
	global_load_lds_dwordx4 v[178:179], off
	s_waitcnt vmcnt(8)
	s_waitcnt lgkmcnt(0)
	s_barrier
	s_setprio 1
	s_waitcnt lgkmcnt(0)
	v_mfma_f32_16x16x32_bf16 v[124:127], v[154:157], v[198:201], 0
	v_mfma_f32_16x16x32_bf16 v[120:123], v[162:165], v[198:201], 0
	v_mfma_f32_16x16x32_bf16 v[116:119], v[154:157], v[212:215], 0
	v_mfma_f32_16x16x32_bf16 v[112:115], v[162:165], v[212:215], 0
	v_mfma_f32_16x16x32_bf16 v[108:111], v[154:157], v[220:223], 0
	v_mfma_f32_16x16x32_bf16 v[104:107], v[162:165], v[220:223], 0
	v_mfma_f32_16x16x32_bf16 v[100:103], v[154:157], v[228:231], 0
	v_mfma_f32_16x16x32_bf16 v[96:99], v[162:165], v[228:231], 0
	v_mfma_f32_16x16x32_bf16 v[124:127], v[158:161], v[208:211], v[124:127]
	v_mfma_f32_16x16x32_bf16 v[120:123], v[174:177], v[208:211], v[120:123]
	v_mfma_f32_16x16x32_bf16 v[116:119], v[158:161], v[216:219], v[116:119]
	v_mfma_f32_16x16x32_bf16 v[112:115], v[174:177], v[216:219], v[112:115]
	v_mfma_f32_16x16x32_bf16 v[108:111], v[158:161], v[224:227], v[108:111]
	v_mfma_f32_16x16x32_bf16 v[104:107], v[174:177], v[224:227], v[104:107]
	v_mfma_f32_16x16x32_bf16 v[100:103], v[158:161], v[232:235], v[100:103]
	v_mfma_f32_16x16x32_bf16 v[96:99], v[174:177], v[232:235], v[96:99]
	s_setprio 0
	s_setprio 1
	v_mfma_f32_16x16x32_bf16 v[68:71], v[182:185], v[198:201], 0
	v_mfma_f32_16x16x32_bf16 v[64:67], v[190:193], v[198:201], 0
	v_mfma_f32_16x16x32_bf16 v[52:55], v[182:185], v[212:215], 0
	v_mfma_f32_16x16x32_bf16 v[48:51], v[190:193], v[212:215], 0
	v_mfma_f32_16x16x32_bf16 v[44:47], v[182:185], v[220:223], 0
	v_mfma_f32_16x16x32_bf16 v[40:43], v[190:193], v[220:223], 0
	v_mfma_f32_16x16x32_bf16 v[36:39], v[182:185], v[228:231], 0
	v_mfma_f32_16x16x32_bf16 v[32:35], v[190:193], v[228:231], 0
	v_mfma_f32_16x16x32_bf16 v[68:71], v[186:189], v[208:211], v[68:71]
	v_mfma_f32_16x16x32_bf16 v[64:67], v[194:197], v[208:211], v[64:67]
	v_mfma_f32_16x16x32_bf16 v[52:55], v[186:189], v[216:219], v[52:55]
	v_mfma_f32_16x16x32_bf16 v[48:51], v[194:197], v[216:219], v[48:51]
	v_mfma_f32_16x16x32_bf16 v[44:47], v[186:189], v[224:227], v[44:47]
	v_mfma_f32_16x16x32_bf16 v[40:43], v[194:197], v[224:227], v[40:43]
	v_mfma_f32_16x16x32_bf16 v[36:39], v[186:189], v[232:235], v[36:39]
	v_mfma_f32_16x16x32_bf16 v[32:35], v[194:197], v[232:235], v[32:35]
	s_setprio 0
	s_barrier
	s_add_i32 s3, s86, s34
	v_lshl_add_u64 v[178:179], s[56:57], 0, v[132:133]
	s_mov_b32 m0, s3
	ds_read_b128 v[198:201], v171 offset:16384
	ds_read_b128 v[208:211], v171 offset:17408
	ds_read_b128 v[212:215], v171 offset:18432
	ds_read_b128 v[216:219], v171 offset:19456
	ds_read_b128 v[220:223], v171 offset:20480
	ds_read_b128 v[224:227], v171 offset:21504
	ds_read_b128 v[228:231], v171 offset:22528
	ds_read_b128 v[232:235], v171 offset:23552
	global_load_lds_dwordx4 v[178:179], off
	s_add_i32 m0, s3, 0x2000
	s_add_u32 s14, s56, 0x40000
	v_lshl_add_u64 v[202:203], s[56:57], 0, v[128:129]
	s_addc_u32 s15, s57, 0
	s_add_i32 s3, s87, s34
	global_load_lds_dwordx4 v[202:203], off
	v_lshl_add_u64 v[236:237], s[14:15], 0, v[132:133]
	s_mov_b32 m0, s3
	global_load_lds_dwordx4 v[236:237], off
	v_lshl_add_u64 v[236:237], s[14:15], 0, v[128:129]
	s_add_i32 m0, s3, 0x2000
	s_nop 0
	global_load_lds_dwordx4 v[236:237], off
	s_waitcnt vmcnt(6)
	s_waitcnt lgkmcnt(0)
	s_barrier
; #define PG8_STAGE(bufoff, gbase, voff) do { _Pragma("unroll") for (int _i = 0; _i < 2; ++_i) \
;         __builtin_amdgcn_global_load_lds((const unsigned*)((const char*)(gbase) + (voff)[_i]), (PG8_LAS unsigned*)(lds + (bufoff) + ldsw + _i * 8192), 16, 0, 0); } while (0)
; #define PG8_LDA(dst, b, h) do { _Pragma("unroll") for (int m = 0; m < 4; ++m) _Pragma("unroll") for (int k = 0; k < 2; ++k) dst[m][k] = *(const PG8_LAS bf16x8*)(lds + PG8_SA(b, h) + aoff + m * 2048 + k * 1024); } while (0)
; #define PG8_LDB(dst, b, h) do { _Pragma("unroll") for (int n = 0; n < 2; ++n) _Pragma("unroll") for (int k = 0; k < 2; ++k) dst[n][k] = *(const PG8_LAS bf16x8*)(lds + PG8_SB(b, h) + boff + n * 2048 + k * 1024); } while (0)
; #define PG8_MMA(ai, bj, At, Bt) do { __builtin_amdgcn_s_setprio(1); _Pragma("unroll") for (int m = 0; m < 4; ++m) _Pragma("unroll") for (int n = 0; n < 2; ++n) _Pragma("unroll") for (int k = 0; k < 2; ++k) \
;         acc[ai][bj][m][n] = __builtin_amdgcn_mfma_f32_16x16x32_bf16(Bt[n][k], At[m][k], acc[ai][bj][m][n], 0, 0, 0); __builtin_amdgcn_s_setprio(0); } while (0)
; #define PG8_WAIT_V(n) asm volatile("s_waitcnt vmcnt(" #n ")" ::: "memory")
; #define PG8_WAIT_L(n) asm volatile("s_waitcnt lgkmcnt(" #n ")" ::: "memory")
; #define PG8_BAR __builtin_amdgcn_s_barrier()
; #define PG8_SCHED __builtin_amdgcn_sched_barrier(0)
; template <class Epi, class Sched, bool ALIGN_EPI = false, bool SP2 = false>
; __device__ __forceinline__ void gemm_phase(PG8_LAS unsigned char* lds, const Gemm g, const Sched& S, const Epi& E) {
;     ...
;             PG8_WAIT_V(8); PG8_WAIT_L(0); PG8_BAR; PG8_MMA(0, 0, At, B0); PG8_MMA(0, 1, At, B1); PG8_BAR; PG8_SCHED;
;             PG8_LDA(At, 0, 1); PG8_STAGE(PG8_SB(0, 0), b2, voffB); PG8_STAGE(PG8_SB(0, 1), b2 + hstep, voffB); PG8_STAGE(PG8_SA(0, 0), a2, voffA);
;             PG8_WAIT_V(8); PG8_WAIT_L(0); PG8_BAR; PG8_MMA(1, 0, At, B0); PG8_MMA(1, 1, At, B1); PG8_BAR; PG8_SCHED;
;             PG8_LDB(B0, 1, 0); PG8_LDB(B1, 1, 1); PG8_SCHED; PG8_LDA(At, 1, 0); PG8_STAGE(PG8_SA(0, 1), a2 + hstep, voffA);
;             PG8_WAIT_V(8); PG8_WAIT_L(0); PG8_BAR; PG8_MMA(0, 0, At, B0); PG8_MMA(0, 1, At, B1); PG8_BAR; PG8_SCHED;
;             PG8_LDA(At, 1, 1); PG8_STAGE(PG8_SB(1, 0), b3, voffB); PG8_STAGE(PG8_SB(1, 1), b3 + hstep, voffB); PG8_STAGE(PG8_SA(1, 0), a3, voffA);
	s_setprio 1
	s_waitcnt lgkmcnt(0)
	v_mfma_f32_16x16x32_bf16 v[92:95], v[154:157], v[198:201], 0
	v_mfma_f32_16x16x32_bf16 v[88:91], v[162:165], v[198:201], 0
	v_mfma_f32_16x16x32_bf16 v[84:87], v[154:157], v[212:215], 0
	v_mfma_f32_16x16x32_bf16 v[80:83], v[162:165], v[212:215], 0
	v_mfma_f32_16x16x32_bf16 v[76:79], v[154:157], v[220:223], 0
	v_mfma_f32_16x16x32_bf16 v[72:75], v[162:165], v[220:223], 0
	v_mfma_f32_16x16x32_bf16 v[60:63], v[154:157], v[228:231], 0
	v_mfma_f32_16x16x32_bf16 v[56:59], v[162:165], v[228:231], 0
	v_mfma_f32_16x16x32_bf16 v[92:95], v[158:161], v[208:211], v[92:95]
	v_mfma_f32_16x16x32_bf16 v[88:91], v[174:177], v[208:211], v[88:91]
	v_mfma_f32_16x16x32_bf16 v[84:87], v[158:161], v[216:219], v[84:87]
	v_mfma_f32_16x16x32_bf16 v[80:83], v[174:177], v[216:219], v[80:83]
	v_mfma_f32_16x16x32_bf16 v[76:79], v[158:161], v[224:227], v[76:79]
	v_mfma_f32_16x16x32_bf16 v[72:75], v[174:177], v[224:227], v[72:75]
	v_lshl_add_u64 v[236:237], s[58:59], 0, v[134:135]
	s_mov_b32 m0, s60
	s_nop 0
	global_load_lds_dwordx4 v[236:237], off
	v_mfma_f32_16x16x32_bf16 v[60:63], v[158:161], v[232:235], v[60:63]
	v_mfma_f32_16x16x32_bf16 v[56:59], v[174:177], v[232:235], v[56:59]
	s_setprio 0
	s_setprio 1
	v_mfma_f32_16x16x32_bf16 v[28:31], v[182:185], v[198:201], 0
	v_mfma_f32_16x16x32_bf16 v[24:27], v[190:193], v[198:201], 0
	v_mfma_f32_16x16x32_bf16 v[20:23], v[182:185], v[212:215], 0
	v_mfma_f32_16x16x32_bf16 v[16:19], v[190:193], v[212:215], 0
	v_mfma_f32_16x16x32_bf16 v[12:15], v[182:185], v[220:223], 0
	v_mfma_f32_16x16x32_bf16 v[8:11], v[190:193], v[220:223], 0
	v_mfma_f32_16x16x32_bf16 v[4:7], v[182:185], v[228:231], 0
	v_mfma_f32_16x16x32_bf16 v[0:3], v[190:193], v[228:231], 0
	v_mfma_f32_16x16x32_bf16 v[28:31], v[186:189], v[208:211], v[28:31]
	v_mfma_f32_16x16x32_bf16 v[24:27], v[194:197], v[208:211], v[24:27]
	v_mfma_f32_16x16x32_bf16 v[20:23], v[186:189], v[216:219], v[20:23]
	v_mfma_f32_16x16x32_bf16 v[16:19], v[194:197], v[216:219], v[16:19]
	v_mfma_f32_16x16x32_bf16 v[12:15], v[186:189], v[224:227], v[12:15]
	v_mfma_f32_16x16x32_bf16 v[8:11], v[194:197], v[224:227], v[8:11]
	v_lshl_add_u64 v[238:239], s[58:59], 0, v[130:131]
	s_mov_b32 m0, s61
	s_nop 0
	global_load_lds_dwordx4 v[238:239], off
	v_mfma_f32_16x16x32_bf16 v[4:7], v[186:189], v[232:235], v[4:7]
	v_mfma_f32_16x16x32_bf16 v[0:3], v[194:197], v[232:235], v[0:3]
	s_setprio 0
	s_barrier
	s_add_i32 s3, 0, 0x18000
	v_add_u32_e32 v136, s3, v143
	s_add_i32 s33, 0, 0x1c000
	ds_read_b128 v[154:157], v136
	ds_read_b128 v[158:161], v136 offset:1024
	ds_read_b128 v[162:165], v136 offset:2048
	ds_read_b128 v[174:177], v136 offset:3072
	v_add_u32_e32 v136, s33, v143
	ds_read_b128 v[182:185], v136
	ds_read_b128 v[186:189], v136 offset:1024
	ds_read_b128 v[190:193], v136 offset:2048
	ds_read_b128 v[194:197], v136 offset:3072
	s_add_u32 s14, s58, 0x40000
	s_addc_u32 s15, s59, 0
	s_mov_b32 m0, s62
	v_lshl_add_u64 v[240:241], s[14:15], 0, v[134:135]
	ds_read_b128 v[198:201], v171 offset:32768
	ds_read_b128 v[208:211], v171 offset:33792
	ds_read_b128 v[212:215], v171 offset:34816
	ds_read_b128 v[216:219], v171 offset:35840
	ds_read_b128 v[220:223], v171 offset:36864
	ds_read_b128 v[224:227], v171 offset:37888
	ds_read_b128 v[228:231], v171 offset:38912
	ds_read_b128 v[232:235], v171 offset:39936
	global_load_lds_dwordx4 v[240:241], off
	v_lshl_add_u64 v[240:241], s[14:15], 0, v[130:131]
	s_mov_b32 m0, s63
	s_nop 0
	global_load_lds_dwordx4 v[240:241], off
	s_waitcnt vmcnt(8)
	s_waitcnt lgkmcnt(0)
	s_barrier
	s_setprio 1
	s_waitcnt lgkmcnt(0)
	v_mfma_f32_16x16x32_bf16 v[124:127], v[154:157], v[198:201], v[124:127]
	v_mfma_f32_16x16x32_bf16 v[120:123], v[162:165], v[198:201], v[120:123]
	v_mfma_f32_16x16x32_bf16 v[116:119], v[154:157], v[212:215], v[116:119]
	v_mfma_f32_16x16x32_bf16 v[112:115], v[162:165], v[212:215], v[112:115]
	v_mfma_f32_16x16x32_bf16 v[108:111], v[154:157], v[220:223], v[108:111]
	v_mfma_f32_16x16x32_bf16 v[104:107], v[162:165], v[220:223], v[104:107]
	v_mfma_f32_16x16x32_bf16 v[100:103], v[154:157], v[228:231], v[100:103]
	v_mfma_f32_16x16x32_bf16 v[96:99], v[162:165], v[228:231], v[96:99]
	v_mfma_f32_16x16x32_bf16 v[124:127], v[158:161], v[208:211], v[124:127]
	v_mfma_f32_16x16x32_bf16 v[120:123], v[174:177], v[208:211], v[120:123]
	v_mfma_f32_16x16x32_bf16 v[116:119], v[158:161], v[216:219], v[116:119]
	v_mfma_f32_16x16x32_bf16 v[112:115], v[174:177], v[216:219], v[112:115]
	v_mfma_f32_16x16x32_bf16 v[108:111], v[158:161], v[224:227], v[108:111]
	v_mfma_f32_16x16x32_bf16 v[104:107], v[174:177], v[224:227], v[104:107]
	v_mfma_f32_16x16x32_bf16 v[100:103], v[158:161], v[232:235], v[100:103]
	v_mfma_f32_16x16x32_bf16 v[96:99], v[174:177], v[232:235], v[96:99]
	s_setprio 0
	s_setprio 1
	v_mfma_f32_16x16x32_bf16 v[68:71], v[182:185], v[198:201], v[68:71]
	v_mfma_f32_16x16x32_bf16 v[64:67], v[190:193], v[198:201], v[64:67]
	v_mfma_f32_16x16x32_bf16 v[52:55], v[182:185], v[212:215], v[52:55]
	v_mfma_f32_16x16x32_bf16 v[48:51], v[190:193], v[212:215], v[48:51]
	v_mfma_f32_16x16x32_bf16 v[44:47], v[182:185], v[220:223], v[44:47]
	v_mfma_f32_16x16x32_bf16 v[40:43], v[190:193], v[220:223], v[40:43]
	v_mfma_f32_16x16x32_bf16 v[36:39], v[182:185], v[228:231], v[36:39]
	v_mfma_f32_16x16x32_bf16 v[32:35], v[190:193], v[228:231], v[32:35]
	v_mfma_f32_16x16x32_bf16 v[68:71], v[186:189], v[208:211], v[68:71]
	v_mfma_f32_16x16x32_bf16 v[64:67], v[194:197], v[208:211], v[64:67]
	v_mfma_f32_16x16x32_bf16 v[52:55], v[186:189], v[216:219], v[52:55]
	v_mfma_f32_16x16x32_bf16 v[48:51], v[194:197], v[216:219], v[48:51]
	v_mfma_f32_16x16x32_bf16 v[44:47], v[186:189], v[224:227], v[44:47]
	v_mfma_f32_16x16x32_bf16 v[40:43], v[194:197], v[224:227], v[40:43]
	v_mfma_f32_16x16x32_bf16 v[36:39], v[186:189], v[232:235], v[36:39]
	v_mfma_f32_16x16x32_bf16 v[32:35], v[194:197], v[232:235], v[32:35]
	s_setprio 0
	s_barrier
; #define PG8_STAGE(bufoff, gbase, voff) do { _Pragma("unroll") for (int _i = 0; _i < 2; ++_i) \
;         __builtin_amdgcn_global_load_lds((const unsigned*)((const char*)(gbase) + (voff)[_i]), (PG8_LAS unsigned*)(lds + (bufoff) + ldsw + _i * 8192), 16, 0, 0); } while (0)
; #define PG8_LDA(dst, b, h) do { _Pragma("unroll") for (int m = 0; m < 4; ++m) _Pragma("unroll") for (int k = 0; k < 2; ++k) dst[m][k] = *(const PG8_LAS bf16x8*)(lds + PG8_SA(b, h) + aoff + m * 2048 + k * 1024); } while (0)
; #define PG8_MMA(ai, bj, At, Bt) do { __builtin_amdgcn_s_setprio(1); _Pragma("unroll") for (int m = 0; m < 4; ++m) _Pragma("unroll") for (int n = 0; n < 2; ++n) _Pragma("unroll") for (int k = 0; k < 2; ++k) \
;         acc[ai][bj][m][n] = __builtin_amdgcn_mfma_f32_16x16x32_bf16(Bt[n][k], At[m][k], acc[ai][bj][m][n], 0, 0, 0); __builtin_amdgcn_s_setprio(0); } while (0)
; #define PG8_WAIT_V(n) asm volatile("s_waitcnt vmcnt(" #n ")" ::: "memory")
; #define PG8_WAIT_L(n) asm volatile("s_waitcnt lgkmcnt(" #n ")" ::: "memory")
; #define PG8_BAR __builtin_amdgcn_s_barrier()
; #define PG8_SCHED __builtin_amdgcn_sched_barrier(0)
; template <class Epi, class Sched, bool ALIGN_EPI = false, bool SP2 = false>
; __device__ __forceinline__ void gemm_phase(PG8_LAS unsigned char* lds, const Gemm g, const Sched& S, const Epi& E) {
;     ...
;         for (int t = 0; t < nt; t += 2) {
;     ...
;             PG8_LDA(At, 1, 1); PG8_STAGE(PG8_SB(1, 0), b3, voffB); PG8_STAGE(PG8_SB(1, 1), b3 + hstep, voffB); PG8_STAGE(PG8_SA(1, 0), a3, voffA);
;             PG8_WAIT_V(8); PG8_WAIT_L(0); PG8_BAR; PG8_MMA(1, 0, At, B0); PG8_MMA(1, 1, At, B1); PG8_BAR; PG8_SCHED;
	s_add_i32 s3, s3, s34
	v_lshl_add_u64 v[178:179], v[178:179], 0, s[8:9]
	s_mov_b32 m0, s3
	ds_read_b128 v[198:201], v171 offset:49152
	ds_read_b128 v[208:211], v171 offset:50176
	ds_read_b128 v[212:215], v171 offset:51200
	ds_read_b128 v[216:219], v171 offset:52224
	ds_read_b128 v[220:223], v171 offset:53248
	ds_read_b128 v[224:227], v171 offset:54272
	ds_read_b128 v[228:231], v171 offset:55296
	ds_read_b128 v[232:235], v171 offset:56320
	global_load_lds_dwordx4 v[178:179], off
	s_add_i32 m0, s3, 0x2000
	s_add_u32 s14, s56, 0x40080
	v_lshl_add_u64 v[178:179], v[202:203], 0, s[8:9]
	s_addc_u32 s15, s57, 0
	s_add_i32 s3, s33, s34
	global_load_lds_dwordx4 v[178:179], off
	v_lshl_add_u64 v[178:179], s[14:15], 0, v[132:133]
	s_mov_b32 m0, s3
	s_nop 0
	global_load_lds_dwordx4 v[178:179], off
	v_lshl_add_u64 v[178:179], s[14:15], 0, v[128:129]
	s_add_i32 m0, s3, 0x2000
	s_nop 0
	global_load_lds_dwordx4 v[178:179], off
	s_waitcnt vmcnt(6)
	s_waitcnt lgkmcnt(0)
	s_barrier
	s_setprio 1
	s_waitcnt lgkmcnt(0)
	v_mfma_f32_16x16x32_bf16 v[92:95], v[154:157], v[198:201], v[92:95]
	v_mfma_f32_16x16x32_bf16 v[88:91], v[162:165], v[198:201], v[88:91]
	v_mfma_f32_16x16x32_bf16 v[84:87], v[154:157], v[212:215], v[84:87]
	v_mfma_f32_16x16x32_bf16 v[80:83], v[162:165], v[212:215], v[80:83]
	v_mfma_f32_16x16x32_bf16 v[76:79], v[154:157], v[220:223], v[76:79]
	v_mfma_f32_16x16x32_bf16 v[72:75], v[162:165], v[220:223], v[72:75]
	v_mfma_f32_16x16x32_bf16 v[60:63], v[154:157], v[228:231], v[60:63]
	v_mfma_f32_16x16x32_bf16 v[56:59], v[162:165], v[228:231], v[56:59]
	v_mfma_f32_16x16x32_bf16 v[92:95], v[158:161], v[208:211], v[92:95]
	v_mfma_f32_16x16x32_bf16 v[88:91], v[174:177], v[208:211], v[88:91]
	v_mfma_f32_16x16x32_bf16 v[84:87], v[158:161], v[216:219], v[84:87]
	v_mfma_f32_16x16x32_bf16 v[80:83], v[174:177], v[216:219], v[80:83]
	v_mfma_f32_16x16x32_bf16 v[76:79], v[158:161], v[224:227], v[76:79]
	v_mfma_f32_16x16x32_bf16 v[72:75], v[174:177], v[224:227], v[72:75]
	v_lshl_add_u64 v[178:179], v[236:237], 0, s[8:9]
	s_mov_b32 m0, s66
	s_nop 0
	global_load_lds_dwordx4 v[178:179], off
	v_mfma_f32_16x16x32_bf16 v[60:63], v[158:161], v[232:235], v[60:63]
	v_mfma_f32_16x16x32_bf16 v[56:59], v[174:177], v[232:235], v[56:59]
	s_setprio 0
	s_setprio 1
	v_mfma_f32_16x16x32_bf16 v[28:31], v[182:185], v[198:201], v[28:31]
	v_mfma_f32_16x16x32_bf16 v[24:27], v[190:193], v[198:201], v[24:27]
	v_mfma_f32_16x16x32_bf16 v[20:23], v[182:185], v[212:215], v[20:23]
	v_mfma_f32_16x16x32_bf16 v[16:19], v[190:193], v[212:215], v[16:19]
	v_mfma_f32_16x16x32_bf16 v[12:15], v[182:185], v[220:223], v[12:15]
	v_mfma_f32_16x16x32_bf16 v[8:11], v[190:193], v[220:223], v[8:11]
	v_mfma_f32_16x16x32_bf16 v[4:7], v[182:185], v[228:231], v[4:7]
	v_mfma_f32_16x16x32_bf16 v[0:3], v[190:193], v[228:231], v[0:3]
	v_mfma_f32_16x16x32_bf16 v[28:31], v[186:189], v[208:211], v[28:31]
	v_mfma_f32_16x16x32_bf16 v[24:27], v[194:197], v[208:211], v[24:27]
	v_mfma_f32_16x16x32_bf16 v[20:23], v[186:189], v[216:219], v[20:23]
	v_mfma_f32_16x16x32_bf16 v[16:19], v[194:197], v[216:219], v[16:19]
	v_mfma_f32_16x16x32_bf16 v[12:15], v[186:189], v[224:227], v[12:15]
	v_mfma_f32_16x16x32_bf16 v[8:11], v[194:197], v[224:227], v[8:11]
	v_lshl_add_u64 v[178:179], v[238:239], 0, s[8:9]
	s_mov_b32 m0, s67
	s_nop 0
	global_load_lds_dwordx4 v[178:179], off
	v_mfma_f32_16x16x32_bf16 v[4:7], v[186:189], v[232:235], v[4:7]
	v_mfma_f32_16x16x32_bf16 v[0:3], v[194:197], v[232:235], v[0:3]
	s_setprio 0
	s_barrier
	s_add_i32 s93, s93, 2
	s_add_u32 s54, s54, 0x100
	s_addc_u32 s55, s55, 0
	s_add_u32 s91, s91, 0x100
	s_addc_u32 s92, s92, 0
	.p2align 6

; #define PG8_STAGE(bufoff, gbase, voff) do { _Pragma("unroll") for (int _i = 0; _i < 2; ++_i) \
;         __builtin_amdgcn_global_load_lds((const unsigned*)((const char*)(gbase) + (voff)[_i]), (PG8_LAS unsigned*)(lds + (bufoff) + ldsw + _i * 8192), 16, 0, 0); } while (0)
; #define PG8_LDA(dst, b, h) do { _Pragma("unroll") for (int m = 0; m < 4; ++m) _Pragma("unroll") for (int k = 0; k < 2; ++k) dst[m][k] = *(const PG8_LAS bf16x8*)(lds + PG8_SA(b, h) + aoff + m * 2048 + k * 1024); } while (0)
; template <class Epi, class Sched, bool ALIGN_EPI = false, bool SP2 = false>
; __device__ __forceinline__ void gemm_phase(PG8_LAS unsigned char* lds, const Gemm g, const Sched& S, const Epi& E) {
;     ...
;     for (;;) {
;         const bool has_next = S.next(ui + 1, nxt);
;         const char* nA = has_next ? (const char*)g.A + (size_t)nxt.pm * tstep : cA; const char* nB = has_next ? (const char*)g.Bt + (size_t)nxt.pn * tstep : cB;
;         for (int t = 0; t < nt; t += 2) {
;             const bool last = (t == nt - 2);
;             const char* a1 = cA + (size_t)(t + 1) * kstep;
;             const char* a2 = last ? nA : cA + (size_t)(t + 2) * kstep; const char* b2 = last ? nB : cB + (size_t)(t + 2) * kstep;
;             const char* a3 = a2 + kstep; const char* b3 = b2 + kstep;
;             if (last && has_next) S.a_ready(nxt);
;             if constexpr (SP2) {
;             PG8_LDB(B0, 0, 0); PG8_LDB(B1, 0, 1); PG8_SCHED; PG8_LDA(At, 0, 0); PG8_STAGE(PG8_SA(1, 1), a1 + hstep, voffA);
;             PG8_WAIT_V(8); PG8_WAIT_L(0); PG8_BAR; PG8_MMA(0, 0, At, B0); PG8_MMA(0, 1, At, B1); PG8_BAR; PG8_SCHED;
;             PG8_LDA(At, 0, 1); PG8_STAGE(PG8_SB(0, 0), b2, voffB); PG8_STAGE(PG8_SB(0, 1), b2 + hstep, voffB); PG8_STAGE(PG8_SA(0, 0), a2, voffA);
;             PG8_WAIT_V(8); PG8_WAIT_L(0); PG8_BAR; PG8_MMA(1, 0, At, B0); PG8_MMA(1, 1, At, B1); PG8_BAR; PG8_SCHED;
;             PG8_LDB(B0, 1, 0); PG8_LDB(B1, 1, 1); PG8_SCHED; PG8_LDA(At, 1, 0); PG8_STAGE(PG8_SA(0, 1), a2 + hstep, voffA);
;             PG8_WAIT_V(8); PG8_WAIT_L(0); PG8_BAR; PG8_MMA(0, 0, At, B0); PG8_MMA(0, 1, At, B1); PG8_BAR; PG8_SCHED;
;             PG8_LDA(At, 1, 1); PG8_STAGE(PG8_SB(1, 0), b3, voffB); PG8_STAGE(PG8_SB(1, 1), b3 + hstep, voffB); PG8_STAGE(PG8_SA(1, 0), a3, voffA);
;             PG8_WAIT_V(8); PG8_WAIT_L(0); PG8_BAR; PG8_MMA(1, 0, At, B0); PG8_MMA(1, 1, At, B1); PG8_BAR; PG8_SCHED;
.LBB0_458:
	s_ashr_i32 s49, s48, 31
	s_lshl_b64 s[14:15], s[48:49], 19
	s_add_u32 s50, s34, s14
	s_addc_u32 s51, s43, s15
	s_and_b64 s[14:15], s[40:41], exec
	s_cselect_b32 s49, s51, s59
	s_cselect_b32 s55, s50, s58
	s_ashr_i32 s45, s44, 31
	s_lshl_b64 s[14:15], s[44:45], 19
	v_readlane_b32 s3, v250, 13
	s_add_u32 s52, s3, s14
	v_readlane_b32 s3, v250, 14
	s_addc_u32 s53, s3, s15
	s_and_b64 s[14:15], s[40:41], exec
	s_cselect_b32 s45, s53, s61
	s_cselect_b32 s57, s52, s60
	s_add_u32 s58, s58, 0x40080
	s_addc_u32 s59, s59, 0
	s_add_u32 s96, s60, 0x100
	s_addc_u32 s97, s61, 0
	s_mov_b32 vcc_lo, -2
	ds_read_b128 v[170:173], v165
	ds_read_b128 v[174:177], v165 offset:1024
	ds_read_b128 v[182:185], v165 offset:2048
	ds_read_b128 v[186:189], v165 offset:3072
	ds_read_b128 v[190:193], v168
	ds_read_b128 v[194:197], v168 offset:1024
	ds_read_b128 v[198:201], v168 offset:2048
	ds_read_b128 v[208:211], v168 offset:3072
	s_add_u32 s3, s58, 0xfffc0080
	s_addc_u32 s14, s59, -1
	s_cmp_eq_u32 vcc_lo, 12
	s_cselect_b32 s63, s49, s14
	s_cselect_b32 s62, s55, s3
	s_cselect_b32 s61, s45, s97
	s_cselect_b32 s60, s57, s96
	v_lshl_add_u64 v[178:179], s[58:59], 0, v[160:161]
	s_add_i32 m0, s85, 0xc000
	ds_read_b128 v[212:215], v164
	ds_read_b128 v[216:219], v164 offset:1024
	ds_read_b128 v[220:223], v164 offset:2048
	ds_read_b128 v[224:227], v164 offset:3072
	ds_read_b128 v[228:231], v164 offset:4096
	ds_read_b128 v[232:235], v164 offset:5120
	ds_read_b128 v[236:239], v164 offset:6144
	ds_read_b128 v[240:243], v164 offset:7168
	global_load_lds_dwordx4 v[178:179], off
	v_lshl_add_u64 v[178:179], s[58:59], 0, v[162:163]
	s_add_i32 m0, s85, 0xe000
	s_nop 0
	global_load_lds_dwordx4 v[178:179], off
	s_waitcnt vmcnt(8)
	s_waitcnt lgkmcnt(0)
	s_barrier
	s_setprio 1
	s_waitcnt lgkmcnt(0)
	v_mfma_f32_16x16x32_bf16 v[124:127], v[170:173], v[212:215], 0
	v_mfma_f32_16x16x32_bf16 v[120:123], v[182:185], v[212:215], 0
	v_mfma_f32_16x16x32_bf16 v[116:119], v[170:173], v[220:223], 0
	v_mfma_f32_16x16x32_bf16 v[112:115], v[182:185], v[220:223], 0
	v_mfma_f32_16x16x32_bf16 v[108:111], v[170:173], v[228:231], 0
	v_mfma_f32_16x16x32_bf16 v[104:107], v[182:185], v[228:231], 0
	v_mfma_f32_16x16x32_bf16 v[100:103], v[170:173], v[236:239], 0
	v_mfma_f32_16x16x32_bf16 v[96:99], v[182:185], v[236:239], 0
	v_mfma_f32_16x16x32_bf16 v[124:127], v[174:177], v[216:219], v[124:127]
	v_mfma_f32_16x16x32_bf16 v[120:123], v[186:189], v[216:219], v[120:123]
	v_mfma_f32_16x16x32_bf16 v[116:119], v[174:177], v[224:227], v[116:119]
	v_mfma_f32_16x16x32_bf16 v[112:115], v[186:189], v[224:227], v[112:115]
	v_mfma_f32_16x16x32_bf16 v[108:111], v[174:177], v[232:235], v[108:111]
	v_mfma_f32_16x16x32_bf16 v[104:107], v[186:189], v[232:235], v[104:107]
	v_mfma_f32_16x16x32_bf16 v[100:103], v[174:177], v[240:243], v[100:103]
	v_mfma_f32_16x16x32_bf16 v[96:99], v[186:189], v[240:243], v[96:99]
	s_setprio 0
	s_setprio 1
	v_mfma_f32_16x16x32_bf16 v[60:63], v[190:193], v[212:215], 0
	v_mfma_f32_16x16x32_bf16 v[56:59], v[198:201], v[212:215], 0
	v_mfma_f32_16x16x32_bf16 v[52:55], v[190:193], v[220:223], 0
	v_mfma_f32_16x16x32_bf16 v[48:51], v[198:201], v[220:223], 0
	v_mfma_f32_16x16x32_bf16 v[44:47], v[190:193], v[228:231], 0
	v_mfma_f32_16x16x32_bf16 v[40:43], v[198:201], v[228:231], 0
	v_mfma_f32_16x16x32_bf16 v[36:39], v[190:193], v[236:239], 0
	v_mfma_f32_16x16x32_bf16 v[32:35], v[198:201], v[236:239], 0
	v_mfma_f32_16x16x32_bf16 v[60:63], v[194:197], v[216:219], v[60:63]
	v_mfma_f32_16x16x32_bf16 v[56:59], v[208:211], v[216:219], v[56:59]
	v_mfma_f32_16x16x32_bf16 v[52:55], v[194:197], v[224:227], v[52:55]
	v_mfma_f32_16x16x32_bf16 v[48:51], v[208:211], v[224:227], v[48:51]
	v_mfma_f32_16x16x32_bf16 v[44:47], v[194:197], v[232:235], v[44:47]
	v_mfma_f32_16x16x32_bf16 v[40:43], v[208:211], v[232:235], v[40:43]
	v_mfma_f32_16x16x32_bf16 v[36:39], v[194:197], v[240:243], v[36:39]
	v_mfma_f32_16x16x32_bf16 v[32:35], v[208:211], v[240:243], v[32:35]
	s_setprio 0
	s_barrier
	s_add_i32 s3, s94, s84
	v_lshl_add_u64 v[178:179], s[60:61], 0, v[130:131]
	s_mov_b32 m0, s3
	ds_read_b128 v[212:215], v164 offset:16384
	ds_read_b128 v[216:219], v164 offset:17408
	ds_read_b128 v[220:223], v164 offset:18432
	ds_read_b128 v[224:227], v164 offset:19456
	ds_read_b128 v[228:231], v164 offset:20480
	ds_read_b128 v[232:235], v164 offset:21504
	ds_read_b128 v[236:239], v164 offset:22528
	ds_read_b128 v[240:243], v164 offset:23552
	global_load_lds_dwordx4 v[178:179], off
	s_add_i32 m0, s3, 0x2000
	s_add_u32 s14, s60, 0x40000
	v_lshl_add_u64 v[202:203], s[60:61], 0, v[134:135]
	s_addc_u32 s15, s61, 0
	s_add_i32 s3, s95, s84
	global_load_lds_dwordx4 v[202:203], off
	v_lshl_add_u64 v[244:245], s[14:15], 0, v[130:131]
	s_mov_b32 m0, s3
	global_load_lds_dwordx4 v[244:245], off
	v_lshl_add_u64 v[244:245], s[14:15], 0, v[134:135]
	s_add_i32 m0, s3, 0x2000
	s_nop 0
	global_load_lds_dwordx4 v[244:245], off
	s_waitcnt vmcnt(6)
	s_waitcnt lgkmcnt(0)
	s_barrier
; #define PG8_STAGE(bufoff, gbase, voff) do { _Pragma("unroll") for (int _i = 0; _i < 2; ++_i) \
;         __builtin_amdgcn_global_load_lds((const unsigned*)((const char*)(gbase) + (voff)[_i]), (PG8_LAS unsigned*)(lds + (bufoff) + ldsw + _i * 8192), 16, 0, 0); } while (0)
; #define PG8_LDA(dst, b, h) do { _Pragma("unroll") for (int m = 0; m < 4; ++m) _Pragma("unroll") for (int k = 0; k < 2; ++k) dst[m][k] = *(const PG8_LAS bf16x8*)(lds + PG8_SA(b, h) + aoff + m * 2048 + k * 1024); } while (0)
; #define PG8_LDB(dst, b, h) do { _Pragma("unroll") for (int n = 0; n < 2; ++n) _Pragma("unroll") for (int k = 0; k < 2; ++k) dst[n][k] = *(const PG8_LAS bf16x8*)(lds + PG8_SB(b, h) + boff + n * 2048 + k * 1024); } while (0)
; #define PG8_MMA(ai, bj, At, Bt) do { __builtin_amdgcn_s_setprio(1); _Pragma("unroll") for (int m = 0; m < 4; ++m) _Pragma("unroll") for (int n = 0; n < 2; ++n) _Pragma("unroll") for (int k = 0; k < 2; ++k) \
;         acc[ai][bj][m][n] = __builtin_amdgcn_mfma_f32_16x16x32_bf16(Bt[n][k], At[m][k], acc[ai][bj][m][n], 0, 0, 0); __builtin_amdgcn_s_setprio(0); } while (0)
; #define PG8_WAIT_V(n) asm volatile("s_waitcnt vmcnt(" #n ")" ::: "memory")
; #define PG8_WAIT_L(n) asm volatile("s_waitcnt lgkmcnt(" #n ")" ::: "memory")
; #define PG8_BAR __builtin_amdgcn_s_barrier()
; #define PG8_SCHED __builtin_amdgcn_sched_barrier(0)
; template <class Epi, class Sched, bool ALIGN_EPI = false, bool SP2 = false>
; __device__ __forceinline__ void gemm_phase(PG8_LAS unsigned char* lds, const Gemm g, const Sched& S, const Epi& E) {
;     ...
;             PG8_WAIT_V(8); PG8_WAIT_L(0); PG8_BAR; PG8_MMA(0, 0, At, B0); PG8_MMA(0, 1, At, B1); PG8_BAR; PG8_SCHED;
;             PG8_LDA(At, 0, 1); PG8_STAGE(PG8_SB(0, 0), b2, voffB); PG8_STAGE(PG8_SB(0, 1), b2 + hstep, voffB); PG8_STAGE(PG8_SA(0, 0), a2, voffA);
;             PG8_WAIT_V(8); PG8_WAIT_L(0); PG8_BAR; PG8_MMA(1, 0, At, B0); PG8_MMA(1, 1, At, B1); PG8_BAR; PG8_SCHED;
;             PG8_LDB(B0, 1, 0); PG8_LDB(B1, 1, 1); PG8_SCHED; PG8_LDA(At, 1, 0); PG8_STAGE(PG8_SA(0, 1), a2 + hstep, voffA);
;             PG8_WAIT_V(8); PG8_WAIT_L(0); PG8_BAR; PG8_MMA(0, 0, At, B0); PG8_MMA(0, 1, At, B1); PG8_BAR; PG8_SCHED;
;             PG8_LDA(At, 1, 1); PG8_STAGE(PG8_SB(1, 0), b3, voffB); PG8_STAGE(PG8_SB(1, 1), b3 + hstep, voffB); PG8_STAGE(PG8_SA(1, 0), a3, voffA);
	s_setprio 1
	s_waitcnt lgkmcnt(0)
	v_mfma_f32_16x16x32_bf16 v[92:95], v[170:173], v[212:215], 0
	v_mfma_f32_16x16x32_bf16 v[88:91], v[182:185], v[212:215], 0
	v_mfma_f32_16x16x32_bf16 v[84:87], v[170:173], v[220:223], 0
	v_mfma_f32_16x16x32_bf16 v[80:83], v[182:185], v[220:223], 0
	v_mfma_f32_16x16x32_bf16 v[76:79], v[170:173], v[228:231], 0
	v_mfma_f32_16x16x32_bf16 v[72:75], v[182:185], v[228:231], 0
	v_mfma_f32_16x16x32_bf16 v[68:71], v[170:173], v[236:239], 0
	v_mfma_f32_16x16x32_bf16 v[64:67], v[182:185], v[236:239], 0
	v_mfma_f32_16x16x32_bf16 v[92:95], v[174:177], v[216:219], v[92:95]
	v_mfma_f32_16x16x32_bf16 v[88:91], v[186:189], v[216:219], v[88:91]
	v_mfma_f32_16x16x32_bf16 v[84:87], v[174:177], v[224:227], v[84:87]
	v_mfma_f32_16x16x32_bf16 v[80:83], v[186:189], v[224:227], v[80:83]
	v_mfma_f32_16x16x32_bf16 v[76:79], v[174:177], v[232:235], v[76:79]
	v_mfma_f32_16x16x32_bf16 v[72:75], v[186:189], v[232:235], v[72:75]
	v_lshl_add_u64 v[244:245], s[62:63], 0, v[128:129]
	s_mov_b32 m0, s85
	s_nop 0
	global_load_lds_dwordx4 v[244:245], off
	v_mfma_f32_16x16x32_bf16 v[68:71], v[174:177], v[240:243], v[68:71]
	v_mfma_f32_16x16x32_bf16 v[64:67], v[186:189], v[240:243], v[64:67]
	s_setprio 0
	s_setprio 1
	v_mfma_f32_16x16x32_bf16 v[28:31], v[190:193], v[212:215], 0
	v_mfma_f32_16x16x32_bf16 v[24:27], v[198:201], v[212:215], 0
	v_mfma_f32_16x16x32_bf16 v[20:23], v[190:193], v[220:223], 0
	v_mfma_f32_16x16x32_bf16 v[16:19], v[198:201], v[220:223], 0
	v_mfma_f32_16x16x32_bf16 v[12:15], v[190:193], v[228:231], 0
	v_mfma_f32_16x16x32_bf16 v[8:11], v[198:201], v[228:231], 0
	v_mfma_f32_16x16x32_bf16 v[4:7], v[190:193], v[236:239], 0
	v_mfma_f32_16x16x32_bf16 v[0:3], v[198:201], v[236:239], 0
	v_mfma_f32_16x16x32_bf16 v[28:31], v[194:197], v[216:219], v[28:31]
	v_mfma_f32_16x16x32_bf16 v[24:27], v[208:211], v[216:219], v[24:27]
	v_mfma_f32_16x16x32_bf16 v[20:23], v[194:197], v[224:227], v[20:23]
	v_mfma_f32_16x16x32_bf16 v[16:19], v[208:211], v[224:227], v[16:19]
	v_mfma_f32_16x16x32_bf16 v[12:15], v[194:197], v[232:235], v[12:15]
	v_mfma_f32_16x16x32_bf16 v[8:11], v[208:211], v[232:235], v[8:11]
	v_lshl_add_u64 v[246:247], s[62:63], 0, v[132:133]
	s_mov_b32 m0, s86
	s_nop 0
	global_load_lds_dwordx4 v[246:247], off
	v_mfma_f32_16x16x32_bf16 v[4:7], v[194:197], v[240:243], v[4:7]
	v_mfma_f32_16x16x32_bf16 v[0:3], v[208:211], v[240:243], v[0:3]
	s_setprio 0
	s_barrier
	s_add_i32 s3, 0, 0x18000
	v_add_u32_e32 v136, s3, v141
	s_add_i32 s33, 0, 0x1c000
	ds_read_b128 v[170:173], v136
	ds_read_b128 v[174:177], v136 offset:1024
	ds_read_b128 v[182:185], v136 offset:2048
	ds_read_b128 v[186:189], v136 offset:3072
	v_add_u32_e32 v136, s33, v141
	ds_read_b128 v[190:193], v136
	ds_read_b128 v[194:197], v136 offset:1024
	ds_read_b128 v[198:201], v136 offset:2048
	ds_read_b128 v[208:211], v136 offset:3072
	s_add_u32 s14, s62, 0x40000
	s_addc_u32 s15, s63, 0
	s_mov_b32 m0, s87
	v_lshl_add_u64 v[248:249], s[14:15], 0, v[128:129]
	ds_read_b128 v[212:215], v164 offset:32768
	ds_read_b128 v[216:219], v164 offset:33792
	ds_read_b128 v[220:223], v164 offset:34816
	ds_read_b128 v[224:227], v164 offset:35840
	ds_read_b128 v[228:231], v164 offset:36864
	ds_read_b128 v[232:235], v164 offset:37888
	ds_read_b128 v[236:239], v164 offset:38912
	ds_read_b128 v[240:243], v164 offset:39936
	global_load_lds_dwordx4 v[248:249], off
	v_lshl_add_u64 v[248:249], s[14:15], 0, v[132:133]
	s_mov_b32 m0, s88
	s_nop 0
	global_load_lds_dwordx4 v[248:249], off
	s_waitcnt vmcnt(8)
	s_waitcnt lgkmcnt(0)
	s_barrier
	s_setprio 1
	s_waitcnt lgkmcnt(0)
	v_mfma_f32_16x16x32_bf16 v[124:127], v[170:173], v[212:215], v[124:127]
	v_mfma_f32_16x16x32_bf16 v[120:123], v[182:185], v[212:215], v[120:123]
	v_mfma_f32_16x16x32_bf16 v[116:119], v[170:173], v[220:223], v[116:119]
	v_mfma_f32_16x16x32_bf16 v[112:115], v[182:185], v[220:223], v[112:115]
	v_mfma_f32_16x16x32_bf16 v[108:111], v[170:173], v[228:231], v[108:111]
	v_mfma_f32_16x16x32_bf16 v[104:107], v[182:185], v[228:231], v[104:107]
	v_mfma_f32_16x16x32_bf16 v[100:103], v[170:173], v[236:239], v[100:103]
	v_mfma_f32_16x16x32_bf16 v[96:99], v[182:185], v[236:239], v[96:99]
	v_mfma_f32_16x16x32_bf16 v[124:127], v[174:177], v[216:219], v[124:127]
	v_mfma_f32_16x16x32_bf16 v[120:123], v[186:189], v[216:219], v[120:123]
	v_mfma_f32_16x16x32_bf16 v[116:119], v[174:177], v[224:227], v[116:119]
	v_mfma_f32_16x16x32_bf16 v[112:115], v[186:189], v[224:227], v[112:115]
	v_mfma_f32_16x16x32_bf16 v[108:111], v[174:177], v[232:235], v[108:111]
	v_mfma_f32_16x16x32_bf16 v[104:107], v[186:189], v[232:235], v[104:107]
	v_mfma_f32_16x16x32_bf16 v[100:103], v[174:177], v[240:243], v[100:103]
	v_mfma_f32_16x16x32_bf16 v[96:99], v[186:189], v[240:243], v[96:99]
	s_setprio 0
	s_setprio 1
	v_mfma_f32_16x16x32_bf16 v[60:63], v[190:193], v[212:215], v[60:63]
	v_mfma_f32_16x16x32_bf16 v[56:59], v[198:201], v[212:215], v[56:59]
	v_mfma_f32_16x16x32_bf16 v[52:55], v[190:193], v[220:223], v[52:55]
	v_mfma_f32_16x16x32_bf16 v[48:51], v[198:201], v[220:223], v[48:51]
	v_mfma_f32_16x16x32_bf16 v[44:47], v[190:193], v[228:231], v[44:47]
	v_mfma_f32_16x16x32_bf16 v[40:43], v[198:201], v[228:231], v[40:43]
	v_mfma_f32_16x16x32_bf16 v[36:39], v[190:193], v[236:239], v[36:39]
	v_mfma_f32_16x16x32_bf16 v[32:35], v[198:201], v[236:239], v[32:35]
	v_mfma_f32_16x16x32_bf16 v[60:63], v[194:197], v[216:219], v[60:63]
	v_mfma_f32_16x16x32_bf16 v[56:59], v[208:211], v[216:219], v[56:59]
	v_mfma_f32_16x16x32_bf16 v[52:55], v[194:197], v[224:227], v[52:55]
	v_mfma_f32_16x16x32_bf16 v[48:51], v[208:211], v[224:227], v[48:51]
	v_mfma_f32_16x16x32_bf16 v[44:47], v[194:197], v[232:235], v[44:47]
	v_mfma_f32_16x16x32_bf16 v[40:43], v[208:211], v[232:235], v[40:43]
	v_mfma_f32_16x16x32_bf16 v[36:39], v[194:197], v[240:243], v[36:39]
	v_mfma_f32_16x16x32_bf16 v[32:35], v[208:211], v[240:243], v[32:35]
	s_setprio 0
	s_barrier
; #define PG8_STAGE(bufoff, gbase, voff) do { _Pragma("unroll") for (int _i = 0; _i < 2; ++_i) \
;         __builtin_amdgcn_global_load_lds((const unsigned*)((const char*)(gbase) + (voff)[_i]), (PG8_LAS unsigned*)(lds + (bufoff) + ldsw + _i * 8192), 16, 0, 0); } while (0)
; #define PG8_LDA(dst, b, h) do { _Pragma("unroll") for (int m = 0; m < 4; ++m) _Pragma("unroll") for (int k = 0; k < 2; ++k) dst[m][k] = *(const PG8_LAS bf16x8*)(lds + PG8_SA(b, h) + aoff + m * 2048 + k * 1024); } while (0)
; #define PG8_MMA(ai, bj, At, Bt) do { __builtin_amdgcn_s_setprio(1); _Pragma("unroll") for (int m = 0; m < 4; ++m) _Pragma("unroll") for (int n = 0; n < 2; ++n) _Pragma("unroll") for (int k = 0; k < 2; ++k) \
;         acc[ai][bj][m][n] = __builtin_amdgcn_mfma_f32_16x16x32_bf16(Bt[n][k], At[m][k], acc[ai][bj][m][n], 0, 0, 0); __builtin_amdgcn_s_setprio(0); } while (0)
; #define PG8_WAIT_V(n) asm volatile("s_waitcnt vmcnt(" #n ")" ::: "memory")
; #define PG8_WAIT_L(n) asm volatile("s_waitcnt lgkmcnt(" #n ")" ::: "memory")
; #define PG8_BAR __builtin_amdgcn_s_barrier()
; #define PG8_SCHED __builtin_amdgcn_sched_barrier(0)
; template <class Epi, class Sched, bool ALIGN_EPI = false, bool SP2 = false>
; __device__ __forceinline__ void gemm_phase(PG8_LAS unsigned char* lds, const Gemm g, const Sched& S, const Epi& E) {
;     ...
;         for (int t = 0; t < nt; t += 2) {
;     ...
;             PG8_LDA(At, 1, 1); PG8_STAGE(PG8_SB(1, 0), b3, voffB); PG8_STAGE(PG8_SB(1, 1), b3 + hstep, voffB); PG8_STAGE(PG8_SA(1, 0), a3, voffA);
;             PG8_WAIT_V(8); PG8_WAIT_L(0); PG8_BAR; PG8_MMA(1, 0, At, B0); PG8_MMA(1, 1, At, B1); PG8_BAR; PG8_SCHED;
	s_add_i32 s3, s3, s84
	v_lshl_add_u64 v[178:179], v[178:179], 0, s[8:9]
	s_mov_b32 m0, s3
	ds_read_b128 v[212:215], v164 offset:49152
	ds_read_b128 v[216:219], v164 offset:50176
	ds_read_b128 v[220:223], v164 offset:51200
	ds_read_b128 v[224:227], v164 offset:52224
	ds_read_b128 v[228:231], v164 offset:53248
	ds_read_b128 v[232:235], v164 offset:54272
	ds_read_b128 v[236:239], v164 offset:55296
	ds_read_b128 v[240:243], v164 offset:56320
	global_load_lds_dwordx4 v[178:179], off
	s_add_i32 m0, s3, 0x2000
	s_add_u32 s14, s60, 0x40080
	v_lshl_add_u64 v[178:179], v[202:203], 0, s[8:9]
	s_addc_u32 s15, s61, 0
	s_add_i32 s3, s33, s84
	global_load_lds_dwordx4 v[178:179], off
	v_lshl_add_u64 v[178:179], s[14:15], 0, v[130:131]
	s_mov_b32 m0, s3
	s_nop 0
	global_load_lds_dwordx4 v[178:179], off
	v_lshl_add_u64 v[178:179], s[14:15], 0, v[134:135]
	s_add_i32 m0, s3, 0x2000
	s_nop 0
	global_load_lds_dwordx4 v[178:179], off
	s_waitcnt vmcnt(6)
	s_waitcnt lgkmcnt(0)
	s_barrier
	s_setprio 1
	s_waitcnt lgkmcnt(0)
	v_mfma_f32_16x16x32_bf16 v[92:95], v[170:173], v[212:215], v[92:95]
	v_mfma_f32_16x16x32_bf16 v[88:91], v[182:185], v[212:215], v[88:91]
	v_mfma_f32_16x16x32_bf16 v[84:87], v[170:173], v[220:223], v[84:87]
	v_mfma_f32_16x16x32_bf16 v[80:83], v[182:185], v[220:223], v[80:83]
	v_mfma_f32_16x16x32_bf16 v[76:79], v[170:173], v[228:231], v[76:79]
	v_mfma_f32_16x16x32_bf16 v[72:75], v[182:185], v[228:231], v[72:75]
	v_mfma_f32_16x16x32_bf16 v[68:71], v[170:173], v[236:239], v[68:71]
	v_mfma_f32_16x16x32_bf16 v[64:67], v[182:185], v[236:239], v[64:67]
	v_mfma_f32_16x16x32_bf16 v[92:95], v[174:177], v[216:219], v[92:95]
	v_mfma_f32_16x16x32_bf16 v[88:91], v[186:189], v[216:219], v[88:91]
	v_mfma_f32_16x16x32_bf16 v[84:87], v[174:177], v[224:227], v[84:87]
	v_mfma_f32_16x16x32_bf16 v[80:83], v[186:189], v[224:227], v[80:83]
	v_mfma_f32_16x16x32_bf16 v[76:79], v[174:177], v[232:235], v[76:79]
	v_mfma_f32_16x16x32_bf16 v[72:75], v[186:189], v[232:235], v[72:75]
	v_lshl_add_u64 v[178:179], v[244:245], 0, s[8:9]
	s_mov_b32 m0, s90
	s_nop 0
	global_load_lds_dwordx4 v[178:179], off
	v_mfma_f32_16x16x32_bf16 v[68:71], v[174:177], v[240:243], v[68:71]
	v_mfma_f32_16x16x32_bf16 v[64:67], v[186:189], v[240:243], v[64:67]
	s_setprio 0
	s_setprio 1
	v_mfma_f32_16x16x32_bf16 v[28:31], v[190:193], v[212:215], v[28:31]
	v_mfma_f32_16x16x32_bf16 v[24:27], v[198:201], v[212:215], v[24:27]
	v_mfma_f32_16x16x32_bf16 v[20:23], v[190:193], v[220:223], v[20:23]
	v_mfma_f32_16x16x32_bf16 v[16:19], v[198:201], v[220:223], v[16:19]
	v_mfma_f32_16x16x32_bf16 v[12:15], v[190:193], v[228:231], v[12:15]
	v_mfma_f32_16x16x32_bf16 v[8:11], v[198:201], v[228:231], v[8:11]
	v_mfma_f32_16x16x32_bf16 v[4:7], v[190:193], v[236:239], v[4:7]
	v_mfma_f32_16x16x32_bf16 v[0:3], v[198:201], v[236:239], v[0:3]
	v_mfma_f32_16x16x32_bf16 v[28:31], v[194:197], v[216:219], v[28:31]
	v_mfma_f32_16x16x32_bf16 v[24:27], v[208:211], v[216:219], v[24:27]
	v_mfma_f32_16x16x32_bf16 v[20:23], v[194:197], v[224:227], v[20:23]
	v_mfma_f32_16x16x32_bf16 v[16:19], v[208:211], v[224:227], v[16:19]
	v_mfma_f32_16x16x32_bf16 v[12:15], v[194:197], v[232:235], v[12:15]
	v_mfma_f32_16x16x32_bf16 v[8:11], v[208:211], v[232:235], v[8:11]
	v_lshl_add_u64 v[178:179], v[246:247], 0, s[8:9]
	s_mov_b32 m0, s91
	s_nop 0
	global_load_lds_dwordx4 v[178:179], off
	v_mfma_f32_16x16x32_bf16 v[4:7], v[194:197], v[240:243], v[4:7]
	v_mfma_f32_16x16x32_bf16 v[0:3], v[208:211], v[240:243], v[0:3]
	s_setprio 0
	s_barrier
	s_add_i32 vcc_lo, vcc_lo, 2
	s_add_u32 s58, s58, 0x100
	s_addc_u32 s59, s59, 0
	s_add_u32 s96, s96, 0x100
	s_addc_u32 s97, s97, 0
	.p2align 6

; template <class Epi, class Sched, bool ALIGN_EPI = false, bool SP2 = false>
; __device__ __forceinline__ void gemm_phase(PG8_LAS unsigned char* lds, const Gemm g, const Sched& S, const Epi& E) {
;     ...
;     for (;;) {
;         const bool has_next = S.next(ui + 1, nxt);
;         const char* nA = has_next ? (const char*)g.A + (size_t)nxt.pm * tstep : cA; const char* nB = has_next ? (const char*)g.Bt + (size_t)nxt.pn * tstep : cB;
;         for (int t = 0; t < nt; t += 2) {
;             const bool last = (t == nt - 2);
;             const char* a1 = cA + (size_t)(t + 1) * kstep;
;             const char* a2 = last ? nA : cA + (size_t)(t + 2) * kstep; const char* b2 = last ? nB : cB + (size_t)(t + 2) * kstep;
;             const char* a3 = a2 + kstep; const char* b3 = b2 + kstep;
;             if (last && has_next) S.a_ready(nxt);
;     ...
; #pragma unroll
;         for (int a = 0; a < 2; ++a)
; #pragma unroll
;             for (int b = 0; b < 2; ++b)
; #pragma unroll
;                 for (int m = 0; m < 4; ++m)
; #pragma unroll
;                     for (int n = 0; n < 2; ++n) acc[a][b][m][n] = (f32x4){0.f, 0.f, 0.f, 0.f};
.LBB0_494:
	s_ashr_i32 s49, s48, 31
	s_lshl_b64 s[14:15], s[48:49], 19
	v_cmp_lt_i64_e64 s[54:55], s[50:51], 32
	s_add_u32 s50, s34, s14
	s_addc_u32 s51, s43, s15
	s_and_b64 s[14:15], s[54:55], exec
	s_cselect_b32 s49, s51, s61
	s_cselect_b32 s57, s50, s60
	s_ashr_i32 s45, s44, 31
	s_lshl_b64 s[14:15], s[44:45], 19
	s_add_u32 s52, s67, s14
	s_addc_u32 s53, s74, s15
	s_and_b64 s[14:15], s[54:55], exec
	s_cselect_b32 s45, s53, s63
	s_cselect_b32 s94, s52, s62
	s_add_u32 s60, s60, 0x40080
	s_addc_u32 s61, s61, 0
	s_add_u32 s95, s62, 0x100
	v_mov_b32_e32 v0, 0
	s_addc_u32 s96, s63, 0
	s_mov_b32 s97, -2
	v_mov_b32_e32 v1, v0
	v_mov_b32_e32 v2, v0
	v_mov_b32_e32 v3, v0
	v_mov_b32_e32 v4, v0
	v_mov_b32_e32 v5, v0
	v_mov_b32_e32 v6, v0
	v_mov_b32_e32 v7, v0
	v_mov_b32_e32 v8, v0
	v_mov_b32_e32 v9, v0
	v_mov_b32_e32 v10, v0
	v_mov_b32_e32 v11, v0
	v_mov_b32_e32 v12, v0
	v_mov_b32_e32 v13, v0
	v_mov_b32_e32 v14, v0
	v_mov_b32_e32 v15, v0
	v_mov_b32_e32 v16, v0
	v_mov_b32_e32 v17, v0
	v_mov_b32_e32 v18, v0
	v_mov_b32_e32 v19, v0
	v_mov_b32_e32 v20, v0
	v_mov_b32_e32 v21, v0
	v_mov_b32_e32 v22, v0
	v_mov_b32_e32 v23, v0
	v_mov_b32_e32 v24, v0
	v_mov_b32_e32 v25, v0
	v_mov_b32_e32 v26, v0
	v_mov_b32_e32 v27, v0
	v_mov_b32_e32 v28, v0
	v_mov_b32_e32 v29, v0
	v_mov_b32_e32 v30, v0
	v_mov_b32_e32 v31, v0
	v_mov_b32_e32 v64, v0
	v_mov_b32_e32 v65, v0
	v_mov_b32_e32 v66, v0
	v_mov_b32_e32 v67, v0
	v_mov_b32_e32 v68, v0
	v_mov_b32_e32 v69, v0
	v_mov_b32_e32 v70, v0
	v_mov_b32_e32 v71, v0
	v_mov_b32_e32 v72, v0
	v_mov_b32_e32 v73, v0
	v_mov_b32_e32 v74, v0
	v_mov_b32_e32 v75, v0
	v_mov_b32_e32 v76, v0
	v_mov_b32_e32 v77, v0
	v_mov_b32_e32 v78, v0
	v_mov_b32_e32 v79, v0
	v_mov_b32_e32 v80, v0
	v_mov_b32_e32 v81, v0
	v_mov_b32_e32 v82, v0
	v_mov_b32_e32 v83, v0
	v_mov_b32_e32 v84, v0
	v_mov_b32_e32 v85, v0
	v_mov_b32_e32 v86, v0
	v_mov_b32_e32 v87, v0
	v_mov_b32_e32 v88, v0
	v_mov_b32_e32 v89, v0
	v_mov_b32_e32 v90, v0
	v_mov_b32_e32 v91, v0
	v_mov_b32_e32 v92, v0
	v_mov_b32_e32 v93, v0
	v_mov_b32_e32 v94, v0
	v_mov_b32_e32 v95, v0
	v_mov_b32_e32 v32, v0
	v_mov_b32_e32 v33, v0
	v_mov_b32_e32 v34, v0
	v_mov_b32_e32 v35, v0
	v_mov_b32_e32 v36, v0
	v_mov_b32_e32 v37, v0
	v_mov_b32_e32 v38, v0
	v_mov_b32_e32 v39, v0
	v_mov_b32_e32 v40, v0
	v_mov_b32_e32 v41, v0
	v_mov_b32_e32 v42, v0
	v_mov_b32_e32 v43, v0
	v_mov_b32_e32 v44, v0
	v_mov_b32_e32 v45, v0
	v_mov_b32_e32 v46, v0
	v_mov_b32_e32 v47, v0
	v_mov_b32_e32 v48, v0
	v_mov_b32_e32 v49, v0
	v_mov_b32_e32 v50, v0
	v_mov_b32_e32 v51, v0
	v_mov_b32_e32 v52, v0
	v_mov_b32_e32 v53, v0
	v_mov_b32_e32 v54, v0
	v_mov_b32_e32 v55, v0
	v_mov_b32_e32 v56, v0
	v_mov_b32_e32 v57, v0
	v_mov_b32_e32 v58, v0
	v_mov_b32_e32 v59, v0
	v_mov_b32_e32 v60, v0
	v_mov_b32_e32 v61, v0
	v_mov_b32_e32 v62, v0
	v_mov_b32_e32 v63, v0
	v_mov_b32_e32 v96, v0
	v_mov_b32_e32 v97, v0
	v_mov_b32_e32 v98, v0
	v_mov_b32_e32 v99, v0
	v_mov_b32_e32 v100, v0
	v_mov_b32_e32 v101, v0
	v_mov_b32_e32 v102, v0
	v_mov_b32_e32 v103, v0
	v_mov_b32_e32 v104, v0
	v_mov_b32_e32 v105, v0
	v_mov_b32_e32 v106, v0
	v_mov_b32_e32 v107, v0
	v_mov_b32_e32 v108, v0
	v_mov_b32_e32 v109, v0
	v_mov_b32_e32 v110, v0
	v_mov_b32_e32 v111, v0
	v_mov_b32_e32 v112, v0
	v_mov_b32_e32 v113, v0
	v_mov_b32_e32 v114, v0
	v_mov_b32_e32 v115, v0
	v_mov_b32_e32 v116, v0
	v_mov_b32_e32 v117, v0
	v_mov_b32_e32 v118, v0
	v_mov_b32_e32 v119, v0
	v_mov_b32_e32 v120, v0
	v_mov_b32_e32 v121, v0
	v_mov_b32_e32 v122, v0
	v_mov_b32_e32 v123, v0
	v_mov_b32_e32 v124, v0
	v_mov_b32_e32 v125, v0
	v_mov_b32_e32 v126, v0
	v_mov_b32_e32 v127, v0
	.p2align 6

; #define PG8_STAGE(bufoff, gbase, voff) do { _Pragma("unroll") for (int _i = 0; _i < 2; ++_i) \
;         __builtin_amdgcn_global_load_lds((const unsigned*)((const char*)(gbase) + (voff)[_i]), (PG8_LAS unsigned*)(lds + (bufoff) + ldsw + _i * 8192), 16, 0, 0); } while (0)
; #define PG8_LDA(dst, b, h) do { _Pragma("unroll") for (int m = 0; m < 4; ++m) _Pragma("unroll") for (int k = 0; k < 2; ++k) dst[m][k] = *(const PG8_LAS bf16x8*)(lds + PG8_SA(b, h) + aoff + m * 2048 + k * 1024); } while (0)
; template <class Epi, class Sched, bool ALIGN_EPI = false, bool SP2 = false>
; __device__ __forceinline__ void gemm_phase(PG8_LAS unsigned char* lds, const Gemm g, const Sched& S, const Epi& E) {
;     ...
;     for (;;) {
;         const bool has_next = S.next(ui + 1, nxt);
;         const char* nA = has_next ? (const char*)g.A + (size_t)nxt.pm * tstep : cA; const char* nB = has_next ? (const char*)g.Bt + (size_t)nxt.pn * tstep : cB;
;         for (int t = 0; t < nt; t += 2) {
;             const bool last = (t == nt - 2);
;             const char* a1 = cA + (size_t)(t + 1) * kstep;
;             const char* a2 = last ? nA : cA + (size_t)(t + 2) * kstep; const char* b2 = last ? nB : cB + (size_t)(t + 2) * kstep;
;             const char* a3 = a2 + kstep; const char* b3 = b2 + kstep;
;             if (last && has_next) S.a_ready(nxt);
;             if constexpr (SP2) {
;             PG8_LDB(B0, 0, 0); PG8_LDB(B1, 0, 1); PG8_SCHED; PG8_LDA(At, 0, 0); PG8_STAGE(PG8_SA(1, 1), a1 + hstep, voffA);
;             PG8_WAIT_V(8); PG8_WAIT_L(0); PG8_BAR; PG8_MMA(0, 0, At, B0); PG8_MMA(0, 1, At, B1); PG8_BAR; PG8_SCHED;
;             PG8_LDA(At, 0, 1); PG8_STAGE(PG8_SB(0, 0), b2, voffB); PG8_STAGE(PG8_SB(0, 1), b2 + hstep, voffB); PG8_STAGE(PG8_SA(0, 0), a2, voffA);
;             PG8_WAIT_V(8); PG8_WAIT_L(0); PG8_BAR; PG8_MMA(1, 0, At, B0); PG8_MMA(1, 1, At, B1); PG8_BAR; PG8_SCHED;
;             PG8_LDB(B0, 1, 0); PG8_LDB(B1, 1, 1); PG8_SCHED; PG8_LDA(At, 1, 0); PG8_STAGE(PG8_SA(0, 1), a2 + hstep, voffA);
;             PG8_WAIT_V(8); PG8_WAIT_L(0); PG8_BAR; PG8_MMA(0, 0, At, B0); PG8_MMA(0, 1, At, B1); PG8_BAR; PG8_SCHED;
;             PG8_LDA(At, 1, 1); PG8_STAGE(PG8_SB(1, 0), b3, voffB); PG8_STAGE(PG8_SB(1, 1), b3 + hstep, voffB); PG8_STAGE(PG8_SA(1, 0), a3, voffA);
;             PG8_WAIT_V(8); PG8_WAIT_L(0); PG8_BAR; PG8_MMA(1, 0, At, B0); PG8_MMA(1, 1, At, B1); PG8_BAR; PG8_SCHED;
.LBB0_649:
	s_ashr_i32 s51, s50, 31
	s_lshl_b64 s[14:15], s[50:51], 19
	s_add_u32 s52, s40, s14
	s_addc_u32 s53, s41, s15
	s_and_b64 s[14:15], s[8:9], exec
	s_cselect_b32 s51, s53, s61
	s_cselect_b32 s57, s52, s60
	s_ashr_i32 s49, s48, 31
	s_lshl_b64 s[14:15], s[48:49], 19
	s_add_u32 s54, s82, s14
	s_addc_u32 s55, s83, s15
	s_and_b64 s[14:15], s[8:9], exec
	s_cselect_b32 s49, s55, s63
	s_cselect_b32 s89, s54, s62
	s_add_u32 s60, s60, 0x40080
	s_addc_u32 s61, s61, 0
	s_add_u32 s90, s62, 0x100
	s_addc_u32 s91, s63, 0
	s_mov_b32 s92, -2
	s_waitcnt lgkmcnt(0)
	s_waitcnt vmcnt(0)
	ds_read_b128 v[148:151], v155
	ds_read_b128 v[160:163], v155 offset:1024
	ds_read_b128 v[164:167], v155 offset:2048
	ds_read_b128 v[168:171], v155 offset:3072
	ds_read_b128 v[172:175], v156
	ds_read_b128 v[176:179], v156 offset:1024
	ds_read_b128 v[182:185], v156 offset:2048
	ds_read_b128 v[186:189], v156 offset:3072
	s_add_u32 s3, s60, 0xfffc0080
	s_addc_u32 s14, s61, -1
	s_cmp_eq_u32 s92, 12
	s_cselect_b32 s65, s51, s14
	s_cselect_b32 s64, s57, s3
	s_cselect_b32 s63, s49, s91
	s_cselect_b32 s62, s89, s90
	v_lshl_add_u64 v[202:203], s[60:61], 0, v[140:141]
	s_add_i32 m0, s43, 0xc000
	ds_read_b128 v[190:193], v157
	ds_read_b128 v[194:197], v157 offset:1024
	ds_read_b128 v[198:201], v157 offset:2048
	ds_read_b128 v[208:211], v157 offset:3072
	ds_read_b128 v[212:215], v157 offset:4096
	ds_read_b128 v[216:219], v157 offset:5120
	ds_read_b128 v[220:223], v157 offset:6144
	ds_read_b128 v[224:227], v157 offset:7168
	global_load_lds_dwordx4 v[202:203], off
	v_lshl_add_u64 v[202:203], s[60:61], 0, v[142:143]
	s_add_i32 m0, s43, 0xe000
	s_nop 0
	global_load_lds_dwordx4 v[202:203], off
	s_waitcnt vmcnt(8)
	s_waitcnt lgkmcnt(0)
	s_barrier
	s_setprio 1
	s_waitcnt lgkmcnt(0)
	v_mfma_f32_16x16x32_bf16 v[124:127], v[148:151], v[190:193], 0
	v_mfma_f32_16x16x32_bf16 v[120:123], v[164:167], v[190:193], 0
	v_mfma_f32_16x16x32_bf16 v[108:111], v[148:151], v[198:201], 0
	v_mfma_f32_16x16x32_bf16 v[104:107], v[164:167], v[198:201], 0
	v_mfma_f32_16x16x32_bf16 v[92:95], v[148:151], v[212:215], 0
	v_mfma_f32_16x16x32_bf16 v[88:91], v[164:167], v[212:215], 0
	v_mfma_f32_16x16x32_bf16 v[76:79], v[148:151], v[220:223], 0
	v_mfma_f32_16x16x32_bf16 v[72:75], v[164:167], v[220:223], 0
	v_mfma_f32_16x16x32_bf16 v[124:127], v[160:163], v[194:197], v[124:127]
	v_mfma_f32_16x16x32_bf16 v[120:123], v[168:171], v[194:197], v[120:123]
	v_mfma_f32_16x16x32_bf16 v[108:111], v[160:163], v[208:211], v[108:111]
	v_mfma_f32_16x16x32_bf16 v[104:107], v[168:171], v[208:211], v[104:107]
	v_mfma_f32_16x16x32_bf16 v[92:95], v[160:163], v[216:219], v[92:95]
	v_mfma_f32_16x16x32_bf16 v[88:91], v[168:171], v[216:219], v[88:91]
	v_mfma_f32_16x16x32_bf16 v[76:79], v[160:163], v[224:227], v[76:79]
	v_mfma_f32_16x16x32_bf16 v[72:75], v[168:171], v[224:227], v[72:75]
	s_setprio 0
	s_setprio 1
	v_mfma_f32_16x16x32_bf16 v[116:119], v[172:175], v[190:193], 0
	v_mfma_f32_16x16x32_bf16 v[112:115], v[182:185], v[190:193], 0
	v_mfma_f32_16x16x32_bf16 v[100:103], v[172:175], v[198:201], 0
	v_mfma_f32_16x16x32_bf16 v[96:99], v[182:185], v[198:201], 0
	v_mfma_f32_16x16x32_bf16 v[84:87], v[172:175], v[212:215], 0
	v_mfma_f32_16x16x32_bf16 v[80:83], v[182:185], v[212:215], 0
	v_mfma_f32_16x16x32_bf16 v[68:71], v[172:175], v[220:223], 0
	v_mfma_f32_16x16x32_bf16 v[64:67], v[182:185], v[220:223], 0
	v_mfma_f32_16x16x32_bf16 v[116:119], v[176:179], v[194:197], v[116:119]
	v_mfma_f32_16x16x32_bf16 v[112:115], v[186:189], v[194:197], v[112:115]
	v_mfma_f32_16x16x32_bf16 v[100:103], v[176:179], v[208:211], v[100:103]
	v_mfma_f32_16x16x32_bf16 v[96:99], v[186:189], v[208:211], v[96:99]
	v_mfma_f32_16x16x32_bf16 v[84:87], v[176:179], v[216:219], v[84:87]
	v_mfma_f32_16x16x32_bf16 v[80:83], v[186:189], v[216:219], v[80:83]
	v_mfma_f32_16x16x32_bf16 v[68:71], v[176:179], v[224:227], v[68:71]
	v_mfma_f32_16x16x32_bf16 v[64:67], v[186:189], v[224:227], v[64:67]
	s_setprio 0
	s_barrier
	s_add_i32 s3, s85, s34
	v_lshl_add_u64 v[202:203], s[62:63], 0, v[134:135]
	s_mov_b32 m0, s3
	ds_read_b128 v[190:193], v157 offset:16384
	ds_read_b128 v[194:197], v157 offset:17408
	ds_read_b128 v[198:201], v157 offset:18432
	ds_read_b128 v[208:211], v157 offset:19456
	ds_read_b128 v[212:215], v157 offset:20480
	ds_read_b128 v[216:219], v157 offset:21504
	ds_read_b128 v[220:223], v157 offset:22528
	ds_read_b128 v[224:227], v157 offset:23552
	global_load_lds_dwordx4 v[202:203], off
	s_add_i32 m0, s3, 0x2000
	s_add_u32 s14, s62, 0x40000
	v_lshl_add_u64 v[228:229], s[62:63], 0, v[138:139]
	s_addc_u32 s15, s63, 0
	s_add_i32 s3, s86, s34
	global_load_lds_dwordx4 v[228:229], off
	v_lshl_add_u64 v[230:231], s[14:15], 0, v[134:135]
	s_mov_b32 m0, s3
	global_load_lds_dwordx4 v[230:231], off
	v_lshl_add_u64 v[230:231], s[14:15], 0, v[138:139]
	s_add_i32 m0, s3, 0x2000
	s_nop 0
	global_load_lds_dwordx4 v[230:231], off
	s_waitcnt vmcnt(6)
	s_waitcnt lgkmcnt(0)
	s_barrier
; #define PG8_STAGE(bufoff, gbase, voff) do { _Pragma("unroll") for (int _i = 0; _i < 2; ++_i) \
;         __builtin_amdgcn_global_load_lds((const unsigned*)((const char*)(gbase) + (voff)[_i]), (PG8_LAS unsigned*)(lds + (bufoff) + ldsw + _i * 8192), 16, 0, 0); } while (0)
; #define PG8_LDA(dst, b, h) do { _Pragma("unroll") for (int m = 0; m < 4; ++m) _Pragma("unroll") for (int k = 0; k < 2; ++k) dst[m][k] = *(const PG8_LAS bf16x8*)(lds + PG8_SA(b, h) + aoff + m * 2048 + k * 1024); } while (0)
; #define PG8_LDB(dst, b, h) do { _Pragma("unroll") for (int n = 0; n < 2; ++n) _Pragma("unroll") for (int k = 0; k < 2; ++k) dst[n][k] = *(const PG8_LAS bf16x8*)(lds + PG8_SB(b, h) + boff + n * 2048 + k * 1024); } while (0)
; #define PG8_MMA(ai, bj, At, Bt) do { __builtin_amdgcn_s_setprio(1); _Pragma("unroll") for (int m = 0; m < 4; ++m) _Pragma("unroll") for (int n = 0; n < 2; ++n) _Pragma("unroll") for (int k = 0; k < 2; ++k) \
;         acc[ai][bj][m][n] = __builtin_amdgcn_mfma_f32_16x16x32_bf16(Bt[n][k], At[m][k], acc[ai][bj][m][n], 0, 0, 0); __builtin_amdgcn_s_setprio(0); } while (0)
; #define PG8_WAIT_V(n) asm volatile("s_waitcnt vmcnt(" #n ")" ::: "memory")
; #define PG8_WAIT_L(n) asm volatile("s_waitcnt lgkmcnt(" #n ")" ::: "memory")
; #define PG8_BAR __builtin_amdgcn_s_barrier()
; #define PG8_SCHED __builtin_amdgcn_sched_barrier(0)
; template <class Epi, class Sched, bool ALIGN_EPI = false, bool SP2 = false>
; __device__ __forceinline__ void gemm_phase(PG8_LAS unsigned char* lds, const Gemm g, const Sched& S, const Epi& E) {
;     ...
;             PG8_WAIT_V(8); PG8_WAIT_L(0); PG8_BAR; PG8_MMA(0, 0, At, B0); PG8_MMA(0, 1, At, B1); PG8_BAR; PG8_SCHED;
;             PG8_LDA(At, 0, 1); PG8_STAGE(PG8_SB(0, 0), b2, voffB); PG8_STAGE(PG8_SB(0, 1), b2 + hstep, voffB); PG8_STAGE(PG8_SA(0, 0), a2, voffA);
;             PG8_WAIT_V(8); PG8_WAIT_L(0); PG8_BAR; PG8_MMA(1, 0, At, B0); PG8_MMA(1, 1, At, B1); PG8_BAR; PG8_SCHED;
;             PG8_LDB(B0, 1, 0); PG8_LDB(B1, 1, 1); PG8_SCHED; PG8_LDA(At, 1, 0); PG8_STAGE(PG8_SA(0, 1), a2 + hstep, voffA);
;             PG8_WAIT_V(8); PG8_WAIT_L(0); PG8_BAR; PG8_MMA(0, 0, At, B0); PG8_MMA(0, 1, At, B1); PG8_BAR; PG8_SCHED;
;             PG8_LDA(At, 1, 1); PG8_STAGE(PG8_SB(1, 0), b3, voffB); PG8_STAGE(PG8_SB(1, 1), b3 + hstep, voffB); PG8_STAGE(PG8_SA(1, 0), a3, voffA);
	s_setprio 1
	s_waitcnt lgkmcnt(0)
	v_mfma_f32_16x16x32_bf16 v[60:63], v[148:151], v[190:193], 0
	v_mfma_f32_16x16x32_bf16 v[56:59], v[164:167], v[190:193], 0
	v_mfma_f32_16x16x32_bf16 v[44:47], v[148:151], v[198:201], 0
	v_mfma_f32_16x16x32_bf16 v[40:43], v[164:167], v[198:201], 0
	v_mfma_f32_16x16x32_bf16 v[28:31], v[148:151], v[212:215], 0
	v_mfma_f32_16x16x32_bf16 v[24:27], v[164:167], v[212:215], 0
	v_mfma_f32_16x16x32_bf16 v[12:15], v[148:151], v[220:223], 0
	v_mfma_f32_16x16x32_bf16 v[8:11], v[164:167], v[220:223], 0
	v_mfma_f32_16x16x32_bf16 v[60:63], v[160:163], v[194:197], v[60:63]
	v_mfma_f32_16x16x32_bf16 v[56:59], v[168:171], v[194:197], v[56:59]
	v_mfma_f32_16x16x32_bf16 v[44:47], v[160:163], v[208:211], v[44:47]
	v_mfma_f32_16x16x32_bf16 v[40:43], v[168:171], v[208:211], v[40:43]
	v_mfma_f32_16x16x32_bf16 v[28:31], v[160:163], v[216:219], v[28:31]
	v_mfma_f32_16x16x32_bf16 v[24:27], v[168:171], v[216:219], v[24:27]
	v_lshl_add_u64 v[230:231], s[64:65], 0, v[132:133]
	s_mov_b32 m0, s43
	s_nop 0
	global_load_lds_dwordx4 v[230:231], off
	v_mfma_f32_16x16x32_bf16 v[12:15], v[160:163], v[224:227], v[12:15]
	v_mfma_f32_16x16x32_bf16 v[8:11], v[168:171], v[224:227], v[8:11]
	s_setprio 0
	s_setprio 1
	v_mfma_f32_16x16x32_bf16 v[52:55], v[172:175], v[190:193], 0
	v_mfma_f32_16x16x32_bf16 v[48:51], v[182:185], v[190:193], 0
	v_mfma_f32_16x16x32_bf16 v[36:39], v[172:175], v[198:201], 0
	v_mfma_f32_16x16x32_bf16 v[32:35], v[182:185], v[198:201], 0
	v_mfma_f32_16x16x32_bf16 v[20:23], v[172:175], v[212:215], 0
	v_mfma_f32_16x16x32_bf16 v[16:19], v[182:185], v[212:215], 0
	v_mfma_f32_16x16x32_bf16 v[4:7], v[172:175], v[220:223], 0
	v_mfma_f32_16x16x32_bf16 v[0:3], v[182:185], v[220:223], 0
	v_mfma_f32_16x16x32_bf16 v[52:55], v[176:179], v[194:197], v[52:55]
	v_mfma_f32_16x16x32_bf16 v[48:51], v[186:189], v[194:197], v[48:51]
	v_mfma_f32_16x16x32_bf16 v[36:39], v[176:179], v[208:211], v[36:39]
	v_mfma_f32_16x16x32_bf16 v[32:35], v[186:189], v[208:211], v[32:35]
	v_mfma_f32_16x16x32_bf16 v[20:23], v[176:179], v[216:219], v[20:23]
	v_mfma_f32_16x16x32_bf16 v[16:19], v[186:189], v[216:219], v[16:19]
	v_lshl_add_u64 v[232:233], s[64:65], 0, v[136:137]
	s_mov_b32 m0, s59
	s_nop 0
	global_load_lds_dwordx4 v[232:233], off
	v_mfma_f32_16x16x32_bf16 v[4:7], v[176:179], v[224:227], v[4:7]
	v_mfma_f32_16x16x32_bf16 v[0:3], v[186:189], v[224:227], v[0:3]
	s_setprio 0
	s_barrier
	s_add_i32 s3, 0, 0x18000
	v_add_u32_e32 v159, s3, v131
	s_add_i32 s33, 0, 0x1c000
	ds_read_b128 v[148:151], v159
	ds_read_b128 v[160:163], v159 offset:1024
	ds_read_b128 v[164:167], v159 offset:2048
	ds_read_b128 v[168:171], v159 offset:3072
	v_add_u32_e32 v159, s33, v131
	ds_read_b128 v[172:175], v159
	ds_read_b128 v[176:179], v159 offset:1024
	ds_read_b128 v[182:185], v159 offset:2048
	ds_read_b128 v[186:189], v159 offset:3072
	s_add_u32 s14, s64, 0x40000
	s_addc_u32 s15, s65, 0
	s_mov_b32 m0, s66
	v_lshl_add_u64 v[234:235], s[14:15], 0, v[132:133]
	ds_read_b128 v[190:193], v157 offset:32768
	ds_read_b128 v[194:197], v157 offset:33792
	ds_read_b128 v[198:201], v157 offset:34816
	ds_read_b128 v[208:211], v157 offset:35840
	ds_read_b128 v[212:215], v157 offset:36864
	ds_read_b128 v[216:219], v157 offset:37888
	ds_read_b128 v[220:223], v157 offset:38912
	ds_read_b128 v[224:227], v157 offset:39936
	global_load_lds_dwordx4 v[234:235], off
	v_lshl_add_u64 v[234:235], s[14:15], 0, v[136:137]
	s_mov_b32 m0, s67
	s_nop 0
	global_load_lds_dwordx4 v[234:235], off
	s_waitcnt vmcnt(8)
	s_waitcnt lgkmcnt(0)
	s_barrier
	s_setprio 1
	s_waitcnt lgkmcnt(0)
	v_mfma_f32_16x16x32_bf16 v[124:127], v[148:151], v[190:193], v[124:127]
	v_mfma_f32_16x16x32_bf16 v[120:123], v[164:167], v[190:193], v[120:123]
	v_mfma_f32_16x16x32_bf16 v[108:111], v[148:151], v[198:201], v[108:111]
	v_mfma_f32_16x16x32_bf16 v[104:107], v[164:167], v[198:201], v[104:107]
	v_mfma_f32_16x16x32_bf16 v[92:95], v[148:151], v[212:215], v[92:95]
	v_mfma_f32_16x16x32_bf16 v[88:91], v[164:167], v[212:215], v[88:91]
	v_mfma_f32_16x16x32_bf16 v[76:79], v[148:151], v[220:223], v[76:79]
	v_mfma_f32_16x16x32_bf16 v[72:75], v[164:167], v[220:223], v[72:75]
	v_mfma_f32_16x16x32_bf16 v[124:127], v[160:163], v[194:197], v[124:127]
	v_mfma_f32_16x16x32_bf16 v[120:123], v[168:171], v[194:197], v[120:123]
	v_mfma_f32_16x16x32_bf16 v[108:111], v[160:163], v[208:211], v[108:111]
	v_mfma_f32_16x16x32_bf16 v[104:107], v[168:171], v[208:211], v[104:107]
	v_mfma_f32_16x16x32_bf16 v[92:95], v[160:163], v[216:219], v[92:95]
	v_mfma_f32_16x16x32_bf16 v[88:91], v[168:171], v[216:219], v[88:91]
	v_mfma_f32_16x16x32_bf16 v[76:79], v[160:163], v[224:227], v[76:79]
	v_mfma_f32_16x16x32_bf16 v[72:75], v[168:171], v[224:227], v[72:75]
	s_setprio 0
	s_setprio 1
	v_mfma_f32_16x16x32_bf16 v[116:119], v[172:175], v[190:193], v[116:119]
	v_mfma_f32_16x16x32_bf16 v[112:115], v[182:185], v[190:193], v[112:115]
	v_mfma_f32_16x16x32_bf16 v[100:103], v[172:175], v[198:201], v[100:103]
	v_mfma_f32_16x16x32_bf16 v[96:99], v[182:185], v[198:201], v[96:99]
	v_mfma_f32_16x16x32_bf16 v[84:87], v[172:175], v[212:215], v[84:87]
	v_mfma_f32_16x16x32_bf16 v[80:83], v[182:185], v[212:215], v[80:83]
	v_mfma_f32_16x16x32_bf16 v[68:71], v[172:175], v[220:223], v[68:71]
	v_mfma_f32_16x16x32_bf16 v[64:67], v[182:185], v[220:223], v[64:67]
	v_mfma_f32_16x16x32_bf16 v[116:119], v[176:179], v[194:197], v[116:119]
	v_mfma_f32_16x16x32_bf16 v[112:115], v[186:189], v[194:197], v[112:115]
	v_mfma_f32_16x16x32_bf16 v[100:103], v[176:179], v[208:211], v[100:103]
	v_mfma_f32_16x16x32_bf16 v[96:99], v[186:189], v[208:211], v[96:99]
	v_mfma_f32_16x16x32_bf16 v[84:87], v[176:179], v[216:219], v[84:87]
	v_mfma_f32_16x16x32_bf16 v[80:83], v[186:189], v[216:219], v[80:83]
	v_mfma_f32_16x16x32_bf16 v[68:71], v[176:179], v[224:227], v[68:71]
	v_mfma_f32_16x16x32_bf16 v[64:67], v[186:189], v[224:227], v[64:67]
	s_setprio 0
	s_barrier
; #define PG8_STAGE(bufoff, gbase, voff) do { _Pragma("unroll") for (int _i = 0; _i < 2; ++_i) \
;         __builtin_amdgcn_global_load_lds((const unsigned*)((const char*)(gbase) + (voff)[_i]), (PG8_LAS unsigned*)(lds + (bufoff) + ldsw + _i * 8192), 16, 0, 0); } while (0)
; #define PG8_LDA(dst, b, h) do { _Pragma("unroll") for (int m = 0; m < 4; ++m) _Pragma("unroll") for (int k = 0; k < 2; ++k) dst[m][k] = *(const PG8_LAS bf16x8*)(lds + PG8_SA(b, h) + aoff + m * 2048 + k * 1024); } while (0)
; #define PG8_MMA(ai, bj, At, Bt) do { __builtin_amdgcn_s_setprio(1); _Pragma("unroll") for (int m = 0; m < 4; ++m) _Pragma("unroll") for (int n = 0; n < 2; ++n) _Pragma("unroll") for (int k = 0; k < 2; ++k) \
;         acc[ai][bj][m][n] = __builtin_amdgcn_mfma_f32_16x16x32_bf16(Bt[n][k], At[m][k], acc[ai][bj][m][n], 0, 0, 0); __builtin_amdgcn_s_setprio(0); } while (0)
; #define PG8_WAIT_V(n) asm volatile("s_waitcnt vmcnt(" #n ")" ::: "memory")
; #define PG8_WAIT_L(n) asm volatile("s_waitcnt lgkmcnt(" #n ")" ::: "memory")
; #define PG8_BAR __builtin_amdgcn_s_barrier()
; #define PG8_SCHED __builtin_amdgcn_sched_barrier(0)
; template <class Epi, class Sched, bool ALIGN_EPI = false, bool SP2 = false>
; __device__ __forceinline__ void gemm_phase(PG8_LAS unsigned char* lds, const Gemm g, const Sched& S, const Epi& E) {
;     ...
;         for (int t = 0; t < nt; t += 2) {
;     ...
;             PG8_LDA(At, 1, 1); PG8_STAGE(PG8_SB(1, 0), b3, voffB); PG8_STAGE(PG8_SB(1, 1), b3 + hstep, voffB); PG8_STAGE(PG8_SA(1, 0), a3, voffA);
;             PG8_WAIT_V(8); PG8_WAIT_L(0); PG8_BAR; PG8_MMA(1, 0, At, B0); PG8_MMA(1, 1, At, B1); PG8_BAR; PG8_SCHED;
	s_add_i32 s3, s3, s34
	v_lshl_add_u64 v[202:203], v[202:203], 0, s[38:39]
	s_mov_b32 m0, s3
	ds_read_b128 v[190:193], v157 offset:49152
	ds_read_b128 v[194:197], v157 offset:50176
	ds_read_b128 v[198:201], v157 offset:51200
	ds_read_b128 v[208:211], v157 offset:52224
	ds_read_b128 v[212:215], v157 offset:53248
	ds_read_b128 v[216:219], v157 offset:54272
	ds_read_b128 v[220:223], v157 offset:55296
	ds_read_b128 v[224:227], v157 offset:56320
	global_load_lds_dwordx4 v[202:203], off
	s_add_i32 m0, s3, 0x2000
	s_add_u32 s14, s62, 0x40080
	v_lshl_add_u64 v[202:203], v[228:229], 0, s[38:39]
	s_addc_u32 s15, s63, 0
	s_add_i32 s3, s33, s34
	global_load_lds_dwordx4 v[202:203], off
	v_lshl_add_u64 v[202:203], s[14:15], 0, v[134:135]
	s_mov_b32 m0, s3
	s_nop 0
	global_load_lds_dwordx4 v[202:203], off
	v_lshl_add_u64 v[202:203], s[14:15], 0, v[138:139]
	s_add_i32 m0, s3, 0x2000
	s_nop 0
	global_load_lds_dwordx4 v[202:203], off
	s_waitcnt vmcnt(6)
	s_waitcnt lgkmcnt(0)
	s_barrier
	s_setprio 1
	s_waitcnt lgkmcnt(0)
	v_mfma_f32_16x16x32_bf16 v[60:63], v[148:151], v[190:193], v[60:63]
	v_mfma_f32_16x16x32_bf16 v[56:59], v[164:167], v[190:193], v[56:59]
	v_mfma_f32_16x16x32_bf16 v[44:47], v[148:151], v[198:201], v[44:47]
	v_mfma_f32_16x16x32_bf16 v[40:43], v[164:167], v[198:201], v[40:43]
	v_mfma_f32_16x16x32_bf16 v[28:31], v[148:151], v[212:215], v[28:31]
	v_mfma_f32_16x16x32_bf16 v[24:27], v[164:167], v[212:215], v[24:27]
	v_mfma_f32_16x16x32_bf16 v[12:15], v[148:151], v[220:223], v[12:15]
	v_mfma_f32_16x16x32_bf16 v[8:11], v[164:167], v[220:223], v[8:11]
	v_mfma_f32_16x16x32_bf16 v[60:63], v[160:163], v[194:197], v[60:63]
	v_mfma_f32_16x16x32_bf16 v[56:59], v[168:171], v[194:197], v[56:59]
	v_mfma_f32_16x16x32_bf16 v[44:47], v[160:163], v[208:211], v[44:47]
	v_mfma_f32_16x16x32_bf16 v[40:43], v[168:171], v[208:211], v[40:43]
	v_mfma_f32_16x16x32_bf16 v[28:31], v[160:163], v[216:219], v[28:31]
	v_mfma_f32_16x16x32_bf16 v[24:27], v[168:171], v[216:219], v[24:27]
	v_lshl_add_u64 v[202:203], v[230:231], 0, s[38:39]
	s_mov_b32 m0, s75
	s_nop 0
	global_load_lds_dwordx4 v[202:203], off
	v_mfma_f32_16x16x32_bf16 v[12:15], v[160:163], v[224:227], v[12:15]
	v_mfma_f32_16x16x32_bf16 v[8:11], v[168:171], v[224:227], v[8:11]
	s_setprio 0
	s_setprio 1
	v_mfma_f32_16x16x32_bf16 v[52:55], v[172:175], v[190:193], v[52:55]
	v_mfma_f32_16x16x32_bf16 v[48:51], v[182:185], v[190:193], v[48:51]
	v_mfma_f32_16x16x32_bf16 v[36:39], v[172:175], v[198:201], v[36:39]
	v_mfma_f32_16x16x32_bf16 v[32:35], v[182:185], v[198:201], v[32:35]
	v_mfma_f32_16x16x32_bf16 v[20:23], v[172:175], v[212:215], v[20:23]
	v_mfma_f32_16x16x32_bf16 v[16:19], v[182:185], v[212:215], v[16:19]
	v_mfma_f32_16x16x32_bf16 v[4:7], v[172:175], v[220:223], v[4:7]
	v_mfma_f32_16x16x32_bf16 v[0:3], v[182:185], v[220:223], v[0:3]
	v_mfma_f32_16x16x32_bf16 v[52:55], v[176:179], v[194:197], v[52:55]
	v_mfma_f32_16x16x32_bf16 v[48:51], v[186:189], v[194:197], v[48:51]
	v_mfma_f32_16x16x32_bf16 v[36:39], v[176:179], v[208:211], v[36:39]
	v_mfma_f32_16x16x32_bf16 v[32:35], v[186:189], v[208:211], v[32:35]
	v_mfma_f32_16x16x32_bf16 v[20:23], v[176:179], v[216:219], v[20:23]
	v_mfma_f32_16x16x32_bf16 v[16:19], v[186:189], v[216:219], v[16:19]
	v_lshl_add_u64 v[202:203], v[232:233], 0, s[38:39]
	s_mov_b32 m0, s84
	s_nop 0
	global_load_lds_dwordx4 v[202:203], off
	v_mfma_f32_16x16x32_bf16 v[4:7], v[176:179], v[224:227], v[4:7]
	v_mfma_f32_16x16x32_bf16 v[0:3], v[186:189], v[224:227], v[0:3]
	s_setprio 0
	s_barrier
	s_add_i32 s92, s92, 2
	s_add_u32 s60, s60, 0x100
	s_addc_u32 s61, s61, 0
	s_add_u32 s90, s90, 0x100
	s_addc_u32 s91, s91, 0
	.p2align 6

; #define PG8_STAGE(bufoff, gbase, voff) do { _Pragma("unroll") for (int _i = 0; _i < 2; ++_i) \
;         __builtin_amdgcn_global_load_lds((const unsigned*)((const char*)(gbase) + (voff)[_i]), (PG8_LAS unsigned*)(lds + (bufoff) + ldsw + _i * 8192), 16, 0, 0); } while (0)
; #define PG8_LDA(dst, b, h) do { _Pragma("unroll") for (int m = 0; m < 4; ++m) _Pragma("unroll") for (int k = 0; k < 2; ++k) dst[m][k] = *(const PG8_LAS bf16x8*)(lds + PG8_SA(b, h) + aoff + m * 2048 + k * 1024); } while (0)
; template <class Epi, class Sched, bool ALIGN_EPI = false, bool SP2 = false>
; __device__ __forceinline__ void gemm_phase(PG8_LAS unsigned char* lds, const Gemm g, const Sched& S, const Epi& E) {
;     ...
;     for (;;) {
;         const bool has_next = S.next(ui + 1, nxt);
;         const char* nA = has_next ? (const char*)g.A + (size_t)nxt.pm * tstep : cA; const char* nB = has_next ? (const char*)g.Bt + (size_t)nxt.pn * tstep : cB;
;         for (int t = 0; t < nt; t += 2) {
;             const bool last = (t == nt - 2);
;             const char* a1 = cA + (size_t)(t + 1) * kstep;
;             const char* a2 = last ? nA : cA + (size_t)(t + 2) * kstep; const char* b2 = last ? nB : cB + (size_t)(t + 2) * kstep;
;             const char* a3 = a2 + kstep; const char* b3 = b2 + kstep;
;             if (last && has_next) S.a_ready(nxt);
;             if constexpr (SP2) {
;             PG8_LDB(B0, 0, 0); PG8_LDB(B1, 0, 1); PG8_SCHED; PG8_LDA(At, 0, 0); PG8_STAGE(PG8_SA(1, 1), a1 + hstep, voffA);
;             PG8_WAIT_V(8); PG8_WAIT_L(0); PG8_BAR; PG8_MMA(0, 0, At, B0); PG8_MMA(0, 1, At, B1); PG8_BAR; PG8_SCHED;
;             PG8_LDA(At, 0, 1); PG8_STAGE(PG8_SB(0, 0), b2, voffB); PG8_STAGE(PG8_SB(0, 1), b2 + hstep, voffB); PG8_STAGE(PG8_SA(0, 0), a2, voffA);
;             PG8_WAIT_V(8); PG8_WAIT_L(0); PG8_BAR; PG8_MMA(1, 0, At, B0); PG8_MMA(1, 1, At, B1); PG8_BAR; PG8_SCHED;
;             PG8_LDB(B0, 1, 0); PG8_LDB(B1, 1, 1); PG8_SCHED; PG8_LDA(At, 1, 0); PG8_STAGE(PG8_SA(0, 1), a2 + hstep, voffA);
;             PG8_WAIT_V(8); PG8_WAIT_L(0); PG8_BAR; PG8_MMA(0, 0, At, B0); PG8_MMA(0, 1, At, B1); PG8_BAR; PG8_SCHED;
;             PG8_LDA(At, 1, 1); PG8_STAGE(PG8_SB(1, 0), b3, voffB); PG8_STAGE(PG8_SB(1, 1), b3 + hstep, voffB); PG8_STAGE(PG8_SA(1, 0), a3, voffA);
;             PG8_WAIT_V(8); PG8_WAIT_L(0); PG8_BAR; PG8_MMA(1, 0, At, B0); PG8_MMA(1, 1, At, B1); PG8_BAR; PG8_SCHED;
.LBB0_737:
	s_ashr_i32 s51, s50, 31
	s_lshl_b64 s[14:15], s[50:51], 19
	s_add_u32 s52, s22, s14
	s_addc_u32 s53, s23, s15
	s_and_b64 s[14:15], s[8:9], exec
	s_cselect_b32 s51, s53, s57
	s_cselect_b32 s82, s52, s56
	s_ashr_i32 s49, s48, 31
	s_lshl_b64 s[14:15], s[48:49], 19
	v_readlane_b32 s3, v250, 15
	s_add_u32 s54, s3, s14
	v_readlane_b32 s3, v250, 16
	s_addc_u32 s55, s3, s15
	s_and_b64 s[14:15], s[8:9], exec
	s_cselect_b32 s49, s55, s59
	s_cselect_b32 s83, s54, s58
	s_add_u32 s56, s56, 0x40080
	s_addc_u32 s57, s57, 0
	s_add_u32 s84, s58, 0x100
	s_addc_u32 s85, s59, 0
	s_mov_b32 s86, -2
	s_waitcnt vmcnt(0)
	ds_read_b128 v[148:151], v155
	ds_read_b128 v[160:163], v155 offset:1024
	ds_read_b128 v[164:167], v155 offset:2048
	ds_read_b128 v[168:171], v155 offset:3072
	ds_read_b128 v[172:175], v156
	ds_read_b128 v[176:179], v156 offset:1024
	ds_read_b128 v[182:185], v156 offset:2048
	ds_read_b128 v[186:189], v156 offset:3072
	s_add_u32 s3, s56, 0xfffc0080
	s_addc_u32 s14, s57, -1
	s_cmp_eq_u32 s86, 12
	s_cselect_b32 s61, s51, s14
	s_cselect_b32 s60, s82, s3
	s_cselect_b32 s59, s49, s85
	s_cselect_b32 s58, s83, s84
	v_lshl_add_u64 v[202:203], s[56:57], 0, v[140:141]
	s_add_i32 m0, s43, 0xc000
	ds_read_b128 v[190:193], v157
	ds_read_b128 v[194:197], v157 offset:1024
	ds_read_b128 v[198:201], v157 offset:2048
	ds_read_b128 v[208:211], v157 offset:3072
	ds_read_b128 v[212:215], v157 offset:4096
	ds_read_b128 v[216:219], v157 offset:5120
	ds_read_b128 v[220:223], v157 offset:6144
	ds_read_b128 v[224:227], v157 offset:7168
	global_load_lds_dwordx4 v[202:203], off
	v_lshl_add_u64 v[202:203], s[56:57], 0, v[142:143]
	s_add_i32 m0, s43, 0xe000
	s_nop 0
	global_load_lds_dwordx4 v[202:203], off
	s_waitcnt vmcnt(8)
	s_waitcnt lgkmcnt(0)
	s_barrier
	s_setprio 1
	s_waitcnt lgkmcnt(0)
	v_mfma_f32_16x16x32_bf16 v[124:127], v[148:151], v[190:193], 0
	v_mfma_f32_16x16x32_bf16 v[120:123], v[164:167], v[190:193], 0
	v_mfma_f32_16x16x32_bf16 v[108:111], v[148:151], v[198:201], 0
	v_mfma_f32_16x16x32_bf16 v[104:107], v[164:167], v[198:201], 0
	v_mfma_f32_16x16x32_bf16 v[92:95], v[148:151], v[212:215], 0
	v_mfma_f32_16x16x32_bf16 v[88:91], v[164:167], v[212:215], 0
	v_mfma_f32_16x16x32_bf16 v[76:79], v[148:151], v[220:223], 0
	v_mfma_f32_16x16x32_bf16 v[72:75], v[164:167], v[220:223], 0
	v_mfma_f32_16x16x32_bf16 v[124:127], v[160:163], v[194:197], v[124:127]
	v_mfma_f32_16x16x32_bf16 v[120:123], v[168:171], v[194:197], v[120:123]
	v_mfma_f32_16x16x32_bf16 v[108:111], v[160:163], v[208:211], v[108:111]
	v_mfma_f32_16x16x32_bf16 v[104:107], v[168:171], v[208:211], v[104:107]
	v_mfma_f32_16x16x32_bf16 v[92:95], v[160:163], v[216:219], v[92:95]
	v_mfma_f32_16x16x32_bf16 v[88:91], v[168:171], v[216:219], v[88:91]
	v_mfma_f32_16x16x32_bf16 v[76:79], v[160:163], v[224:227], v[76:79]
	v_mfma_f32_16x16x32_bf16 v[72:75], v[168:171], v[224:227], v[72:75]
	s_setprio 0
	s_setprio 1
	v_mfma_f32_16x16x32_bf16 v[116:119], v[172:175], v[190:193], 0
	v_mfma_f32_16x16x32_bf16 v[112:115], v[182:185], v[190:193], 0
	v_mfma_f32_16x16x32_bf16 v[100:103], v[172:175], v[198:201], 0
	v_mfma_f32_16x16x32_bf16 v[96:99], v[182:185], v[198:201], 0
	v_mfma_f32_16x16x32_bf16 v[84:87], v[172:175], v[212:215], 0
	v_mfma_f32_16x16x32_bf16 v[80:83], v[182:185], v[212:215], 0
	v_mfma_f32_16x16x32_bf16 v[68:71], v[172:175], v[220:223], 0
	v_mfma_f32_16x16x32_bf16 v[64:67], v[182:185], v[220:223], 0
	v_mfma_f32_16x16x32_bf16 v[116:119], v[176:179], v[194:197], v[116:119]
	v_mfma_f32_16x16x32_bf16 v[112:115], v[186:189], v[194:197], v[112:115]
	v_mfma_f32_16x16x32_bf16 v[100:103], v[176:179], v[208:211], v[100:103]
	v_mfma_f32_16x16x32_bf16 v[96:99], v[186:189], v[208:211], v[96:99]
	v_mfma_f32_16x16x32_bf16 v[84:87], v[176:179], v[216:219], v[84:87]
	v_mfma_f32_16x16x32_bf16 v[80:83], v[186:189], v[216:219], v[80:83]
	v_mfma_f32_16x16x32_bf16 v[68:71], v[176:179], v[224:227], v[68:71]
	v_mfma_f32_16x16x32_bf16 v[64:67], v[186:189], v[224:227], v[64:67]
	s_setprio 0
	s_barrier
	s_add_i32 s3, s74, s34
	v_lshl_add_u64 v[202:203], s[58:59], 0, v[136:137]
	s_mov_b32 m0, s3
	ds_read_b128 v[190:193], v157 offset:16384
	ds_read_b128 v[194:197], v157 offset:17408
	ds_read_b128 v[198:201], v157 offset:18432
	ds_read_b128 v[208:211], v157 offset:19456
	ds_read_b128 v[212:215], v157 offset:20480
	ds_read_b128 v[216:219], v157 offset:21504
	ds_read_b128 v[220:223], v157 offset:22528
	ds_read_b128 v[224:227], v157 offset:23552
	global_load_lds_dwordx4 v[202:203], off
	s_add_i32 m0, s3, 0x2000
	s_add_u32 s14, s58, 0x40000
	v_lshl_add_u64 v[228:229], s[58:59], 0, v[132:133]
	s_addc_u32 s15, s59, 0
	s_add_i32 s3, s75, s34
	global_load_lds_dwordx4 v[228:229], off
	v_lshl_add_u64 v[230:231], s[14:15], 0, v[136:137]
	s_mov_b32 m0, s3
	global_load_lds_dwordx4 v[230:231], off
	v_lshl_add_u64 v[230:231], s[14:15], 0, v[132:133]
	s_add_i32 m0, s3, 0x2000
	s_nop 0
	global_load_lds_dwordx4 v[230:231], off
	s_waitcnt vmcnt(6)
	s_waitcnt lgkmcnt(0)
	s_barrier
; #define PG8_STAGE(bufoff, gbase, voff) do { _Pragma("unroll") for (int _i = 0; _i < 2; ++_i) \
;         __builtin_amdgcn_global_load_lds((const unsigned*)((const char*)(gbase) + (voff)[_i]), (PG8_LAS unsigned*)(lds + (bufoff) + ldsw + _i * 8192), 16, 0, 0); } while (0)
; #define PG8_LDA(dst, b, h) do { _Pragma("unroll") for (int m = 0; m < 4; ++m) _Pragma("unroll") for (int k = 0; k < 2; ++k) dst[m][k] = *(const PG8_LAS bf16x8*)(lds + PG8_SA(b, h) + aoff + m * 2048 + k * 1024); } while (0)
; #define PG8_LDB(dst, b, h) do { _Pragma("unroll") for (int n = 0; n < 2; ++n) _Pragma("unroll") for (int k = 0; k < 2; ++k) dst[n][k] = *(const PG8_LAS bf16x8*)(lds + PG8_SB(b, h) + boff + n * 2048 + k * 1024); } while (0)
; #define PG8_MMA(ai, bj, At, Bt) do { __builtin_amdgcn_s_setprio(1); _Pragma("unroll") for (int m = 0; m < 4; ++m) _Pragma("unroll") for (int n = 0; n < 2; ++n) _Pragma("unroll") for (int k = 0; k < 2; ++k) \
;         acc[ai][bj][m][n] = __builtin_amdgcn_mfma_f32_16x16x32_bf16(Bt[n][k], At[m][k], acc[ai][bj][m][n], 0, 0, 0); __builtin_amdgcn_s_setprio(0); } while (0)
; #define PG8_WAIT_V(n) asm volatile("s_waitcnt vmcnt(" #n ")" ::: "memory")
; #define PG8_WAIT_L(n) asm volatile("s_waitcnt lgkmcnt(" #n ")" ::: "memory")
; #define PG8_BAR __builtin_amdgcn_s_barrier()
; #define PG8_SCHED __builtin_amdgcn_sched_barrier(0)
; template <class Epi, class Sched, bool ALIGN_EPI = false, bool SP2 = false>
; __device__ __forceinline__ void gemm_phase(PG8_LAS unsigned char* lds, const Gemm g, const Sched& S, const Epi& E) {
;     ...
;             PG8_WAIT_V(8); PG8_WAIT_L(0); PG8_BAR; PG8_MMA(0, 0, At, B0); PG8_MMA(0, 1, At, B1); PG8_BAR; PG8_SCHED;
;             PG8_LDA(At, 0, 1); PG8_STAGE(PG8_SB(0, 0), b2, voffB); PG8_STAGE(PG8_SB(0, 1), b2 + hstep, voffB); PG8_STAGE(PG8_SA(0, 0), a2, voffA);
;             PG8_WAIT_V(8); PG8_WAIT_L(0); PG8_BAR; PG8_MMA(1, 0, At, B0); PG8_MMA(1, 1, At, B1); PG8_BAR; PG8_SCHED;
;             PG8_LDB(B0, 1, 0); PG8_LDB(B1, 1, 1); PG8_SCHED; PG8_LDA(At, 1, 0); PG8_STAGE(PG8_SA(0, 1), a2 + hstep, voffA);
;             PG8_WAIT_V(8); PG8_WAIT_L(0); PG8_BAR; PG8_MMA(0, 0, At, B0); PG8_MMA(0, 1, At, B1); PG8_BAR; PG8_SCHED;
;             PG8_LDA(At, 1, 1); PG8_STAGE(PG8_SB(1, 0), b3, voffB); PG8_STAGE(PG8_SB(1, 1), b3 + hstep, voffB); PG8_STAGE(PG8_SA(1, 0), a3, voffA);
	s_setprio 1
	s_waitcnt lgkmcnt(0)
	v_mfma_f32_16x16x32_bf16 v[60:63], v[148:151], v[190:193], 0
	v_mfma_f32_16x16x32_bf16 v[56:59], v[164:167], v[190:193], 0
	v_mfma_f32_16x16x32_bf16 v[44:47], v[148:151], v[198:201], 0
	v_mfma_f32_16x16x32_bf16 v[40:43], v[164:167], v[198:201], 0
	v_mfma_f32_16x16x32_bf16 v[28:31], v[148:151], v[212:215], 0
	v_mfma_f32_16x16x32_bf16 v[24:27], v[164:167], v[212:215], 0
	v_mfma_f32_16x16x32_bf16 v[12:15], v[148:151], v[220:223], 0
	v_mfma_f32_16x16x32_bf16 v[8:11], v[164:167], v[220:223], 0
	v_mfma_f32_16x16x32_bf16 v[60:63], v[160:163], v[194:197], v[60:63]
	v_mfma_f32_16x16x32_bf16 v[56:59], v[168:171], v[194:197], v[56:59]
	v_mfma_f32_16x16x32_bf16 v[44:47], v[160:163], v[208:211], v[44:47]
	v_mfma_f32_16x16x32_bf16 v[40:43], v[168:171], v[208:211], v[40:43]
	v_mfma_f32_16x16x32_bf16 v[28:31], v[160:163], v[216:219], v[28:31]
	v_mfma_f32_16x16x32_bf16 v[24:27], v[168:171], v[216:219], v[24:27]
	v_lshl_add_u64 v[230:231], s[60:61], 0, v[138:139]
	s_mov_b32 m0, s43
	s_nop 0
	global_load_lds_dwordx4 v[230:231], off
	v_mfma_f32_16x16x32_bf16 v[12:15], v[160:163], v[224:227], v[12:15]
	v_mfma_f32_16x16x32_bf16 v[8:11], v[168:171], v[224:227], v[8:11]
	s_setprio 0
	s_setprio 1
	v_mfma_f32_16x16x32_bf16 v[52:55], v[172:175], v[190:193], 0
	v_mfma_f32_16x16x32_bf16 v[48:51], v[182:185], v[190:193], 0
	v_mfma_f32_16x16x32_bf16 v[36:39], v[172:175], v[198:201], 0
	v_mfma_f32_16x16x32_bf16 v[32:35], v[182:185], v[198:201], 0
	v_mfma_f32_16x16x32_bf16 v[20:23], v[172:175], v[212:215], 0
	v_mfma_f32_16x16x32_bf16 v[16:19], v[182:185], v[212:215], 0
	v_mfma_f32_16x16x32_bf16 v[4:7], v[172:175], v[220:223], 0
	v_mfma_f32_16x16x32_bf16 v[0:3], v[182:185], v[220:223], 0
	v_mfma_f32_16x16x32_bf16 v[52:55], v[176:179], v[194:197], v[52:55]
	v_mfma_f32_16x16x32_bf16 v[48:51], v[186:189], v[194:197], v[48:51]
	v_mfma_f32_16x16x32_bf16 v[36:39], v[176:179], v[208:211], v[36:39]
	v_mfma_f32_16x16x32_bf16 v[32:35], v[186:189], v[208:211], v[32:35]
	v_mfma_f32_16x16x32_bf16 v[20:23], v[176:179], v[216:219], v[20:23]
	v_mfma_f32_16x16x32_bf16 v[16:19], v[186:189], v[216:219], v[16:19]
	v_lshl_add_u64 v[232:233], s[60:61], 0, v[134:135]
	s_mov_b32 m0, s62
	s_nop 0
	global_load_lds_dwordx4 v[232:233], off
	v_mfma_f32_16x16x32_bf16 v[4:7], v[176:179], v[224:227], v[4:7]
	v_mfma_f32_16x16x32_bf16 v[0:3], v[186:189], v[224:227], v[0:3]
	s_setprio 0
	s_barrier
	s_add_i32 s3, 0, 0x18000
	v_add_u32_e32 v159, s3, v131
	s_add_i32 s33, 0, 0x1c000
	ds_read_b128 v[148:151], v159
	ds_read_b128 v[160:163], v159 offset:1024
	ds_read_b128 v[164:167], v159 offset:2048
	ds_read_b128 v[168:171], v159 offset:3072
	v_add_u32_e32 v159, s33, v131
	ds_read_b128 v[172:175], v159
	ds_read_b128 v[176:179], v159 offset:1024
	ds_read_b128 v[182:185], v159 offset:2048
	ds_read_b128 v[186:189], v159 offset:3072
	s_add_u32 s14, s60, 0x40000
	s_addc_u32 s15, s61, 0
	s_mov_b32 m0, s63
	v_lshl_add_u64 v[234:235], s[14:15], 0, v[138:139]
	ds_read_b128 v[190:193], v157 offset:32768
	ds_read_b128 v[194:197], v157 offset:33792
	ds_read_b128 v[198:201], v157 offset:34816
	ds_read_b128 v[208:211], v157 offset:35840
	ds_read_b128 v[212:215], v157 offset:36864
	ds_read_b128 v[216:219], v157 offset:37888
	ds_read_b128 v[220:223], v157 offset:38912
	ds_read_b128 v[224:227], v157 offset:39936
	global_load_lds_dwordx4 v[234:235], off
	v_lshl_add_u64 v[234:235], s[14:15], 0, v[134:135]
	s_mov_b32 m0, s64
	s_nop 0
	global_load_lds_dwordx4 v[234:235], off
	s_waitcnt vmcnt(8)
	s_waitcnt lgkmcnt(0)
	s_barrier
	s_setprio 1
	s_waitcnt lgkmcnt(0)
	v_mfma_f32_16x16x32_bf16 v[124:127], v[148:151], v[190:193], v[124:127]
	v_mfma_f32_16x16x32_bf16 v[120:123], v[164:167], v[190:193], v[120:123]
	v_mfma_f32_16x16x32_bf16 v[108:111], v[148:151], v[198:201], v[108:111]
	v_mfma_f32_16x16x32_bf16 v[104:107], v[164:167], v[198:201], v[104:107]
	v_mfma_f32_16x16x32_bf16 v[92:95], v[148:151], v[212:215], v[92:95]
	v_mfma_f32_16x16x32_bf16 v[88:91], v[164:167], v[212:215], v[88:91]
	v_mfma_f32_16x16x32_bf16 v[76:79], v[148:151], v[220:223], v[76:79]
	v_mfma_f32_16x16x32_bf16 v[72:75], v[164:167], v[220:223], v[72:75]
	v_mfma_f32_16x16x32_bf16 v[124:127], v[160:163], v[194:197], v[124:127]
	v_mfma_f32_16x16x32_bf16 v[120:123], v[168:171], v[194:197], v[120:123]
	v_mfma_f32_16x16x32_bf16 v[108:111], v[160:163], v[208:211], v[108:111]
	v_mfma_f32_16x16x32_bf16 v[104:107], v[168:171], v[208:211], v[104:107]
	v_mfma_f32_16x16x32_bf16 v[92:95], v[160:163], v[216:219], v[92:95]
	v_mfma_f32_16x16x32_bf16 v[88:91], v[168:171], v[216:219], v[88:91]
	v_mfma_f32_16x16x32_bf16 v[76:79], v[160:163], v[224:227], v[76:79]
	v_mfma_f32_16x16x32_bf16 v[72:75], v[168:171], v[224:227], v[72:75]
	s_setprio 0
	s_setprio 1
	v_mfma_f32_16x16x32_bf16 v[116:119], v[172:175], v[190:193], v[116:119]
	v_mfma_f32_16x16x32_bf16 v[112:115], v[182:185], v[190:193], v[112:115]
	v_mfma_f32_16x16x32_bf16 v[100:103], v[172:175], v[198:201], v[100:103]
	v_mfma_f32_16x16x32_bf16 v[96:99], v[182:185], v[198:201], v[96:99]
	v_mfma_f32_16x16x32_bf16 v[84:87], v[172:175], v[212:215], v[84:87]
	v_mfma_f32_16x16x32_bf16 v[80:83], v[182:185], v[212:215], v[80:83]
	v_mfma_f32_16x16x32_bf16 v[68:71], v[172:175], v[220:223], v[68:71]
	v_mfma_f32_16x16x32_bf16 v[64:67], v[182:185], v[220:223], v[64:67]
	v_mfma_f32_16x16x32_bf16 v[116:119], v[176:179], v[194:197], v[116:119]
	v_mfma_f32_16x16x32_bf16 v[112:115], v[186:189], v[194:197], v[112:115]
	v_mfma_f32_16x16x32_bf16 v[100:103], v[176:179], v[208:211], v[100:103]
	v_mfma_f32_16x16x32_bf16 v[96:99], v[186:189], v[208:211], v[96:99]
	v_mfma_f32_16x16x32_bf16 v[84:87], v[176:179], v[216:219], v[84:87]
	v_mfma_f32_16x16x32_bf16 v[80:83], v[186:189], v[216:219], v[80:83]
	v_mfma_f32_16x16x32_bf16 v[68:71], v[176:179], v[224:227], v[68:71]
	v_mfma_f32_16x16x32_bf16 v[64:67], v[186:189], v[224:227], v[64:67]
	s_setprio 0
	s_barrier
; #define PG8_STAGE(bufoff, gbase, voff) do { _Pragma("unroll") for (int _i = 0; _i < 2; ++_i) \
;         __builtin_amdgcn_global_load_lds((const unsigned*)((const char*)(gbase) + (voff)[_i]), (PG8_LAS unsigned*)(lds + (bufoff) + ldsw + _i * 8192), 16, 0, 0); } while (0)
; #define PG8_LDA(dst, b, h) do { _Pragma("unroll") for (int m = 0; m < 4; ++m) _Pragma("unroll") for (int k = 0; k < 2; ++k) dst[m][k] = *(const PG8_LAS bf16x8*)(lds + PG8_SA(b, h) + aoff + m * 2048 + k * 1024); } while (0)
; #define PG8_MMA(ai, bj, At, Bt) do { __builtin_amdgcn_s_setprio(1); _Pragma("unroll") for (int m = 0; m < 4; ++m) _Pragma("unroll") for (int n = 0; n < 2; ++n) _Pragma("unroll") for (int k = 0; k < 2; ++k) \
;         acc[ai][bj][m][n] = __builtin_amdgcn_mfma_f32_16x16x32_bf16(Bt[n][k], At[m][k], acc[ai][bj][m][n], 0, 0, 0); __builtin_amdgcn_s_setprio(0); } while (0)
; #define PG8_WAIT_V(n) asm volatile("s_waitcnt vmcnt(" #n ")" ::: "memory")
; #define PG8_WAIT_L(n) asm volatile("s_waitcnt lgkmcnt(" #n ")" ::: "memory")
; #define PG8_BAR __builtin_amdgcn_s_barrier()
; #define PG8_SCHED __builtin_amdgcn_sched_barrier(0)
; template <class Epi, class Sched, bool ALIGN_EPI = false, bool SP2 = false>
; __device__ __forceinline__ void gemm_phase(PG8_LAS unsigned char* lds, const Gemm g, const Sched& S, const Epi& E) {
;     ...
;         for (int t = 0; t < nt; t += 2) {
;     ...
;             PG8_LDA(At, 1, 1); PG8_STAGE(PG8_SB(1, 0), b3, voffB); PG8_STAGE(PG8_SB(1, 1), b3 + hstep, voffB); PG8_STAGE(PG8_SA(1, 0), a3, voffA);
;             PG8_WAIT_V(8); PG8_WAIT_L(0); PG8_BAR; PG8_MMA(1, 0, At, B0); PG8_MMA(1, 1, At, B1); PG8_BAR; PG8_SCHED;
	s_add_i32 s3, s3, s34
	v_lshl_add_u64 v[202:203], v[202:203], 0, s[38:39]
	s_mov_b32 m0, s3
	ds_read_b128 v[190:193], v157 offset:49152
	ds_read_b128 v[194:197], v157 offset:50176
	ds_read_b128 v[198:201], v157 offset:51200
	ds_read_b128 v[208:211], v157 offset:52224
	ds_read_b128 v[212:215], v157 offset:53248
	ds_read_b128 v[216:219], v157 offset:54272
	ds_read_b128 v[220:223], v157 offset:55296
	ds_read_b128 v[224:227], v157 offset:56320
	global_load_lds_dwordx4 v[202:203], off
	s_add_i32 m0, s3, 0x2000
	s_add_u32 s14, s58, 0x40080
	v_lshl_add_u64 v[202:203], v[228:229], 0, s[38:39]
	s_addc_u32 s15, s59, 0
	s_add_i32 s3, s33, s34
	global_load_lds_dwordx4 v[202:203], off
	v_lshl_add_u64 v[202:203], s[14:15], 0, v[136:137]
	s_mov_b32 m0, s3
	s_nop 0
	global_load_lds_dwordx4 v[202:203], off
	v_lshl_add_u64 v[202:203], s[14:15], 0, v[132:133]
	s_add_i32 m0, s3, 0x2000
	s_nop 0
	global_load_lds_dwordx4 v[202:203], off
	s_waitcnt vmcnt(6)
	s_waitcnt lgkmcnt(0)
	s_barrier
	s_setprio 1
	s_waitcnt lgkmcnt(0)
	v_mfma_f32_16x16x32_bf16 v[60:63], v[148:151], v[190:193], v[60:63]
	v_mfma_f32_16x16x32_bf16 v[56:59], v[164:167], v[190:193], v[56:59]
	v_mfma_f32_16x16x32_bf16 v[44:47], v[148:151], v[198:201], v[44:47]
	v_mfma_f32_16x16x32_bf16 v[40:43], v[164:167], v[198:201], v[40:43]
	v_mfma_f32_16x16x32_bf16 v[28:31], v[148:151], v[212:215], v[28:31]
	v_mfma_f32_16x16x32_bf16 v[24:27], v[164:167], v[212:215], v[24:27]
	v_mfma_f32_16x16x32_bf16 v[12:15], v[148:151], v[220:223], v[12:15]
	v_mfma_f32_16x16x32_bf16 v[8:11], v[164:167], v[220:223], v[8:11]
	v_mfma_f32_16x16x32_bf16 v[60:63], v[160:163], v[194:197], v[60:63]
	v_mfma_f32_16x16x32_bf16 v[56:59], v[168:171], v[194:197], v[56:59]
	v_mfma_f32_16x16x32_bf16 v[44:47], v[160:163], v[208:211], v[44:47]
	v_mfma_f32_16x16x32_bf16 v[40:43], v[168:171], v[208:211], v[40:43]
	v_mfma_f32_16x16x32_bf16 v[28:31], v[160:163], v[216:219], v[28:31]
	v_mfma_f32_16x16x32_bf16 v[24:27], v[168:171], v[216:219], v[24:27]
	v_lshl_add_u64 v[202:203], v[230:231], 0, s[38:39]
	s_mov_b32 m0, s66
	s_nop 0
	global_load_lds_dwordx4 v[202:203], off
	v_mfma_f32_16x16x32_bf16 v[12:15], v[160:163], v[224:227], v[12:15]
	v_mfma_f32_16x16x32_bf16 v[8:11], v[168:171], v[224:227], v[8:11]
	s_setprio 0
	s_setprio 1
	v_mfma_f32_16x16x32_bf16 v[52:55], v[172:175], v[190:193], v[52:55]
	v_mfma_f32_16x16x32_bf16 v[48:51], v[182:185], v[190:193], v[48:51]
	v_mfma_f32_16x16x32_bf16 v[36:39], v[172:175], v[198:201], v[36:39]
	v_mfma_f32_16x16x32_bf16 v[32:35], v[182:185], v[198:201], v[32:35]
	v_mfma_f32_16x16x32_bf16 v[20:23], v[172:175], v[212:215], v[20:23]
	v_mfma_f32_16x16x32_bf16 v[16:19], v[182:185], v[212:215], v[16:19]
	v_mfma_f32_16x16x32_bf16 v[4:7], v[172:175], v[220:223], v[4:7]
	v_mfma_f32_16x16x32_bf16 v[0:3], v[182:185], v[220:223], v[0:3]
	v_mfma_f32_16x16x32_bf16 v[52:55], v[176:179], v[194:197], v[52:55]
	v_mfma_f32_16x16x32_bf16 v[48:51], v[186:189], v[194:197], v[48:51]
	v_mfma_f32_16x16x32_bf16 v[36:39], v[176:179], v[208:211], v[36:39]
	v_mfma_f32_16x16x32_bf16 v[32:35], v[186:189], v[208:211], v[32:35]
	v_mfma_f32_16x16x32_bf16 v[20:23], v[176:179], v[216:219], v[20:23]
	v_mfma_f32_16x16x32_bf16 v[16:19], v[186:189], v[216:219], v[16:19]
	v_lshl_add_u64 v[202:203], v[232:233], 0, s[38:39]
	s_mov_b32 m0, s67
	s_nop 0
	global_load_lds_dwordx4 v[202:203], off
	v_mfma_f32_16x16x32_bf16 v[4:7], v[176:179], v[224:227], v[4:7]
	v_mfma_f32_16x16x32_bf16 v[0:3], v[186:189], v[224:227], v[0:3]
	s_setprio 0
	s_barrier
	s_add_i32 s86, s86, 2
	s_add_u32 s56, s56, 0x100
	s_addc_u32 s57, s57, 0
	s_add_u32 s84, s84, 0x100
	s_addc_u32 s85, s85, 0
	.p2align 6

; #define PG8_STAGE(bufoff, gbase, voff) do { _Pragma("unroll") for (int _i = 0; _i < 2; ++_i) \
;         __builtin_amdgcn_global_load_lds((const unsigned*)((const char*)(gbase) + (voff)[_i]), (PG8_LAS unsigned*)(lds + (bufoff) + ldsw + _i * 8192), 16, 0, 0); } while (0)
; #define PG8_LDA(dst, b, h) do { _Pragma("unroll") for (int m = 0; m < 4; ++m) _Pragma("unroll") for (int k = 0; k < 2; ++k) dst[m][k] = *(const PG8_LAS bf16x8*)(lds + PG8_SA(b, h) + aoff + m * 2048 + k * 1024); } while (0)
; template <class Epi, class Sched, bool ALIGN_EPI = false, bool SP2 = false>
; __device__ __forceinline__ void gemm_phase(PG8_LAS unsigned char* lds, const Gemm g, const Sched& S, const Epi& E) {
;     ...
;     for (;;) {
;         const bool has_next = S.next(ui + 1, nxt);
;         const char* nA = has_next ? (const char*)g.A + (size_t)nxt.pm * tstep : cA; const char* nB = has_next ? (const char*)g.Bt + (size_t)nxt.pn * tstep : cB;
;         for (int t = 0; t < nt; t += 2) {
;             const bool last = (t == nt - 2);
;             const char* a1 = cA + (size_t)(t + 1) * kstep;
;             const char* a2 = last ? nA : cA + (size_t)(t + 2) * kstep; const char* b2 = last ? nB : cB + (size_t)(t + 2) * kstep;
;             const char* a3 = a2 + kstep; const char* b3 = b2 + kstep;
;             if (last && has_next) S.a_ready(nxt);
;             if constexpr (SP2) {
;             PG8_LDB(B0, 0, 0); PG8_LDB(B1, 0, 1); PG8_SCHED; PG8_LDA(At, 0, 0); PG8_STAGE(PG8_SA(1, 1), a1 + hstep, voffA);
;             PG8_WAIT_V(8); PG8_WAIT_L(0); PG8_BAR; PG8_MMA(0, 0, At, B0); PG8_MMA(0, 1, At, B1); PG8_BAR; PG8_SCHED;
;             PG8_LDA(At, 0, 1); PG8_STAGE(PG8_SB(0, 0), b2, voffB); PG8_STAGE(PG8_SB(0, 1), b2 + hstep, voffB); PG8_STAGE(PG8_SA(0, 0), a2, voffA);
;             PG8_WAIT_V(8); PG8_WAIT_L(0); PG8_BAR; PG8_MMA(1, 0, At, B0); PG8_MMA(1, 1, At, B1); PG8_BAR; PG8_SCHED;
;             PG8_LDB(B0, 1, 0); PG8_LDB(B1, 1, 1); PG8_SCHED; PG8_LDA(At, 1, 0); PG8_STAGE(PG8_SA(0, 1), a2 + hstep, voffA);
;             PG8_WAIT_V(8); PG8_WAIT_L(0); PG8_BAR; PG8_MMA(0, 0, At, B0); PG8_MMA(0, 1, At, B1); PG8_BAR; PG8_SCHED;
;             PG8_LDA(At, 1, 1); PG8_STAGE(PG8_SB(1, 0), b3, voffB); PG8_STAGE(PG8_SB(1, 1), b3 + hstep, voffB); PG8_STAGE(PG8_SA(1, 0), a3, voffA);
;             PG8_WAIT_V(8); PG8_WAIT_L(0); PG8_BAR; PG8_MMA(1, 0, At, B0); PG8_MMA(1, 1, At, B1); PG8_BAR; PG8_SCHED;
.LBB0_872:
	s_ashr_i32 s49, s48, 31
	s_lshl_b64 s[50:51], s[48:49], 18
	s_add_u32 s50, s92, s50
	s_addc_u32 s51, s93, s51
	s_and_b64 s[52:53], s[10:11], exec
	s_cselect_b32 s49, s51, s59
	s_cselect_b32 s55, s50, s58
	s_ashr_i32 s45, s44, 31
	s_lshl_b64 s[52:53], s[44:45], 18
	s_add_u32 s52, s76, s52
	s_addc_u32 s53, s77, s53
	s_and_b64 s[62:63], s[10:11], exec
	s_cselect_b32 s45, s53, s61
	s_cselect_b32 s84, s52, s60
	s_add_u32 s58, s58, 0x20080
	s_addc_u32 s59, s59, 0
	s_add_u32 s85, s60, 0x100
	s_addc_u32 s86, s61, 0
	s_mov_b32 s87, -2
	s_waitcnt lgkmcnt(0)
	ds_read_b128 v[144:147], v151
	ds_read_b128 v[156:159], v151 offset:1024
	ds_read_b128 v[160:163], v151 offset:2048
	ds_read_b128 v[164:167], v151 offset:3072
	ds_read_b128 v[168:171], v152
	ds_read_b128 v[172:175], v152 offset:1024
	ds_read_b128 v[176:179], v152 offset:2048
	ds_read_b128 v[182:185], v152 offset:3072
	s_add_u32 s3, s58, 0xfffe0080
	s_addc_u32 s33, s59, -1
	s_cmp_eq_u32 s87, 4
	s_cselect_b32 s63, s49, s33
	s_cselect_b32 s62, s55, s3
	s_cselect_b32 s61, s45, s86
	s_cselect_b32 s60, s84, s85
	v_lshl_add_u64 v[202:203], s[58:59], 0, v[136:137]
	s_add_i32 m0, s15, 0xc000
	ds_read_b128 v[186:189], v153
	ds_read_b128 v[190:193], v153 offset:1024
	ds_read_b128 v[194:197], v153 offset:2048
	ds_read_b128 v[198:201], v153 offset:3072
	ds_read_b128 v[208:211], v153 offset:4096
	ds_read_b128 v[212:215], v153 offset:5120
	ds_read_b128 v[216:219], v153 offset:6144
	ds_read_b128 v[220:223], v153 offset:7168
	global_load_lds_dwordx4 v[202:203], off
	v_lshl_add_u64 v[202:203], s[58:59], 0, v[138:139]
	s_add_i32 m0, s15, 0xe000
	s_nop 0
	global_load_lds_dwordx4 v[202:203], off
	s_waitcnt vmcnt(8)
	s_waitcnt lgkmcnt(0)
	s_barrier
	s_setprio 1
	s_waitcnt lgkmcnt(0)
	v_mfma_f32_16x16x32_bf16 v[124:127], v[144:147], v[186:189], 0
	v_mfma_f32_16x16x32_bf16 v[120:123], v[160:163], v[186:189], 0
	v_mfma_f32_16x16x32_bf16 v[108:111], v[144:147], v[194:197], 0
	v_mfma_f32_16x16x32_bf16 v[104:107], v[160:163], v[194:197], 0
	v_mfma_f32_16x16x32_bf16 v[92:95], v[144:147], v[208:211], 0
	v_mfma_f32_16x16x32_bf16 v[88:91], v[160:163], v[208:211], 0
	v_mfma_f32_16x16x32_bf16 v[76:79], v[144:147], v[216:219], 0
	v_mfma_f32_16x16x32_bf16 v[72:75], v[160:163], v[216:219], 0
	v_mfma_f32_16x16x32_bf16 v[124:127], v[156:159], v[190:193], v[124:127]
	v_mfma_f32_16x16x32_bf16 v[120:123], v[164:167], v[190:193], v[120:123]
	v_mfma_f32_16x16x32_bf16 v[108:111], v[156:159], v[198:201], v[108:111]
	v_mfma_f32_16x16x32_bf16 v[104:107], v[164:167], v[198:201], v[104:107]
	v_mfma_f32_16x16x32_bf16 v[92:95], v[156:159], v[212:215], v[92:95]
	v_mfma_f32_16x16x32_bf16 v[88:91], v[164:167], v[212:215], v[88:91]
	v_mfma_f32_16x16x32_bf16 v[76:79], v[156:159], v[220:223], v[76:79]
	v_mfma_f32_16x16x32_bf16 v[72:75], v[164:167], v[220:223], v[72:75]
	s_setprio 0
	s_setprio 1
	v_mfma_f32_16x16x32_bf16 v[116:119], v[168:171], v[186:189], 0
	v_mfma_f32_16x16x32_bf16 v[112:115], v[176:179], v[186:189], 0
	v_mfma_f32_16x16x32_bf16 v[100:103], v[168:171], v[194:197], 0
	v_mfma_f32_16x16x32_bf16 v[96:99], v[176:179], v[194:197], 0
	v_mfma_f32_16x16x32_bf16 v[84:87], v[168:171], v[208:211], 0
	v_mfma_f32_16x16x32_bf16 v[80:83], v[176:179], v[208:211], 0
	v_mfma_f32_16x16x32_bf16 v[68:71], v[168:171], v[216:219], 0
	v_mfma_f32_16x16x32_bf16 v[64:67], v[176:179], v[216:219], 0
	v_mfma_f32_16x16x32_bf16 v[116:119], v[172:175], v[190:193], v[116:119]
	v_mfma_f32_16x16x32_bf16 v[112:115], v[182:185], v[190:193], v[112:115]
	v_mfma_f32_16x16x32_bf16 v[100:103], v[172:175], v[198:201], v[100:103]
	v_mfma_f32_16x16x32_bf16 v[96:99], v[182:185], v[198:201], v[96:99]
	v_mfma_f32_16x16x32_bf16 v[84:87], v[172:175], v[212:215], v[84:87]
	v_mfma_f32_16x16x32_bf16 v[80:83], v[182:185], v[212:215], v[80:83]
	v_mfma_f32_16x16x32_bf16 v[68:71], v[172:175], v[220:223], v[68:71]
	v_mfma_f32_16x16x32_bf16 v[64:67], v[182:185], v[220:223], v[64:67]
	s_setprio 0
	s_barrier
	s_add_i32 s3, s74, s14
	v_lshl_add_u64 v[202:203], s[60:61], 0, v[130:131]
	s_mov_b32 m0, s3
	ds_read_b128 v[186:189], v153 offset:16384
	ds_read_b128 v[190:193], v153 offset:17408
	ds_read_b128 v[194:197], v153 offset:18432
	ds_read_b128 v[198:201], v153 offset:19456
	ds_read_b128 v[208:211], v153 offset:20480
	ds_read_b128 v[212:215], v153 offset:21504
	ds_read_b128 v[216:219], v153 offset:22528
	ds_read_b128 v[220:223], v153 offset:23552
	global_load_lds_dwordx4 v[202:203], off
	s_add_i32 m0, s3, 0x2000
	s_add_u32 s78, s60, 0x20000
	v_lshl_add_u64 v[224:225], s[60:61], 0, v[134:135]
	s_addc_u32 s79, s61, 0
	s_add_i32 s3, s75, s14
	global_load_lds_dwordx4 v[224:225], off
	v_lshl_add_u64 v[226:227], s[78:79], 0, v[130:131]
	s_mov_b32 m0, s3
	global_load_lds_dwordx4 v[226:227], off
	v_lshl_add_u64 v[226:227], s[78:79], 0, v[134:135]
	s_add_i32 m0, s3, 0x2000
	s_nop 0
	global_load_lds_dwordx4 v[226:227], off
	s_waitcnt vmcnt(6)
	s_waitcnt lgkmcnt(0)
	s_barrier
; #define PG8_STAGE(bufoff, gbase, voff) do { _Pragma("unroll") for (int _i = 0; _i < 2; ++_i) \
;         __builtin_amdgcn_global_load_lds((const unsigned*)((const char*)(gbase) + (voff)[_i]), (PG8_LAS unsigned*)(lds + (bufoff) + ldsw + _i * 8192), 16, 0, 0); } while (0)
; #define PG8_LDA(dst, b, h) do { _Pragma("unroll") for (int m = 0; m < 4; ++m) _Pragma("unroll") for (int k = 0; k < 2; ++k) dst[m][k] = *(const PG8_LAS bf16x8*)(lds + PG8_SA(b, h) + aoff + m * 2048 + k * 1024); } while (0)
; #define PG8_LDB(dst, b, h) do { _Pragma("unroll") for (int n = 0; n < 2; ++n) _Pragma("unroll") for (int k = 0; k < 2; ++k) dst[n][k] = *(const PG8_LAS bf16x8*)(lds + PG8_SB(b, h) + boff + n * 2048 + k * 1024); } while (0)
; #define PG8_MMA(ai, bj, At, Bt) do { __builtin_amdgcn_s_setprio(1); _Pragma("unroll") for (int m = 0; m < 4; ++m) _Pragma("unroll") for (int n = 0; n < 2; ++n) _Pragma("unroll") for (int k = 0; k < 2; ++k) \
;         acc[ai][bj][m][n] = __builtin_amdgcn_mfma_f32_16x16x32_bf16(Bt[n][k], At[m][k], acc[ai][bj][m][n], 0, 0, 0); __builtin_amdgcn_s_setprio(0); } while (0)
; #define PG8_WAIT_V(n) asm volatile("s_waitcnt vmcnt(" #n ")" ::: "memory")
; #define PG8_WAIT_L(n) asm volatile("s_waitcnt lgkmcnt(" #n ")" ::: "memory")
; #define PG8_BAR __builtin_amdgcn_s_barrier()
; #define PG8_SCHED __builtin_amdgcn_sched_barrier(0)
; template <class Epi, class Sched, bool ALIGN_EPI = false, bool SP2 = false>
; __device__ __forceinline__ void gemm_phase(PG8_LAS unsigned char* lds, const Gemm g, const Sched& S, const Epi& E) {
;     ...
;             PG8_WAIT_V(8); PG8_WAIT_L(0); PG8_BAR; PG8_MMA(1, 0, At, B0); PG8_MMA(1, 1, At, B1); PG8_BAR; PG8_SCHED;
;             PG8_LDB(B0, 1, 0); PG8_LDB(B1, 1, 1); PG8_SCHED; PG8_LDA(At, 1, 0); PG8_STAGE(PG8_SA(0, 1), a2 + hstep, voffA);
;             PG8_WAIT_V(8); PG8_WAIT_L(0); PG8_BAR; PG8_MMA(0, 0, At, B0); PG8_MMA(0, 1, At, B1); PG8_BAR; PG8_SCHED;
	s_setprio 1
	s_waitcnt lgkmcnt(0)
	v_mfma_f32_16x16x32_bf16 v[60:63], v[144:147], v[186:189], 0
	v_mfma_f32_16x16x32_bf16 v[56:59], v[160:163], v[186:189], 0
	v_mfma_f32_16x16x32_bf16 v[44:47], v[144:147], v[194:197], 0
	v_mfma_f32_16x16x32_bf16 v[40:43], v[160:163], v[194:197], 0
	v_mfma_f32_16x16x32_bf16 v[28:31], v[144:147], v[208:211], 0
	v_mfma_f32_16x16x32_bf16 v[24:27], v[160:163], v[208:211], 0
	v_mfma_f32_16x16x32_bf16 v[12:15], v[144:147], v[216:219], 0
	v_mfma_f32_16x16x32_bf16 v[8:11], v[160:163], v[216:219], 0
	v_mfma_f32_16x16x32_bf16 v[60:63], v[156:159], v[190:193], v[60:63]
	v_mfma_f32_16x16x32_bf16 v[56:59], v[164:167], v[190:193], v[56:59]
	v_mfma_f32_16x16x32_bf16 v[44:47], v[156:159], v[198:201], v[44:47]
	v_mfma_f32_16x16x32_bf16 v[40:43], v[164:167], v[198:201], v[40:43]
	v_mfma_f32_16x16x32_bf16 v[28:31], v[156:159], v[212:215], v[28:31]
	v_mfma_f32_16x16x32_bf16 v[24:27], v[164:167], v[212:215], v[24:27]
	v_lshl_add_u64 v[226:227], s[62:63], 0, v[128:129]
	s_mov_b32 m0, s15
	s_nop 0
	global_load_lds_dwordx4 v[226:227], off
	v_mfma_f32_16x16x32_bf16 v[12:15], v[156:159], v[220:223], v[12:15]
	v_mfma_f32_16x16x32_bf16 v[8:11], v[164:167], v[220:223], v[8:11]
	s_setprio 0
	s_setprio 1
	v_mfma_f32_16x16x32_bf16 v[52:55], v[168:171], v[186:189], 0
	v_mfma_f32_16x16x32_bf16 v[48:51], v[176:179], v[186:189], 0
	v_mfma_f32_16x16x32_bf16 v[36:39], v[168:171], v[194:197], 0
	v_mfma_f32_16x16x32_bf16 v[32:35], v[176:179], v[194:197], 0
	v_mfma_f32_16x16x32_bf16 v[20:23], v[168:171], v[208:211], 0
	v_mfma_f32_16x16x32_bf16 v[16:19], v[176:179], v[208:211], 0
	v_mfma_f32_16x16x32_bf16 v[4:7], v[168:171], v[216:219], 0
	v_mfma_f32_16x16x32_bf16 v[0:3], v[176:179], v[216:219], 0
	v_mfma_f32_16x16x32_bf16 v[52:55], v[172:175], v[190:193], v[52:55]
	v_mfma_f32_16x16x32_bf16 v[48:51], v[182:185], v[190:193], v[48:51]
	v_mfma_f32_16x16x32_bf16 v[36:39], v[172:175], v[198:201], v[36:39]
	v_mfma_f32_16x16x32_bf16 v[32:35], v[182:185], v[198:201], v[32:35]
	v_mfma_f32_16x16x32_bf16 v[20:23], v[172:175], v[212:215], v[20:23]
	v_mfma_f32_16x16x32_bf16 v[16:19], v[182:185], v[212:215], v[16:19]
	v_lshl_add_u64 v[228:229], s[62:63], 0, v[132:133]
	s_mov_b32 m0, s34
	s_nop 0
	global_load_lds_dwordx4 v[228:229], off
	v_mfma_f32_16x16x32_bf16 v[4:7], v[172:175], v[220:223], v[4:7]
	v_mfma_f32_16x16x32_bf16 v[0:3], v[182:185], v[220:223], v[0:3]
	s_setprio 0
	s_barrier
	s_add_i32 s3, 0, 0x18000
	v_add_u32_e32 v155, s3, v149
	s_add_i32 s33, 0, 0x1c000
	ds_read_b128 v[144:147], v155
	ds_read_b128 v[156:159], v155 offset:1024
	ds_read_b128 v[160:163], v155 offset:2048
	ds_read_b128 v[164:167], v155 offset:3072
	v_add_u32_e32 v155, s33, v149
	ds_read_b128 v[168:171], v155
	ds_read_b128 v[172:175], v155 offset:1024
	ds_read_b128 v[176:179], v155 offset:2048
	ds_read_b128 v[182:185], v155 offset:3072
	s_add_u32 s62, s62, 0x20000
	s_addc_u32 s63, s63, 0
	s_mov_b32 m0, s57
	v_lshl_add_u64 v[230:231], s[62:63], 0, v[128:129]
	ds_read_b128 v[186:189], v153 offset:32768
	ds_read_b128 v[190:193], v153 offset:33792
	ds_read_b128 v[194:197], v153 offset:34816
	ds_read_b128 v[198:201], v153 offset:35840
	ds_read_b128 v[208:211], v153 offset:36864
	ds_read_b128 v[212:215], v153 offset:37888
	ds_read_b128 v[216:219], v153 offset:38912
	ds_read_b128 v[220:223], v153 offset:39936
	global_load_lds_dwordx4 v[230:231], off
	v_lshl_add_u64 v[230:231], s[62:63], 0, v[132:133]
	s_mov_b32 m0, s64
	s_nop 0
	global_load_lds_dwordx4 v[230:231], off
	s_waitcnt vmcnt(8)
	s_waitcnt lgkmcnt(0)
	s_barrier
	s_setprio 1
	s_waitcnt lgkmcnt(0)
	v_mfma_f32_16x16x32_bf16 v[124:127], v[144:147], v[186:189], v[124:127]
	v_mfma_f32_16x16x32_bf16 v[120:123], v[160:163], v[186:189], v[120:123]
	v_mfma_f32_16x16x32_bf16 v[108:111], v[144:147], v[194:197], v[108:111]
	v_mfma_f32_16x16x32_bf16 v[104:107], v[160:163], v[194:197], v[104:107]
	v_mfma_f32_16x16x32_bf16 v[92:95], v[144:147], v[208:211], v[92:95]
	v_mfma_f32_16x16x32_bf16 v[88:91], v[160:163], v[208:211], v[88:91]
	v_mfma_f32_16x16x32_bf16 v[76:79], v[144:147], v[216:219], v[76:79]
	v_mfma_f32_16x16x32_bf16 v[72:75], v[160:163], v[216:219], v[72:75]
	v_mfma_f32_16x16x32_bf16 v[124:127], v[156:159], v[190:193], v[124:127]
	v_mfma_f32_16x16x32_bf16 v[120:123], v[164:167], v[190:193], v[120:123]
	v_mfma_f32_16x16x32_bf16 v[108:111], v[156:159], v[198:201], v[108:111]
	v_mfma_f32_16x16x32_bf16 v[104:107], v[164:167], v[198:201], v[104:107]
	v_mfma_f32_16x16x32_bf16 v[92:95], v[156:159], v[212:215], v[92:95]
	v_mfma_f32_16x16x32_bf16 v[88:91], v[164:167], v[212:215], v[88:91]
	v_mfma_f32_16x16x32_bf16 v[76:79], v[156:159], v[220:223], v[76:79]
	v_mfma_f32_16x16x32_bf16 v[72:75], v[164:167], v[220:223], v[72:75]
	s_setprio 0
	s_setprio 1
	v_mfma_f32_16x16x32_bf16 v[116:119], v[168:171], v[186:189], v[116:119]
	v_mfma_f32_16x16x32_bf16 v[112:115], v[176:179], v[186:189], v[112:115]
	v_mfma_f32_16x16x32_bf16 v[100:103], v[168:171], v[194:197], v[100:103]
	v_mfma_f32_16x16x32_bf16 v[96:99], v[176:179], v[194:197], v[96:99]
	v_mfma_f32_16x16x32_bf16 v[84:87], v[168:171], v[208:211], v[84:87]
	v_mfma_f32_16x16x32_bf16 v[80:83], v[176:179], v[208:211], v[80:83]
	v_mfma_f32_16x16x32_bf16 v[68:71], v[168:171], v[216:219], v[68:71]
	v_mfma_f32_16x16x32_bf16 v[64:67], v[176:179], v[216:219], v[64:67]
	v_mfma_f32_16x16x32_bf16 v[116:119], v[172:175], v[190:193], v[116:119]
	v_mfma_f32_16x16x32_bf16 v[112:115], v[182:185], v[190:193], v[112:115]
	v_mfma_f32_16x16x32_bf16 v[100:103], v[172:175], v[198:201], v[100:103]
	v_mfma_f32_16x16x32_bf16 v[96:99], v[182:185], v[198:201], v[96:99]
	v_mfma_f32_16x16x32_bf16 v[84:87], v[172:175], v[212:215], v[84:87]
	v_mfma_f32_16x16x32_bf16 v[80:83], v[182:185], v[212:215], v[80:83]
	v_mfma_f32_16x16x32_bf16 v[68:71], v[172:175], v[220:223], v[68:71]
	v_mfma_f32_16x16x32_bf16 v[64:67], v[182:185], v[220:223], v[64:67]
	s_setprio 0
	s_barrier
; #define PG8_STAGE(bufoff, gbase, voff) do { _Pragma("unroll") for (int _i = 0; _i < 2; ++_i) \
;         __builtin_amdgcn_global_load_lds((const unsigned*)((const char*)(gbase) + (voff)[_i]), (PG8_LAS unsigned*)(lds + (bufoff) + ldsw + _i * 8192), 16, 0, 0); } while (0)
; #define PG8_LDA(dst, b, h) do { _Pragma("unroll") for (int m = 0; m < 4; ++m) _Pragma("unroll") for (int k = 0; k < 2; ++k) dst[m][k] = *(const PG8_LAS bf16x8*)(lds + PG8_SA(b, h) + aoff + m * 2048 + k * 1024); } while (0)
; #define PG8_MMA(ai, bj, At, Bt) do { __builtin_amdgcn_s_setprio(1); _Pragma("unroll") for (int m = 0; m < 4; ++m) _Pragma("unroll") for (int n = 0; n < 2; ++n) _Pragma("unroll") for (int k = 0; k < 2; ++k) \
;         acc[ai][bj][m][n] = __builtin_amdgcn_mfma_f32_16x16x32_bf16(Bt[n][k], At[m][k], acc[ai][bj][m][n], 0, 0, 0); __builtin_amdgcn_s_setprio(0); } while (0)
; #define PG8_WAIT_V(n) asm volatile("s_waitcnt vmcnt(" #n ")" ::: "memory")
; #define PG8_WAIT_L(n) asm volatile("s_waitcnt lgkmcnt(" #n ")" ::: "memory")
; #define PG8_BAR __builtin_amdgcn_s_barrier()
; #define PG8_SCHED __builtin_amdgcn_sched_barrier(0)
; template <class Epi, class Sched, bool ALIGN_EPI = false, bool SP2 = false>
; __device__ __forceinline__ void gemm_phase(PG8_LAS unsigned char* lds, const Gemm g, const Sched& S, const Epi& E) {
;     ...
;         for (int t = 0; t < nt; t += 2) {
;             const bool last = (t == nt - 2);
;             const char* a1 = cA + (size_t)(t + 1) * kstep;
;             const char* a2 = last ? nA : cA + (size_t)(t + 2) * kstep; const char* b2 = last ? nB : cB + (size_t)(t + 2) * kstep;
;             const char* a3 = a2 + kstep; const char* b3 = b2 + kstep;
;     ...
;             PG8_LDA(At, 1, 1); PG8_STAGE(PG8_SB(1, 0), b3, voffB); PG8_STAGE(PG8_SB(1, 1), b3 + hstep, voffB); PG8_STAGE(PG8_SA(1, 0), a3, voffA);
;             PG8_WAIT_V(8); PG8_WAIT_L(0); PG8_BAR; PG8_MMA(1, 0, At, B0); PG8_MMA(1, 1, At, B1); PG8_BAR; PG8_SCHED;
	s_add_i32 s3, s3, s14
	v_lshl_add_u64 v[202:203], v[202:203], 0, s[38:39]
	s_mov_b32 m0, s3
	ds_read_b128 v[186:189], v153 offset:49152
	ds_read_b128 v[190:193], v153 offset:50176
	ds_read_b128 v[194:197], v153 offset:51200
	ds_read_b128 v[198:201], v153 offset:52224
	ds_read_b128 v[208:211], v153 offset:53248
	ds_read_b128 v[212:215], v153 offset:54272
	ds_read_b128 v[216:219], v153 offset:55296
	ds_read_b128 v[220:223], v153 offset:56320
	global_load_lds_dwordx4 v[202:203], off
	s_add_i32 m0, s3, 0x2000
	s_add_u32 s60, s60, 0x20080
	v_lshl_add_u64 v[202:203], v[224:225], 0, s[38:39]
	s_addc_u32 s61, s61, 0
	s_add_i32 s3, s33, s14
	global_load_lds_dwordx4 v[202:203], off
	v_lshl_add_u64 v[202:203], s[60:61], 0, v[130:131]
	s_mov_b32 m0, s3
	s_nop 0
	global_load_lds_dwordx4 v[202:203], off
	v_lshl_add_u64 v[202:203], s[60:61], 0, v[134:135]
	s_add_i32 m0, s3, 0x2000
	s_nop 0
	global_load_lds_dwordx4 v[202:203], off
	s_waitcnt vmcnt(6)
	s_waitcnt lgkmcnt(0)
	s_barrier
	s_setprio 1
	s_waitcnt lgkmcnt(0)
	v_mfma_f32_16x16x32_bf16 v[60:63], v[144:147], v[186:189], v[60:63]
	v_mfma_f32_16x16x32_bf16 v[56:59], v[160:163], v[186:189], v[56:59]
	v_mfma_f32_16x16x32_bf16 v[44:47], v[144:147], v[194:197], v[44:47]
	v_mfma_f32_16x16x32_bf16 v[40:43], v[160:163], v[194:197], v[40:43]
	v_mfma_f32_16x16x32_bf16 v[28:31], v[144:147], v[208:211], v[28:31]
	v_mfma_f32_16x16x32_bf16 v[24:27], v[160:163], v[208:211], v[24:27]
	v_mfma_f32_16x16x32_bf16 v[12:15], v[144:147], v[216:219], v[12:15]
	v_mfma_f32_16x16x32_bf16 v[8:11], v[160:163], v[216:219], v[8:11]
	v_mfma_f32_16x16x32_bf16 v[60:63], v[156:159], v[190:193], v[60:63]
	v_mfma_f32_16x16x32_bf16 v[56:59], v[164:167], v[190:193], v[56:59]
	v_mfma_f32_16x16x32_bf16 v[44:47], v[156:159], v[198:201], v[44:47]
	v_mfma_f32_16x16x32_bf16 v[40:43], v[164:167], v[198:201], v[40:43]
	v_mfma_f32_16x16x32_bf16 v[28:31], v[156:159], v[212:215], v[28:31]
	v_mfma_f32_16x16x32_bf16 v[24:27], v[164:167], v[212:215], v[24:27]
	v_lshl_add_u64 v[202:203], v[226:227], 0, s[38:39]
	s_mov_b32 m0, s66
	s_nop 0
	global_load_lds_dwordx4 v[202:203], off
	v_mfma_f32_16x16x32_bf16 v[12:15], v[156:159], v[220:223], v[12:15]
	v_mfma_f32_16x16x32_bf16 v[8:11], v[164:167], v[220:223], v[8:11]
	s_setprio 0
	s_setprio 1
	v_mfma_f32_16x16x32_bf16 v[52:55], v[168:171], v[186:189], v[52:55]
	v_mfma_f32_16x16x32_bf16 v[48:51], v[176:179], v[186:189], v[48:51]
	v_mfma_f32_16x16x32_bf16 v[36:39], v[168:171], v[194:197], v[36:39]
	v_mfma_f32_16x16x32_bf16 v[32:35], v[176:179], v[194:197], v[32:35]
	v_mfma_f32_16x16x32_bf16 v[20:23], v[168:171], v[208:211], v[20:23]
	v_mfma_f32_16x16x32_bf16 v[16:19], v[176:179], v[208:211], v[16:19]
	v_mfma_f32_16x16x32_bf16 v[4:7], v[168:171], v[216:219], v[4:7]
	v_mfma_f32_16x16x32_bf16 v[0:3], v[176:179], v[216:219], v[0:3]
	v_mfma_f32_16x16x32_bf16 v[52:55], v[172:175], v[190:193], v[52:55]
	v_mfma_f32_16x16x32_bf16 v[48:51], v[182:185], v[190:193], v[48:51]
	v_mfma_f32_16x16x32_bf16 v[36:39], v[172:175], v[198:201], v[36:39]
	v_mfma_f32_16x16x32_bf16 v[32:35], v[182:185], v[198:201], v[32:35]
	v_mfma_f32_16x16x32_bf16 v[20:23], v[172:175], v[212:215], v[20:23]
	v_mfma_f32_16x16x32_bf16 v[16:19], v[182:185], v[212:215], v[16:19]
	v_lshl_add_u64 v[202:203], v[228:229], 0, s[38:39]
	s_mov_b32 m0, s67
	s_nop 0
	global_load_lds_dwordx4 v[202:203], off
	v_mfma_f32_16x16x32_bf16 v[4:7], v[172:175], v[220:223], v[4:7]
	v_mfma_f32_16x16x32_bf16 v[0:3], v[182:185], v[220:223], v[0:3]
	s_setprio 0
	s_barrier
	s_add_i32 s87, s87, 2
	s_add_u32 s58, s58, 0x100
	s_addc_u32 s59, s59, 0
	s_add_u32 s85, s85, 0x100
	s_addc_u32 s86, s86, 0
	.p2align 6

; #define PG8_STAGE(bufoff, gbase, voff) do { _Pragma("unroll") for (int _i = 0; _i < 2; ++_i) \
;         __builtin_amdgcn_global_load_lds((const unsigned*)((const char*)(gbase) + (voff)[_i]), (PG8_LAS unsigned*)(lds + (bufoff) + ldsw + _i * 8192), 16, 0, 0); } while (0)
; #define PG8_LDA(dst, b, h) do { _Pragma("unroll") for (int m = 0; m < 4; ++m) _Pragma("unroll") for (int k = 0; k < 2; ++k) dst[m][k] = *(const PG8_LAS bf16x8*)(lds + PG8_SA(b, h) + aoff + m * 2048 + k * 1024); } while (0)
; #define PG8_LDB(dst, b, h) do { _Pragma("unroll") for (int n = 0; n < 2; ++n) _Pragma("unroll") for (int k = 0; k < 2; ++k) dst[n][k] = *(const PG8_LAS bf16x8*)(lds + PG8_SB(b, h) + boff + n * 2048 + k * 1024); } while (0)
; #define PG8_WAIT_V(n) asm volatile("s_waitcnt vmcnt(" #n ")" ::: "memory")
; #define PG8_WAIT_L(n) asm volatile("s_waitcnt lgkmcnt(" #n ")" ::: "memory")
; #define PG8_BAR __builtin_amdgcn_s_barrier()
; #define PG8_SCHED __builtin_amdgcn_sched_barrier(0)
; template <class Epi, class Sched, bool ALIGN_EPI = false, bool SP2 = false>
; __device__ __forceinline__ void gemm_phase(PG8_LAS unsigned char* lds, const Gemm g, const Sched& S, const Epi& E) {
;     ...
;         const bool has_next = S.next(ui + 1, nxt);
;         const char* nA = has_next ? (const char*)g.A + (size_t)nxt.pm * tstep : cA; const char* nB = has_next ? (const char*)g.Bt + (size_t)nxt.pn * tstep : cB;
;         for (int t = 0; t < nt; t += 2) {
;             const bool last = (t == nt - 2);
;             const char* a1 = cA + (size_t)(t + 1) * kstep;
;             const char* a2 = last ? nA : cA + (size_t)(t + 2) * kstep; const char* b2 = last ? nB : cB + (size_t)(t + 2) * kstep;
;             const char* a3 = a2 + kstep; const char* b3 = b2 + kstep;
;             if (last && has_next) S.a_ready(nxt);
;             if constexpr (SP2) {
;             PG8_LDB(B0, 0, 0); PG8_LDB(B1, 0, 1); PG8_SCHED; PG8_LDA(At, 0, 0); PG8_STAGE(PG8_SA(1, 1), a1 + hstep, voffA);
;             PG8_WAIT_V(8); PG8_WAIT_L(0); PG8_BAR; PG8_MMA(0, 0, At, B0); PG8_MMA(0, 1, At, B1); PG8_BAR; PG8_SCHED;
;             PG8_LDA(At, 0, 1); PG8_STAGE(PG8_SB(0, 0), b2, voffB); PG8_STAGE(PG8_SB(0, 1), b2 + hstep, voffB); PG8_STAGE(PG8_SA(0, 0), a2, voffA);
;             PG8_WAIT_V(8); PG8_WAIT_L(0); PG8_BAR; PG8_MMA(1, 0, At, B0); PG8_MMA(1, 1, At, B1); PG8_BAR; PG8_SCHED;
.LBB0_956:
	s_ashr_i32 s45, s44, 31
	s_lshl_b64 s[48:49], s[44:45], 19
	s_add_u32 s48, s22, s48
	s_addc_u32 s49, s23, s49
	s_and_b64 s[50:51], s[10:11], exec
	s_cselect_b32 s45, s49, s55
	s_cselect_b32 s75, s48, s54
	s_ashr_i32 s43, s42, 31
	s_lshl_b64 s[50:51], s[42:43], 19
	v_readlane_b32 s3, v250, 18
	s_add_u32 s50, s3, s50
	v_readlane_b32 s3, v250, 19
	s_addc_u32 s51, s3, s51
	s_and_b64 s[58:59], s[10:11], exec
	s_cselect_b32 s43, s51, s57
	s_cselect_b32 s76, s50, s56
	s_add_u32 s54, s54, 0x40080
	s_addc_u32 s55, s55, 0
	s_add_u32 s77, s56, 0x100
	s_addc_u32 s82, s57, 0
	s_mov_b32 s83, -2
	ds_read_b128 v[144:147], v155
	ds_read_b128 v[148:151], v155 offset:1024
	ds_read_b128 v[160:163], v155 offset:2048
	ds_read_b128 v[164:167], v155 offset:3072
	ds_read_b128 v[168:171], v156
	ds_read_b128 v[172:175], v156 offset:1024
	ds_read_b128 v[176:179], v156 offset:2048
	ds_read_b128 v[182:185], v156 offset:3072
	s_add_u32 s3, s54, 0xfffc0080
	s_addc_u32 s33, s55, -1
	s_cmp_eq_u32 s83, 12
	s_cselect_b32 s59, s45, s33
	s_cselect_b32 s58, s75, s3
	s_cselect_b32 s57, s43, s82
	s_cselect_b32 s56, s76, s77
	v_lshl_add_u64 v[202:203], s[54:55], 0, v[136:137]
	s_add_i32 m0, s34, 0xc000
	ds_read_b128 v[186:189], v157
	ds_read_b128 v[190:193], v157 offset:1024
	ds_read_b128 v[194:197], v157 offset:2048
	ds_read_b128 v[198:201], v157 offset:3072
	ds_read_b128 v[208:211], v157 offset:4096
	ds_read_b128 v[212:215], v157 offset:5120
	ds_read_b128 v[216:219], v157 offset:6144
	ds_read_b128 v[220:223], v157 offset:7168
	global_load_lds_dwordx4 v[202:203], off
	v_lshl_add_u64 v[202:203], s[54:55], 0, v[138:139]
	s_add_i32 m0, s34, 0xe000
	s_nop 0
	global_load_lds_dwordx4 v[202:203], off
	s_waitcnt vmcnt(8)
	s_waitcnt lgkmcnt(0)
	s_barrier
	s_setprio 1
	s_waitcnt lgkmcnt(0)
	v_mfma_f32_16x16x32_bf16 v[124:127], v[144:147], v[186:189], 0
	v_mfma_f32_16x16x32_bf16 v[120:123], v[160:163], v[186:189], 0
	v_mfma_f32_16x16x32_bf16 v[108:111], v[144:147], v[194:197], 0
	v_mfma_f32_16x16x32_bf16 v[104:107], v[160:163], v[194:197], 0
	v_mfma_f32_16x16x32_bf16 v[92:95], v[144:147], v[208:211], 0
	v_mfma_f32_16x16x32_bf16 v[88:91], v[160:163], v[208:211], 0
	v_mfma_f32_16x16x32_bf16 v[76:79], v[144:147], v[216:219], 0
	v_mfma_f32_16x16x32_bf16 v[72:75], v[160:163], v[216:219], 0
	v_mfma_f32_16x16x32_bf16 v[124:127], v[148:151], v[190:193], v[124:127]
	v_mfma_f32_16x16x32_bf16 v[120:123], v[164:167], v[190:193], v[120:123]
	v_mfma_f32_16x16x32_bf16 v[108:111], v[148:151], v[198:201], v[108:111]
	v_mfma_f32_16x16x32_bf16 v[104:107], v[164:167], v[198:201], v[104:107]
	v_mfma_f32_16x16x32_bf16 v[92:95], v[148:151], v[212:215], v[92:95]
	v_mfma_f32_16x16x32_bf16 v[88:91], v[164:167], v[212:215], v[88:91]
	v_mfma_f32_16x16x32_bf16 v[76:79], v[148:151], v[220:223], v[76:79]
	v_mfma_f32_16x16x32_bf16 v[72:75], v[164:167], v[220:223], v[72:75]
	s_setprio 0
	s_setprio 1
	v_mfma_f32_16x16x32_bf16 v[116:119], v[168:171], v[186:189], 0
	v_mfma_f32_16x16x32_bf16 v[112:115], v[176:179], v[186:189], 0
	v_mfma_f32_16x16x32_bf16 v[100:103], v[168:171], v[194:197], 0
	v_mfma_f32_16x16x32_bf16 v[96:99], v[176:179], v[194:197], 0
	v_mfma_f32_16x16x32_bf16 v[84:87], v[168:171], v[208:211], 0
	v_mfma_f32_16x16x32_bf16 v[80:83], v[176:179], v[208:211], 0
	v_mfma_f32_16x16x32_bf16 v[68:71], v[168:171], v[216:219], 0
	v_mfma_f32_16x16x32_bf16 v[64:67], v[176:179], v[216:219], 0
	v_mfma_f32_16x16x32_bf16 v[116:119], v[172:175], v[190:193], v[116:119]
	v_mfma_f32_16x16x32_bf16 v[112:115], v[182:185], v[190:193], v[112:115]
	v_mfma_f32_16x16x32_bf16 v[100:103], v[172:175], v[198:201], v[100:103]
	v_mfma_f32_16x16x32_bf16 v[96:99], v[182:185], v[198:201], v[96:99]
	v_mfma_f32_16x16x32_bf16 v[84:87], v[172:175], v[212:215], v[84:87]
	v_mfma_f32_16x16x32_bf16 v[80:83], v[182:185], v[212:215], v[80:83]
	v_mfma_f32_16x16x32_bf16 v[68:71], v[172:175], v[220:223], v[68:71]
	v_mfma_f32_16x16x32_bf16 v[64:67], v[182:185], v[220:223], v[64:67]
	s_setprio 0
	s_barrier
	s_add_i32 s3, s65, s14
	v_lshl_add_u64 v[202:203], s[56:57], 0, v[132:133]
	s_mov_b32 m0, s3
	ds_read_b128 v[186:189], v157 offset:16384
	ds_read_b128 v[190:193], v157 offset:17408
	ds_read_b128 v[194:197], v157 offset:18432
	ds_read_b128 v[198:201], v157 offset:19456
	ds_read_b128 v[208:211], v157 offset:20480
	ds_read_b128 v[212:215], v157 offset:21504
	ds_read_b128 v[216:219], v157 offset:22528
	ds_read_b128 v[220:223], v157 offset:23552
	global_load_lds_dwordx4 v[202:203], off
	s_add_i32 m0, s3, 0x2000
	s_add_u32 s78, s56, 0x40000
	v_lshl_add_u64 v[224:225], s[56:57], 0, v[128:129]
	s_addc_u32 s79, s57, 0
	s_add_i32 s3, s66, s14
	global_load_lds_dwordx4 v[224:225], off
	v_lshl_add_u64 v[226:227], s[78:79], 0, v[132:133]
	s_mov_b32 m0, s3
	global_load_lds_dwordx4 v[226:227], off
	v_lshl_add_u64 v[226:227], s[78:79], 0, v[128:129]
	s_add_i32 m0, s3, 0x2000
	s_nop 0
	global_load_lds_dwordx4 v[226:227], off
	s_waitcnt vmcnt(6)
	s_waitcnt lgkmcnt(0)
	s_barrier
; #define PG8_STAGE(bufoff, gbase, voff) do { _Pragma("unroll") for (int _i = 0; _i < 2; ++_i) \
;         __builtin_amdgcn_global_load_lds((const unsigned*)((const char*)(gbase) + (voff)[_i]), (PG8_LAS unsigned*)(lds + (bufoff) + ldsw + _i * 8192), 16, 0, 0); } while (0)
; #define PG8_LDA(dst, b, h) do { _Pragma("unroll") for (int m = 0; m < 4; ++m) _Pragma("unroll") for (int k = 0; k < 2; ++k) dst[m][k] = *(const PG8_LAS bf16x8*)(lds + PG8_SA(b, h) + aoff + m * 2048 + k * 1024); } while (0)
; #define PG8_LDB(dst, b, h) do { _Pragma("unroll") for (int n = 0; n < 2; ++n) _Pragma("unroll") for (int k = 0; k < 2; ++k) dst[n][k] = *(const PG8_LAS bf16x8*)(lds + PG8_SB(b, h) + boff + n * 2048 + k * 1024); } while (0)
; #define PG8_MMA(ai, bj, At, Bt) do { __builtin_amdgcn_s_setprio(1); _Pragma("unroll") for (int m = 0; m < 4; ++m) _Pragma("unroll") for (int n = 0; n < 2; ++n) _Pragma("unroll") for (int k = 0; k < 2; ++k) \
;         acc[ai][bj][m][n] = __builtin_amdgcn_mfma_f32_16x16x32_bf16(Bt[n][k], At[m][k], acc[ai][bj][m][n], 0, 0, 0); __builtin_amdgcn_s_setprio(0); } while (0)
; #define PG8_WAIT_V(n) asm volatile("s_waitcnt vmcnt(" #n ")" ::: "memory")
; #define PG8_WAIT_L(n) asm volatile("s_waitcnt lgkmcnt(" #n ")" ::: "memory")
; #define PG8_BAR __builtin_amdgcn_s_barrier()
; #define PG8_SCHED __builtin_amdgcn_sched_barrier(0)
; template <class Epi, class Sched, bool ALIGN_EPI = false, bool SP2 = false>
; __device__ __forceinline__ void gemm_phase(PG8_LAS unsigned char* lds, const Gemm g, const Sched& S, const Epi& E) {
;     ...
;             PG8_WAIT_V(8); PG8_WAIT_L(0); PG8_BAR; PG8_MMA(1, 0, At, B0); PG8_MMA(1, 1, At, B1); PG8_BAR; PG8_SCHED;
;             PG8_LDB(B0, 1, 0); PG8_LDB(B1, 1, 1); PG8_SCHED; PG8_LDA(At, 1, 0); PG8_STAGE(PG8_SA(0, 1), a2 + hstep, voffA);
;             PG8_WAIT_V(8); PG8_WAIT_L(0); PG8_BAR; PG8_MMA(0, 0, At, B0); PG8_MMA(0, 1, At, B1); PG8_BAR; PG8_SCHED;
	s_setprio 1
	s_waitcnt lgkmcnt(0)
	v_mfma_f32_16x16x32_bf16 v[60:63], v[144:147], v[186:189], 0
	v_mfma_f32_16x16x32_bf16 v[56:59], v[160:163], v[186:189], 0
	v_mfma_f32_16x16x32_bf16 v[44:47], v[144:147], v[194:197], 0
	v_mfma_f32_16x16x32_bf16 v[40:43], v[160:163], v[194:197], 0
	v_mfma_f32_16x16x32_bf16 v[28:31], v[144:147], v[208:211], 0
	v_mfma_f32_16x16x32_bf16 v[24:27], v[160:163], v[208:211], 0
	v_mfma_f32_16x16x32_bf16 v[12:15], v[144:147], v[216:219], 0
	v_mfma_f32_16x16x32_bf16 v[8:11], v[160:163], v[216:219], 0
	v_mfma_f32_16x16x32_bf16 v[60:63], v[148:151], v[190:193], v[60:63]
	v_mfma_f32_16x16x32_bf16 v[56:59], v[164:167], v[190:193], v[56:59]
	v_mfma_f32_16x16x32_bf16 v[44:47], v[148:151], v[198:201], v[44:47]
	v_mfma_f32_16x16x32_bf16 v[40:43], v[164:167], v[198:201], v[40:43]
	v_mfma_f32_16x16x32_bf16 v[28:31], v[148:151], v[212:215], v[28:31]
	v_mfma_f32_16x16x32_bf16 v[24:27], v[164:167], v[212:215], v[24:27]
	v_lshl_add_u64 v[226:227], s[58:59], 0, v[134:135]
	s_mov_b32 m0, s34
	s_nop 0
	global_load_lds_dwordx4 v[226:227], off
	v_mfma_f32_16x16x32_bf16 v[12:15], v[148:151], v[220:223], v[12:15]
	v_mfma_f32_16x16x32_bf16 v[8:11], v[164:167], v[220:223], v[8:11]
	s_setprio 0
	s_setprio 1
	v_mfma_f32_16x16x32_bf16 v[52:55], v[168:171], v[186:189], 0
	v_mfma_f32_16x16x32_bf16 v[48:51], v[176:179], v[186:189], 0
	v_mfma_f32_16x16x32_bf16 v[36:39], v[168:171], v[194:197], 0
	v_mfma_f32_16x16x32_bf16 v[32:35], v[176:179], v[194:197], 0
	v_mfma_f32_16x16x32_bf16 v[20:23], v[168:171], v[208:211], 0
	v_mfma_f32_16x16x32_bf16 v[16:19], v[176:179], v[208:211], 0
	v_mfma_f32_16x16x32_bf16 v[4:7], v[168:171], v[216:219], 0
	v_mfma_f32_16x16x32_bf16 v[0:3], v[176:179], v[216:219], 0
	v_mfma_f32_16x16x32_bf16 v[52:55], v[172:175], v[190:193], v[52:55]
	v_mfma_f32_16x16x32_bf16 v[48:51], v[182:185], v[190:193], v[48:51]
	v_mfma_f32_16x16x32_bf16 v[36:39], v[172:175], v[198:201], v[36:39]
	v_mfma_f32_16x16x32_bf16 v[32:35], v[182:185], v[198:201], v[32:35]
	v_mfma_f32_16x16x32_bf16 v[20:23], v[172:175], v[212:215], v[20:23]
	v_mfma_f32_16x16x32_bf16 v[16:19], v[182:185], v[212:215], v[16:19]
	v_lshl_add_u64 v[228:229], s[58:59], 0, v[130:131]
	s_mov_b32 m0, s53
	s_nop 0
	global_load_lds_dwordx4 v[228:229], off
	v_mfma_f32_16x16x32_bf16 v[4:7], v[172:175], v[220:223], v[4:7]
	v_mfma_f32_16x16x32_bf16 v[0:3], v[182:185], v[220:223], v[0:3]
	s_setprio 0
	s_barrier
	s_add_i32 s3, 0, 0x18000
	v_add_u32_e32 v159, s3, v153
	s_add_i32 s33, 0, 0x1c000
	ds_read_b128 v[144:147], v159
	ds_read_b128 v[148:151], v159 offset:1024
	ds_read_b128 v[160:163], v159 offset:2048
	ds_read_b128 v[164:167], v159 offset:3072
	v_add_u32_e32 v159, s33, v153
	ds_read_b128 v[168:171], v159
	ds_read_b128 v[172:175], v159 offset:1024
	ds_read_b128 v[176:179], v159 offset:2048
	ds_read_b128 v[182:185], v159 offset:3072
	s_add_u32 s58, s58, 0x40000
	s_addc_u32 s59, s59, 0
	s_mov_b32 m0, s60
	v_lshl_add_u64 v[230:231], s[58:59], 0, v[134:135]
	ds_read_b128 v[186:189], v157 offset:32768
	ds_read_b128 v[190:193], v157 offset:33792
	ds_read_b128 v[194:197], v157 offset:34816
	ds_read_b128 v[198:201], v157 offset:35840
	ds_read_b128 v[208:211], v157 offset:36864
	ds_read_b128 v[212:215], v157 offset:37888
	ds_read_b128 v[216:219], v157 offset:38912
	ds_read_b128 v[220:223], v157 offset:39936
	global_load_lds_dwordx4 v[230:231], off
	v_lshl_add_u64 v[230:231], s[58:59], 0, v[130:131]
	s_mov_b32 m0, s61
	s_nop 0
	global_load_lds_dwordx4 v[230:231], off
	s_waitcnt vmcnt(8)
	s_waitcnt lgkmcnt(0)
	s_barrier
	s_setprio 1
	s_waitcnt lgkmcnt(0)
	v_mfma_f32_16x16x32_bf16 v[124:127], v[144:147], v[186:189], v[124:127]
	v_mfma_f32_16x16x32_bf16 v[120:123], v[160:163], v[186:189], v[120:123]
	v_mfma_f32_16x16x32_bf16 v[108:111], v[144:147], v[194:197], v[108:111]
	v_mfma_f32_16x16x32_bf16 v[104:107], v[160:163], v[194:197], v[104:107]
	v_mfma_f32_16x16x32_bf16 v[92:95], v[144:147], v[208:211], v[92:95]
	v_mfma_f32_16x16x32_bf16 v[88:91], v[160:163], v[208:211], v[88:91]
	v_mfma_f32_16x16x32_bf16 v[76:79], v[144:147], v[216:219], v[76:79]
	v_mfma_f32_16x16x32_bf16 v[72:75], v[160:163], v[216:219], v[72:75]
	v_mfma_f32_16x16x32_bf16 v[124:127], v[148:151], v[190:193], v[124:127]
	v_mfma_f32_16x16x32_bf16 v[120:123], v[164:167], v[190:193], v[120:123]
	v_mfma_f32_16x16x32_bf16 v[108:111], v[148:151], v[198:201], v[108:111]
	v_mfma_f32_16x16x32_bf16 v[104:107], v[164:167], v[198:201], v[104:107]
	v_mfma_f32_16x16x32_bf16 v[92:95], v[148:151], v[212:215], v[92:95]
	v_mfma_f32_16x16x32_bf16 v[88:91], v[164:167], v[212:215], v[88:91]
	v_mfma_f32_16x16x32_bf16 v[76:79], v[148:151], v[220:223], v[76:79]
	v_mfma_f32_16x16x32_bf16 v[72:75], v[164:167], v[220:223], v[72:75]
	s_setprio 0
	s_setprio 1
	v_mfma_f32_16x16x32_bf16 v[116:119], v[168:171], v[186:189], v[116:119]
	v_mfma_f32_16x16x32_bf16 v[112:115], v[176:179], v[186:189], v[112:115]
	v_mfma_f32_16x16x32_bf16 v[100:103], v[168:171], v[194:197], v[100:103]
	v_mfma_f32_16x16x32_bf16 v[96:99], v[176:179], v[194:197], v[96:99]
	v_mfma_f32_16x16x32_bf16 v[84:87], v[168:171], v[208:211], v[84:87]
	v_mfma_f32_16x16x32_bf16 v[80:83], v[176:179], v[208:211], v[80:83]
	v_mfma_f32_16x16x32_bf16 v[68:71], v[168:171], v[216:219], v[68:71]
	v_mfma_f32_16x16x32_bf16 v[64:67], v[176:179], v[216:219], v[64:67]
	v_mfma_f32_16x16x32_bf16 v[116:119], v[172:175], v[190:193], v[116:119]
	v_mfma_f32_16x16x32_bf16 v[112:115], v[182:185], v[190:193], v[112:115]
	v_mfma_f32_16x16x32_bf16 v[100:103], v[172:175], v[198:201], v[100:103]
	v_mfma_f32_16x16x32_bf16 v[96:99], v[182:185], v[198:201], v[96:99]
	v_mfma_f32_16x16x32_bf16 v[84:87], v[172:175], v[212:215], v[84:87]
	v_mfma_f32_16x16x32_bf16 v[80:83], v[182:185], v[212:215], v[80:83]
	v_mfma_f32_16x16x32_bf16 v[68:71], v[172:175], v[220:223], v[68:71]
	v_mfma_f32_16x16x32_bf16 v[64:67], v[182:185], v[220:223], v[64:67]
	s_setprio 0
	s_barrier
; #define PG8_STAGE(bufoff, gbase, voff) do { _Pragma("unroll") for (int _i = 0; _i < 2; ++_i) \
;         __builtin_amdgcn_global_load_lds((const unsigned*)((const char*)(gbase) + (voff)[_i]), (PG8_LAS unsigned*)(lds + (bufoff) + ldsw + _i * 8192), 16, 0, 0); } while (0)
; #define PG8_LDA(dst, b, h) do { _Pragma("unroll") for (int m = 0; m < 4; ++m) _Pragma("unroll") for (int k = 0; k < 2; ++k) dst[m][k] = *(const PG8_LAS bf16x8*)(lds + PG8_SA(b, h) + aoff + m * 2048 + k * 1024); } while (0)
; #define PG8_MMA(ai, bj, At, Bt) do { __builtin_amdgcn_s_setprio(1); _Pragma("unroll") for (int m = 0; m < 4; ++m) _Pragma("unroll") for (int n = 0; n < 2; ++n) _Pragma("unroll") for (int k = 0; k < 2; ++k) \
;         acc[ai][bj][m][n] = __builtin_amdgcn_mfma_f32_16x16x32_bf16(Bt[n][k], At[m][k], acc[ai][bj][m][n], 0, 0, 0); __builtin_amdgcn_s_setprio(0); } while (0)
; #define PG8_WAIT_V(n) asm volatile("s_waitcnt vmcnt(" #n ")" ::: "memory")
; #define PG8_WAIT_L(n) asm volatile("s_waitcnt lgkmcnt(" #n ")" ::: "memory")
; #define PG8_BAR __builtin_amdgcn_s_barrier()
; #define PG8_SCHED __builtin_amdgcn_sched_barrier(0)
; template <class Epi, class Sched, bool ALIGN_EPI = false, bool SP2 = false>
; __device__ __forceinline__ void gemm_phase(PG8_LAS unsigned char* lds, const Gemm g, const Sched& S, const Epi& E) {
;     ...
;         for (int t = 0; t < nt; t += 2) {
;             const bool last = (t == nt - 2);
;             const char* a1 = cA + (size_t)(t + 1) * kstep;
;             const char* a2 = last ? nA : cA + (size_t)(t + 2) * kstep; const char* b2 = last ? nB : cB + (size_t)(t + 2) * kstep;
;             const char* a3 = a2 + kstep; const char* b3 = b2 + kstep;
;     ...
;             PG8_LDA(At, 1, 1); PG8_STAGE(PG8_SB(1, 0), b3, voffB); PG8_STAGE(PG8_SB(1, 1), b3 + hstep, voffB); PG8_STAGE(PG8_SA(1, 0), a3, voffA);
;             PG8_WAIT_V(8); PG8_WAIT_L(0); PG8_BAR; PG8_MMA(1, 0, At, B0); PG8_MMA(1, 1, At, B1); PG8_BAR; PG8_SCHED;
	s_add_i32 s3, s3, s14
	v_lshl_add_u64 v[202:203], v[202:203], 0, s[36:37]
	s_mov_b32 m0, s3
	ds_read_b128 v[186:189], v157 offset:49152
	ds_read_b128 v[190:193], v157 offset:50176
	ds_read_b128 v[194:197], v157 offset:51200
	ds_read_b128 v[198:201], v157 offset:52224
	ds_read_b128 v[208:211], v157 offset:53248
	ds_read_b128 v[212:215], v157 offset:54272
	ds_read_b128 v[216:219], v157 offset:55296
	ds_read_b128 v[220:223], v157 offset:56320
	global_load_lds_dwordx4 v[202:203], off
	s_add_i32 m0, s3, 0x2000
	s_add_u32 s56, s56, 0x40080
	v_lshl_add_u64 v[202:203], v[224:225], 0, s[36:37]
	s_addc_u32 s57, s57, 0
	s_add_i32 s3, s33, s14
	global_load_lds_dwordx4 v[202:203], off
	v_lshl_add_u64 v[202:203], s[56:57], 0, v[132:133]
	s_mov_b32 m0, s3
	s_nop 0
	global_load_lds_dwordx4 v[202:203], off
	v_lshl_add_u64 v[202:203], s[56:57], 0, v[128:129]
	s_add_i32 m0, s3, 0x2000
	s_nop 0
	global_load_lds_dwordx4 v[202:203], off
	s_waitcnt vmcnt(6)
	s_waitcnt lgkmcnt(0)
	s_barrier
	s_setprio 1
	s_waitcnt lgkmcnt(0)
	v_mfma_f32_16x16x32_bf16 v[60:63], v[144:147], v[186:189], v[60:63]
	v_mfma_f32_16x16x32_bf16 v[56:59], v[160:163], v[186:189], v[56:59]
	v_mfma_f32_16x16x32_bf16 v[44:47], v[144:147], v[194:197], v[44:47]
	v_mfma_f32_16x16x32_bf16 v[40:43], v[160:163], v[194:197], v[40:43]
	v_mfma_f32_16x16x32_bf16 v[28:31], v[144:147], v[208:211], v[28:31]
	v_mfma_f32_16x16x32_bf16 v[24:27], v[160:163], v[208:211], v[24:27]
	v_mfma_f32_16x16x32_bf16 v[12:15], v[144:147], v[216:219], v[12:15]
	v_mfma_f32_16x16x32_bf16 v[8:11], v[160:163], v[216:219], v[8:11]
	v_mfma_f32_16x16x32_bf16 v[60:63], v[148:151], v[190:193], v[60:63]
	v_mfma_f32_16x16x32_bf16 v[56:59], v[164:167], v[190:193], v[56:59]
	v_mfma_f32_16x16x32_bf16 v[44:47], v[148:151], v[198:201], v[44:47]
	v_mfma_f32_16x16x32_bf16 v[40:43], v[164:167], v[198:201], v[40:43]
	v_mfma_f32_16x16x32_bf16 v[28:31], v[148:151], v[212:215], v[28:31]
	v_mfma_f32_16x16x32_bf16 v[24:27], v[164:167], v[212:215], v[24:27]
	v_lshl_add_u64 v[202:203], v[226:227], 0, s[36:37]
	s_mov_b32 m0, s63
	s_nop 0
	global_load_lds_dwordx4 v[202:203], off
	v_mfma_f32_16x16x32_bf16 v[12:15], v[148:151], v[220:223], v[12:15]
	v_mfma_f32_16x16x32_bf16 v[8:11], v[164:167], v[220:223], v[8:11]
	s_setprio 0
	s_setprio 1
	v_mfma_f32_16x16x32_bf16 v[52:55], v[168:171], v[186:189], v[52:55]
	v_mfma_f32_16x16x32_bf16 v[48:51], v[176:179], v[186:189], v[48:51]
	v_mfma_f32_16x16x32_bf16 v[36:39], v[168:171], v[194:197], v[36:39]
	v_mfma_f32_16x16x32_bf16 v[32:35], v[176:179], v[194:197], v[32:35]
	v_mfma_f32_16x16x32_bf16 v[20:23], v[168:171], v[208:211], v[20:23]
	v_mfma_f32_16x16x32_bf16 v[16:19], v[176:179], v[208:211], v[16:19]
	v_mfma_f32_16x16x32_bf16 v[4:7], v[168:171], v[216:219], v[4:7]
	v_mfma_f32_16x16x32_bf16 v[0:3], v[176:179], v[216:219], v[0:3]
	v_mfma_f32_16x16x32_bf16 v[52:55], v[172:175], v[190:193], v[52:55]
	v_mfma_f32_16x16x32_bf16 v[48:51], v[182:185], v[190:193], v[48:51]
	v_mfma_f32_16x16x32_bf16 v[36:39], v[172:175], v[198:201], v[36:39]
	v_mfma_f32_16x16x32_bf16 v[32:35], v[182:185], v[198:201], v[32:35]
	v_mfma_f32_16x16x32_bf16 v[20:23], v[172:175], v[212:215], v[20:23]
	v_mfma_f32_16x16x32_bf16 v[16:19], v[182:185], v[212:215], v[16:19]
	v_lshl_add_u64 v[202:203], v[228:229], 0, s[36:37]
	s_mov_b32 m0, s64
	s_nop 0
	global_load_lds_dwordx4 v[202:203], off
	v_mfma_f32_16x16x32_bf16 v[4:7], v[172:175], v[220:223], v[4:7]
	v_mfma_f32_16x16x32_bf16 v[0:3], v[182:185], v[220:223], v[0:3]
	s_setprio 0
	s_barrier
	s_add_i32 s83, s83, 2
	s_add_u32 s54, s54, 0x100
	s_addc_u32 s55, s55, 0
	s_add_u32 s77, s77, 0x100
	s_addc_u32 s82, s82, 0
	.p2align 6

; #define PG8_STAGE(bufoff, gbase, voff) do { _Pragma("unroll") for (int _i = 0; _i < 2; ++_i) \
;         __builtin_amdgcn_global_load_lds((const unsigned*)((const char*)(gbase) + (voff)[_i]), (PG8_LAS unsigned*)(lds + (bufoff) + ldsw + _i * 8192), 16, 0, 0); } while (0)
; #define PG8_LDA(dst, b, h) do { _Pragma("unroll") for (int m = 0; m < 4; ++m) _Pragma("unroll") for (int k = 0; k < 2; ++k) dst[m][k] = *(const PG8_LAS bf16x8*)(lds + PG8_SA(b, h) + aoff + m * 2048 + k * 1024); } while (0)
; #define PG8_LDB(dst, b, h) do { _Pragma("unroll") for (int n = 0; n < 2; ++n) _Pragma("unroll") for (int k = 0; k < 2; ++k) dst[n][k] = *(const PG8_LAS bf16x8*)(lds + PG8_SB(b, h) + boff + n * 2048 + k * 1024); } while (0)
; #define PG8_MMA(ai, bj, At, Bt) do { __builtin_amdgcn_s_setprio(1); _Pragma("unroll") for (int m = 0; m < 4; ++m) _Pragma("unroll") for (int n = 0; n < 2; ++n) _Pragma("unroll") for (int k = 0; k < 2; ++k) \
;         acc[ai][bj][m][n] = __builtin_amdgcn_mfma_f32_16x16x32_bf16(Bt[n][k], At[m][k], acc[ai][bj][m][n], 0, 0, 0); __builtin_amdgcn_s_setprio(0); } while (0)
; #define PG8_WAIT_V(n) asm volatile("s_waitcnt vmcnt(" #n ")" ::: "memory")
; #define PG8_WAIT_L(n) asm volatile("s_waitcnt lgkmcnt(" #n ")" ::: "memory")
; #define PG8_BAR __builtin_amdgcn_s_barrier()
; template <class Epi, class Sched, bool ALIGN_EPI = false, bool SP2 = false>
; __device__ __forceinline__ void gemm_phase(PG8_LAS unsigned char* lds, const Gemm g, const Sched& S, const Epi& E) {
;     ...
;             const char* a1 = cA + (size_t)(t + 1) * kstep;
;             const char* a2 = last ? nA : cA + (size_t)(t + 2) * kstep; const char* b2 = last ? nB : cB + (size_t)(t + 2) * kstep;
;             const char* a3 = a2 + kstep; const char* b3 = b2 + kstep;
;             if (last && has_next) S.a_ready(nxt);
;             if constexpr (SP2) {
;             PG8_LDB(B0, 0, 0); PG8_LDB(B1, 0, 1); PG8_SCHED; PG8_LDA(At, 0, 0); PG8_STAGE(PG8_SA(1, 1), a1 + hstep, voffA);
;             PG8_WAIT_V(8); PG8_WAIT_L(0); PG8_BAR; PG8_MMA(0, 0, At, B0); PG8_MMA(0, 1, At, B1); PG8_BAR; PG8_SCHED;
;             PG8_LDA(At, 0, 1); PG8_STAGE(PG8_SB(0, 0), b2, voffB); PG8_STAGE(PG8_SB(0, 1), b2 + hstep, voffB); PG8_STAGE(PG8_SA(0, 0), a2, voffA);
;             PG8_WAIT_V(8); PG8_WAIT_L(0); PG8_BAR; PG8_MMA(1, 0, At, B0); PG8_MMA(1, 1, At, B1); PG8_BAR; PG8_SCHED;
.LBB0_1034:
	s_add_u32 s75, s52, 0x100
	s_addc_u32 s76, s53, 0
	s_mov_b32 s77, -2
	s_waitcnt lgkmcnt(0)
	ds_read_b128 v[144:147], v151
	ds_read_b128 v[156:159], v151 offset:1024
	ds_read_b128 v[160:163], v151 offset:2048
	ds_read_b128 v[164:167], v151 offset:3072
	ds_read_b128 v[168:171], v152
	ds_read_b128 v[172:175], v152 offset:1024
	ds_read_b128 v[176:179], v152 offset:2048
	ds_read_b128 v[182:185], v152 offset:3072
	s_add_u32 s52, s50, 0x100
	s_addc_u32 s53, s51, 0
	s_cmp_eq_u32 s77, 40
	s_cselect_b32 s57, s1, s53
	s_cselect_b32 s56, s0, s52
	s_cselect_b32 s55, s49, s76
	s_cselect_b32 s54, s48, s75
	v_lshl_add_u64 v[202:203], s[50:51], 0, v[136:137]
	s_add_i32 m0, s14, 0xc000
	ds_read_b128 v[186:189], v153
	ds_read_b128 v[190:193], v153 offset:1024
	ds_read_b128 v[194:197], v153 offset:2048
	ds_read_b128 v[198:201], v153 offset:3072
	ds_read_b128 v[208:211], v153 offset:4096
	ds_read_b128 v[212:215], v153 offset:5120
	ds_read_b128 v[216:219], v153 offset:6144
	ds_read_b128 v[220:223], v153 offset:7168
	global_load_lds_dwordx4 v[202:203], off
	v_lshl_add_u64 v[202:203], s[50:51], 0, v[138:139]
	s_add_i32 m0, s14, 0xe000
	s_nop 0
	global_load_lds_dwordx4 v[202:203], off
	s_waitcnt vmcnt(8)
	s_waitcnt lgkmcnt(0)
	s_barrier
	s_setprio 1
	s_waitcnt lgkmcnt(0)
	v_mfma_f32_16x16x32_bf16 v[124:127], v[144:147], v[186:189], 0
	v_mfma_f32_16x16x32_bf16 v[120:123], v[160:163], v[186:189], 0
	v_mfma_f32_16x16x32_bf16 v[108:111], v[144:147], v[194:197], 0
	v_mfma_f32_16x16x32_bf16 v[104:107], v[160:163], v[194:197], 0
	v_mfma_f32_16x16x32_bf16 v[92:95], v[144:147], v[208:211], 0
	v_mfma_f32_16x16x32_bf16 v[88:91], v[160:163], v[208:211], 0
	v_mfma_f32_16x16x32_bf16 v[76:79], v[144:147], v[216:219], 0
	v_mfma_f32_16x16x32_bf16 v[72:75], v[160:163], v[216:219], 0
	v_mfma_f32_16x16x32_bf16 v[124:127], v[156:159], v[190:193], v[124:127]
	v_mfma_f32_16x16x32_bf16 v[120:123], v[164:167], v[190:193], v[120:123]
	v_mfma_f32_16x16x32_bf16 v[108:111], v[156:159], v[198:201], v[108:111]
	v_mfma_f32_16x16x32_bf16 v[104:107], v[164:167], v[198:201], v[104:107]
	v_mfma_f32_16x16x32_bf16 v[92:95], v[156:159], v[212:215], v[92:95]
	v_mfma_f32_16x16x32_bf16 v[88:91], v[164:167], v[212:215], v[88:91]
	v_mfma_f32_16x16x32_bf16 v[76:79], v[156:159], v[220:223], v[76:79]
	v_mfma_f32_16x16x32_bf16 v[72:75], v[164:167], v[220:223], v[72:75]
	s_setprio 0
	s_setprio 1
	v_mfma_f32_16x16x32_bf16 v[116:119], v[168:171], v[186:189], 0
	v_mfma_f32_16x16x32_bf16 v[112:115], v[176:179], v[186:189], 0
	v_mfma_f32_16x16x32_bf16 v[100:103], v[168:171], v[194:197], 0
	v_mfma_f32_16x16x32_bf16 v[96:99], v[176:179], v[194:197], 0
	v_mfma_f32_16x16x32_bf16 v[84:87], v[168:171], v[208:211], 0
	v_mfma_f32_16x16x32_bf16 v[80:83], v[176:179], v[208:211], 0
	v_mfma_f32_16x16x32_bf16 v[68:71], v[168:171], v[216:219], 0
	v_mfma_f32_16x16x32_bf16 v[64:67], v[176:179], v[216:219], 0
	v_mfma_f32_16x16x32_bf16 v[116:119], v[172:175], v[190:193], v[116:119]
	v_mfma_f32_16x16x32_bf16 v[112:115], v[182:185], v[190:193], v[112:115]
	v_mfma_f32_16x16x32_bf16 v[100:103], v[172:175], v[198:201], v[100:103]
	v_mfma_f32_16x16x32_bf16 v[96:99], v[182:185], v[198:201], v[96:99]
	v_mfma_f32_16x16x32_bf16 v[84:87], v[172:175], v[212:215], v[84:87]
	v_mfma_f32_16x16x32_bf16 v[80:83], v[182:185], v[212:215], v[80:83]
	v_mfma_f32_16x16x32_bf16 v[68:71], v[172:175], v[220:223], v[68:71]
	v_mfma_f32_16x16x32_bf16 v[64:67], v[182:185], v[220:223], v[64:67]
	s_setprio 0
	s_barrier
	s_add_i32 s50, s61, s3
	v_lshl_add_u64 v[202:203], s[54:55], 0, v[130:131]
	s_mov_b32 m0, s50
	ds_read_b128 v[186:189], v153 offset:16384
	ds_read_b128 v[190:193], v153 offset:17408
	ds_read_b128 v[194:197], v153 offset:18432
	ds_read_b128 v[198:201], v153 offset:19456
	ds_read_b128 v[208:211], v153 offset:20480
	ds_read_b128 v[212:215], v153 offset:21504
	ds_read_b128 v[216:219], v153 offset:22528
	ds_read_b128 v[220:223], v153 offset:23552
	global_load_lds_dwordx4 v[202:203], off
	s_add_i32 m0, s50, 0x2000
	s_add_u32 s50, s54, 0xb0000
	v_lshl_add_u64 v[224:225], s[54:55], 0, v[134:135]
	s_addc_u32 s51, s55, 0
	s_add_i32 s78, s62, s3
	global_load_lds_dwordx4 v[224:225], off
	v_lshl_add_u64 v[226:227], s[50:51], 0, v[130:131]
	s_mov_b32 m0, s78
	global_load_lds_dwordx4 v[226:227], off
	v_lshl_add_u64 v[226:227], s[50:51], 0, v[134:135]
	s_add_i32 m0, s78, 0x2000
	s_nop 0
	global_load_lds_dwordx4 v[226:227], off
	s_waitcnt vmcnt(6)
	s_waitcnt lgkmcnt(0)
	s_barrier
; #define PG8_STAGE(bufoff, gbase, voff) do { _Pragma("unroll") for (int _i = 0; _i < 2; ++_i) \
;         __builtin_amdgcn_global_load_lds((const unsigned*)((const char*)(gbase) + (voff)[_i]), (PG8_LAS unsigned*)(lds + (bufoff) + ldsw + _i * 8192), 16, 0, 0); } while (0)
; #define PG8_LDA(dst, b, h) do { _Pragma("unroll") for (int m = 0; m < 4; ++m) _Pragma("unroll") for (int k = 0; k < 2; ++k) dst[m][k] = *(const PG8_LAS bf16x8*)(lds + PG8_SA(b, h) + aoff + m * 2048 + k * 1024); } while (0)
; #define PG8_LDB(dst, b, h) do { _Pragma("unroll") for (int n = 0; n < 2; ++n) _Pragma("unroll") for (int k = 0; k < 2; ++k) dst[n][k] = *(const PG8_LAS bf16x8*)(lds + PG8_SB(b, h) + boff + n * 2048 + k * 1024); } while (0)
; #define PG8_MMA(ai, bj, At, Bt) do { __builtin_amdgcn_s_setprio(1); _Pragma("unroll") for (int m = 0; m < 4; ++m) _Pragma("unroll") for (int n = 0; n < 2; ++n) _Pragma("unroll") for (int k = 0; k < 2; ++k) \
;         acc[ai][bj][m][n] = __builtin_amdgcn_mfma_f32_16x16x32_bf16(Bt[n][k], At[m][k], acc[ai][bj][m][n], 0, 0, 0); __builtin_amdgcn_s_setprio(0); } while (0)
; #define PG8_WAIT_V(n) asm volatile("s_waitcnt vmcnt(" #n ")" ::: "memory")
; #define PG8_WAIT_L(n) asm volatile("s_waitcnt lgkmcnt(" #n ")" ::: "memory")
; #define PG8_BAR __builtin_amdgcn_s_barrier()
; #define PG8_SCHED __builtin_amdgcn_sched_barrier(0)
; template <class Epi, class Sched, bool ALIGN_EPI = false, bool SP2 = false>
; __device__ __forceinline__ void gemm_phase(PG8_LAS unsigned char* lds, const Gemm g, const Sched& S, const Epi& E) {
;     ...
;             PG8_WAIT_V(8); PG8_WAIT_L(0); PG8_BAR; PG8_MMA(1, 0, At, B0); PG8_MMA(1, 1, At, B1); PG8_BAR; PG8_SCHED;
;             PG8_LDB(B0, 1, 0); PG8_LDB(B1, 1, 1); PG8_SCHED; PG8_LDA(At, 1, 0); PG8_STAGE(PG8_SA(0, 1), a2 + hstep, voffA);
;             PG8_WAIT_V(8); PG8_WAIT_L(0); PG8_BAR; PG8_MMA(0, 0, At, B0); PG8_MMA(0, 1, At, B1); PG8_BAR; PG8_SCHED;
	s_setprio 1
	s_waitcnt lgkmcnt(0)
	v_mfma_f32_16x16x32_bf16 v[60:63], v[144:147], v[186:189], 0
	v_mfma_f32_16x16x32_bf16 v[56:59], v[160:163], v[186:189], 0
	v_mfma_f32_16x16x32_bf16 v[44:47], v[144:147], v[194:197], 0
	v_mfma_f32_16x16x32_bf16 v[40:43], v[160:163], v[194:197], 0
	v_mfma_f32_16x16x32_bf16 v[28:31], v[144:147], v[208:211], 0
	v_mfma_f32_16x16x32_bf16 v[24:27], v[160:163], v[208:211], 0
	v_mfma_f32_16x16x32_bf16 v[12:15], v[144:147], v[216:219], 0
	v_mfma_f32_16x16x32_bf16 v[8:11], v[160:163], v[216:219], 0
	v_mfma_f32_16x16x32_bf16 v[60:63], v[156:159], v[190:193], v[60:63]
	v_mfma_f32_16x16x32_bf16 v[56:59], v[164:167], v[190:193], v[56:59]
	v_mfma_f32_16x16x32_bf16 v[44:47], v[156:159], v[198:201], v[44:47]
	v_mfma_f32_16x16x32_bf16 v[40:43], v[164:167], v[198:201], v[40:43]
	v_mfma_f32_16x16x32_bf16 v[28:31], v[156:159], v[212:215], v[28:31]
	v_mfma_f32_16x16x32_bf16 v[24:27], v[164:167], v[212:215], v[24:27]
	v_lshl_add_u64 v[226:227], s[56:57], 0, v[128:129]
	s_mov_b32 m0, s14
	s_nop 0
	global_load_lds_dwordx4 v[226:227], off
	v_mfma_f32_16x16x32_bf16 v[12:15], v[156:159], v[220:223], v[12:15]
	v_mfma_f32_16x16x32_bf16 v[8:11], v[164:167], v[220:223], v[8:11]
	s_setprio 0
	s_setprio 1
	v_mfma_f32_16x16x32_bf16 v[52:55], v[168:171], v[186:189], 0
	v_mfma_f32_16x16x32_bf16 v[48:51], v[176:179], v[186:189], 0
	v_mfma_f32_16x16x32_bf16 v[36:39], v[168:171], v[194:197], 0
	v_mfma_f32_16x16x32_bf16 v[32:35], v[176:179], v[194:197], 0
	v_mfma_f32_16x16x32_bf16 v[20:23], v[168:171], v[208:211], 0
	v_mfma_f32_16x16x32_bf16 v[16:19], v[176:179], v[208:211], 0
	v_mfma_f32_16x16x32_bf16 v[4:7], v[168:171], v[216:219], 0
	v_mfma_f32_16x16x32_bf16 v[0:3], v[176:179], v[216:219], 0
	v_mfma_f32_16x16x32_bf16 v[52:55], v[172:175], v[190:193], v[52:55]
	v_mfma_f32_16x16x32_bf16 v[48:51], v[182:185], v[190:193], v[48:51]
	v_mfma_f32_16x16x32_bf16 v[36:39], v[172:175], v[198:201], v[36:39]
	v_mfma_f32_16x16x32_bf16 v[32:35], v[182:185], v[198:201], v[32:35]
	v_mfma_f32_16x16x32_bf16 v[20:23], v[172:175], v[212:215], v[20:23]
	v_mfma_f32_16x16x32_bf16 v[16:19], v[182:185], v[212:215], v[16:19]
	v_lshl_add_u64 v[228:229], s[56:57], 0, v[132:133]
	s_mov_b32 m0, s15
	s_nop 0
	global_load_lds_dwordx4 v[228:229], off
	v_mfma_f32_16x16x32_bf16 v[4:7], v[172:175], v[220:223], v[4:7]
	v_mfma_f32_16x16x32_bf16 v[0:3], v[182:185], v[220:223], v[0:3]
	s_setprio 0
	s_barrier
	s_add_i32 s78, 0, 0x18000
	v_add_u32_e32 v155, s78, v149
	s_add_i32 s79, 0, 0x1c000
	ds_read_b128 v[144:147], v155
	ds_read_b128 v[156:159], v155 offset:1024
	ds_read_b128 v[160:163], v155 offset:2048
	ds_read_b128 v[164:167], v155 offset:3072
	v_add_u32_e32 v155, s79, v149
	ds_read_b128 v[168:171], v155
	ds_read_b128 v[172:175], v155 offset:1024
	ds_read_b128 v[176:179], v155 offset:2048
	ds_read_b128 v[182:185], v155 offset:3072
	s_add_u32 s50, s56, 0xb0000
	s_addc_u32 s51, s57, 0
	s_mov_b32 m0, s33
	v_lshl_add_u64 v[230:231], s[50:51], 0, v[128:129]
	ds_read_b128 v[186:189], v153 offset:32768
	ds_read_b128 v[190:193], v153 offset:33792
	ds_read_b128 v[194:197], v153 offset:34816
	ds_read_b128 v[198:201], v153 offset:35840
	ds_read_b128 v[208:211], v153 offset:36864
	ds_read_b128 v[212:215], v153 offset:37888
	ds_read_b128 v[216:219], v153 offset:38912
	ds_read_b128 v[220:223], v153 offset:39936
	global_load_lds_dwordx4 v[230:231], off
	v_lshl_add_u64 v[230:231], s[50:51], 0, v[132:133]
	s_mov_b32 m0, s34
	s_nop 0
	global_load_lds_dwordx4 v[230:231], off
	s_waitcnt vmcnt(8)
	s_waitcnt lgkmcnt(0)
	s_barrier
	s_setprio 1
	s_waitcnt lgkmcnt(0)
	v_mfma_f32_16x16x32_bf16 v[124:127], v[144:147], v[186:189], v[124:127]
	v_mfma_f32_16x16x32_bf16 v[120:123], v[160:163], v[186:189], v[120:123]
	v_mfma_f32_16x16x32_bf16 v[108:111], v[144:147], v[194:197], v[108:111]
	v_mfma_f32_16x16x32_bf16 v[104:107], v[160:163], v[194:197], v[104:107]
	v_mfma_f32_16x16x32_bf16 v[92:95], v[144:147], v[208:211], v[92:95]
	v_mfma_f32_16x16x32_bf16 v[88:91], v[160:163], v[208:211], v[88:91]
	v_mfma_f32_16x16x32_bf16 v[76:79], v[144:147], v[216:219], v[76:79]
	v_mfma_f32_16x16x32_bf16 v[72:75], v[160:163], v[216:219], v[72:75]
	v_mfma_f32_16x16x32_bf16 v[124:127], v[156:159], v[190:193], v[124:127]
	v_mfma_f32_16x16x32_bf16 v[120:123], v[164:167], v[190:193], v[120:123]
	v_mfma_f32_16x16x32_bf16 v[108:111], v[156:159], v[198:201], v[108:111]
	v_mfma_f32_16x16x32_bf16 v[104:107], v[164:167], v[198:201], v[104:107]
	v_mfma_f32_16x16x32_bf16 v[92:95], v[156:159], v[212:215], v[92:95]
	v_mfma_f32_16x16x32_bf16 v[88:91], v[164:167], v[212:215], v[88:91]
	v_mfma_f32_16x16x32_bf16 v[76:79], v[156:159], v[220:223], v[76:79]
	v_mfma_f32_16x16x32_bf16 v[72:75], v[164:167], v[220:223], v[72:75]
	s_setprio 0
	s_setprio 1
	v_mfma_f32_16x16x32_bf16 v[116:119], v[168:171], v[186:189], v[116:119]
	v_mfma_f32_16x16x32_bf16 v[112:115], v[176:179], v[186:189], v[112:115]
	v_mfma_f32_16x16x32_bf16 v[100:103], v[168:171], v[194:197], v[100:103]
	v_mfma_f32_16x16x32_bf16 v[96:99], v[176:179], v[194:197], v[96:99]
	v_mfma_f32_16x16x32_bf16 v[84:87], v[168:171], v[208:211], v[84:87]
	v_mfma_f32_16x16x32_bf16 v[80:83], v[176:179], v[208:211], v[80:83]
	v_mfma_f32_16x16x32_bf16 v[68:71], v[168:171], v[216:219], v[68:71]
	v_mfma_f32_16x16x32_bf16 v[64:67], v[176:179], v[216:219], v[64:67]
	v_mfma_f32_16x16x32_bf16 v[116:119], v[172:175], v[190:193], v[116:119]
	v_mfma_f32_16x16x32_bf16 v[112:115], v[182:185], v[190:193], v[112:115]
	v_mfma_f32_16x16x32_bf16 v[100:103], v[172:175], v[198:201], v[100:103]
	v_mfma_f32_16x16x32_bf16 v[96:99], v[182:185], v[198:201], v[96:99]
	v_mfma_f32_16x16x32_bf16 v[84:87], v[172:175], v[212:215], v[84:87]
	v_mfma_f32_16x16x32_bf16 v[80:83], v[182:185], v[212:215], v[80:83]
	v_mfma_f32_16x16x32_bf16 v[68:71], v[172:175], v[220:223], v[68:71]
	v_mfma_f32_16x16x32_bf16 v[64:67], v[182:185], v[220:223], v[64:67]
	s_setprio 0
	s_barrier
; #define PG8_STAGE(bufoff, gbase, voff) do { _Pragma("unroll") for (int _i = 0; _i < 2; ++_i) \
;         __builtin_amdgcn_global_load_lds((const unsigned*)((const char*)(gbase) + (voff)[_i]), (PG8_LAS unsigned*)(lds + (bufoff) + ldsw + _i * 8192), 16, 0, 0); } while (0)
; #define PG8_LDA(dst, b, h) do { _Pragma("unroll") for (int m = 0; m < 4; ++m) _Pragma("unroll") for (int k = 0; k < 2; ++k) dst[m][k] = *(const PG8_LAS bf16x8*)(lds + PG8_SA(b, h) + aoff + m * 2048 + k * 1024); } while (0)
; #define PG8_MMA(ai, bj, At, Bt) do { __builtin_amdgcn_s_setprio(1); _Pragma("unroll") for (int m = 0; m < 4; ++m) _Pragma("unroll") for (int n = 0; n < 2; ++n) _Pragma("unroll") for (int k = 0; k < 2; ++k) \
;         acc[ai][bj][m][n] = __builtin_amdgcn_mfma_f32_16x16x32_bf16(Bt[n][k], At[m][k], acc[ai][bj][m][n], 0, 0, 0); __builtin_amdgcn_s_setprio(0); } while (0)
; #define PG8_WAIT_V(n) asm volatile("s_waitcnt vmcnt(" #n ")" ::: "memory")
; #define PG8_WAIT_L(n) asm volatile("s_waitcnt lgkmcnt(" #n ")" ::: "memory")
; #define PG8_BAR __builtin_amdgcn_s_barrier()
; #define PG8_SCHED __builtin_amdgcn_sched_barrier(0)
; template <class Epi, class Sched, bool ALIGN_EPI = false, bool SP2 = false>
; __device__ __forceinline__ void gemm_phase(PG8_LAS unsigned char* lds, const Gemm g, const Sched& S, const Epi& E) {
;     ...
;         for (int t = 0; t < nt; t += 2) {
;             const bool last = (t == nt - 2);
;             const char* a1 = cA + (size_t)(t + 1) * kstep;
;             const char* a2 = last ? nA : cA + (size_t)(t + 2) * kstep; const char* b2 = last ? nB : cB + (size_t)(t + 2) * kstep;
;             const char* a3 = a2 + kstep; const char* b3 = b2 + kstep;
;     ...
;             PG8_LDA(At, 1, 1); PG8_STAGE(PG8_SB(1, 0), b3, voffB); PG8_STAGE(PG8_SB(1, 1), b3 + hstep, voffB); PG8_STAGE(PG8_SA(1, 0), a3, voffA);
;             PG8_WAIT_V(8); PG8_WAIT_L(0); PG8_BAR; PG8_MMA(1, 0, At, B0); PG8_MMA(1, 1, At, B1); PG8_BAR; PG8_SCHED;
	s_add_i32 s50, s78, s3
	v_lshl_add_u64 v[202:203], v[202:203], 0, s[42:43]
	s_mov_b32 m0, s50
	ds_read_b128 v[186:189], v153 offset:49152
	ds_read_b128 v[190:193], v153 offset:50176
	ds_read_b128 v[194:197], v153 offset:51200
	ds_read_b128 v[198:201], v153 offset:52224
	ds_read_b128 v[208:211], v153 offset:53248
	ds_read_b128 v[212:215], v153 offset:54272
	ds_read_b128 v[216:219], v153 offset:55296
	ds_read_b128 v[220:223], v153 offset:56320
	global_load_lds_dwordx4 v[202:203], off
	s_add_i32 m0, s50, 0x2000
	s_add_u32 s50, s54, 0xb0080
	v_lshl_add_u64 v[202:203], v[224:225], 0, s[42:43]
	s_addc_u32 s51, s55, 0
	s_add_i32 s54, s79, s3
	global_load_lds_dwordx4 v[202:203], off
	v_lshl_add_u64 v[202:203], s[50:51], 0, v[130:131]
	s_mov_b32 m0, s54
	s_nop 0
	global_load_lds_dwordx4 v[202:203], off
	v_lshl_add_u64 v[202:203], s[50:51], 0, v[134:135]
	s_add_i32 m0, s54, 0x2000
	s_nop 0
	global_load_lds_dwordx4 v[202:203], off
	s_waitcnt vmcnt(6)
	s_waitcnt lgkmcnt(0)
	s_barrier
	s_setprio 1
	s_waitcnt lgkmcnt(0)
	v_mfma_f32_16x16x32_bf16 v[60:63], v[144:147], v[186:189], v[60:63]
	v_mfma_f32_16x16x32_bf16 v[56:59], v[160:163], v[186:189], v[56:59]
	v_mfma_f32_16x16x32_bf16 v[44:47], v[144:147], v[194:197], v[44:47]
	v_mfma_f32_16x16x32_bf16 v[40:43], v[160:163], v[194:197], v[40:43]
	v_mfma_f32_16x16x32_bf16 v[28:31], v[144:147], v[208:211], v[28:31]
	v_mfma_f32_16x16x32_bf16 v[24:27], v[160:163], v[208:211], v[24:27]
	v_mfma_f32_16x16x32_bf16 v[12:15], v[144:147], v[216:219], v[12:15]
	v_mfma_f32_16x16x32_bf16 v[8:11], v[160:163], v[216:219], v[8:11]
	v_mfma_f32_16x16x32_bf16 v[60:63], v[156:159], v[190:193], v[60:63]
	v_mfma_f32_16x16x32_bf16 v[56:59], v[164:167], v[190:193], v[56:59]
	v_mfma_f32_16x16x32_bf16 v[44:47], v[156:159], v[198:201], v[44:47]
	v_mfma_f32_16x16x32_bf16 v[40:43], v[164:167], v[198:201], v[40:43]
	v_mfma_f32_16x16x32_bf16 v[28:31], v[156:159], v[212:215], v[28:31]
	v_mfma_f32_16x16x32_bf16 v[24:27], v[164:167], v[212:215], v[24:27]
	v_lshl_add_u64 v[202:203], v[226:227], 0, s[42:43]
	s_mov_b32 m0, s59
	s_nop 0
	global_load_lds_dwordx4 v[202:203], off
	v_mfma_f32_16x16x32_bf16 v[12:15], v[156:159], v[220:223], v[12:15]
	v_mfma_f32_16x16x32_bf16 v[8:11], v[164:167], v[220:223], v[8:11]
	s_setprio 0
	s_setprio 1
	v_mfma_f32_16x16x32_bf16 v[52:55], v[168:171], v[186:189], v[52:55]
	v_mfma_f32_16x16x32_bf16 v[48:51], v[176:179], v[186:189], v[48:51]
	v_mfma_f32_16x16x32_bf16 v[36:39], v[168:171], v[194:197], v[36:39]
	v_mfma_f32_16x16x32_bf16 v[32:35], v[176:179], v[194:197], v[32:35]
	v_mfma_f32_16x16x32_bf16 v[20:23], v[168:171], v[208:211], v[20:23]
	v_mfma_f32_16x16x32_bf16 v[16:19], v[176:179], v[208:211], v[16:19]
	v_mfma_f32_16x16x32_bf16 v[4:7], v[168:171], v[216:219], v[4:7]
	v_mfma_f32_16x16x32_bf16 v[0:3], v[176:179], v[216:219], v[0:3]
	v_mfma_f32_16x16x32_bf16 v[52:55], v[172:175], v[190:193], v[52:55]
	v_mfma_f32_16x16x32_bf16 v[48:51], v[182:185], v[190:193], v[48:51]
	v_mfma_f32_16x16x32_bf16 v[36:39], v[172:175], v[198:201], v[36:39]
	v_mfma_f32_16x16x32_bf16 v[32:35], v[182:185], v[198:201], v[32:35]
	v_mfma_f32_16x16x32_bf16 v[20:23], v[172:175], v[212:215], v[20:23]
	v_mfma_f32_16x16x32_bf16 v[16:19], v[182:185], v[212:215], v[16:19]
	v_lshl_add_u64 v[202:203], v[228:229], 0, s[42:43]
	s_mov_b32 m0, s60
	s_nop 0
	global_load_lds_dwordx4 v[202:203], off
	v_mfma_f32_16x16x32_bf16 v[4:7], v[172:175], v[220:223], v[4:7]
	v_mfma_f32_16x16x32_bf16 v[0:3], v[182:185], v[220:223], v[0:3]
	s_setprio 0
	s_barrier
	s_add_i32 s77, s77, 2
	s_add_u32 s75, s75, 0x100
	s_addc_u32 s76, s76, 0
	s_mov_b64 s[50:51], s[52:53]
	.p2align 6

; #define PG8_STAGE(bufoff, gbase, voff) do { _Pragma("unroll") for (int _i = 0; _i < 2; ++_i) \
;         __builtin_amdgcn_global_load_lds((const unsigned*)((const char*)(gbase) + (voff)[_i]), (PG8_LAS unsigned*)(lds + (bufoff) + ldsw + _i * 8192), 16, 0, 0); } while (0)
; #define PG8_LDA(dst, b, h) do { _Pragma("unroll") for (int m = 0; m < 4; ++m) _Pragma("unroll") for (int k = 0; k < 2; ++k) dst[m][k] = *(const PG8_LAS bf16x8*)(lds + PG8_SA(b, h) + aoff + m * 2048 + k * 1024); } while (0)
; #define PG8_LDB(dst, b, h) do { _Pragma("unroll") for (int n = 0; n < 2; ++n) _Pragma("unroll") for (int k = 0; k < 2; ++k) dst[n][k] = *(const PG8_LAS bf16x8*)(lds + PG8_SB(b, h) + boff + n * 2048 + k * 1024); } while (0)
; #define PG8_WAIT_V(n) asm volatile("s_waitcnt vmcnt(" #n ")" ::: "memory")
; #define PG8_WAIT_L(n) asm volatile("s_waitcnt lgkmcnt(" #n ")" ::: "memory")
; #define PG8_BAR __builtin_amdgcn_s_barrier()
; #define PG8_SCHED __builtin_amdgcn_sched_barrier(0)
; template <class Epi, class Sched, bool ALIGN_EPI = false, bool SP2 = false>
; __device__ __forceinline__ void gemm_phase(PG8_LAS unsigned char* lds, const Gemm g, const Sched& S, const Epi& E) {
;     ...
;         const bool has_next = S.next(ui + 1, nxt);
;         const char* nA = has_next ? (const char*)g.A + (size_t)nxt.pm * tstep : cA; const char* nB = has_next ? (const char*)g.Bt + (size_t)nxt.pn * tstep : cB;
;         for (int t = 0; t < nt; t += 2) {
;             const bool last = (t == nt - 2);
;             const char* a1 = cA + (size_t)(t + 1) * kstep;
;             const char* a2 = last ? nA : cA + (size_t)(t + 2) * kstep; const char* b2 = last ? nB : cB + (size_t)(t + 2) * kstep;
;             const char* a3 = a2 + kstep; const char* b3 = b2 + kstep;
;             if (last && has_next) S.a_ready(nxt);
;             if constexpr (SP2) {
;             PG8_LDB(B0, 0, 0); PG8_LDB(B1, 0, 1); PG8_SCHED; PG8_LDA(At, 0, 0); PG8_STAGE(PG8_SA(1, 1), a1 + hstep, voffA);
;             PG8_WAIT_V(8); PG8_WAIT_L(0); PG8_BAR; PG8_MMA(0, 0, At, B0); PG8_MMA(0, 1, At, B1); PG8_BAR; PG8_SCHED;
;             PG8_LDA(At, 0, 1); PG8_STAGE(PG8_SB(0, 0), b2, voffB); PG8_STAGE(PG8_SB(0, 1), b2 + hstep, voffB); PG8_STAGE(PG8_SA(0, 0), a2, voffA);
;             PG8_WAIT_V(8); PG8_WAIT_L(0); PG8_BAR; PG8_MMA(1, 0, At, B0); PG8_MMA(1, 1, At, B1); PG8_BAR; PG8_SCHED;
.LBB0_1118:
	s_ashr_i32 s45, s44, 31
	s_lshl_b64 s[48:49], s[44:45], 19
	s_add_u32 s48, s22, s48
	s_addc_u32 s49, s23, s49
	s_and_b64 s[50:51], s[10:11], exec
	s_cselect_b32 s45, s49, s55
	s_cselect_b32 s76, s48, s54
	s_ashr_i32 s43, s42, 31
	s_lshl_b64 s[50:51], s[42:43], 19
	s_add_u32 s50, s14, s50
	s_addc_u32 s51, s15, s51
	s_and_b64 s[58:59], s[10:11], exec
	s_cselect_b32 s43, s51, s57
	s_cselect_b32 s77, s50, s56
	s_add_u32 s54, s54, 0x40080
	s_addc_u32 s55, s55, 0
	s_add_u32 s82, s56, 0x100
	s_addc_u32 s83, s57, 0
	s_mov_b32 s84, -2
	ds_read_b128 v[144:147], v155
	ds_read_b128 v[148:151], v155 offset:1024
	ds_read_b128 v[160:163], v155 offset:2048
	ds_read_b128 v[164:167], v155 offset:3072
	ds_read_b128 v[168:171], v156
	ds_read_b128 v[172:175], v156 offset:1024
	ds_read_b128 v[176:179], v156 offset:2048
	ds_read_b128 v[182:185], v156 offset:3072
	s_add_u32 s56, s54, 0xfffc0080
	s_addc_u32 s57, s55, -1
	s_cmp_eq_u32 s84, 12
	s_cselect_b32 s59, s45, s57
	s_cselect_b32 s58, s76, s56
	s_cselect_b32 s57, s43, s83
	s_cselect_b32 s56, s77, s82
	v_lshl_add_u64 v[224:225], s[54:55], 0, v[136:137]
	s_add_i32 m0, s53, 0xc000
	ds_read_b128 v[186:189], v157
	ds_read_b128 v[190:193], v157 offset:1024
	ds_read_b128 v[194:197], v157 offset:2048
	ds_read_b128 v[198:201], v157 offset:3072
	ds_read_b128 v[208:211], v157 offset:4096
	ds_read_b128 v[212:215], v157 offset:5120
	ds_read_b128 v[216:219], v157 offset:6144
	ds_read_b128 v[220:223], v157 offset:7168
	global_load_lds_dwordx4 v[224:225], off
	v_lshl_add_u64 v[224:225], s[54:55], 0, v[138:139]
	s_add_i32 m0, s53, 0xe000
	s_nop 0
	global_load_lds_dwordx4 v[224:225], off
	s_waitcnt vmcnt(8)
	s_waitcnt lgkmcnt(0)
	s_barrier
	s_setprio 1
	s_waitcnt lgkmcnt(0)
	v_mfma_f32_16x16x32_bf16 v[124:127], v[144:147], v[186:189], 0
	v_mfma_f32_16x16x32_bf16 v[120:123], v[160:163], v[186:189], 0
	v_mfma_f32_16x16x32_bf16 v[108:111], v[144:147], v[194:197], 0
	v_mfma_f32_16x16x32_bf16 v[104:107], v[160:163], v[194:197], 0
	v_mfma_f32_16x16x32_bf16 v[92:95], v[144:147], v[208:211], 0
	v_mfma_f32_16x16x32_bf16 v[88:91], v[160:163], v[208:211], 0
	v_mfma_f32_16x16x32_bf16 v[76:79], v[144:147], v[216:219], 0
	v_mfma_f32_16x16x32_bf16 v[72:75], v[160:163], v[216:219], 0
	v_mfma_f32_16x16x32_bf16 v[124:127], v[148:151], v[190:193], v[124:127]
	v_mfma_f32_16x16x32_bf16 v[120:123], v[164:167], v[190:193], v[120:123]
	v_mfma_f32_16x16x32_bf16 v[108:111], v[148:151], v[198:201], v[108:111]
	v_mfma_f32_16x16x32_bf16 v[104:107], v[164:167], v[198:201], v[104:107]
	v_mfma_f32_16x16x32_bf16 v[92:95], v[148:151], v[212:215], v[92:95]
	v_mfma_f32_16x16x32_bf16 v[88:91], v[164:167], v[212:215], v[88:91]
	v_mfma_f32_16x16x32_bf16 v[76:79], v[148:151], v[220:223], v[76:79]
	v_mfma_f32_16x16x32_bf16 v[72:75], v[164:167], v[220:223], v[72:75]
	s_setprio 0
	s_setprio 1
	v_mfma_f32_16x16x32_bf16 v[116:119], v[168:171], v[186:189], 0
	v_mfma_f32_16x16x32_bf16 v[112:115], v[176:179], v[186:189], 0
	v_mfma_f32_16x16x32_bf16 v[100:103], v[168:171], v[194:197], 0
	v_mfma_f32_16x16x32_bf16 v[96:99], v[176:179], v[194:197], 0
	v_mfma_f32_16x16x32_bf16 v[84:87], v[168:171], v[208:211], 0
	v_mfma_f32_16x16x32_bf16 v[80:83], v[176:179], v[208:211], 0
	v_mfma_f32_16x16x32_bf16 v[68:71], v[168:171], v[216:219], 0
	v_mfma_f32_16x16x32_bf16 v[64:67], v[176:179], v[216:219], 0
	v_mfma_f32_16x16x32_bf16 v[116:119], v[172:175], v[190:193], v[116:119]
	v_mfma_f32_16x16x32_bf16 v[112:115], v[182:185], v[190:193], v[112:115]
	v_mfma_f32_16x16x32_bf16 v[100:103], v[172:175], v[198:201], v[100:103]
	v_mfma_f32_16x16x32_bf16 v[96:99], v[182:185], v[198:201], v[96:99]
	v_mfma_f32_16x16x32_bf16 v[84:87], v[172:175], v[212:215], v[84:87]
	v_mfma_f32_16x16x32_bf16 v[80:83], v[182:185], v[212:215], v[80:83]
	v_mfma_f32_16x16x32_bf16 v[68:71], v[172:175], v[220:223], v[68:71]
	v_mfma_f32_16x16x32_bf16 v[64:67], v[182:185], v[220:223], v[64:67]
	s_setprio 0
	s_barrier
	s_add_i32 s78, s66, s33
	v_lshl_add_u64 v[224:225], s[56:57], 0, v[132:133]
	s_mov_b32 m0, s78
	ds_read_b128 v[186:189], v157 offset:16384
	ds_read_b128 v[190:193], v157 offset:17408
	ds_read_b128 v[194:197], v157 offset:18432
	ds_read_b128 v[198:201], v157 offset:19456
	ds_read_b128 v[208:211], v157 offset:20480
	ds_read_b128 v[212:215], v157 offset:21504
	ds_read_b128 v[216:219], v157 offset:22528
	ds_read_b128 v[220:223], v157 offset:23552
	global_load_lds_dwordx4 v[224:225], off
	s_add_i32 m0, s78, 0x2000
	s_add_u32 s78, s56, 0x40000
	v_lshl_add_u64 v[226:227], s[56:57], 0, v[128:129]
	s_addc_u32 s79, s57, 0
	s_add_i32 s85, s67, s33
	global_load_lds_dwordx4 v[226:227], off
	v_lshl_add_u64 v[228:229], s[78:79], 0, v[132:133]
	s_mov_b32 m0, s85
	global_load_lds_dwordx4 v[228:229], off
	v_lshl_add_u64 v[228:229], s[78:79], 0, v[128:129]
	s_add_i32 m0, s85, 0x2000
	s_nop 0
	global_load_lds_dwordx4 v[228:229], off
	s_waitcnt vmcnt(6)
	s_waitcnt lgkmcnt(0)
	s_barrier
; #define PG8_STAGE(bufoff, gbase, voff) do { _Pragma("unroll") for (int _i = 0; _i < 2; ++_i) \
;         __builtin_amdgcn_global_load_lds((const unsigned*)((const char*)(gbase) + (voff)[_i]), (PG8_LAS unsigned*)(lds + (bufoff) + ldsw + _i * 8192), 16, 0, 0); } while (0)
; #define PG8_LDA(dst, b, h) do { _Pragma("unroll") for (int m = 0; m < 4; ++m) _Pragma("unroll") for (int k = 0; k < 2; ++k) dst[m][k] = *(const PG8_LAS bf16x8*)(lds + PG8_SA(b, h) + aoff + m * 2048 + k * 1024); } while (0)
; #define PG8_LDB(dst, b, h) do { _Pragma("unroll") for (int n = 0; n < 2; ++n) _Pragma("unroll") for (int k = 0; k < 2; ++k) dst[n][k] = *(const PG8_LAS bf16x8*)(lds + PG8_SB(b, h) + boff + n * 2048 + k * 1024); } while (0)
; #define PG8_MMA(ai, bj, At, Bt) do { __builtin_amdgcn_s_setprio(1); _Pragma("unroll") for (int m = 0; m < 4; ++m) _Pragma("unroll") for (int n = 0; n < 2; ++n) _Pragma("unroll") for (int k = 0; k < 2; ++k) \
;         acc[ai][bj][m][n] = __builtin_amdgcn_mfma_f32_16x16x32_bf16(Bt[n][k], At[m][k], acc[ai][bj][m][n], 0, 0, 0); __builtin_amdgcn_s_setprio(0); } while (0)
; #define PG8_WAIT_V(n) asm volatile("s_waitcnt vmcnt(" #n ")" ::: "memory")
; #define PG8_WAIT_L(n) asm volatile("s_waitcnt lgkmcnt(" #n ")" ::: "memory")
; #define PG8_BAR __builtin_amdgcn_s_barrier()
; #define PG8_SCHED __builtin_amdgcn_sched_barrier(0)
; template <class Epi, class Sched, bool ALIGN_EPI = false, bool SP2 = false>
; __device__ __forceinline__ void gemm_phase(PG8_LAS unsigned char* lds, const Gemm g, const Sched& S, const Epi& E) {
;     ...
;             PG8_WAIT_V(8); PG8_WAIT_L(0); PG8_BAR; PG8_MMA(1, 0, At, B0); PG8_MMA(1, 1, At, B1); PG8_BAR; PG8_SCHED;
;             PG8_LDB(B0, 1, 0); PG8_LDB(B1, 1, 1); PG8_SCHED; PG8_LDA(At, 1, 0); PG8_STAGE(PG8_SA(0, 1), a2 + hstep, voffA);
;             PG8_WAIT_V(8); PG8_WAIT_L(0); PG8_BAR; PG8_MMA(0, 0, At, B0); PG8_MMA(0, 1, At, B1); PG8_BAR; PG8_SCHED;
	s_setprio 1
	s_waitcnt lgkmcnt(0)
	v_mfma_f32_16x16x32_bf16 v[60:63], v[144:147], v[186:189], 0
	v_mfma_f32_16x16x32_bf16 v[56:59], v[160:163], v[186:189], 0
	v_mfma_f32_16x16x32_bf16 v[44:47], v[144:147], v[194:197], 0
	v_mfma_f32_16x16x32_bf16 v[40:43], v[160:163], v[194:197], 0
	v_mfma_f32_16x16x32_bf16 v[28:31], v[144:147], v[208:211], 0
	v_mfma_f32_16x16x32_bf16 v[24:27], v[160:163], v[208:211], 0
	v_mfma_f32_16x16x32_bf16 v[12:15], v[144:147], v[216:219], 0
	v_mfma_f32_16x16x32_bf16 v[8:11], v[160:163], v[216:219], 0
	v_mfma_f32_16x16x32_bf16 v[60:63], v[148:151], v[190:193], v[60:63]
	v_mfma_f32_16x16x32_bf16 v[56:59], v[164:167], v[190:193], v[56:59]
	v_mfma_f32_16x16x32_bf16 v[44:47], v[148:151], v[198:201], v[44:47]
	v_mfma_f32_16x16x32_bf16 v[40:43], v[164:167], v[198:201], v[40:43]
	v_mfma_f32_16x16x32_bf16 v[28:31], v[148:151], v[212:215], v[28:31]
	v_mfma_f32_16x16x32_bf16 v[24:27], v[164:167], v[212:215], v[24:27]
	v_lshl_add_u64 v[228:229], s[58:59], 0, v[134:135]
	s_mov_b32 m0, s53
	s_nop 0
	global_load_lds_dwordx4 v[228:229], off
	v_mfma_f32_16x16x32_bf16 v[12:15], v[148:151], v[220:223], v[12:15]
	v_mfma_f32_16x16x32_bf16 v[8:11], v[164:167], v[220:223], v[8:11]
	s_setprio 0
	s_setprio 1
	v_mfma_f32_16x16x32_bf16 v[52:55], v[168:171], v[186:189], 0
	v_mfma_f32_16x16x32_bf16 v[48:51], v[176:179], v[186:189], 0
	v_mfma_f32_16x16x32_bf16 v[36:39], v[168:171], v[194:197], 0
	v_mfma_f32_16x16x32_bf16 v[32:35], v[176:179], v[194:197], 0
	v_mfma_f32_16x16x32_bf16 v[20:23], v[168:171], v[208:211], 0
	v_mfma_f32_16x16x32_bf16 v[16:19], v[176:179], v[208:211], 0
	v_mfma_f32_16x16x32_bf16 v[4:7], v[168:171], v[216:219], 0
	v_mfma_f32_16x16x32_bf16 v[0:3], v[176:179], v[216:219], 0
	v_mfma_f32_16x16x32_bf16 v[52:55], v[172:175], v[190:193], v[52:55]
	v_mfma_f32_16x16x32_bf16 v[48:51], v[182:185], v[190:193], v[48:51]
	v_mfma_f32_16x16x32_bf16 v[36:39], v[172:175], v[198:201], v[36:39]
	v_mfma_f32_16x16x32_bf16 v[32:35], v[182:185], v[198:201], v[32:35]
	v_mfma_f32_16x16x32_bf16 v[20:23], v[172:175], v[212:215], v[20:23]
	v_mfma_f32_16x16x32_bf16 v[16:19], v[182:185], v[212:215], v[16:19]
	v_lshl_add_u64 v[230:231], s[58:59], 0, v[130:131]
	s_mov_b32 m0, s60
	s_nop 0
	global_load_lds_dwordx4 v[230:231], off
	v_mfma_f32_16x16x32_bf16 v[4:7], v[172:175], v[220:223], v[4:7]
	v_mfma_f32_16x16x32_bf16 v[0:3], v[182:185], v[220:223], v[0:3]
	s_setprio 0
	s_barrier
	s_add_i32 s78, 0, 0x18000
	v_add_u32_e32 v159, s78, v153
	s_add_i32 s79, 0, 0x1c000
	ds_read_b128 v[144:147], v159
	ds_read_b128 v[148:151], v159 offset:1024
	ds_read_b128 v[160:163], v159 offset:2048
	ds_read_b128 v[164:167], v159 offset:3072
	v_add_u32_e32 v159, s79, v153
	ds_read_b128 v[168:171], v159
	ds_read_b128 v[172:175], v159 offset:1024
	ds_read_b128 v[176:179], v159 offset:2048
	ds_read_b128 v[182:185], v159 offset:3072
	s_add_u32 s58, s58, 0x40000
	s_addc_u32 s59, s59, 0
	s_mov_b32 m0, s61
	v_lshl_add_u64 v[232:233], s[58:59], 0, v[134:135]
	ds_read_b128 v[186:189], v157 offset:32768
	ds_read_b128 v[190:193], v157 offset:33792
	ds_read_b128 v[194:197], v157 offset:34816
	ds_read_b128 v[198:201], v157 offset:35840
	ds_read_b128 v[208:211], v157 offset:36864
	ds_read_b128 v[212:215], v157 offset:37888
	ds_read_b128 v[216:219], v157 offset:38912
	ds_read_b128 v[220:223], v157 offset:39936
	global_load_lds_dwordx4 v[232:233], off
	v_lshl_add_u64 v[232:233], s[58:59], 0, v[130:131]
	s_mov_b32 m0, s62
	s_nop 0
	global_load_lds_dwordx4 v[232:233], off
	s_waitcnt vmcnt(8)
	s_waitcnt lgkmcnt(0)
	s_barrier
	s_setprio 1
	s_waitcnt lgkmcnt(0)
	v_mfma_f32_16x16x32_bf16 v[124:127], v[144:147], v[186:189], v[124:127]
	v_mfma_f32_16x16x32_bf16 v[120:123], v[160:163], v[186:189], v[120:123]
	v_mfma_f32_16x16x32_bf16 v[108:111], v[144:147], v[194:197], v[108:111]
	v_mfma_f32_16x16x32_bf16 v[104:107], v[160:163], v[194:197], v[104:107]
	v_mfma_f32_16x16x32_bf16 v[92:95], v[144:147], v[208:211], v[92:95]
	v_mfma_f32_16x16x32_bf16 v[88:91], v[160:163], v[208:211], v[88:91]
	v_mfma_f32_16x16x32_bf16 v[76:79], v[144:147], v[216:219], v[76:79]
	v_mfma_f32_16x16x32_bf16 v[72:75], v[160:163], v[216:219], v[72:75]
	v_mfma_f32_16x16x32_bf16 v[124:127], v[148:151], v[190:193], v[124:127]
	v_mfma_f32_16x16x32_bf16 v[120:123], v[164:167], v[190:193], v[120:123]
	v_mfma_f32_16x16x32_bf16 v[108:111], v[148:151], v[198:201], v[108:111]
	v_mfma_f32_16x16x32_bf16 v[104:107], v[164:167], v[198:201], v[104:107]
	v_mfma_f32_16x16x32_bf16 v[92:95], v[148:151], v[212:215], v[92:95]
	v_mfma_f32_16x16x32_bf16 v[88:91], v[164:167], v[212:215], v[88:91]
	v_mfma_f32_16x16x32_bf16 v[76:79], v[148:151], v[220:223], v[76:79]
	v_mfma_f32_16x16x32_bf16 v[72:75], v[164:167], v[220:223], v[72:75]
	s_setprio 0
	s_setprio 1
	v_mfma_f32_16x16x32_bf16 v[116:119], v[168:171], v[186:189], v[116:119]
	v_mfma_f32_16x16x32_bf16 v[112:115], v[176:179], v[186:189], v[112:115]
	v_mfma_f32_16x16x32_bf16 v[100:103], v[168:171], v[194:197], v[100:103]
	v_mfma_f32_16x16x32_bf16 v[96:99], v[176:179], v[194:197], v[96:99]
	v_mfma_f32_16x16x32_bf16 v[84:87], v[168:171], v[208:211], v[84:87]
	v_mfma_f32_16x16x32_bf16 v[80:83], v[176:179], v[208:211], v[80:83]
	v_mfma_f32_16x16x32_bf16 v[68:71], v[168:171], v[216:219], v[68:71]
	v_mfma_f32_16x16x32_bf16 v[64:67], v[176:179], v[216:219], v[64:67]
	v_mfma_f32_16x16x32_bf16 v[116:119], v[172:175], v[190:193], v[116:119]
	v_mfma_f32_16x16x32_bf16 v[112:115], v[182:185], v[190:193], v[112:115]
	v_mfma_f32_16x16x32_bf16 v[100:103], v[172:175], v[198:201], v[100:103]
	v_mfma_f32_16x16x32_bf16 v[96:99], v[182:185], v[198:201], v[96:99]
	v_mfma_f32_16x16x32_bf16 v[84:87], v[172:175], v[212:215], v[84:87]
	v_mfma_f32_16x16x32_bf16 v[80:83], v[182:185], v[212:215], v[80:83]
	v_mfma_f32_16x16x32_bf16 v[68:71], v[172:175], v[220:223], v[68:71]
	v_mfma_f32_16x16x32_bf16 v[64:67], v[182:185], v[220:223], v[64:67]
	s_setprio 0
	s_barrier
; #define PG8_STAGE(bufoff, gbase, voff) do { _Pragma("unroll") for (int _i = 0; _i < 2; ++_i) \
;         __builtin_amdgcn_global_load_lds((const unsigned*)((const char*)(gbase) + (voff)[_i]), (PG8_LAS unsigned*)(lds + (bufoff) + ldsw + _i * 8192), 16, 0, 0); } while (0)
; #define PG8_LDA(dst, b, h) do { _Pragma("unroll") for (int m = 0; m < 4; ++m) _Pragma("unroll") for (int k = 0; k < 2; ++k) dst[m][k] = *(const PG8_LAS bf16x8*)(lds + PG8_SA(b, h) + aoff + m * 2048 + k * 1024); } while (0)
; #define PG8_MMA(ai, bj, At, Bt) do { __builtin_amdgcn_s_setprio(1); _Pragma("unroll") for (int m = 0; m < 4; ++m) _Pragma("unroll") for (int n = 0; n < 2; ++n) _Pragma("unroll") for (int k = 0; k < 2; ++k) \
;         acc[ai][bj][m][n] = __builtin_amdgcn_mfma_f32_16x16x32_bf16(Bt[n][k], At[m][k], acc[ai][bj][m][n], 0, 0, 0); __builtin_amdgcn_s_setprio(0); } while (0)
; #define PG8_WAIT_V(n) asm volatile("s_waitcnt vmcnt(" #n ")" ::: "memory")
; #define PG8_WAIT_L(n) asm volatile("s_waitcnt lgkmcnt(" #n ")" ::: "memory")
; #define PG8_BAR __builtin_amdgcn_s_barrier()
; #define PG8_SCHED __builtin_amdgcn_sched_barrier(0)
; template <class Epi, class Sched, bool ALIGN_EPI = false, bool SP2 = false>
; __device__ __forceinline__ void gemm_phase(PG8_LAS unsigned char* lds, const Gemm g, const Sched& S, const Epi& E) {
;     ...
;         for (int t = 0; t < nt; t += 2) {
;             const bool last = (t == nt - 2);
;             const char* a1 = cA + (size_t)(t + 1) * kstep;
;             const char* a2 = last ? nA : cA + (size_t)(t + 2) * kstep; const char* b2 = last ? nB : cB + (size_t)(t + 2) * kstep;
;             const char* a3 = a2 + kstep; const char* b3 = b2 + kstep;
;     ...
;             PG8_LDA(At, 1, 1); PG8_STAGE(PG8_SB(1, 0), b3, voffB); PG8_STAGE(PG8_SB(1, 1), b3 + hstep, voffB); PG8_STAGE(PG8_SA(1, 0), a3, voffA);
;             PG8_WAIT_V(8); PG8_WAIT_L(0); PG8_BAR; PG8_MMA(1, 0, At, B0); PG8_MMA(1, 1, At, B1); PG8_BAR; PG8_SCHED;
	s_add_i32 s58, s78, s33
	v_lshl_add_u64 v[224:225], v[224:225], 0, s[12:13]
	s_mov_b32 m0, s58
	ds_read_b128 v[186:189], v157 offset:49152
	ds_read_b128 v[190:193], v157 offset:50176
	ds_read_b128 v[194:197], v157 offset:51200
	ds_read_b128 v[198:201], v157 offset:52224
	ds_read_b128 v[208:211], v157 offset:53248
	ds_read_b128 v[212:215], v157 offset:54272
	ds_read_b128 v[216:219], v157 offset:55296
	ds_read_b128 v[220:223], v157 offset:56320
	global_load_lds_dwordx4 v[224:225], off
	s_add_i32 m0, s58, 0x2000
	s_add_u32 s56, s56, 0x40080
	v_lshl_add_u64 v[224:225], v[226:227], 0, s[12:13]
	s_addc_u32 s57, s57, 0
	s_add_i32 s58, s79, s33
	global_load_lds_dwordx4 v[224:225], off
	v_lshl_add_u64 v[224:225], s[56:57], 0, v[132:133]
	s_mov_b32 m0, s58
	s_nop 0
	global_load_lds_dwordx4 v[224:225], off
	v_lshl_add_u64 v[224:225], s[56:57], 0, v[128:129]
	s_add_i32 m0, s58, 0x2000
	s_nop 0
	global_load_lds_dwordx4 v[224:225], off
	s_waitcnt vmcnt(6)
	s_waitcnt lgkmcnt(0)
	s_barrier
	s_setprio 1
	s_waitcnt lgkmcnt(0)
	v_mfma_f32_16x16x32_bf16 v[60:63], v[144:147], v[186:189], v[60:63]
	v_mfma_f32_16x16x32_bf16 v[56:59], v[160:163], v[186:189], v[56:59]
	v_mfma_f32_16x16x32_bf16 v[44:47], v[144:147], v[194:197], v[44:47]
	v_mfma_f32_16x16x32_bf16 v[40:43], v[160:163], v[194:197], v[40:43]
	v_mfma_f32_16x16x32_bf16 v[28:31], v[144:147], v[208:211], v[28:31]
	v_mfma_f32_16x16x32_bf16 v[24:27], v[160:163], v[208:211], v[24:27]
	v_mfma_f32_16x16x32_bf16 v[12:15], v[144:147], v[216:219], v[12:15]
	v_mfma_f32_16x16x32_bf16 v[8:11], v[160:163], v[216:219], v[8:11]
	v_mfma_f32_16x16x32_bf16 v[60:63], v[148:151], v[190:193], v[60:63]
	v_mfma_f32_16x16x32_bf16 v[56:59], v[164:167], v[190:193], v[56:59]
	v_mfma_f32_16x16x32_bf16 v[44:47], v[148:151], v[198:201], v[44:47]
	v_mfma_f32_16x16x32_bf16 v[40:43], v[164:167], v[198:201], v[40:43]
	v_mfma_f32_16x16x32_bf16 v[28:31], v[148:151], v[212:215], v[28:31]
	v_mfma_f32_16x16x32_bf16 v[24:27], v[164:167], v[212:215], v[24:27]
	v_lshl_add_u64 v[224:225], v[228:229], 0, s[12:13]
	s_mov_b32 m0, s64
	s_nop 0
	global_load_lds_dwordx4 v[224:225], off
	v_mfma_f32_16x16x32_bf16 v[12:15], v[148:151], v[220:223], v[12:15]
	v_mfma_f32_16x16x32_bf16 v[8:11], v[164:167], v[220:223], v[8:11]
	s_setprio 0
	s_setprio 1
	v_mfma_f32_16x16x32_bf16 v[52:55], v[168:171], v[186:189], v[52:55]
	v_mfma_f32_16x16x32_bf16 v[48:51], v[176:179], v[186:189], v[48:51]
	v_mfma_f32_16x16x32_bf16 v[36:39], v[168:171], v[194:197], v[36:39]
	v_mfma_f32_16x16x32_bf16 v[32:35], v[176:179], v[194:197], v[32:35]
	v_mfma_f32_16x16x32_bf16 v[20:23], v[168:171], v[208:211], v[20:23]
	v_mfma_f32_16x16x32_bf16 v[16:19], v[176:179], v[208:211], v[16:19]
	v_mfma_f32_16x16x32_bf16 v[4:7], v[168:171], v[216:219], v[4:7]
	v_mfma_f32_16x16x32_bf16 v[0:3], v[176:179], v[216:219], v[0:3]
	v_mfma_f32_16x16x32_bf16 v[52:55], v[172:175], v[190:193], v[52:55]
	v_mfma_f32_16x16x32_bf16 v[48:51], v[182:185], v[190:193], v[48:51]
	v_mfma_f32_16x16x32_bf16 v[36:39], v[172:175], v[198:201], v[36:39]
	v_mfma_f32_16x16x32_bf16 v[32:35], v[182:185], v[198:201], v[32:35]
	v_mfma_f32_16x16x32_bf16 v[20:23], v[172:175], v[212:215], v[20:23]
	v_mfma_f32_16x16x32_bf16 v[16:19], v[182:185], v[212:215], v[16:19]
	v_lshl_add_u64 v[224:225], v[230:231], 0, s[12:13]
	s_mov_b32 m0, s65
	s_nop 0
	global_load_lds_dwordx4 v[224:225], off
	v_mfma_f32_16x16x32_bf16 v[4:7], v[172:175], v[220:223], v[4:7]
	v_mfma_f32_16x16x32_bf16 v[0:3], v[182:185], v[220:223], v[0:3]
	s_setprio 0
	s_barrier
	s_add_i32 s84, s84, 2
	s_add_u32 s54, s54, 0x100
	s_addc_u32 s55, s55, 0
	s_add_u32 s82, s82, 0x100
	s_addc_u32 s83, s83, 0
	.p2align 6

; #define PG8_STAGE(bufoff, gbase, voff) do { _Pragma("unroll") for (int _i = 0; _i < 2; ++_i) \
;         __builtin_amdgcn_global_load_lds((const unsigned*)((const char*)(gbase) + (voff)[_i]), (PG8_LAS unsigned*)(lds + (bufoff) + ldsw + _i * 8192), 16, 0, 0); } while (0)
; #define PG8_LDA(dst, b, h) do { _Pragma("unroll") for (int m = 0; m < 4; ++m) _Pragma("unroll") for (int k = 0; k < 2; ++k) dst[m][k] = *(const PG8_LAS bf16x8*)(lds + PG8_SA(b, h) + aoff + m * 2048 + k * 1024); } while (0)
; #define PG8_LDB(dst, b, h) do { _Pragma("unroll") for (int n = 0; n < 2; ++n) _Pragma("unroll") for (int k = 0; k < 2; ++k) dst[n][k] = *(const PG8_LAS bf16x8*)(lds + PG8_SB(b, h) + boff + n * 2048 + k * 1024); } while (0)
; #define PG8_MMA(ai, bj, At, Bt) do { __builtin_amdgcn_s_setprio(1); _Pragma("unroll") for (int m = 0; m < 4; ++m) _Pragma("unroll") for (int n = 0; n < 2; ++n) _Pragma("unroll") for (int k = 0; k < 2; ++k) \
;         acc[ai][bj][m][n] = __builtin_amdgcn_mfma_f32_16x16x32_bf16(Bt[n][k], At[m][k], acc[ai][bj][m][n], 0, 0, 0); __builtin_amdgcn_s_setprio(0); } while (0)
; #define PG8_WAIT_V(n) asm volatile("s_waitcnt vmcnt(" #n ")" ::: "memory")
; #define PG8_WAIT_L(n) asm volatile("s_waitcnt lgkmcnt(" #n ")" ::: "memory")
; #define PG8_BAR __builtin_amdgcn_s_barrier()
; template <class Epi, class Sched, bool ALIGN_EPI = false, bool SP2 = false>
; __device__ __forceinline__ void gemm_phase(PG8_LAS unsigned char* lds, const Gemm g, const Sched& S, const Epi& E) {
;     ...
;             const char* a1 = cA + (size_t)(t + 1) * kstep;
;             const char* a2 = last ? nA : cA + (size_t)(t + 2) * kstep; const char* b2 = last ? nB : cB + (size_t)(t + 2) * kstep;
;             const char* a3 = a2 + kstep; const char* b3 = b2 + kstep;
;             if (last && has_next) S.a_ready(nxt);
;             if constexpr (SP2) {
;             PG8_LDB(B0, 0, 0); PG8_LDB(B1, 0, 1); PG8_SCHED; PG8_LDA(At, 0, 0); PG8_STAGE(PG8_SA(1, 1), a1 + hstep, voffA);
;             PG8_WAIT_V(8); PG8_WAIT_L(0); PG8_BAR; PG8_MMA(0, 0, At, B0); PG8_MMA(0, 1, At, B1); PG8_BAR; PG8_SCHED;
;             PG8_LDA(At, 0, 1); PG8_STAGE(PG8_SB(0, 0), b2, voffB); PG8_STAGE(PG8_SB(0, 1), b2 + hstep, voffB); PG8_STAGE(PG8_SA(0, 0), a2, voffA);
;             PG8_WAIT_V(8); PG8_WAIT_L(0); PG8_BAR; PG8_MMA(1, 0, At, B0); PG8_MMA(1, 1, At, B1); PG8_BAR; PG8_SCHED;
.LBB0_1196:
	s_add_u32 s82, s52, 0x100
	s_addc_u32 s83, s53, 0
	s_mov_b32 s84, -2
	s_waitcnt lgkmcnt(0)
	ds_read_b128 v[144:147], v151
	ds_read_b128 v[156:159], v151 offset:1024
	ds_read_b128 v[160:163], v151 offset:2048
	ds_read_b128 v[164:167], v151 offset:3072
	ds_read_b128 v[168:171], v152
	ds_read_b128 v[172:175], v152 offset:1024
	ds_read_b128 v[176:179], v152 offset:2048
	ds_read_b128 v[182:185], v152 offset:3072
	s_add_u32 s52, s50, 0x100
	s_addc_u32 s53, s51, 0
	s_cmp_eq_u32 s84, 40
	s_cselect_b32 s57, s1, s53
	s_cselect_b32 s56, s0, s52
	s_cselect_b32 s55, s49, s83
	s_cselect_b32 s54, s48, s82
	v_lshl_add_u64 v[224:225], s[50:51], 0, v[136:137]
	s_add_i32 m0, s34, 0xc000
	ds_read_b128 v[186:189], v153
	ds_read_b128 v[190:193], v153 offset:1024
	ds_read_b128 v[194:197], v153 offset:2048
	ds_read_b128 v[198:201], v153 offset:3072
	ds_read_b128 v[208:211], v153 offset:4096
	ds_read_b128 v[212:215], v153 offset:5120
	ds_read_b128 v[216:219], v153 offset:6144
	ds_read_b128 v[220:223], v153 offset:7168
	global_load_lds_dwordx4 v[224:225], off
	v_lshl_add_u64 v[224:225], s[50:51], 0, v[138:139]
	s_add_i32 m0, s34, 0xe000
	s_nop 0
	global_load_lds_dwordx4 v[224:225], off
	s_waitcnt vmcnt(8)
	s_waitcnt lgkmcnt(0)
	s_barrier
	s_setprio 1
	s_waitcnt lgkmcnt(0)
	v_mfma_f32_16x16x32_bf16 v[124:127], v[144:147], v[186:189], 0
	v_mfma_f32_16x16x32_bf16 v[120:123], v[160:163], v[186:189], 0
	v_mfma_f32_16x16x32_bf16 v[108:111], v[144:147], v[194:197], 0
	v_mfma_f32_16x16x32_bf16 v[104:107], v[160:163], v[194:197], 0
	v_mfma_f32_16x16x32_bf16 v[92:95], v[144:147], v[208:211], 0
	v_mfma_f32_16x16x32_bf16 v[88:91], v[160:163], v[208:211], 0
	v_mfma_f32_16x16x32_bf16 v[76:79], v[144:147], v[216:219], 0
	v_mfma_f32_16x16x32_bf16 v[72:75], v[160:163], v[216:219], 0
	v_mfma_f32_16x16x32_bf16 v[124:127], v[156:159], v[190:193], v[124:127]
	v_mfma_f32_16x16x32_bf16 v[120:123], v[164:167], v[190:193], v[120:123]
	v_mfma_f32_16x16x32_bf16 v[108:111], v[156:159], v[198:201], v[108:111]
	v_mfma_f32_16x16x32_bf16 v[104:107], v[164:167], v[198:201], v[104:107]
	v_mfma_f32_16x16x32_bf16 v[92:95], v[156:159], v[212:215], v[92:95]
	v_mfma_f32_16x16x32_bf16 v[88:91], v[164:167], v[212:215], v[88:91]
	v_mfma_f32_16x16x32_bf16 v[76:79], v[156:159], v[220:223], v[76:79]
	v_mfma_f32_16x16x32_bf16 v[72:75], v[164:167], v[220:223], v[72:75]
	s_setprio 0
	s_setprio 1
	v_mfma_f32_16x16x32_bf16 v[116:119], v[168:171], v[186:189], 0
	v_mfma_f32_16x16x32_bf16 v[112:115], v[176:179], v[186:189], 0
	v_mfma_f32_16x16x32_bf16 v[100:103], v[168:171], v[194:197], 0
	v_mfma_f32_16x16x32_bf16 v[96:99], v[176:179], v[194:197], 0
	v_mfma_f32_16x16x32_bf16 v[84:87], v[168:171], v[208:211], 0
	v_mfma_f32_16x16x32_bf16 v[80:83], v[176:179], v[208:211], 0
	v_mfma_f32_16x16x32_bf16 v[68:71], v[168:171], v[216:219], 0
	v_mfma_f32_16x16x32_bf16 v[64:67], v[176:179], v[216:219], 0
	v_mfma_f32_16x16x32_bf16 v[116:119], v[172:175], v[190:193], v[116:119]
	v_mfma_f32_16x16x32_bf16 v[112:115], v[182:185], v[190:193], v[112:115]
	v_mfma_f32_16x16x32_bf16 v[100:103], v[172:175], v[198:201], v[100:103]
	v_mfma_f32_16x16x32_bf16 v[96:99], v[182:185], v[198:201], v[96:99]
	v_mfma_f32_16x16x32_bf16 v[84:87], v[172:175], v[212:215], v[84:87]
	v_mfma_f32_16x16x32_bf16 v[80:83], v[182:185], v[212:215], v[80:83]
	v_mfma_f32_16x16x32_bf16 v[68:71], v[172:175], v[220:223], v[68:71]
	v_mfma_f32_16x16x32_bf16 v[64:67], v[182:185], v[220:223], v[64:67]
	s_setprio 0
	s_barrier
	s_add_i32 s50, s64, s33
	v_lshl_add_u64 v[224:225], s[54:55], 0, v[130:131]
	s_mov_b32 m0, s50
	ds_read_b128 v[186:189], v153 offset:16384
	ds_read_b128 v[190:193], v153 offset:17408
	ds_read_b128 v[194:197], v153 offset:18432
	ds_read_b128 v[198:201], v153 offset:19456
	ds_read_b128 v[208:211], v153 offset:20480
	ds_read_b128 v[212:215], v153 offset:21504
	ds_read_b128 v[216:219], v153 offset:22528
	ds_read_b128 v[220:223], v153 offset:23552
	global_load_lds_dwordx4 v[224:225], off
	s_add_i32 m0, s50, 0x2000
	s_add_u32 s50, s54, 0xb0000
	v_lshl_add_u64 v[226:227], s[54:55], 0, v[134:135]
	s_addc_u32 s51, s55, 0
	s_add_i32 s78, s65, s33
	global_load_lds_dwordx4 v[226:227], off
	v_lshl_add_u64 v[228:229], s[50:51], 0, v[130:131]
	s_mov_b32 m0, s78
	global_load_lds_dwordx4 v[228:229], off
	v_lshl_add_u64 v[228:229], s[50:51], 0, v[134:135]
	s_add_i32 m0, s78, 0x2000
	s_nop 0
	global_load_lds_dwordx4 v[228:229], off
	s_waitcnt vmcnt(6)
	s_waitcnt lgkmcnt(0)
	s_barrier
; #define PG8_STAGE(bufoff, gbase, voff) do { _Pragma("unroll") for (int _i = 0; _i < 2; ++_i) \
;         __builtin_amdgcn_global_load_lds((const unsigned*)((const char*)(gbase) + (voff)[_i]), (PG8_LAS unsigned*)(lds + (bufoff) + ldsw + _i * 8192), 16, 0, 0); } while (0)
; #define PG8_LDA(dst, b, h) do { _Pragma("unroll") for (int m = 0; m < 4; ++m) _Pragma("unroll") for (int k = 0; k < 2; ++k) dst[m][k] = *(const PG8_LAS bf16x8*)(lds + PG8_SA(b, h) + aoff + m * 2048 + k * 1024); } while (0)
; #define PG8_LDB(dst, b, h) do { _Pragma("unroll") for (int n = 0; n < 2; ++n) _Pragma("unroll") for (int k = 0; k < 2; ++k) dst[n][k] = *(const PG8_LAS bf16x8*)(lds + PG8_SB(b, h) + boff + n * 2048 + k * 1024); } while (0)
; #define PG8_MMA(ai, bj, At, Bt) do { __builtin_amdgcn_s_setprio(1); _Pragma("unroll") for (int m = 0; m < 4; ++m) _Pragma("unroll") for (int n = 0; n < 2; ++n) _Pragma("unroll") for (int k = 0; k < 2; ++k) \
;         acc[ai][bj][m][n] = __builtin_amdgcn_mfma_f32_16x16x32_bf16(Bt[n][k], At[m][k], acc[ai][bj][m][n], 0, 0, 0); __builtin_amdgcn_s_setprio(0); } while (0)
; #define PG8_WAIT_V(n) asm volatile("s_waitcnt vmcnt(" #n ")" ::: "memory")
; #define PG8_WAIT_L(n) asm volatile("s_waitcnt lgkmcnt(" #n ")" ::: "memory")
; #define PG8_BAR __builtin_amdgcn_s_barrier()
; #define PG8_SCHED __builtin_amdgcn_sched_barrier(0)
; template <class Epi, class Sched, bool ALIGN_EPI = false, bool SP2 = false>
; __device__ __forceinline__ void gemm_phase(PG8_LAS unsigned char* lds, const Gemm g, const Sched& S, const Epi& E) {
;     ...
;             PG8_WAIT_V(8); PG8_WAIT_L(0); PG8_BAR; PG8_MMA(1, 0, At, B0); PG8_MMA(1, 1, At, B1); PG8_BAR; PG8_SCHED;
;             PG8_LDB(B0, 1, 0); PG8_LDB(B1, 1, 1); PG8_SCHED; PG8_LDA(At, 1, 0); PG8_STAGE(PG8_SA(0, 1), a2 + hstep, voffA);
;             PG8_WAIT_V(8); PG8_WAIT_L(0); PG8_BAR; PG8_MMA(0, 0, At, B0); PG8_MMA(0, 1, At, B1); PG8_BAR; PG8_SCHED;
	s_setprio 1
	s_waitcnt lgkmcnt(0)
	v_mfma_f32_16x16x32_bf16 v[60:63], v[144:147], v[186:189], 0
	v_mfma_f32_16x16x32_bf16 v[56:59], v[160:163], v[186:189], 0
	v_mfma_f32_16x16x32_bf16 v[44:47], v[144:147], v[194:197], 0
	v_mfma_f32_16x16x32_bf16 v[40:43], v[160:163], v[194:197], 0
	v_mfma_f32_16x16x32_bf16 v[28:31], v[144:147], v[208:211], 0
	v_mfma_f32_16x16x32_bf16 v[24:27], v[160:163], v[208:211], 0
	v_mfma_f32_16x16x32_bf16 v[12:15], v[144:147], v[216:219], 0
	v_mfma_f32_16x16x32_bf16 v[8:11], v[160:163], v[216:219], 0
	v_mfma_f32_16x16x32_bf16 v[60:63], v[156:159], v[190:193], v[60:63]
	v_mfma_f32_16x16x32_bf16 v[56:59], v[164:167], v[190:193], v[56:59]
	v_mfma_f32_16x16x32_bf16 v[44:47], v[156:159], v[198:201], v[44:47]
	v_mfma_f32_16x16x32_bf16 v[40:43], v[164:167], v[198:201], v[40:43]
	v_mfma_f32_16x16x32_bf16 v[28:31], v[156:159], v[212:215], v[28:31]
	v_mfma_f32_16x16x32_bf16 v[24:27], v[164:167], v[212:215], v[24:27]
	v_lshl_add_u64 v[228:229], s[56:57], 0, v[128:129]
	s_mov_b32 m0, s34
	s_nop 0
	global_load_lds_dwordx4 v[228:229], off
	v_mfma_f32_16x16x32_bf16 v[12:15], v[156:159], v[220:223], v[12:15]
	v_mfma_f32_16x16x32_bf16 v[8:11], v[164:167], v[220:223], v[8:11]
	s_setprio 0
	s_setprio 1
	v_mfma_f32_16x16x32_bf16 v[52:55], v[168:171], v[186:189], 0
	v_mfma_f32_16x16x32_bf16 v[48:51], v[176:179], v[186:189], 0
	v_mfma_f32_16x16x32_bf16 v[36:39], v[168:171], v[194:197], 0
	v_mfma_f32_16x16x32_bf16 v[32:35], v[176:179], v[194:197], 0
	v_mfma_f32_16x16x32_bf16 v[20:23], v[168:171], v[208:211], 0
	v_mfma_f32_16x16x32_bf16 v[16:19], v[176:179], v[208:211], 0
	v_mfma_f32_16x16x32_bf16 v[4:7], v[168:171], v[216:219], 0
	v_mfma_f32_16x16x32_bf16 v[0:3], v[176:179], v[216:219], 0
	v_mfma_f32_16x16x32_bf16 v[52:55], v[172:175], v[190:193], v[52:55]
	v_mfma_f32_16x16x32_bf16 v[48:51], v[182:185], v[190:193], v[48:51]
	v_mfma_f32_16x16x32_bf16 v[36:39], v[172:175], v[198:201], v[36:39]
	v_mfma_f32_16x16x32_bf16 v[32:35], v[182:185], v[198:201], v[32:35]
	v_mfma_f32_16x16x32_bf16 v[20:23], v[172:175], v[212:215], v[20:23]
	v_mfma_f32_16x16x32_bf16 v[16:19], v[182:185], v[212:215], v[16:19]
	v_lshl_add_u64 v[230:231], s[56:57], 0, v[132:133]
	s_mov_b32 m0, s58
	s_nop 0
	global_load_lds_dwordx4 v[230:231], off
	v_mfma_f32_16x16x32_bf16 v[4:7], v[172:175], v[220:223], v[4:7]
	v_mfma_f32_16x16x32_bf16 v[0:3], v[182:185], v[220:223], v[0:3]
	s_setprio 0
	s_barrier
	s_add_i32 s78, 0, 0x18000
	v_add_u32_e32 v155, s78, v149
	s_add_i32 s79, 0, 0x1c000
	ds_read_b128 v[144:147], v155
	ds_read_b128 v[156:159], v155 offset:1024
	ds_read_b128 v[160:163], v155 offset:2048
	ds_read_b128 v[164:167], v155 offset:3072
	v_add_u32_e32 v155, s79, v149
	ds_read_b128 v[168:171], v155
	ds_read_b128 v[172:175], v155 offset:1024
	ds_read_b128 v[176:179], v155 offset:2048
	ds_read_b128 v[182:185], v155 offset:3072
	s_add_u32 s50, s56, 0xb0000
	s_addc_u32 s51, s57, 0
	s_mov_b32 m0, s59
	v_lshl_add_u64 v[232:233], s[50:51], 0, v[128:129]
	ds_read_b128 v[186:189], v153 offset:32768
	ds_read_b128 v[190:193], v153 offset:33792
	ds_read_b128 v[194:197], v153 offset:34816
	ds_read_b128 v[198:201], v153 offset:35840
	ds_read_b128 v[208:211], v153 offset:36864
	ds_read_b128 v[212:215], v153 offset:37888
	ds_read_b128 v[216:219], v153 offset:38912
	ds_read_b128 v[220:223], v153 offset:39936
	global_load_lds_dwordx4 v[232:233], off
	v_lshl_add_u64 v[232:233], s[50:51], 0, v[132:133]
	s_mov_b32 m0, s60
	s_nop 0
	global_load_lds_dwordx4 v[232:233], off
	s_waitcnt vmcnt(8)
	s_waitcnt lgkmcnt(0)
	s_barrier
	s_setprio 1
	s_waitcnt lgkmcnt(0)
	v_mfma_f32_16x16x32_bf16 v[124:127], v[144:147], v[186:189], v[124:127]
	v_mfma_f32_16x16x32_bf16 v[120:123], v[160:163], v[186:189], v[120:123]
	v_mfma_f32_16x16x32_bf16 v[108:111], v[144:147], v[194:197], v[108:111]
	v_mfma_f32_16x16x32_bf16 v[104:107], v[160:163], v[194:197], v[104:107]
	v_mfma_f32_16x16x32_bf16 v[92:95], v[144:147], v[208:211], v[92:95]
	v_mfma_f32_16x16x32_bf16 v[88:91], v[160:163], v[208:211], v[88:91]
	v_mfma_f32_16x16x32_bf16 v[76:79], v[144:147], v[216:219], v[76:79]
	v_mfma_f32_16x16x32_bf16 v[72:75], v[160:163], v[216:219], v[72:75]
	v_mfma_f32_16x16x32_bf16 v[124:127], v[156:159], v[190:193], v[124:127]
	v_mfma_f32_16x16x32_bf16 v[120:123], v[164:167], v[190:193], v[120:123]
	v_mfma_f32_16x16x32_bf16 v[108:111], v[156:159], v[198:201], v[108:111]
	v_mfma_f32_16x16x32_bf16 v[104:107], v[164:167], v[198:201], v[104:107]
	v_mfma_f32_16x16x32_bf16 v[92:95], v[156:159], v[212:215], v[92:95]
	v_mfma_f32_16x16x32_bf16 v[88:91], v[164:167], v[212:215], v[88:91]
	v_mfma_f32_16x16x32_bf16 v[76:79], v[156:159], v[220:223], v[76:79]
	v_mfma_f32_16x16x32_bf16 v[72:75], v[164:167], v[220:223], v[72:75]
	s_setprio 0
	s_setprio 1
	v_mfma_f32_16x16x32_bf16 v[116:119], v[168:171], v[186:189], v[116:119]
	v_mfma_f32_16x16x32_bf16 v[112:115], v[176:179], v[186:189], v[112:115]
	v_mfma_f32_16x16x32_bf16 v[100:103], v[168:171], v[194:197], v[100:103]
	v_mfma_f32_16x16x32_bf16 v[96:99], v[176:179], v[194:197], v[96:99]
	v_mfma_f32_16x16x32_bf16 v[84:87], v[168:171], v[208:211], v[84:87]
	v_mfma_f32_16x16x32_bf16 v[80:83], v[176:179], v[208:211], v[80:83]
	v_mfma_f32_16x16x32_bf16 v[68:71], v[168:171], v[216:219], v[68:71]
	v_mfma_f32_16x16x32_bf16 v[64:67], v[176:179], v[216:219], v[64:67]
	v_mfma_f32_16x16x32_bf16 v[116:119], v[172:175], v[190:193], v[116:119]
	v_mfma_f32_16x16x32_bf16 v[112:115], v[182:185], v[190:193], v[112:115]
	v_mfma_f32_16x16x32_bf16 v[100:103], v[172:175], v[198:201], v[100:103]
	v_mfma_f32_16x16x32_bf16 v[96:99], v[182:185], v[198:201], v[96:99]
	v_mfma_f32_16x16x32_bf16 v[84:87], v[172:175], v[212:215], v[84:87]
	v_mfma_f32_16x16x32_bf16 v[80:83], v[182:185], v[212:215], v[80:83]
	v_mfma_f32_16x16x32_bf16 v[68:71], v[172:175], v[220:223], v[68:71]
	v_mfma_f32_16x16x32_bf16 v[64:67], v[182:185], v[220:223], v[64:67]
	s_setprio 0
	s_barrier
; #define PG8_STAGE(bufoff, gbase, voff) do { _Pragma("unroll") for (int _i = 0; _i < 2; ++_i) \
;         __builtin_amdgcn_global_load_lds((const unsigned*)((const char*)(gbase) + (voff)[_i]), (PG8_LAS unsigned*)(lds + (bufoff) + ldsw + _i * 8192), 16, 0, 0); } while (0)
; #define PG8_LDA(dst, b, h) do { _Pragma("unroll") for (int m = 0; m < 4; ++m) _Pragma("unroll") for (int k = 0; k < 2; ++k) dst[m][k] = *(const PG8_LAS bf16x8*)(lds + PG8_SA(b, h) + aoff + m * 2048 + k * 1024); } while (0)
; #define PG8_MMA(ai, bj, At, Bt) do { __builtin_amdgcn_s_setprio(1); _Pragma("unroll") for (int m = 0; m < 4; ++m) _Pragma("unroll") for (int n = 0; n < 2; ++n) _Pragma("unroll") for (int k = 0; k < 2; ++k) \
;         acc[ai][bj][m][n] = __builtin_amdgcn_mfma_f32_16x16x32_bf16(Bt[n][k], At[m][k], acc[ai][bj][m][n], 0, 0, 0); __builtin_amdgcn_s_setprio(0); } while (0)
; #define PG8_WAIT_V(n) asm volatile("s_waitcnt vmcnt(" #n ")" ::: "memory")
; #define PG8_WAIT_L(n) asm volatile("s_waitcnt lgkmcnt(" #n ")" ::: "memory")
; #define PG8_BAR __builtin_amdgcn_s_barrier()
; #define PG8_SCHED __builtin_amdgcn_sched_barrier(0)
; template <class Epi, class Sched, bool ALIGN_EPI = false, bool SP2 = false>
; __device__ __forceinline__ void gemm_phase(PG8_LAS unsigned char* lds, const Gemm g, const Sched& S, const Epi& E) {
;     ...
;         for (int t = 0; t < nt; t += 2) {
;             const bool last = (t == nt - 2);
;             const char* a1 = cA + (size_t)(t + 1) * kstep;
;             const char* a2 = last ? nA : cA + (size_t)(t + 2) * kstep; const char* b2 = last ? nB : cB + (size_t)(t + 2) * kstep;
;             const char* a3 = a2 + kstep; const char* b3 = b2 + kstep;
;     ...
;             PG8_LDA(At, 1, 1); PG8_STAGE(PG8_SB(1, 0), b3, voffB); PG8_STAGE(PG8_SB(1, 1), b3 + hstep, voffB); PG8_STAGE(PG8_SA(1, 0), a3, voffA);
;             PG8_WAIT_V(8); PG8_WAIT_L(0); PG8_BAR; PG8_MMA(1, 0, At, B0); PG8_MMA(1, 1, At, B1); PG8_BAR; PG8_SCHED;
	s_add_i32 s50, s78, s33
	v_lshl_add_u64 v[224:225], v[224:225], 0, s[42:43]
	s_mov_b32 m0, s50
	ds_read_b128 v[186:189], v153 offset:49152
	ds_read_b128 v[190:193], v153 offset:50176
	ds_read_b128 v[194:197], v153 offset:51200
	ds_read_b128 v[198:201], v153 offset:52224
	ds_read_b128 v[208:211], v153 offset:53248
	ds_read_b128 v[212:215], v153 offset:54272
	ds_read_b128 v[216:219], v153 offset:55296
	ds_read_b128 v[220:223], v153 offset:56320
	global_load_lds_dwordx4 v[224:225], off
	s_add_i32 m0, s50, 0x2000
	s_add_u32 s50, s54, 0xb0080
	v_lshl_add_u64 v[224:225], v[226:227], 0, s[42:43]
	s_addc_u32 s51, s55, 0
	s_add_i32 s54, s79, s33
	global_load_lds_dwordx4 v[224:225], off
	v_lshl_add_u64 v[224:225], s[50:51], 0, v[130:131]
	s_mov_b32 m0, s54
	s_nop 0
	global_load_lds_dwordx4 v[224:225], off
	v_lshl_add_u64 v[224:225], s[50:51], 0, v[134:135]
	s_add_i32 m0, s54, 0x2000
	s_nop 0
	global_load_lds_dwordx4 v[224:225], off
	s_waitcnt vmcnt(6)
	s_waitcnt lgkmcnt(0)
	s_barrier
	s_setprio 1
	s_waitcnt lgkmcnt(0)
	v_mfma_f32_16x16x32_bf16 v[60:63], v[144:147], v[186:189], v[60:63]
	v_mfma_f32_16x16x32_bf16 v[56:59], v[160:163], v[186:189], v[56:59]
	v_mfma_f32_16x16x32_bf16 v[44:47], v[144:147], v[194:197], v[44:47]
	v_mfma_f32_16x16x32_bf16 v[40:43], v[160:163], v[194:197], v[40:43]
	v_mfma_f32_16x16x32_bf16 v[28:31], v[144:147], v[208:211], v[28:31]
	v_mfma_f32_16x16x32_bf16 v[24:27], v[160:163], v[208:211], v[24:27]
	v_mfma_f32_16x16x32_bf16 v[12:15], v[144:147], v[216:219], v[12:15]
	v_mfma_f32_16x16x32_bf16 v[8:11], v[160:163], v[216:219], v[8:11]
	v_mfma_f32_16x16x32_bf16 v[60:63], v[156:159], v[190:193], v[60:63]
	v_mfma_f32_16x16x32_bf16 v[56:59], v[164:167], v[190:193], v[56:59]
	v_mfma_f32_16x16x32_bf16 v[44:47], v[156:159], v[198:201], v[44:47]
	v_mfma_f32_16x16x32_bf16 v[40:43], v[164:167], v[198:201], v[40:43]
	v_mfma_f32_16x16x32_bf16 v[28:31], v[156:159], v[212:215], v[28:31]
	v_mfma_f32_16x16x32_bf16 v[24:27], v[164:167], v[212:215], v[24:27]
	v_lshl_add_u64 v[224:225], v[228:229], 0, s[42:43]
	s_mov_b32 m0, s62
	s_nop 0
	global_load_lds_dwordx4 v[224:225], off
	v_mfma_f32_16x16x32_bf16 v[12:15], v[156:159], v[220:223], v[12:15]
	v_mfma_f32_16x16x32_bf16 v[8:11], v[164:167], v[220:223], v[8:11]
	s_setprio 0
	s_setprio 1
	v_mfma_f32_16x16x32_bf16 v[52:55], v[168:171], v[186:189], v[52:55]
	v_mfma_f32_16x16x32_bf16 v[48:51], v[176:179], v[186:189], v[48:51]
	v_mfma_f32_16x16x32_bf16 v[36:39], v[168:171], v[194:197], v[36:39]
	v_mfma_f32_16x16x32_bf16 v[32:35], v[176:179], v[194:197], v[32:35]
	v_mfma_f32_16x16x32_bf16 v[20:23], v[168:171], v[208:211], v[20:23]
	v_mfma_f32_16x16x32_bf16 v[16:19], v[176:179], v[208:211], v[16:19]
	v_mfma_f32_16x16x32_bf16 v[4:7], v[168:171], v[216:219], v[4:7]
	v_mfma_f32_16x16x32_bf16 v[0:3], v[176:179], v[216:219], v[0:3]
	v_mfma_f32_16x16x32_bf16 v[52:55], v[172:175], v[190:193], v[52:55]
	v_mfma_f32_16x16x32_bf16 v[48:51], v[182:185], v[190:193], v[48:51]
	v_mfma_f32_16x16x32_bf16 v[36:39], v[172:175], v[198:201], v[36:39]
	v_mfma_f32_16x16x32_bf16 v[32:35], v[182:185], v[198:201], v[32:35]
	v_mfma_f32_16x16x32_bf16 v[20:23], v[172:175], v[212:215], v[20:23]
	v_mfma_f32_16x16x32_bf16 v[16:19], v[182:185], v[212:215], v[16:19]
	v_lshl_add_u64 v[224:225], v[230:231], 0, s[42:43]
	s_mov_b32 m0, s63
	s_nop 0
	global_load_lds_dwordx4 v[224:225], off
	v_mfma_f32_16x16x32_bf16 v[4:7], v[172:175], v[220:223], v[4:7]
	v_mfma_f32_16x16x32_bf16 v[0:3], v[182:185], v[220:223], v[0:3]
	s_setprio 0
	s_barrier
	s_add_i32 s84, s84, 2
	s_add_u32 s82, s82, 0x100
	s_addc_u32 s83, s83, 0
	s_mov_b64 s[50:51], s[52:53]
	.p2align 6

; #define PG8_STAGE(bufoff, gbase, voff) do { _Pragma("unroll") for (int _i = 0; _i < 2; ++_i) \
;         __builtin_amdgcn_global_load_lds((const unsigned*)((const char*)(gbase) + (voff)[_i]), (PG8_LAS unsigned*)(lds + (bufoff) + ldsw + _i * 8192), 16, 0, 0); } while (0)
; #define PG8_LDA(dst, b, h) do { _Pragma("unroll") for (int m = 0; m < 4; ++m) _Pragma("unroll") for (int k = 0; k < 2; ++k) dst[m][k] = *(const PG8_LAS bf16x8*)(lds + PG8_SA(b, h) + aoff + m * 2048 + k * 1024); } while (0)
; #define PG8_LDB(dst, b, h) do { _Pragma("unroll") for (int n = 0; n < 2; ++n) _Pragma("unroll") for (int k = 0; k < 2; ++k) dst[n][k] = *(const PG8_LAS bf16x8*)(lds + PG8_SB(b, h) + boff + n * 2048 + k * 1024); } while (0)
; #define PG8_WAIT_V(n) asm volatile("s_waitcnt vmcnt(" #n ")" ::: "memory")
; #define PG8_WAIT_L(n) asm volatile("s_waitcnt lgkmcnt(" #n ")" ::: "memory")
; #define PG8_BAR __builtin_amdgcn_s_barrier()
; #define PG8_SCHED __builtin_amdgcn_sched_barrier(0)
; template <class Epi, class Sched, bool ALIGN_EPI = false, bool SP2 = false>
; __device__ __forceinline__ void gemm_phase(PG8_LAS unsigned char* lds, const Gemm g, const Sched& S, const Epi& E) {
;     ...
;         const bool has_next = S.next(ui + 1, nxt);
;         const char* nA = has_next ? (const char*)g.A + (size_t)nxt.pm * tstep : cA; const char* nB = has_next ? (const char*)g.Bt + (size_t)nxt.pn * tstep : cB;
;         for (int t = 0; t < nt; t += 2) {
;             const bool last = (t == nt - 2);
;             const char* a1 = cA + (size_t)(t + 1) * kstep;
;             const char* a2 = last ? nA : cA + (size_t)(t + 2) * kstep; const char* b2 = last ? nB : cB + (size_t)(t + 2) * kstep;
;             const char* a3 = a2 + kstep; const char* b3 = b2 + kstep;
;             if (last && has_next) S.a_ready(nxt);
;             if constexpr (SP2) {
;             PG8_LDB(B0, 0, 0); PG8_LDB(B1, 0, 1); PG8_SCHED; PG8_LDA(At, 0, 0); PG8_STAGE(PG8_SA(1, 1), a1 + hstep, voffA);
;             PG8_WAIT_V(8); PG8_WAIT_L(0); PG8_BAR; PG8_MMA(0, 0, At, B0); PG8_MMA(0, 1, At, B1); PG8_BAR; PG8_SCHED;
;             PG8_LDA(At, 0, 1); PG8_STAGE(PG8_SB(0, 0), b2, voffB); PG8_STAGE(PG8_SB(0, 1), b2 + hstep, voffB); PG8_STAGE(PG8_SA(0, 0), a2, voffA);
;             PG8_WAIT_V(8); PG8_WAIT_L(0); PG8_BAR; PG8_MMA(1, 0, At, B0); PG8_MMA(1, 1, At, B1); PG8_BAR; PG8_SCHED;
.LBB0_1286:
	s_ashr_i32 s51, s50, 31
	s_lshl_b64 s[52:53], s[50:51], 19
	s_add_u32 s52, s22, s52
	s_addc_u32 s53, s23, s53
	s_and_b64 s[54:55], s[12:13], exec
	s_cselect_b32 s51, s53, s59
	s_cselect_b32 s61, s52, s58
	s_ashr_i32 s49, s48, 31
	s_lshl_b64 s[54:55], s[48:49], 19
	v_readlane_b32 s64, v250, 9
	v_readlane_b32 s65, v250, 10
	s_add_u32 s54, s64, s54
	s_addc_u32 s55, s65, s55
	s_and_b64 s[64:65], s[12:13], exec
	s_cselect_b32 s49, s55, s63
	s_cselect_b32 s87, s54, s62
	s_add_u32 s58, s58, 0x40080
	s_addc_u32 s59, s59, 0
	s_add_u32 s88, s62, 0x100
	s_addc_u32 s89, s63, 0
	s_mov_b32 s90, -2
	s_waitcnt lgkmcnt(0)
	ds_read_b128 v[128:131], v181
	ds_read_b128 v[160:163], v181 offset:1024
	ds_read_b128 v[164:167], v181 offset:2048
	ds_read_b128 v[168:171], v181 offset:3072
	ds_read_b128 v[172:175], v203
	ds_read_b128 v[176:179], v203 offset:1024
	ds_read_b128 v[182:185], v203 offset:2048
	ds_read_b128 v[186:189], v203 offset:3072
	s_add_u32 s62, s58, 0xfffc0080
	s_addc_u32 s63, s59, -1
	s_cmp_eq_u32 s90, 12
	s_cselect_b32 s65, s51, s63
	s_cselect_b32 s64, s61, s62
	s_cselect_b32 s63, s49, s89
	s_cselect_b32 s62, s87, s88
	v_lshl_add_u64 v[232:233], s[58:59], 0, v[152:153]
	s_add_i32 m0, s15, 0xc000
	ds_read_b128 v[190:193], v208
	ds_read_b128 v[194:197], v208 offset:1024
	ds_read_b128 v[198:201], v208 offset:2048
	ds_read_b128 v[212:215], v208 offset:3072
	ds_read_b128 v[216:219], v208 offset:4096
	ds_read_b128 v[220:223], v208 offset:5120
	ds_read_b128 v[224:227], v208 offset:6144
	ds_read_b128 v[228:231], v208 offset:7168
	global_load_lds_dwordx4 v[232:233], off
	v_lshl_add_u64 v[232:233], s[58:59], 0, v[154:155]
	s_add_i32 m0, s15, 0xe000
	s_nop 0
	global_load_lds_dwordx4 v[232:233], off
	s_waitcnt vmcnt(8)
	s_waitcnt lgkmcnt(0)
	s_barrier
	s_setprio 1
	s_waitcnt lgkmcnt(0)
	v_mfma_f32_16x16x32_bf16 v[124:127], v[128:131], v[190:193], 0
	v_mfma_f32_16x16x32_bf16 v[120:123], v[164:167], v[190:193], 0
	v_mfma_f32_16x16x32_bf16 v[116:119], v[128:131], v[198:201], 0
	v_mfma_f32_16x16x32_bf16 v[112:115], v[164:167], v[198:201], 0
	v_mfma_f32_16x16x32_bf16 v[108:111], v[128:131], v[216:219], 0
	v_mfma_f32_16x16x32_bf16 v[104:107], v[164:167], v[216:219], 0
	v_mfma_f32_16x16x32_bf16 v[100:103], v[128:131], v[224:227], 0
	v_mfma_f32_16x16x32_bf16 v[96:99], v[164:167], v[224:227], 0
	v_mfma_f32_16x16x32_bf16 v[124:127], v[160:163], v[194:197], v[124:127]
	v_mfma_f32_16x16x32_bf16 v[120:123], v[168:171], v[194:197], v[120:123]
	v_mfma_f32_16x16x32_bf16 v[116:119], v[160:163], v[212:215], v[116:119]
	v_mfma_f32_16x16x32_bf16 v[112:115], v[168:171], v[212:215], v[112:115]
	v_mfma_f32_16x16x32_bf16 v[108:111], v[160:163], v[220:223], v[108:111]
	v_mfma_f32_16x16x32_bf16 v[104:107], v[168:171], v[220:223], v[104:107]
	v_mfma_f32_16x16x32_bf16 v[100:103], v[160:163], v[228:231], v[100:103]
	v_mfma_f32_16x16x32_bf16 v[96:99], v[168:171], v[228:231], v[96:99]
	s_setprio 0
	s_setprio 1
	v_mfma_f32_16x16x32_bf16 v[60:63], v[172:175], v[190:193], 0
	v_mfma_f32_16x16x32_bf16 v[56:59], v[182:185], v[190:193], 0
	v_mfma_f32_16x16x32_bf16 v[52:55], v[172:175], v[198:201], 0
	v_mfma_f32_16x16x32_bf16 v[48:51], v[182:185], v[198:201], 0
	v_mfma_f32_16x16x32_bf16 v[44:47], v[172:175], v[216:219], 0
	v_mfma_f32_16x16x32_bf16 v[40:43], v[182:185], v[216:219], 0
	v_mfma_f32_16x16x32_bf16 v[36:39], v[172:175], v[224:227], 0
	v_mfma_f32_16x16x32_bf16 v[32:35], v[182:185], v[224:227], 0
	v_mfma_f32_16x16x32_bf16 v[60:63], v[176:179], v[194:197], v[60:63]
	v_mfma_f32_16x16x32_bf16 v[56:59], v[186:189], v[194:197], v[56:59]
	v_mfma_f32_16x16x32_bf16 v[52:55], v[176:179], v[212:215], v[52:55]
	v_mfma_f32_16x16x32_bf16 v[48:51], v[186:189], v[212:215], v[48:51]
	v_mfma_f32_16x16x32_bf16 v[44:47], v[176:179], v[220:223], v[44:47]
	v_mfma_f32_16x16x32_bf16 v[40:43], v[186:189], v[220:223], v[40:43]
	v_mfma_f32_16x16x32_bf16 v[36:39], v[176:179], v[228:231], v[36:39]
	v_mfma_f32_16x16x32_bf16 v[32:35], v[186:189], v[228:231], v[32:35]
	s_setprio 0
	s_barrier
	s_add_i32 s78, s75, s14
	v_lshl_add_u64 v[232:233], s[62:63], 0, v[134:135]
	s_mov_b32 m0, s78
	ds_read_b128 v[190:193], v208 offset:16384
	ds_read_b128 v[194:197], v208 offset:17408
	ds_read_b128 v[198:201], v208 offset:18432
	ds_read_b128 v[212:215], v208 offset:19456
	ds_read_b128 v[216:219], v208 offset:20480
	ds_read_b128 v[220:223], v208 offset:21504
	ds_read_b128 v[224:227], v208 offset:22528
	ds_read_b128 v[228:231], v208 offset:23552
	global_load_lds_dwordx4 v[232:233], off
	s_add_i32 m0, s78, 0x2000
	s_add_u32 s78, s62, 0x40000
	v_lshl_add_u64 v[234:235], s[62:63], 0, v[138:139]
	s_addc_u32 s79, s63, 0
	s_add_i32 s91, s76, s14
	global_load_lds_dwordx4 v[234:235], off
	v_lshl_add_u64 v[236:237], s[78:79], 0, v[134:135]
	s_mov_b32 m0, s91
	global_load_lds_dwordx4 v[236:237], off
	v_lshl_add_u64 v[236:237], s[78:79], 0, v[138:139]
	s_add_i32 m0, s91, 0x2000
	s_nop 0
	global_load_lds_dwordx4 v[236:237], off
	s_waitcnt vmcnt(6)
	s_waitcnt lgkmcnt(0)
	s_barrier
; #define PG8_STAGE(bufoff, gbase, voff) do { _Pragma("unroll") for (int _i = 0; _i < 2; ++_i) \
;         __builtin_amdgcn_global_load_lds((const unsigned*)((const char*)(gbase) + (voff)[_i]), (PG8_LAS unsigned*)(lds + (bufoff) + ldsw + _i * 8192), 16, 0, 0); } while (0)
; #define PG8_LDA(dst, b, h) do { _Pragma("unroll") for (int m = 0; m < 4; ++m) _Pragma("unroll") for (int k = 0; k < 2; ++k) dst[m][k] = *(const PG8_LAS bf16x8*)(lds + PG8_SA(b, h) + aoff + m * 2048 + k * 1024); } while (0)
; #define PG8_LDB(dst, b, h) do { _Pragma("unroll") for (int n = 0; n < 2; ++n) _Pragma("unroll") for (int k = 0; k < 2; ++k) dst[n][k] = *(const PG8_LAS bf16x8*)(lds + PG8_SB(b, h) + boff + n * 2048 + k * 1024); } while (0)
; #define PG8_MMA(ai, bj, At, Bt) do { __builtin_amdgcn_s_setprio(1); _Pragma("unroll") for (int m = 0; m < 4; ++m) _Pragma("unroll") for (int n = 0; n < 2; ++n) _Pragma("unroll") for (int k = 0; k < 2; ++k) \
;         acc[ai][bj][m][n] = __builtin_amdgcn_mfma_f32_16x16x32_bf16(Bt[n][k], At[m][k], acc[ai][bj][m][n], 0, 0, 0); __builtin_amdgcn_s_setprio(0); } while (0)
; #define PG8_WAIT_V(n) asm volatile("s_waitcnt vmcnt(" #n ")" ::: "memory")
; #define PG8_WAIT_L(n) asm volatile("s_waitcnt lgkmcnt(" #n ")" ::: "memory")
; #define PG8_BAR __builtin_amdgcn_s_barrier()
; #define PG8_SCHED __builtin_amdgcn_sched_barrier(0)
; template <class Epi, class Sched, bool ALIGN_EPI = false, bool SP2 = false>
; __device__ __forceinline__ void gemm_phase(PG8_LAS unsigned char* lds, const Gemm g, const Sched& S, const Epi& E) {
;     ...
;             PG8_WAIT_V(8); PG8_WAIT_L(0); PG8_BAR; PG8_MMA(1, 0, At, B0); PG8_MMA(1, 1, At, B1); PG8_BAR; PG8_SCHED;
;             PG8_LDB(B0, 1, 0); PG8_LDB(B1, 1, 1); PG8_SCHED; PG8_LDA(At, 1, 0); PG8_STAGE(PG8_SA(0, 1), a2 + hstep, voffA);
;             PG8_WAIT_V(8); PG8_WAIT_L(0); PG8_BAR; PG8_MMA(0, 0, At, B0); PG8_MMA(0, 1, At, B1); PG8_BAR; PG8_SCHED;
	s_setprio 1
	s_waitcnt lgkmcnt(0)
	v_mfma_f32_16x16x32_bf16 v[92:95], v[128:131], v[190:193], 0
	v_mfma_f32_16x16x32_bf16 v[88:91], v[164:167], v[190:193], 0
	v_mfma_f32_16x16x32_bf16 v[84:87], v[128:131], v[198:201], 0
	v_mfma_f32_16x16x32_bf16 v[80:83], v[164:167], v[198:201], 0
	v_mfma_f32_16x16x32_bf16 v[76:79], v[128:131], v[216:219], 0
	v_mfma_f32_16x16x32_bf16 v[72:75], v[164:167], v[216:219], 0
	v_mfma_f32_16x16x32_bf16 v[68:71], v[128:131], v[224:227], 0
	v_mfma_f32_16x16x32_bf16 v[64:67], v[164:167], v[224:227], 0
	v_mfma_f32_16x16x32_bf16 v[92:95], v[160:163], v[194:197], v[92:95]
	v_mfma_f32_16x16x32_bf16 v[88:91], v[168:171], v[194:197], v[88:91]
	v_mfma_f32_16x16x32_bf16 v[84:87], v[160:163], v[212:215], v[84:87]
	v_mfma_f32_16x16x32_bf16 v[80:83], v[168:171], v[212:215], v[80:83]
	v_mfma_f32_16x16x32_bf16 v[76:79], v[160:163], v[220:223], v[76:79]
	v_mfma_f32_16x16x32_bf16 v[72:75], v[168:171], v[220:223], v[72:75]
	v_lshl_add_u64 v[236:237], s[64:65], 0, v[132:133]
	s_mov_b32 m0, s15
	s_nop 0
	global_load_lds_dwordx4 v[236:237], off
	v_mfma_f32_16x16x32_bf16 v[68:71], v[160:163], v[228:231], v[68:71]
	v_mfma_f32_16x16x32_bf16 v[64:67], v[168:171], v[228:231], v[64:67]
	s_setprio 0
	s_setprio 1
	v_mfma_f32_16x16x32_bf16 v[28:31], v[172:175], v[190:193], 0
	v_mfma_f32_16x16x32_bf16 v[24:27], v[182:185], v[190:193], 0
	v_mfma_f32_16x16x32_bf16 v[20:23], v[172:175], v[198:201], 0
	v_mfma_f32_16x16x32_bf16 v[16:19], v[182:185], v[198:201], 0
	v_mfma_f32_16x16x32_bf16 v[12:15], v[172:175], v[216:219], 0
	v_mfma_f32_16x16x32_bf16 v[8:11], v[182:185], v[216:219], 0
	v_mfma_f32_16x16x32_bf16 v[4:7], v[172:175], v[224:227], 0
	v_mfma_f32_16x16x32_bf16 v[0:3], v[182:185], v[224:227], 0
	v_mfma_f32_16x16x32_bf16 v[28:31], v[176:179], v[194:197], v[28:31]
	v_mfma_f32_16x16x32_bf16 v[24:27], v[186:189], v[194:197], v[24:27]
	v_mfma_f32_16x16x32_bf16 v[20:23], v[176:179], v[212:215], v[20:23]
	v_mfma_f32_16x16x32_bf16 v[16:19], v[186:189], v[212:215], v[16:19]
	v_mfma_f32_16x16x32_bf16 v[12:15], v[176:179], v[220:223], v[12:15]
	v_mfma_f32_16x16x32_bf16 v[8:11], v[186:189], v[220:223], v[8:11]
	v_lshl_add_u64 v[238:239], s[64:65], 0, v[136:137]
	s_mov_b32 m0, s33
	s_nop 0
	global_load_lds_dwordx4 v[238:239], off
	v_mfma_f32_16x16x32_bf16 v[4:7], v[176:179], v[228:231], v[4:7]
	v_mfma_f32_16x16x32_bf16 v[0:3], v[186:189], v[228:231], v[0:3]
	s_setprio 0
	s_barrier
	s_add_i32 s78, 0, 0x18000
	v_add_u32_e32 v140, s78, v147
	s_add_i32 s79, 0, 0x1c000
	ds_read_b128 v[128:131], v140
	ds_read_b128 v[160:163], v140 offset:1024
	ds_read_b128 v[164:167], v140 offset:2048
	ds_read_b128 v[168:171], v140 offset:3072
	v_add_u32_e32 v140, s79, v147
	ds_read_b128 v[172:175], v140
	ds_read_b128 v[176:179], v140 offset:1024
	ds_read_b128 v[182:185], v140 offset:2048
	ds_read_b128 v[186:189], v140 offset:3072
	s_add_u32 s64, s64, 0x40000
	s_addc_u32 s65, s65, 0
	s_mov_b32 m0, s34
	v_lshl_add_u64 v[240:241], s[64:65], 0, v[132:133]
	ds_read_b128 v[190:193], v208 offset:32768
	ds_read_b128 v[194:197], v208 offset:33792
	ds_read_b128 v[198:201], v208 offset:34816
	ds_read_b128 v[212:215], v208 offset:35840
	ds_read_b128 v[216:219], v208 offset:36864
	ds_read_b128 v[220:223], v208 offset:37888
	ds_read_b128 v[224:227], v208 offset:38912
	ds_read_b128 v[228:231], v208 offset:39936
	global_load_lds_dwordx4 v[240:241], off
	v_lshl_add_u64 v[240:241], s[64:65], 0, v[136:137]
	s_mov_b32 m0, s57
	s_nop 0
	global_load_lds_dwordx4 v[240:241], off
	s_waitcnt vmcnt(8)
	s_waitcnt lgkmcnt(0)
	s_barrier
	s_setprio 1
	s_waitcnt lgkmcnt(0)
	v_mfma_f32_16x16x32_bf16 v[124:127], v[128:131], v[190:193], v[124:127]
	v_mfma_f32_16x16x32_bf16 v[120:123], v[164:167], v[190:193], v[120:123]
	v_mfma_f32_16x16x32_bf16 v[116:119], v[128:131], v[198:201], v[116:119]
	v_mfma_f32_16x16x32_bf16 v[112:115], v[164:167], v[198:201], v[112:115]
	v_mfma_f32_16x16x32_bf16 v[108:111], v[128:131], v[216:219], v[108:111]
	v_mfma_f32_16x16x32_bf16 v[104:107], v[164:167], v[216:219], v[104:107]
	v_mfma_f32_16x16x32_bf16 v[100:103], v[128:131], v[224:227], v[100:103]
	v_mfma_f32_16x16x32_bf16 v[96:99], v[164:167], v[224:227], v[96:99]
	v_mfma_f32_16x16x32_bf16 v[124:127], v[160:163], v[194:197], v[124:127]
	v_mfma_f32_16x16x32_bf16 v[120:123], v[168:171], v[194:197], v[120:123]
	v_mfma_f32_16x16x32_bf16 v[116:119], v[160:163], v[212:215], v[116:119]
	v_mfma_f32_16x16x32_bf16 v[112:115], v[168:171], v[212:215], v[112:115]
	v_mfma_f32_16x16x32_bf16 v[108:111], v[160:163], v[220:223], v[108:111]
	v_mfma_f32_16x16x32_bf16 v[104:107], v[168:171], v[220:223], v[104:107]
	v_mfma_f32_16x16x32_bf16 v[100:103], v[160:163], v[228:231], v[100:103]
	v_mfma_f32_16x16x32_bf16 v[96:99], v[168:171], v[228:231], v[96:99]
	s_setprio 0
	s_setprio 1
	v_mfma_f32_16x16x32_bf16 v[60:63], v[172:175], v[190:193], v[60:63]
	v_mfma_f32_16x16x32_bf16 v[56:59], v[182:185], v[190:193], v[56:59]
	v_mfma_f32_16x16x32_bf16 v[52:55], v[172:175], v[198:201], v[52:55]
	v_mfma_f32_16x16x32_bf16 v[48:51], v[182:185], v[198:201], v[48:51]
	v_mfma_f32_16x16x32_bf16 v[44:47], v[172:175], v[216:219], v[44:47]
	v_mfma_f32_16x16x32_bf16 v[40:43], v[182:185], v[216:219], v[40:43]
	v_mfma_f32_16x16x32_bf16 v[36:39], v[172:175], v[224:227], v[36:39]
	v_mfma_f32_16x16x32_bf16 v[32:35], v[182:185], v[224:227], v[32:35]
	v_mfma_f32_16x16x32_bf16 v[60:63], v[176:179], v[194:197], v[60:63]
	v_mfma_f32_16x16x32_bf16 v[56:59], v[186:189], v[194:197], v[56:59]
	v_mfma_f32_16x16x32_bf16 v[52:55], v[176:179], v[212:215], v[52:55]
	v_mfma_f32_16x16x32_bf16 v[48:51], v[186:189], v[212:215], v[48:51]
	v_mfma_f32_16x16x32_bf16 v[44:47], v[176:179], v[220:223], v[44:47]
	v_mfma_f32_16x16x32_bf16 v[40:43], v[186:189], v[220:223], v[40:43]
	v_mfma_f32_16x16x32_bf16 v[36:39], v[176:179], v[228:231], v[36:39]
	v_mfma_f32_16x16x32_bf16 v[32:35], v[186:189], v[228:231], v[32:35]
	s_setprio 0
	s_barrier
; #define PG8_STAGE(bufoff, gbase, voff) do { _Pragma("unroll") for (int _i = 0; _i < 2; ++_i) \
;         __builtin_amdgcn_global_load_lds((const unsigned*)((const char*)(gbase) + (voff)[_i]), (PG8_LAS unsigned*)(lds + (bufoff) + ldsw + _i * 8192), 16, 0, 0); } while (0)
; #define PG8_LDA(dst, b, h) do { _Pragma("unroll") for (int m = 0; m < 4; ++m) _Pragma("unroll") for (int k = 0; k < 2; ++k) dst[m][k] = *(const PG8_LAS bf16x8*)(lds + PG8_SA(b, h) + aoff + m * 2048 + k * 1024); } while (0)
; #define PG8_MMA(ai, bj, At, Bt) do { __builtin_amdgcn_s_setprio(1); _Pragma("unroll") for (int m = 0; m < 4; ++m) _Pragma("unroll") for (int n = 0; n < 2; ++n) _Pragma("unroll") for (int k = 0; k < 2; ++k) \
;         acc[ai][bj][m][n] = __builtin_amdgcn_mfma_f32_16x16x32_bf16(Bt[n][k], At[m][k], acc[ai][bj][m][n], 0, 0, 0); __builtin_amdgcn_s_setprio(0); } while (0)
; #define PG8_WAIT_V(n) asm volatile("s_waitcnt vmcnt(" #n ")" ::: "memory")
; #define PG8_WAIT_L(n) asm volatile("s_waitcnt lgkmcnt(" #n ")" ::: "memory")
; #define PG8_BAR __builtin_amdgcn_s_barrier()
; #define PG8_SCHED __builtin_amdgcn_sched_barrier(0)
; template <class Epi, class Sched, bool ALIGN_EPI = false, bool SP2 = false>
; __device__ __forceinline__ void gemm_phase(PG8_LAS unsigned char* lds, const Gemm g, const Sched& S, const Epi& E) {
;     ...
;         for (int t = 0; t < nt; t += 2) {
;             const bool last = (t == nt - 2);
;             const char* a1 = cA + (size_t)(t + 1) * kstep;
;             const char* a2 = last ? nA : cA + (size_t)(t + 2) * kstep; const char* b2 = last ? nB : cB + (size_t)(t + 2) * kstep;
;             const char* a3 = a2 + kstep; const char* b3 = b2 + kstep;
;     ...
;             PG8_LDA(At, 1, 1); PG8_STAGE(PG8_SB(1, 0), b3, voffB); PG8_STAGE(PG8_SB(1, 1), b3 + hstep, voffB); PG8_STAGE(PG8_SA(1, 0), a3, voffA);
;             PG8_WAIT_V(8); PG8_WAIT_L(0); PG8_BAR; PG8_MMA(1, 0, At, B0); PG8_MMA(1, 1, At, B1); PG8_BAR; PG8_SCHED;
	s_add_i32 s64, s78, s14
	v_lshl_add_u64 v[232:233], v[232:233], 0, s[42:43]
	s_mov_b32 m0, s64
	ds_read_b128 v[190:193], v208 offset:49152
	ds_read_b128 v[194:197], v208 offset:50176
	ds_read_b128 v[198:201], v208 offset:51200
	ds_read_b128 v[212:215], v208 offset:52224
	ds_read_b128 v[216:219], v208 offset:53248
	ds_read_b128 v[220:223], v208 offset:54272
	ds_read_b128 v[224:227], v208 offset:55296
	ds_read_b128 v[228:231], v208 offset:56320
	global_load_lds_dwordx4 v[232:233], off
	s_add_i32 m0, s64, 0x2000
	s_add_u32 s62, s62, 0x40080
	v_lshl_add_u64 v[232:233], v[234:235], 0, s[42:43]
	s_addc_u32 s63, s63, 0
	s_add_i32 s64, s79, s14
	global_load_lds_dwordx4 v[232:233], off
	v_lshl_add_u64 v[232:233], s[62:63], 0, v[134:135]
	s_mov_b32 m0, s64
	s_nop 0
	global_load_lds_dwordx4 v[232:233], off
	v_lshl_add_u64 v[232:233], s[62:63], 0, v[138:139]
	s_add_i32 m0, s64, 0x2000
	s_nop 0
	global_load_lds_dwordx4 v[232:233], off
	s_waitcnt vmcnt(6)
	s_waitcnt lgkmcnt(0)
	s_barrier
	s_setprio 1
	s_waitcnt lgkmcnt(0)
	v_mfma_f32_16x16x32_bf16 v[92:95], v[128:131], v[190:193], v[92:95]
	v_mfma_f32_16x16x32_bf16 v[88:91], v[164:167], v[190:193], v[88:91]
	v_mfma_f32_16x16x32_bf16 v[84:87], v[128:131], v[198:201], v[84:87]
	v_mfma_f32_16x16x32_bf16 v[80:83], v[164:167], v[198:201], v[80:83]
	v_mfma_f32_16x16x32_bf16 v[76:79], v[128:131], v[216:219], v[76:79]
	v_mfma_f32_16x16x32_bf16 v[72:75], v[164:167], v[216:219], v[72:75]
	v_mfma_f32_16x16x32_bf16 v[68:71], v[128:131], v[224:227], v[68:71]
	v_mfma_f32_16x16x32_bf16 v[64:67], v[164:167], v[224:227], v[64:67]
	v_mfma_f32_16x16x32_bf16 v[92:95], v[160:163], v[194:197], v[92:95]
	v_mfma_f32_16x16x32_bf16 v[88:91], v[168:171], v[194:197], v[88:91]
	v_mfma_f32_16x16x32_bf16 v[84:87], v[160:163], v[212:215], v[84:87]
	v_mfma_f32_16x16x32_bf16 v[80:83], v[168:171], v[212:215], v[80:83]
	v_mfma_f32_16x16x32_bf16 v[76:79], v[160:163], v[220:223], v[76:79]
	v_mfma_f32_16x16x32_bf16 v[72:75], v[168:171], v[220:223], v[72:75]
	v_lshl_add_u64 v[232:233], v[236:237], 0, s[42:43]
	s_mov_b32 m0, s67
	s_nop 0
	global_load_lds_dwordx4 v[232:233], off
	v_mfma_f32_16x16x32_bf16 v[68:71], v[160:163], v[228:231], v[68:71]
	v_mfma_f32_16x16x32_bf16 v[64:67], v[168:171], v[228:231], v[64:67]
	s_setprio 0
	s_setprio 1
	v_mfma_f32_16x16x32_bf16 v[28:31], v[172:175], v[190:193], v[28:31]
	v_mfma_f32_16x16x32_bf16 v[24:27], v[182:185], v[190:193], v[24:27]
	v_mfma_f32_16x16x32_bf16 v[20:23], v[172:175], v[198:201], v[20:23]
	v_mfma_f32_16x16x32_bf16 v[16:19], v[182:185], v[198:201], v[16:19]
	v_mfma_f32_16x16x32_bf16 v[12:15], v[172:175], v[216:219], v[12:15]
	v_mfma_f32_16x16x32_bf16 v[8:11], v[182:185], v[216:219], v[8:11]
	v_mfma_f32_16x16x32_bf16 v[4:7], v[172:175], v[224:227], v[4:7]
	v_mfma_f32_16x16x32_bf16 v[0:3], v[182:185], v[224:227], v[0:3]
	v_mfma_f32_16x16x32_bf16 v[28:31], v[176:179], v[194:197], v[28:31]
	v_mfma_f32_16x16x32_bf16 v[24:27], v[186:189], v[194:197], v[24:27]
	v_mfma_f32_16x16x32_bf16 v[20:23], v[176:179], v[212:215], v[20:23]
	v_mfma_f32_16x16x32_bf16 v[16:19], v[186:189], v[212:215], v[16:19]
	v_mfma_f32_16x16x32_bf16 v[12:15], v[176:179], v[220:223], v[12:15]
	v_mfma_f32_16x16x32_bf16 v[8:11], v[186:189], v[220:223], v[8:11]
	v_lshl_add_u64 v[232:233], v[238:239], 0, s[42:43]
	s_mov_b32 m0, s74
	s_nop 0
	global_load_lds_dwordx4 v[232:233], off
	v_mfma_f32_16x16x32_bf16 v[4:7], v[176:179], v[228:231], v[4:7]
	v_mfma_f32_16x16x32_bf16 v[0:3], v[186:189], v[228:231], v[0:3]
	s_setprio 0
	s_barrier
	s_add_i32 s90, s90, 2
	s_add_u32 s58, s58, 0x100
	s_addc_u32 s59, s59, 0
	s_add_u32 s88, s88, 0x100
	s_addc_u32 s89, s89, 0
	.p2align 6

; #define PG8_STAGE(bufoff, gbase, voff) do { _Pragma("unroll") for (int _i = 0; _i < 2; ++_i) \
;         __builtin_amdgcn_global_load_lds((const unsigned*)((const char*)(gbase) + (voff)[_i]), (PG8_LAS unsigned*)(lds + (bufoff) + ldsw + _i * 8192), 16, 0, 0); } while (0)
; #define PG8_LDA(dst, b, h) do { _Pragma("unroll") for (int m = 0; m < 4; ++m) _Pragma("unroll") for (int k = 0; k < 2; ++k) dst[m][k] = *(const PG8_LAS bf16x8*)(lds + PG8_SA(b, h) + aoff + m * 2048 + k * 1024); } while (0)
; #define PG8_LDB(dst, b, h) do { _Pragma("unroll") for (int n = 0; n < 2; ++n) _Pragma("unroll") for (int k = 0; k < 2; ++k) dst[n][k] = *(const PG8_LAS bf16x8*)(lds + PG8_SB(b, h) + boff + n * 2048 + k * 1024); } while (0)
; #define PG8_WAIT_V(n) asm volatile("s_waitcnt vmcnt(" #n ")" ::: "memory")
; #define PG8_WAIT_L(n) asm volatile("s_waitcnt lgkmcnt(" #n ")" ::: "memory")
; #define PG8_BAR __builtin_amdgcn_s_barrier()
; #define PG8_SCHED __builtin_amdgcn_sched_barrier(0)
; template <class Epi, class Sched, bool ALIGN_EPI = false, bool SP2 = false>
; __device__ __forceinline__ void gemm_phase(PG8_LAS unsigned char* lds, const Gemm g, const Sched& S, const Epi& E) {
;     ...
;         const bool has_next = S.next(ui + 1, nxt);
;         const char* nA = has_next ? (const char*)g.A + (size_t)nxt.pm * tstep : cA; const char* nB = has_next ? (const char*)g.Bt + (size_t)nxt.pn * tstep : cB;
;         for (int t = 0; t < nt; t += 2) {
;             const bool last = (t == nt - 2);
;             const char* a1 = cA + (size_t)(t + 1) * kstep;
;             const char* a2 = last ? nA : cA + (size_t)(t + 2) * kstep; const char* b2 = last ? nB : cB + (size_t)(t + 2) * kstep;
;             const char* a3 = a2 + kstep; const char* b3 = b2 + kstep;
;             if (last && has_next) S.a_ready(nxt);
;             if constexpr (SP2) {
;             PG8_LDB(B0, 0, 0); PG8_LDB(B1, 0, 1); PG8_SCHED; PG8_LDA(At, 0, 0); PG8_STAGE(PG8_SA(1, 1), a1 + hstep, voffA);
;             PG8_WAIT_V(8); PG8_WAIT_L(0); PG8_BAR; PG8_MMA(0, 0, At, B0); PG8_MMA(0, 1, At, B1); PG8_BAR; PG8_SCHED;
;             PG8_LDA(At, 0, 1); PG8_STAGE(PG8_SB(0, 0), b2, voffB); PG8_STAGE(PG8_SB(0, 1), b2 + hstep, voffB); PG8_STAGE(PG8_SA(0, 0), a2, voffA);
;             PG8_WAIT_V(8); PG8_WAIT_L(0); PG8_BAR; PG8_MMA(1, 0, At, B0); PG8_MMA(1, 1, At, B1); PG8_BAR; PG8_SCHED;
.LBB0_1592:
	s_ashr_i32 s39, s38, 31
	s_lshl_b64 s[42:43], s[38:39], 19
	s_add_u32 s42, s40, s42
	s_addc_u32 s43, s41, s43
	s_and_b64 s[44:45], s[10:11], exec
	s_cselect_b32 s39, s43, s51
	s_cselect_b32 s47, s42, s50
	s_ashr_i32 s37, s36, 31
	s_lshl_b64 s[44:45], s[36:37], 19
	v_readlane_b32 s54, v250, 11
	v_readlane_b32 s55, v250, 12
	s_add_u32 s44, s54, s44
	s_addc_u32 s45, s55, s45
	s_and_b64 s[54:55], s[10:11], exec
	s_cselect_b32 s37, s45, s53
	s_cselect_b32 s64, s44, s52
	s_add_u32 s50, s50, 0x40080
	s_addc_u32 s51, s51, 0
	s_add_u32 s65, s52, 0x100
	s_addc_u32 s66, s53, 0
	s_mov_b32 s67, -2
	s_waitcnt lgkmcnt(0)
	ds_read_b128 v[146:149], v152
	ds_read_b128 v[156:159], v152 offset:1024
	ds_read_b128 v[160:163], v152 offset:2048
	ds_read_b128 v[164:167], v152 offset:3072
	ds_read_b128 v[168:171], v153
	ds_read_b128 v[172:175], v153 offset:1024
	ds_read_b128 v[180:183], v153 offset:2048
	ds_read_b128 v[184:187], v153 offset:3072
	s_add_u32 s52, s50, 0xfffc0080
	s_addc_u32 s53, s51, -1
	s_cmp_eq_u32 s67, 12
	s_cselect_b32 s55, s39, s53
	s_cselect_b32 s54, s47, s52
	s_cselect_b32 s53, s37, s66
	s_cselect_b32 s52, s64, s65
	v_lshl_add_u64 v[200:201], s[50:51], 0, v[136:137]
	s_add_i32 m0, s33, 0xc000
	ds_read_b128 v[188:191], v154
	ds_read_b128 v[192:195], v154 offset:1024
	ds_read_b128 v[196:199], v154 offset:2048
	ds_read_b128 v[206:209], v154 offset:3072
	ds_read_b128 v[210:213], v154 offset:4096
	ds_read_b128 v[214:217], v154 offset:5120
	ds_read_b128 v[218:221], v154 offset:6144
	ds_read_b128 v[222:225], v154 offset:7168
	global_load_lds_dwordx4 v[200:201], off
	v_lshl_add_u64 v[200:201], s[50:51], 0, v[138:139]
	s_add_i32 m0, s33, 0xe000
	s_nop 0
	global_load_lds_dwordx4 v[200:201], off
	s_waitcnt vmcnt(8)
	s_waitcnt lgkmcnt(0)
	s_barrier
	s_setprio 1
	s_waitcnt lgkmcnt(0)
	v_mfma_f32_16x16x32_bf16 v[124:127], v[146:149], v[188:191], 0
	v_mfma_f32_16x16x32_bf16 v[120:123], v[160:163], v[188:191], 0
	v_mfma_f32_16x16x32_bf16 v[108:111], v[146:149], v[196:199], 0
	v_mfma_f32_16x16x32_bf16 v[104:107], v[160:163], v[196:199], 0
	v_mfma_f32_16x16x32_bf16 v[92:95], v[146:149], v[210:213], 0
	v_mfma_f32_16x16x32_bf16 v[88:91], v[160:163], v[210:213], 0
	v_mfma_f32_16x16x32_bf16 v[76:79], v[146:149], v[218:221], 0
	v_mfma_f32_16x16x32_bf16 v[72:75], v[160:163], v[218:221], 0
	v_mfma_f32_16x16x32_bf16 v[124:127], v[156:159], v[192:195], v[124:127]
	v_mfma_f32_16x16x32_bf16 v[120:123], v[164:167], v[192:195], v[120:123]
	v_mfma_f32_16x16x32_bf16 v[108:111], v[156:159], v[206:209], v[108:111]
	v_mfma_f32_16x16x32_bf16 v[104:107], v[164:167], v[206:209], v[104:107]
	v_mfma_f32_16x16x32_bf16 v[92:95], v[156:159], v[214:217], v[92:95]
	v_mfma_f32_16x16x32_bf16 v[88:91], v[164:167], v[214:217], v[88:91]
	v_mfma_f32_16x16x32_bf16 v[76:79], v[156:159], v[222:225], v[76:79]
	v_mfma_f32_16x16x32_bf16 v[72:75], v[164:167], v[222:225], v[72:75]
	s_setprio 0
	s_setprio 1
	v_mfma_f32_16x16x32_bf16 v[116:119], v[168:171], v[188:191], 0
	v_mfma_f32_16x16x32_bf16 v[112:115], v[180:183], v[188:191], 0
	v_mfma_f32_16x16x32_bf16 v[100:103], v[168:171], v[196:199], 0
	v_mfma_f32_16x16x32_bf16 v[96:99], v[180:183], v[196:199], 0
	v_mfma_f32_16x16x32_bf16 v[84:87], v[168:171], v[210:213], 0
	v_mfma_f32_16x16x32_bf16 v[80:83], v[180:183], v[210:213], 0
	v_mfma_f32_16x16x32_bf16 v[68:71], v[168:171], v[218:221], 0
	v_mfma_f32_16x16x32_bf16 v[64:67], v[180:183], v[218:221], 0
	v_mfma_f32_16x16x32_bf16 v[116:119], v[172:175], v[192:195], v[116:119]
	v_mfma_f32_16x16x32_bf16 v[112:115], v[184:187], v[192:195], v[112:115]
	v_mfma_f32_16x16x32_bf16 v[100:103], v[172:175], v[206:209], v[100:103]
	v_mfma_f32_16x16x32_bf16 v[96:99], v[184:187], v[206:209], v[96:99]
	v_mfma_f32_16x16x32_bf16 v[84:87], v[172:175], v[214:217], v[84:87]
	v_mfma_f32_16x16x32_bf16 v[80:83], v[184:187], v[214:217], v[80:83]
	v_mfma_f32_16x16x32_bf16 v[68:71], v[172:175], v[222:225], v[68:71]
	v_mfma_f32_16x16x32_bf16 v[64:67], v[184:187], v[222:225], v[64:67]
	s_setprio 0
	s_barrier
	s_add_i32 s74, s60, s15
	v_lshl_add_u64 v[200:201], s[52:53], 0, v[130:131]
	s_mov_b32 m0, s74
	ds_read_b128 v[188:191], v154 offset:16384
	ds_read_b128 v[192:195], v154 offset:17408
	ds_read_b128 v[196:199], v154 offset:18432
	ds_read_b128 v[206:209], v154 offset:19456
	ds_read_b128 v[210:213], v154 offset:20480
	ds_read_b128 v[214:217], v154 offset:21504
	ds_read_b128 v[218:221], v154 offset:22528
	ds_read_b128 v[222:225], v154 offset:23552
	global_load_lds_dwordx4 v[200:201], off
	s_add_i32 m0, s74, 0x2000
	s_add_u32 s74, s52, 0x40000
	v_lshl_add_u64 v[226:227], s[52:53], 0, v[134:135]
	s_addc_u32 s75, s53, 0
	s_add_i32 s76, s61, s15
	global_load_lds_dwordx4 v[226:227], off
	v_lshl_add_u64 v[228:229], s[74:75], 0, v[130:131]
	s_mov_b32 m0, s76
	global_load_lds_dwordx4 v[228:229], off
	v_lshl_add_u64 v[228:229], s[74:75], 0, v[134:135]
	s_add_i32 m0, s76, 0x2000
	s_nop 0
	global_load_lds_dwordx4 v[228:229], off
	s_waitcnt vmcnt(6)
	s_waitcnt lgkmcnt(0)
	s_barrier
; #define PG8_STAGE(bufoff, gbase, voff) do { _Pragma("unroll") for (int _i = 0; _i < 2; ++_i) \
;         __builtin_amdgcn_global_load_lds((const unsigned*)((const char*)(gbase) + (voff)[_i]), (PG8_LAS unsigned*)(lds + (bufoff) + ldsw + _i * 8192), 16, 0, 0); } while (0)
; #define PG8_LDA(dst, b, h) do { _Pragma("unroll") for (int m = 0; m < 4; ++m) _Pragma("unroll") for (int k = 0; k < 2; ++k) dst[m][k] = *(const PG8_LAS bf16x8*)(lds + PG8_SA(b, h) + aoff + m * 2048 + k * 1024); } while (0)
; #define PG8_LDB(dst, b, h) do { _Pragma("unroll") for (int n = 0; n < 2; ++n) _Pragma("unroll") for (int k = 0; k < 2; ++k) dst[n][k] = *(const PG8_LAS bf16x8*)(lds + PG8_SB(b, h) + boff + n * 2048 + k * 1024); } while (0)
; #define PG8_MMA(ai, bj, At, Bt) do { __builtin_amdgcn_s_setprio(1); _Pragma("unroll") for (int m = 0; m < 4; ++m) _Pragma("unroll") for (int n = 0; n < 2; ++n) _Pragma("unroll") for (int k = 0; k < 2; ++k) \
;         acc[ai][bj][m][n] = __builtin_amdgcn_mfma_f32_16x16x32_bf16(Bt[n][k], At[m][k], acc[ai][bj][m][n], 0, 0, 0); __builtin_amdgcn_s_setprio(0); } while (0)
; #define PG8_WAIT_V(n) asm volatile("s_waitcnt vmcnt(" #n ")" ::: "memory")
; #define PG8_WAIT_L(n) asm volatile("s_waitcnt lgkmcnt(" #n ")" ::: "memory")
; #define PG8_BAR __builtin_amdgcn_s_barrier()
; #define PG8_SCHED __builtin_amdgcn_sched_barrier(0)
; template <class Epi, class Sched, bool ALIGN_EPI = false, bool SP2 = false>
; __device__ __forceinline__ void gemm_phase(PG8_LAS unsigned char* lds, const Gemm g, const Sched& S, const Epi& E) {
;     ...
;             PG8_WAIT_V(8); PG8_WAIT_L(0); PG8_BAR; PG8_MMA(1, 0, At, B0); PG8_MMA(1, 1, At, B1); PG8_BAR; PG8_SCHED;
;             PG8_LDB(B0, 1, 0); PG8_LDB(B1, 1, 1); PG8_SCHED; PG8_LDA(At, 1, 0); PG8_STAGE(PG8_SA(0, 1), a2 + hstep, voffA);
;             PG8_WAIT_V(8); PG8_WAIT_L(0); PG8_BAR; PG8_MMA(0, 0, At, B0); PG8_MMA(0, 1, At, B1); PG8_BAR; PG8_SCHED;
	s_setprio 1
	s_waitcnt lgkmcnt(0)
	v_mfma_f32_16x16x32_bf16 v[60:63], v[146:149], v[188:191], 0
	v_mfma_f32_16x16x32_bf16 v[56:59], v[160:163], v[188:191], 0
	v_mfma_f32_16x16x32_bf16 v[44:47], v[146:149], v[196:199], 0
	v_mfma_f32_16x16x32_bf16 v[40:43], v[160:163], v[196:199], 0
	v_mfma_f32_16x16x32_bf16 v[28:31], v[146:149], v[210:213], 0
	v_mfma_f32_16x16x32_bf16 v[24:27], v[160:163], v[210:213], 0
	v_mfma_f32_16x16x32_bf16 v[12:15], v[146:149], v[218:221], 0
	v_mfma_f32_16x16x32_bf16 v[8:11], v[160:163], v[218:221], 0
	v_mfma_f32_16x16x32_bf16 v[60:63], v[156:159], v[192:195], v[60:63]
	v_mfma_f32_16x16x32_bf16 v[56:59], v[164:167], v[192:195], v[56:59]
	v_mfma_f32_16x16x32_bf16 v[44:47], v[156:159], v[206:209], v[44:47]
	v_mfma_f32_16x16x32_bf16 v[40:43], v[164:167], v[206:209], v[40:43]
	v_mfma_f32_16x16x32_bf16 v[28:31], v[156:159], v[214:217], v[28:31]
	v_mfma_f32_16x16x32_bf16 v[24:27], v[164:167], v[214:217], v[24:27]
	v_lshl_add_u64 v[228:229], s[54:55], 0, v[128:129]
	s_mov_b32 m0, s33
	s_nop 0
	global_load_lds_dwordx4 v[228:229], off
	v_mfma_f32_16x16x32_bf16 v[12:15], v[156:159], v[222:225], v[12:15]
	v_mfma_f32_16x16x32_bf16 v[8:11], v[164:167], v[222:225], v[8:11]
	s_setprio 0
	s_setprio 1
	v_mfma_f32_16x16x32_bf16 v[52:55], v[168:171], v[188:191], 0
	v_mfma_f32_16x16x32_bf16 v[48:51], v[180:183], v[188:191], 0
	v_mfma_f32_16x16x32_bf16 v[36:39], v[168:171], v[196:199], 0
	v_mfma_f32_16x16x32_bf16 v[32:35], v[180:183], v[196:199], 0
	v_mfma_f32_16x16x32_bf16 v[20:23], v[168:171], v[210:213], 0
	v_mfma_f32_16x16x32_bf16 v[16:19], v[180:183], v[210:213], 0
	v_mfma_f32_16x16x32_bf16 v[4:7], v[168:171], v[218:221], 0
	v_mfma_f32_16x16x32_bf16 v[0:3], v[180:183], v[218:221], 0
	v_mfma_f32_16x16x32_bf16 v[52:55], v[172:175], v[192:195], v[52:55]
	v_mfma_f32_16x16x32_bf16 v[48:51], v[184:187], v[192:195], v[48:51]
	v_mfma_f32_16x16x32_bf16 v[36:39], v[172:175], v[206:209], v[36:39]
	v_mfma_f32_16x16x32_bf16 v[32:35], v[184:187], v[206:209], v[32:35]
	v_mfma_f32_16x16x32_bf16 v[20:23], v[172:175], v[214:217], v[20:23]
	v_mfma_f32_16x16x32_bf16 v[16:19], v[184:187], v[214:217], v[16:19]
	v_lshl_add_u64 v[230:231], s[54:55], 0, v[132:133]
	s_mov_b32 m0, s34
	s_nop 0
	global_load_lds_dwordx4 v[230:231], off
	v_mfma_f32_16x16x32_bf16 v[4:7], v[172:175], v[222:225], v[4:7]
	v_mfma_f32_16x16x32_bf16 v[0:3], v[184:187], v[222:225], v[0:3]
	s_setprio 0
	s_barrier
	s_add_i32 s74, 0, 0x18000
	s_add_i32 s75, 0, 0x1c000
	v_add_u32_e32 v164, s74, v150
	v_add_u32_e32 v179, s75, v150
	ds_read_b128 v[146:149], v164
	ds_read_b128 v[156:159], v164 offset:1024
	ds_read_b128 v[160:163], v164 offset:2048
	ds_read_b128 v[164:167], v164 offset:3072
	ds_read_b128 v[168:171], v179
	ds_read_b128 v[172:175], v179 offset:1024
	ds_read_b128 v[180:183], v179 offset:2048
	ds_read_b128 v[184:187], v179 offset:3072
	s_add_u32 s54, s54, 0x40000
	s_addc_u32 s55, s55, 0
	s_mov_b32 m0, s49
	v_lshl_add_u64 v[232:233], s[54:55], 0, v[128:129]
	ds_read_b128 v[188:191], v154 offset:32768
	ds_read_b128 v[192:195], v154 offset:33792
	ds_read_b128 v[196:199], v154 offset:34816
	ds_read_b128 v[206:209], v154 offset:35840
	ds_read_b128 v[210:213], v154 offset:36864
	ds_read_b128 v[214:217], v154 offset:37888
	ds_read_b128 v[218:221], v154 offset:38912
	ds_read_b128 v[222:225], v154 offset:39936
	global_load_lds_dwordx4 v[232:233], off
	v_lshl_add_u64 v[232:233], s[54:55], 0, v[132:133]
	s_mov_b32 m0, s56
	s_nop 0
	global_load_lds_dwordx4 v[232:233], off
	s_waitcnt vmcnt(8)
	s_waitcnt lgkmcnt(0)
	s_barrier
	s_setprio 1
	s_waitcnt lgkmcnt(0)
	v_mfma_f32_16x16x32_bf16 v[124:127], v[146:149], v[188:191], v[124:127]
	v_mfma_f32_16x16x32_bf16 v[120:123], v[160:163], v[188:191], v[120:123]
	v_mfma_f32_16x16x32_bf16 v[108:111], v[146:149], v[196:199], v[108:111]
	v_mfma_f32_16x16x32_bf16 v[104:107], v[160:163], v[196:199], v[104:107]
	v_mfma_f32_16x16x32_bf16 v[92:95], v[146:149], v[210:213], v[92:95]
	v_mfma_f32_16x16x32_bf16 v[88:91], v[160:163], v[210:213], v[88:91]
	v_mfma_f32_16x16x32_bf16 v[76:79], v[146:149], v[218:221], v[76:79]
	v_mfma_f32_16x16x32_bf16 v[72:75], v[160:163], v[218:221], v[72:75]
	v_mfma_f32_16x16x32_bf16 v[124:127], v[156:159], v[192:195], v[124:127]
	v_mfma_f32_16x16x32_bf16 v[120:123], v[164:167], v[192:195], v[120:123]
	v_mfma_f32_16x16x32_bf16 v[108:111], v[156:159], v[206:209], v[108:111]
	v_mfma_f32_16x16x32_bf16 v[104:107], v[164:167], v[206:209], v[104:107]
	v_mfma_f32_16x16x32_bf16 v[92:95], v[156:159], v[214:217], v[92:95]
	v_mfma_f32_16x16x32_bf16 v[88:91], v[164:167], v[214:217], v[88:91]
	v_mfma_f32_16x16x32_bf16 v[76:79], v[156:159], v[222:225], v[76:79]
	v_mfma_f32_16x16x32_bf16 v[72:75], v[164:167], v[222:225], v[72:75]
	s_setprio 0
	s_setprio 1
	v_mfma_f32_16x16x32_bf16 v[116:119], v[168:171], v[188:191], v[116:119]
	v_mfma_f32_16x16x32_bf16 v[112:115], v[180:183], v[188:191], v[112:115]
	v_mfma_f32_16x16x32_bf16 v[100:103], v[168:171], v[196:199], v[100:103]
	v_mfma_f32_16x16x32_bf16 v[96:99], v[180:183], v[196:199], v[96:99]
	v_mfma_f32_16x16x32_bf16 v[84:87], v[168:171], v[210:213], v[84:87]
	v_mfma_f32_16x16x32_bf16 v[80:83], v[180:183], v[210:213], v[80:83]
	v_mfma_f32_16x16x32_bf16 v[68:71], v[168:171], v[218:221], v[68:71]
	v_mfma_f32_16x16x32_bf16 v[64:67], v[180:183], v[218:221], v[64:67]
	v_mfma_f32_16x16x32_bf16 v[116:119], v[172:175], v[192:195], v[116:119]
	v_mfma_f32_16x16x32_bf16 v[112:115], v[184:187], v[192:195], v[112:115]
	v_mfma_f32_16x16x32_bf16 v[100:103], v[172:175], v[206:209], v[100:103]
	v_mfma_f32_16x16x32_bf16 v[96:99], v[184:187], v[206:209], v[96:99]
	v_mfma_f32_16x16x32_bf16 v[84:87], v[172:175], v[214:217], v[84:87]
	v_mfma_f32_16x16x32_bf16 v[80:83], v[184:187], v[214:217], v[80:83]
	v_mfma_f32_16x16x32_bf16 v[68:71], v[172:175], v[222:225], v[68:71]
	v_mfma_f32_16x16x32_bf16 v[64:67], v[184:187], v[222:225], v[64:67]
	s_setprio 0
	s_barrier
; #define PG8_STAGE(bufoff, gbase, voff) do { _Pragma("unroll") for (int _i = 0; _i < 2; ++_i) \
;         __builtin_amdgcn_global_load_lds((const unsigned*)((const char*)(gbase) + (voff)[_i]), (PG8_LAS unsigned*)(lds + (bufoff) + ldsw + _i * 8192), 16, 0, 0); } while (0)
; #define PG8_LDA(dst, b, h) do { _Pragma("unroll") for (int m = 0; m < 4; ++m) _Pragma("unroll") for (int k = 0; k < 2; ++k) dst[m][k] = *(const PG8_LAS bf16x8*)(lds + PG8_SA(b, h) + aoff + m * 2048 + k * 1024); } while (0)
; #define PG8_MMA(ai, bj, At, Bt) do { __builtin_amdgcn_s_setprio(1); _Pragma("unroll") for (int m = 0; m < 4; ++m) _Pragma("unroll") for (int n = 0; n < 2; ++n) _Pragma("unroll") for (int k = 0; k < 2; ++k) \
;         acc[ai][bj][m][n] = __builtin_amdgcn_mfma_f32_16x16x32_bf16(Bt[n][k], At[m][k], acc[ai][bj][m][n], 0, 0, 0); __builtin_amdgcn_s_setprio(0); } while (0)
; #define PG8_WAIT_V(n) asm volatile("s_waitcnt vmcnt(" #n ")" ::: "memory")
; #define PG8_WAIT_L(n) asm volatile("s_waitcnt lgkmcnt(" #n ")" ::: "memory")
; #define PG8_BAR __builtin_amdgcn_s_barrier()
; #define PG8_SCHED __builtin_amdgcn_sched_barrier(0)
; template <class Epi, class Sched, bool ALIGN_EPI = false, bool SP2 = false>
; __device__ __forceinline__ void gemm_phase(PG8_LAS unsigned char* lds, const Gemm g, const Sched& S, const Epi& E) {
;     ...
;         for (int t = 0; t < nt; t += 2) {
;             const bool last = (t == nt - 2);
;             const char* a1 = cA + (size_t)(t + 1) * kstep;
;             const char* a2 = last ? nA : cA + (size_t)(t + 2) * kstep; const char* b2 = last ? nB : cB + (size_t)(t + 2) * kstep;
;             const char* a3 = a2 + kstep; const char* b3 = b2 + kstep;
;     ...
;             PG8_LDA(At, 1, 1); PG8_STAGE(PG8_SB(1, 0), b3, voffB); PG8_STAGE(PG8_SB(1, 1), b3 + hstep, voffB); PG8_STAGE(PG8_SA(1, 0), a3, voffA);
;             PG8_WAIT_V(8); PG8_WAIT_L(0); PG8_BAR; PG8_MMA(1, 0, At, B0); PG8_MMA(1, 1, At, B1); PG8_BAR; PG8_SCHED;
	s_add_i32 s54, s74, s15
	v_lshl_add_u64 v[200:201], v[200:201], 0, s[26:27]
	s_mov_b32 m0, s54
	ds_read_b128 v[188:191], v154 offset:49152
	ds_read_b128 v[192:195], v154 offset:50176
	ds_read_b128 v[196:199], v154 offset:51200
	ds_read_b128 v[206:209], v154 offset:52224
	ds_read_b128 v[210:213], v154 offset:53248
	ds_read_b128 v[214:217], v154 offset:54272
	ds_read_b128 v[218:221], v154 offset:55296
	ds_read_b128 v[222:225], v154 offset:56320
	global_load_lds_dwordx4 v[200:201], off
	s_add_i32 m0, s54, 0x2000
	s_add_u32 s52, s52, 0x40080
	v_lshl_add_u64 v[200:201], v[226:227], 0, s[26:27]
	s_addc_u32 s53, s53, 0
	s_add_i32 s54, s75, s15
	global_load_lds_dwordx4 v[200:201], off
	v_lshl_add_u64 v[200:201], s[52:53], 0, v[130:131]
	s_mov_b32 m0, s54
	s_nop 0
	global_load_lds_dwordx4 v[200:201], off
	v_lshl_add_u64 v[200:201], s[52:53], 0, v[134:135]
	s_add_i32 m0, s54, 0x2000
	s_nop 0
	global_load_lds_dwordx4 v[200:201], off
	s_waitcnt vmcnt(6)
	s_waitcnt lgkmcnt(0)
	s_barrier
	s_setprio 1
	s_waitcnt lgkmcnt(0)
	v_mfma_f32_16x16x32_bf16 v[60:63], v[146:149], v[188:191], v[60:63]
	v_mfma_f32_16x16x32_bf16 v[56:59], v[160:163], v[188:191], v[56:59]
	v_mfma_f32_16x16x32_bf16 v[44:47], v[146:149], v[196:199], v[44:47]
	v_mfma_f32_16x16x32_bf16 v[40:43], v[160:163], v[196:199], v[40:43]
	v_mfma_f32_16x16x32_bf16 v[28:31], v[146:149], v[210:213], v[28:31]
	v_mfma_f32_16x16x32_bf16 v[24:27], v[160:163], v[210:213], v[24:27]
	v_mfma_f32_16x16x32_bf16 v[12:15], v[146:149], v[218:221], v[12:15]
	v_mfma_f32_16x16x32_bf16 v[8:11], v[160:163], v[218:221], v[8:11]
	v_mfma_f32_16x16x32_bf16 v[60:63], v[156:159], v[192:195], v[60:63]
	v_mfma_f32_16x16x32_bf16 v[56:59], v[164:167], v[192:195], v[56:59]
	v_mfma_f32_16x16x32_bf16 v[44:47], v[156:159], v[206:209], v[44:47]
	v_mfma_f32_16x16x32_bf16 v[40:43], v[164:167], v[206:209], v[40:43]
	v_mfma_f32_16x16x32_bf16 v[28:31], v[156:159], v[214:217], v[28:31]
	v_mfma_f32_16x16x32_bf16 v[24:27], v[164:167], v[214:217], v[24:27]
	v_lshl_add_u64 v[200:201], v[228:229], 0, s[26:27]
	s_mov_b32 m0, s58
	s_nop 0
	global_load_lds_dwordx4 v[200:201], off
	v_mfma_f32_16x16x32_bf16 v[12:15], v[156:159], v[222:225], v[12:15]
	v_mfma_f32_16x16x32_bf16 v[8:11], v[164:167], v[222:225], v[8:11]
	s_setprio 0
	s_setprio 1
	v_mfma_f32_16x16x32_bf16 v[52:55], v[168:171], v[188:191], v[52:55]
	v_mfma_f32_16x16x32_bf16 v[48:51], v[180:183], v[188:191], v[48:51]
	v_mfma_f32_16x16x32_bf16 v[36:39], v[168:171], v[196:199], v[36:39]
	v_mfma_f32_16x16x32_bf16 v[32:35], v[180:183], v[196:199], v[32:35]
	v_mfma_f32_16x16x32_bf16 v[20:23], v[168:171], v[210:213], v[20:23]
	v_mfma_f32_16x16x32_bf16 v[16:19], v[180:183], v[210:213], v[16:19]
	v_mfma_f32_16x16x32_bf16 v[4:7], v[168:171], v[218:221], v[4:7]
	v_mfma_f32_16x16x32_bf16 v[0:3], v[180:183], v[218:221], v[0:3]
	v_mfma_f32_16x16x32_bf16 v[52:55], v[172:175], v[192:195], v[52:55]
	v_mfma_f32_16x16x32_bf16 v[48:51], v[184:187], v[192:195], v[48:51]
	v_mfma_f32_16x16x32_bf16 v[36:39], v[172:175], v[206:209], v[36:39]
	v_mfma_f32_16x16x32_bf16 v[32:35], v[184:187], v[206:209], v[32:35]
	v_mfma_f32_16x16x32_bf16 v[20:23], v[172:175], v[214:217], v[20:23]
	v_mfma_f32_16x16x32_bf16 v[16:19], v[184:187], v[214:217], v[16:19]
	v_lshl_add_u64 v[200:201], v[230:231], 0, s[26:27]
	s_mov_b32 m0, s59
	s_nop 0
	global_load_lds_dwordx4 v[200:201], off
	v_mfma_f32_16x16x32_bf16 v[4:7], v[172:175], v[222:225], v[4:7]
	v_mfma_f32_16x16x32_bf16 v[0:3], v[184:187], v[222:225], v[0:3]
	s_setprio 0
	s_barrier
	s_add_i32 s67, s67, 2
	s_add_u32 s50, s50, 0x100
	s_addc_u32 s51, s51, 0
	s_add_u32 s65, s65, 0x100
	s_addc_u32 s66, s66, 0
	.p2align 6

; #define PG8_STAGE(bufoff, gbase, voff) do { _Pragma("unroll") for (int _i = 0; _i < 2; ++_i) \
;         __builtin_amdgcn_global_load_lds((const unsigned*)((const char*)(gbase) + (voff)[_i]), (PG8_LAS unsigned*)(lds + (bufoff) + ldsw + _i * 8192), 16, 0, 0); } while (0)
; #define PG8_LDA(dst, b, h) do { _Pragma("unroll") for (int m = 0; m < 4; ++m) _Pragma("unroll") for (int k = 0; k < 2; ++k) dst[m][k] = *(const PG8_LAS bf16x8*)(lds + PG8_SA(b, h) + aoff + m * 2048 + k * 1024); } while (0)
; #define PG8_LDB(dst, b, h) do { _Pragma("unroll") for (int n = 0; n < 2; ++n) _Pragma("unroll") for (int k = 0; k < 2; ++k) dst[n][k] = *(const PG8_LAS bf16x8*)(lds + PG8_SB(b, h) + boff + n * 2048 + k * 1024); } while (0)
; #define PG8_WAIT_V(n) asm volatile("s_waitcnt vmcnt(" #n ")" ::: "memory")
; #define PG8_WAIT_L(n) asm volatile("s_waitcnt lgkmcnt(" #n ")" ::: "memory")
; #define PG8_BAR __builtin_amdgcn_s_barrier()
; #define PG8_SCHED __builtin_amdgcn_sched_barrier(0)
; template <class Epi, class Sched, bool ALIGN_EPI = false, bool SP2 = false>
; __device__ __forceinline__ void gemm_phase(PG8_LAS unsigned char* lds, const Gemm g, const Sched& S, const Epi& E) {
;     ...
;         const bool has_next = S.next(ui + 1, nxt);
;         const char* nA = has_next ? (const char*)g.A + (size_t)nxt.pm * tstep : cA; const char* nB = has_next ? (const char*)g.Bt + (size_t)nxt.pn * tstep : cB;
;         for (int t = 0; t < nt; t += 2) {
;             const bool last = (t == nt - 2);
;             const char* a1 = cA + (size_t)(t + 1) * kstep;
;             const char* a2 = last ? nA : cA + (size_t)(t + 2) * kstep; const char* b2 = last ? nB : cB + (size_t)(t + 2) * kstep;
;             const char* a3 = a2 + kstep; const char* b3 = b2 + kstep;
;             if (last && has_next) S.a_ready(nxt);
;             if constexpr (SP2) {
;             PG8_LDB(B0, 0, 0); PG8_LDB(B1, 0, 1); PG8_SCHED; PG8_LDA(At, 0, 0); PG8_STAGE(PG8_SA(1, 1), a1 + hstep, voffA);
;             PG8_WAIT_V(8); PG8_WAIT_L(0); PG8_BAR; PG8_MMA(0, 0, At, B0); PG8_MMA(0, 1, At, B1); PG8_BAR; PG8_SCHED;
;             PG8_LDA(At, 0, 1); PG8_STAGE(PG8_SB(0, 0), b2, voffB); PG8_STAGE(PG8_SB(0, 1), b2 + hstep, voffB); PG8_STAGE(PG8_SA(0, 0), a2, voffA);
;             PG8_WAIT_V(8); PG8_WAIT_L(0); PG8_BAR; PG8_MMA(1, 0, At, B0); PG8_MMA(1, 1, At, B1); PG8_BAR; PG8_SCHED;
.LBB0_1680:
	s_ashr_i32 s47, s46, 31
	s_lshl_b64 s[48:49], s[46:47], 19
	s_add_u32 s48, s22, s48
	s_addc_u32 s49, s23, s49
	s_and_b64 s[50:51], s[4:5], exec
	s_cselect_b32 s47, s49, s53
	s_cselect_b32 s77, s48, s52
	s_ashr_i32 s45, s44, 31
	s_lshl_b64 s[50:51], s[44:45], 19
	s_add_u32 s50, s15, s50
	s_addc_u32 s51, s33, s51
	s_and_b64 s[56:57], s[4:5], exec
	s_cselect_b32 s45, s51, s55
	s_cselect_b32 s78, s50, s54
	s_add_u32 s52, s52, 0x40080
	s_addc_u32 s53, s53, 0
	s_add_u32 s79, s54, 0x100
	s_addc_u32 s80, s55, 0
	s_mov_b32 s81, -2
	ds_read_b128 v[146:149], v152
	ds_read_b128 v[156:159], v152 offset:1024
	ds_read_b128 v[160:163], v152 offset:2048
	ds_read_b128 v[164:167], v152 offset:3072
	ds_read_b128 v[168:171], v153
	ds_read_b128 v[172:175], v153 offset:1024
	ds_read_b128 v[180:183], v153 offset:2048
	ds_read_b128 v[184:187], v153 offset:3072
	s_add_u32 s54, s52, 0xfffc0080
	s_addc_u32 s55, s53, -1
	s_cmp_eq_u32 s81, 12
	s_cselect_b32 s57, s47, s55
	s_cselect_b32 s56, s77, s54
	s_cselect_b32 s55, s45, s80
	s_cselect_b32 s54, s78, s79
	v_lshl_add_u64 v[200:201], s[52:53], 0, v[136:137]
	s_add_i32 m0, s58, 0xc000
	ds_read_b128 v[188:191], v154
	ds_read_b128 v[192:195], v154 offset:1024
	ds_read_b128 v[196:199], v154 offset:2048
	ds_read_b128 v[206:209], v154 offset:3072
	ds_read_b128 v[210:213], v154 offset:4096
	ds_read_b128 v[214:217], v154 offset:5120
	ds_read_b128 v[218:221], v154 offset:6144
	ds_read_b128 v[222:225], v154 offset:7168
	global_load_lds_dwordx4 v[200:201], off
	v_lshl_add_u64 v[200:201], s[52:53], 0, v[138:139]
	s_add_i32 m0, s58, 0xe000
	s_nop 0
	global_load_lds_dwordx4 v[200:201], off
	s_waitcnt vmcnt(8)
	s_waitcnt lgkmcnt(0)
	s_barrier
	s_setprio 1
	s_waitcnt lgkmcnt(0)
	v_mfma_f32_16x16x32_bf16 v[124:127], v[146:149], v[188:191], 0
	v_mfma_f32_16x16x32_bf16 v[120:123], v[160:163], v[188:191], 0
	v_mfma_f32_16x16x32_bf16 v[108:111], v[146:149], v[196:199], 0
	v_mfma_f32_16x16x32_bf16 v[104:107], v[160:163], v[196:199], 0
	v_mfma_f32_16x16x32_bf16 v[92:95], v[146:149], v[210:213], 0
	v_mfma_f32_16x16x32_bf16 v[88:91], v[160:163], v[210:213], 0
	v_mfma_f32_16x16x32_bf16 v[76:79], v[146:149], v[218:221], 0
	v_mfma_f32_16x16x32_bf16 v[72:75], v[160:163], v[218:221], 0
	v_mfma_f32_16x16x32_bf16 v[124:127], v[156:159], v[192:195], v[124:127]
	v_mfma_f32_16x16x32_bf16 v[120:123], v[164:167], v[192:195], v[120:123]
	v_mfma_f32_16x16x32_bf16 v[108:111], v[156:159], v[206:209], v[108:111]
	v_mfma_f32_16x16x32_bf16 v[104:107], v[164:167], v[206:209], v[104:107]
	v_mfma_f32_16x16x32_bf16 v[92:95], v[156:159], v[214:217], v[92:95]
	v_mfma_f32_16x16x32_bf16 v[88:91], v[164:167], v[214:217], v[88:91]
	v_mfma_f32_16x16x32_bf16 v[76:79], v[156:159], v[222:225], v[76:79]
	v_mfma_f32_16x16x32_bf16 v[72:75], v[164:167], v[222:225], v[72:75]
	s_setprio 0
	s_setprio 1
	v_mfma_f32_16x16x32_bf16 v[116:119], v[168:171], v[188:191], 0
	v_mfma_f32_16x16x32_bf16 v[112:115], v[180:183], v[188:191], 0
	v_mfma_f32_16x16x32_bf16 v[100:103], v[168:171], v[196:199], 0
	v_mfma_f32_16x16x32_bf16 v[96:99], v[180:183], v[196:199], 0
	v_mfma_f32_16x16x32_bf16 v[84:87], v[168:171], v[210:213], 0
	v_mfma_f32_16x16x32_bf16 v[80:83], v[180:183], v[210:213], 0
	v_mfma_f32_16x16x32_bf16 v[68:71], v[168:171], v[218:221], 0
	v_mfma_f32_16x16x32_bf16 v[64:67], v[180:183], v[218:221], 0
	v_mfma_f32_16x16x32_bf16 v[116:119], v[172:175], v[192:195], v[116:119]
	v_mfma_f32_16x16x32_bf16 v[112:115], v[184:187], v[192:195], v[112:115]
	v_mfma_f32_16x16x32_bf16 v[100:103], v[172:175], v[206:209], v[100:103]
	v_mfma_f32_16x16x32_bf16 v[96:99], v[184:187], v[206:209], v[96:99]
	v_mfma_f32_16x16x32_bf16 v[84:87], v[172:175], v[214:217], v[84:87]
	v_mfma_f32_16x16x32_bf16 v[80:83], v[184:187], v[214:217], v[80:83]
	v_mfma_f32_16x16x32_bf16 v[68:71], v[172:175], v[222:225], v[68:71]
	v_mfma_f32_16x16x32_bf16 v[64:67], v[184:187], v[222:225], v[64:67]
	s_setprio 0
	s_barrier
	s_add_i32 s82, s65, s34
	v_lshl_add_u64 v[200:201], s[54:55], 0, v[132:133]
	s_mov_b32 m0, s82
	ds_read_b128 v[188:191], v154 offset:16384
	ds_read_b128 v[192:195], v154 offset:17408
	ds_read_b128 v[196:199], v154 offset:18432
	ds_read_b128 v[206:209], v154 offset:19456
	ds_read_b128 v[210:213], v154 offset:20480
	ds_read_b128 v[214:217], v154 offset:21504
	ds_read_b128 v[218:221], v154 offset:22528
	ds_read_b128 v[222:225], v154 offset:23552
	global_load_lds_dwordx4 v[200:201], off
	s_add_i32 m0, s82, 0x2000
	s_add_u32 s82, s54, 0x40000
	v_lshl_add_u64 v[226:227], s[54:55], 0, v[128:129]
	s_addc_u32 s83, s55, 0
	s_add_i32 s84, s66, s34
	global_load_lds_dwordx4 v[226:227], off
	v_lshl_add_u64 v[228:229], s[82:83], 0, v[132:133]
	s_mov_b32 m0, s84
	global_load_lds_dwordx4 v[228:229], off
	v_lshl_add_u64 v[228:229], s[82:83], 0, v[128:129]
	s_add_i32 m0, s84, 0x2000
	s_nop 0
	global_load_lds_dwordx4 v[228:229], off
	s_waitcnt vmcnt(6)
	s_waitcnt lgkmcnt(0)
	s_barrier
; #define PG8_STAGE(bufoff, gbase, voff) do { _Pragma("unroll") for (int _i = 0; _i < 2; ++_i) \
;         __builtin_amdgcn_global_load_lds((const unsigned*)((const char*)(gbase) + (voff)[_i]), (PG8_LAS unsigned*)(lds + (bufoff) + ldsw + _i * 8192), 16, 0, 0); } while (0)
; #define PG8_LDA(dst, b, h) do { _Pragma("unroll") for (int m = 0; m < 4; ++m) _Pragma("unroll") for (int k = 0; k < 2; ++k) dst[m][k] = *(const PG8_LAS bf16x8*)(lds + PG8_SA(b, h) + aoff + m * 2048 + k * 1024); } while (0)
; #define PG8_LDB(dst, b, h) do { _Pragma("unroll") for (int n = 0; n < 2; ++n) _Pragma("unroll") for (int k = 0; k < 2; ++k) dst[n][k] = *(const PG8_LAS bf16x8*)(lds + PG8_SB(b, h) + boff + n * 2048 + k * 1024); } while (0)
; #define PG8_MMA(ai, bj, At, Bt) do { __builtin_amdgcn_s_setprio(1); _Pragma("unroll") for (int m = 0; m < 4; ++m) _Pragma("unroll") for (int n = 0; n < 2; ++n) _Pragma("unroll") for (int k = 0; k < 2; ++k) \
;         acc[ai][bj][m][n] = __builtin_amdgcn_mfma_f32_16x16x32_bf16(Bt[n][k], At[m][k], acc[ai][bj][m][n], 0, 0, 0); __builtin_amdgcn_s_setprio(0); } while (0)
; #define PG8_WAIT_V(n) asm volatile("s_waitcnt vmcnt(" #n ")" ::: "memory")
; #define PG8_WAIT_L(n) asm volatile("s_waitcnt lgkmcnt(" #n ")" ::: "memory")
; #define PG8_BAR __builtin_amdgcn_s_barrier()
; #define PG8_SCHED __builtin_amdgcn_sched_barrier(0)
; template <class Epi, class Sched, bool ALIGN_EPI = false, bool SP2 = false>
; __device__ __forceinline__ void gemm_phase(PG8_LAS unsigned char* lds, const Gemm g, const Sched& S, const Epi& E) {
;     ...
;             PG8_WAIT_V(8); PG8_WAIT_L(0); PG8_BAR; PG8_MMA(1, 0, At, B0); PG8_MMA(1, 1, At, B1); PG8_BAR; PG8_SCHED;
;             PG8_LDB(B0, 1, 0); PG8_LDB(B1, 1, 1); PG8_SCHED; PG8_LDA(At, 1, 0); PG8_STAGE(PG8_SA(0, 1), a2 + hstep, voffA);
;             PG8_WAIT_V(8); PG8_WAIT_L(0); PG8_BAR; PG8_MMA(0, 0, At, B0); PG8_MMA(0, 1, At, B1); PG8_BAR; PG8_SCHED;
	s_setprio 1
	s_waitcnt lgkmcnt(0)
	v_mfma_f32_16x16x32_bf16 v[60:63], v[146:149], v[188:191], 0
	v_mfma_f32_16x16x32_bf16 v[56:59], v[160:163], v[188:191], 0
	v_mfma_f32_16x16x32_bf16 v[44:47], v[146:149], v[196:199], 0
	v_mfma_f32_16x16x32_bf16 v[40:43], v[160:163], v[196:199], 0
	v_mfma_f32_16x16x32_bf16 v[28:31], v[146:149], v[210:213], 0
	v_mfma_f32_16x16x32_bf16 v[24:27], v[160:163], v[210:213], 0
	v_mfma_f32_16x16x32_bf16 v[12:15], v[146:149], v[218:221], 0
	v_mfma_f32_16x16x32_bf16 v[8:11], v[160:163], v[218:221], 0
	v_mfma_f32_16x16x32_bf16 v[60:63], v[156:159], v[192:195], v[60:63]
	v_mfma_f32_16x16x32_bf16 v[56:59], v[164:167], v[192:195], v[56:59]
	v_mfma_f32_16x16x32_bf16 v[44:47], v[156:159], v[206:209], v[44:47]
	v_mfma_f32_16x16x32_bf16 v[40:43], v[164:167], v[206:209], v[40:43]
	v_mfma_f32_16x16x32_bf16 v[28:31], v[156:159], v[214:217], v[28:31]
	v_mfma_f32_16x16x32_bf16 v[24:27], v[164:167], v[214:217], v[24:27]
	v_lshl_add_u64 v[228:229], s[56:57], 0, v[134:135]
	s_mov_b32 m0, s58
	s_nop 0
	global_load_lds_dwordx4 v[228:229], off
	v_mfma_f32_16x16x32_bf16 v[12:15], v[156:159], v[222:225], v[12:15]
	v_mfma_f32_16x16x32_bf16 v[8:11], v[164:167], v[222:225], v[8:11]
	s_setprio 0
	s_setprio 1
	v_mfma_f32_16x16x32_bf16 v[52:55], v[168:171], v[188:191], 0
	v_mfma_f32_16x16x32_bf16 v[48:51], v[180:183], v[188:191], 0
	v_mfma_f32_16x16x32_bf16 v[36:39], v[168:171], v[196:199], 0
	v_mfma_f32_16x16x32_bf16 v[32:35], v[180:183], v[196:199], 0
	v_mfma_f32_16x16x32_bf16 v[20:23], v[168:171], v[210:213], 0
	v_mfma_f32_16x16x32_bf16 v[16:19], v[180:183], v[210:213], 0
	v_mfma_f32_16x16x32_bf16 v[4:7], v[168:171], v[218:221], 0
	v_mfma_f32_16x16x32_bf16 v[0:3], v[180:183], v[218:221], 0
	v_mfma_f32_16x16x32_bf16 v[52:55], v[172:175], v[192:195], v[52:55]
	v_mfma_f32_16x16x32_bf16 v[48:51], v[184:187], v[192:195], v[48:51]
	v_mfma_f32_16x16x32_bf16 v[36:39], v[172:175], v[206:209], v[36:39]
	v_mfma_f32_16x16x32_bf16 v[32:35], v[184:187], v[206:209], v[32:35]
	v_mfma_f32_16x16x32_bf16 v[20:23], v[172:175], v[214:217], v[20:23]
	v_mfma_f32_16x16x32_bf16 v[16:19], v[184:187], v[214:217], v[16:19]
	v_lshl_add_u64 v[230:231], s[56:57], 0, v[130:131]
	s_mov_b32 m0, s59
	s_nop 0
	global_load_lds_dwordx4 v[230:231], off
	v_mfma_f32_16x16x32_bf16 v[4:7], v[172:175], v[222:225], v[4:7]
	v_mfma_f32_16x16x32_bf16 v[0:3], v[184:187], v[222:225], v[0:3]
	s_setprio 0
	s_barrier
	s_add_i32 s82, 0, 0x18000
	s_add_i32 s83, 0, 0x1c000
	v_add_u32_e32 v164, s82, v150
	v_add_u32_e32 v179, s83, v150
	ds_read_b128 v[146:149], v164
	ds_read_b128 v[156:159], v164 offset:1024
	ds_read_b128 v[160:163], v164 offset:2048
	ds_read_b128 v[164:167], v164 offset:3072
	ds_read_b128 v[168:171], v179
	ds_read_b128 v[172:175], v179 offset:1024
	ds_read_b128 v[180:183], v179 offset:2048
	ds_read_b128 v[184:187], v179 offset:3072
	s_add_u32 s56, s56, 0x40000
	s_addc_u32 s57, s57, 0
	s_mov_b32 m0, s60
	v_lshl_add_u64 v[232:233], s[56:57], 0, v[134:135]
	ds_read_b128 v[188:191], v154 offset:32768
	ds_read_b128 v[192:195], v154 offset:33792
	ds_read_b128 v[196:199], v154 offset:34816
	ds_read_b128 v[206:209], v154 offset:35840
	ds_read_b128 v[210:213], v154 offset:36864
	ds_read_b128 v[214:217], v154 offset:37888
	ds_read_b128 v[218:221], v154 offset:38912
	ds_read_b128 v[222:225], v154 offset:39936
	global_load_lds_dwordx4 v[232:233], off
	v_lshl_add_u64 v[232:233], s[56:57], 0, v[130:131]
	s_mov_b32 m0, s61
	s_nop 0
	global_load_lds_dwordx4 v[232:233], off
	s_waitcnt vmcnt(8)
	s_waitcnt lgkmcnt(0)
	s_barrier
	s_setprio 1
	s_waitcnt lgkmcnt(0)
	v_mfma_f32_16x16x32_bf16 v[124:127], v[146:149], v[188:191], v[124:127]
	v_mfma_f32_16x16x32_bf16 v[120:123], v[160:163], v[188:191], v[120:123]
	v_mfma_f32_16x16x32_bf16 v[108:111], v[146:149], v[196:199], v[108:111]
	v_mfma_f32_16x16x32_bf16 v[104:107], v[160:163], v[196:199], v[104:107]
	v_mfma_f32_16x16x32_bf16 v[92:95], v[146:149], v[210:213], v[92:95]
	v_mfma_f32_16x16x32_bf16 v[88:91], v[160:163], v[210:213], v[88:91]
	v_mfma_f32_16x16x32_bf16 v[76:79], v[146:149], v[218:221], v[76:79]
	v_mfma_f32_16x16x32_bf16 v[72:75], v[160:163], v[218:221], v[72:75]
	v_mfma_f32_16x16x32_bf16 v[124:127], v[156:159], v[192:195], v[124:127]
	v_mfma_f32_16x16x32_bf16 v[120:123], v[164:167], v[192:195], v[120:123]
	v_mfma_f32_16x16x32_bf16 v[108:111], v[156:159], v[206:209], v[108:111]
	v_mfma_f32_16x16x32_bf16 v[104:107], v[164:167], v[206:209], v[104:107]
	v_mfma_f32_16x16x32_bf16 v[92:95], v[156:159], v[214:217], v[92:95]
	v_mfma_f32_16x16x32_bf16 v[88:91], v[164:167], v[214:217], v[88:91]
	v_mfma_f32_16x16x32_bf16 v[76:79], v[156:159], v[222:225], v[76:79]
	v_mfma_f32_16x16x32_bf16 v[72:75], v[164:167], v[222:225], v[72:75]
	s_setprio 0
	s_setprio 1
	v_mfma_f32_16x16x32_bf16 v[116:119], v[168:171], v[188:191], v[116:119]
	v_mfma_f32_16x16x32_bf16 v[112:115], v[180:183], v[188:191], v[112:115]
	v_mfma_f32_16x16x32_bf16 v[100:103], v[168:171], v[196:199], v[100:103]
	v_mfma_f32_16x16x32_bf16 v[96:99], v[180:183], v[196:199], v[96:99]
	v_mfma_f32_16x16x32_bf16 v[84:87], v[168:171], v[210:213], v[84:87]
	v_mfma_f32_16x16x32_bf16 v[80:83], v[180:183], v[210:213], v[80:83]
	v_mfma_f32_16x16x32_bf16 v[68:71], v[168:171], v[218:221], v[68:71]
	v_mfma_f32_16x16x32_bf16 v[64:67], v[180:183], v[218:221], v[64:67]
	v_mfma_f32_16x16x32_bf16 v[116:119], v[172:175], v[192:195], v[116:119]
	v_mfma_f32_16x16x32_bf16 v[112:115], v[184:187], v[192:195], v[112:115]
	v_mfma_f32_16x16x32_bf16 v[100:103], v[172:175], v[206:209], v[100:103]
	v_mfma_f32_16x16x32_bf16 v[96:99], v[184:187], v[206:209], v[96:99]
	v_mfma_f32_16x16x32_bf16 v[84:87], v[172:175], v[214:217], v[84:87]
	v_mfma_f32_16x16x32_bf16 v[80:83], v[184:187], v[214:217], v[80:83]
	v_mfma_f32_16x16x32_bf16 v[68:71], v[172:175], v[222:225], v[68:71]
	v_mfma_f32_16x16x32_bf16 v[64:67], v[184:187], v[222:225], v[64:67]
	s_setprio 0
	s_barrier
; #define PG8_STAGE(bufoff, gbase, voff) do { _Pragma("unroll") for (int _i = 0; _i < 2; ++_i) \
;         __builtin_amdgcn_global_load_lds((const unsigned*)((const char*)(gbase) + (voff)[_i]), (PG8_LAS unsigned*)(lds + (bufoff) + ldsw + _i * 8192), 16, 0, 0); } while (0)
; #define PG8_LDA(dst, b, h) do { _Pragma("unroll") for (int m = 0; m < 4; ++m) _Pragma("unroll") for (int k = 0; k < 2; ++k) dst[m][k] = *(const PG8_LAS bf16x8*)(lds + PG8_SA(b, h) + aoff + m * 2048 + k * 1024); } while (0)
; #define PG8_MMA(ai, bj, At, Bt) do { __builtin_amdgcn_s_setprio(1); _Pragma("unroll") for (int m = 0; m < 4; ++m) _Pragma("unroll") for (int n = 0; n < 2; ++n) _Pragma("unroll") for (int k = 0; k < 2; ++k) \
;         acc[ai][bj][m][n] = __builtin_amdgcn_mfma_f32_16x16x32_bf16(Bt[n][k], At[m][k], acc[ai][bj][m][n], 0, 0, 0); __builtin_amdgcn_s_setprio(0); } while (0)
; #define PG8_WAIT_V(n) asm volatile("s_waitcnt vmcnt(" #n ")" ::: "memory")
; #define PG8_WAIT_L(n) asm volatile("s_waitcnt lgkmcnt(" #n ")" ::: "memory")
; #define PG8_BAR __builtin_amdgcn_s_barrier()
; #define PG8_SCHED __builtin_amdgcn_sched_barrier(0)
; template <class Epi, class Sched, bool ALIGN_EPI = false, bool SP2 = false>
; __device__ __forceinline__ void gemm_phase(PG8_LAS unsigned char* lds, const Gemm g, const Sched& S, const Epi& E) {
;     ...
;         for (int t = 0; t < nt; t += 2) {
;             const bool last = (t == nt - 2);
;             const char* a1 = cA + (size_t)(t + 1) * kstep;
;             const char* a2 = last ? nA : cA + (size_t)(t + 2) * kstep; const char* b2 = last ? nB : cB + (size_t)(t + 2) * kstep;
;             const char* a3 = a2 + kstep; const char* b3 = b2 + kstep;
;     ...
;             PG8_LDA(At, 1, 1); PG8_STAGE(PG8_SB(1, 0), b3, voffB); PG8_STAGE(PG8_SB(1, 1), b3 + hstep, voffB); PG8_STAGE(PG8_SA(1, 0), a3, voffA);
;             PG8_WAIT_V(8); PG8_WAIT_L(0); PG8_BAR; PG8_MMA(1, 0, At, B0); PG8_MMA(1, 1, At, B1); PG8_BAR; PG8_SCHED;
	s_add_i32 s56, s82, s34
	v_lshl_add_u64 v[200:201], v[200:201], 0, s[26:27]
	s_mov_b32 m0, s56
	ds_read_b128 v[188:191], v154 offset:49152
	ds_read_b128 v[192:195], v154 offset:50176
	ds_read_b128 v[196:199], v154 offset:51200
	ds_read_b128 v[206:209], v154 offset:52224
	ds_read_b128 v[210:213], v154 offset:53248
	ds_read_b128 v[214:217], v154 offset:54272
	ds_read_b128 v[218:221], v154 offset:55296
	ds_read_b128 v[222:225], v154 offset:56320
	global_load_lds_dwordx4 v[200:201], off
	s_add_i32 m0, s56, 0x2000
	s_add_u32 s54, s54, 0x40080
	v_lshl_add_u64 v[200:201], v[226:227], 0, s[26:27]
	s_addc_u32 s55, s55, 0
	s_add_i32 s56, s83, s34
	global_load_lds_dwordx4 v[200:201], off
	v_lshl_add_u64 v[200:201], s[54:55], 0, v[132:133]
	s_mov_b32 m0, s56
	s_nop 0
	global_load_lds_dwordx4 v[200:201], off
	v_lshl_add_u64 v[200:201], s[54:55], 0, v[128:129]
	s_add_i32 m0, s56, 0x2000
	s_nop 0
	global_load_lds_dwordx4 v[200:201], off
	s_waitcnt vmcnt(6)
	s_waitcnt lgkmcnt(0)
	s_barrier
	s_setprio 1
	s_waitcnt lgkmcnt(0)
	v_mfma_f32_16x16x32_bf16 v[60:63], v[146:149], v[188:191], v[60:63]
	v_mfma_f32_16x16x32_bf16 v[56:59], v[160:163], v[188:191], v[56:59]
	v_mfma_f32_16x16x32_bf16 v[44:47], v[146:149], v[196:199], v[44:47]
	v_mfma_f32_16x16x32_bf16 v[40:43], v[160:163], v[196:199], v[40:43]
	v_mfma_f32_16x16x32_bf16 v[28:31], v[146:149], v[210:213], v[28:31]
	v_mfma_f32_16x16x32_bf16 v[24:27], v[160:163], v[210:213], v[24:27]
	v_mfma_f32_16x16x32_bf16 v[12:15], v[146:149], v[218:221], v[12:15]
	v_mfma_f32_16x16x32_bf16 v[8:11], v[160:163], v[218:221], v[8:11]
	v_mfma_f32_16x16x32_bf16 v[60:63], v[156:159], v[192:195], v[60:63]
	v_mfma_f32_16x16x32_bf16 v[56:59], v[164:167], v[192:195], v[56:59]
	v_mfma_f32_16x16x32_bf16 v[44:47], v[156:159], v[206:209], v[44:47]
	v_mfma_f32_16x16x32_bf16 v[40:43], v[164:167], v[206:209], v[40:43]
	v_mfma_f32_16x16x32_bf16 v[28:31], v[156:159], v[214:217], v[28:31]
	v_mfma_f32_16x16x32_bf16 v[24:27], v[164:167], v[214:217], v[24:27]
	v_lshl_add_u64 v[200:201], v[228:229], 0, s[26:27]
	s_mov_b32 m0, s63
	s_nop 0
	global_load_lds_dwordx4 v[200:201], off
	v_mfma_f32_16x16x32_bf16 v[12:15], v[156:159], v[222:225], v[12:15]
	v_mfma_f32_16x16x32_bf16 v[8:11], v[164:167], v[222:225], v[8:11]
	s_setprio 0
	s_setprio 1
	v_mfma_f32_16x16x32_bf16 v[52:55], v[168:171], v[188:191], v[52:55]
	v_mfma_f32_16x16x32_bf16 v[48:51], v[180:183], v[188:191], v[48:51]
	v_mfma_f32_16x16x32_bf16 v[36:39], v[168:171], v[196:199], v[36:39]
	v_mfma_f32_16x16x32_bf16 v[32:35], v[180:183], v[196:199], v[32:35]
	v_mfma_f32_16x16x32_bf16 v[20:23], v[168:171], v[210:213], v[20:23]
	v_mfma_f32_16x16x32_bf16 v[16:19], v[180:183], v[210:213], v[16:19]
	v_mfma_f32_16x16x32_bf16 v[4:7], v[168:171], v[218:221], v[4:7]
	v_mfma_f32_16x16x32_bf16 v[0:3], v[180:183], v[218:221], v[0:3]
	v_mfma_f32_16x16x32_bf16 v[52:55], v[172:175], v[192:195], v[52:55]
	v_mfma_f32_16x16x32_bf16 v[48:51], v[184:187], v[192:195], v[48:51]
	v_mfma_f32_16x16x32_bf16 v[36:39], v[172:175], v[206:209], v[36:39]
	v_mfma_f32_16x16x32_bf16 v[32:35], v[184:187], v[206:209], v[32:35]
	v_mfma_f32_16x16x32_bf16 v[20:23], v[172:175], v[214:217], v[20:23]
	v_mfma_f32_16x16x32_bf16 v[16:19], v[184:187], v[214:217], v[16:19]
	v_lshl_add_u64 v[200:201], v[230:231], 0, s[26:27]
	s_mov_b32 m0, s64
	s_nop 0
	global_load_lds_dwordx4 v[200:201], off
	v_mfma_f32_16x16x32_bf16 v[4:7], v[172:175], v[222:225], v[4:7]
	v_mfma_f32_16x16x32_bf16 v[0:3], v[184:187], v[222:225], v[0:3]
	s_setprio 0
	s_barrier
	s_add_i32 s81, s81, 2
	s_add_u32 s52, s52, 0x100
	s_addc_u32 s53, s53, 0
	s_add_u32 s79, s79, 0x100
	s_addc_u32 s80, s80, 0
	.p2align 6

; #define PG8_STAGE(bufoff, gbase, voff) do { _Pragma("unroll") for (int _i = 0; _i < 2; ++_i) \
;         __builtin_amdgcn_global_load_lds((const unsigned*)((const char*)(gbase) + (voff)[_i]), (PG8_LAS unsigned*)(lds + (bufoff) + ldsw + _i * 8192), 16, 0, 0); } while (0)
; #define PG8_LDA(dst, b, h) do { _Pragma("unroll") for (int m = 0; m < 4; ++m) _Pragma("unroll") for (int k = 0; k < 2; ++k) dst[m][k] = *(const PG8_LAS bf16x8*)(lds + PG8_SA(b, h) + aoff + m * 2048 + k * 1024); } while (0)
; #define PG8_LDB(dst, b, h) do { _Pragma("unroll") for (int n = 0; n < 2; ++n) _Pragma("unroll") for (int k = 0; k < 2; ++k) dst[n][k] = *(const PG8_LAS bf16x8*)(lds + PG8_SB(b, h) + boff + n * 2048 + k * 1024); } while (0)
; #define PG8_WAIT_V(n) asm volatile("s_waitcnt vmcnt(" #n ")" ::: "memory")
; #define PG8_WAIT_L(n) asm volatile("s_waitcnt lgkmcnt(" #n ")" ::: "memory")
; #define PG8_BAR __builtin_amdgcn_s_barrier()
; #define PG8_SCHED __builtin_amdgcn_sched_barrier(0)
; template <class Epi, class Sched, bool ALIGN_EPI = false, bool SP2 = false>
; __device__ __forceinline__ void gemm_phase(PG8_LAS unsigned char* lds, const Gemm g, const Sched& S, const Epi& E) {
;     ...
;         const bool has_next = S.next(ui + 1, nxt);
;         const char* nA = has_next ? (const char*)g.A + (size_t)nxt.pm * tstep : cA; const char* nB = has_next ? (const char*)g.Bt + (size_t)nxt.pn * tstep : cB;
;         for (int t = 0; t < nt; t += 2) {
;             const bool last = (t == nt - 2);
;             const char* a1 = cA + (size_t)(t + 1) * kstep;
;             const char* a2 = last ? nA : cA + (size_t)(t + 2) * kstep; const char* b2 = last ? nB : cB + (size_t)(t + 2) * kstep;
;             const char* a3 = a2 + kstep; const char* b3 = b2 + kstep;
;             if (last && has_next) S.a_ready(nxt);
;             if constexpr (SP2) {
;             PG8_LDB(B0, 0, 0); PG8_LDB(B1, 0, 1); PG8_SCHED; PG8_LDA(At, 0, 0); PG8_STAGE(PG8_SA(1, 1), a1 + hstep, voffA);
;             PG8_WAIT_V(8); PG8_WAIT_L(0); PG8_BAR; PG8_MMA(0, 0, At, B0); PG8_MMA(0, 1, At, B1); PG8_BAR; PG8_SCHED;
;             PG8_LDA(At, 0, 1); PG8_STAGE(PG8_SB(0, 0), b2, voffB); PG8_STAGE(PG8_SB(0, 1), b2 + hstep, voffB); PG8_STAGE(PG8_SA(0, 0), a2, voffA);
;             PG8_WAIT_V(8); PG8_WAIT_L(0); PG8_BAR; PG8_MMA(1, 0, At, B0); PG8_MMA(1, 1, At, B1); PG8_BAR; PG8_SCHED;
.LBB0_1815:
	s_ashr_i32 s29, s28, 31
	s_lshl_b64 s[36:37], s[28:29], 18
	s_add_u32 s36, s92, s36
	s_addc_u32 s37, s93, s37
	s_and_b64 s[38:39], s[6:7], exec
	s_cselect_b32 s29, s37, s45
	s_cselect_b32 s41, s36, s44
	s_ashr_i32 s27, s26, 31
	s_lshl_b64 s[38:39], s[26:27], 18
	s_add_u32 s38, s3, s38
	s_addc_u32 s39, s14, s39
	s_and_b64 s[48:49], s[6:7], exec
	s_cselect_b32 s27, s39, s47
	s_cselect_b32 s58, s38, s46
	s_add_u32 s44, s44, 0x20080
	s_addc_u32 s45, s45, 0
	s_add_u32 s59, s46, 0x100
	s_addc_u32 s60, s47, 0
	s_mov_b32 s61, -2
	s_waitcnt lgkmcnt(0)
	ds_read_b128 v[144:147], v151
	ds_read_b128 v[156:159], v151 offset:1024
	ds_read_b128 v[160:163], v151 offset:2048
	ds_read_b128 v[164:167], v151 offset:3072
	ds_read_b128 v[168:171], v152
	ds_read_b128 v[172:175], v152 offset:1024
	ds_read_b128 v[176:179], v152 offset:2048
	ds_read_b128 v[180:183], v152 offset:3072
	s_add_u32 s46, s44, 0xfffe0080
	s_addc_u32 s47, s45, -1
	s_cmp_eq_u32 s61, 4
	s_cselect_b32 s49, s29, s47
	s_cselect_b32 s48, s41, s46
	s_cselect_b32 s47, s27, s60
	s_cselect_b32 s46, s58, s59
	v_lshl_add_u64 v[218:219], s[44:45], 0, v[136:137]
	s_add_i32 m0, s33, 0xc000
	ds_read_b128 v[184:187], v153
	ds_read_b128 v[188:191], v153 offset:1024
	ds_read_b128 v[192:195], v153 offset:2048
	ds_read_b128 v[196:199], v153 offset:3072
	ds_read_b128 v[200:203], v153 offset:4096
	ds_read_b128 v[206:209], v153 offset:5120
	ds_read_b128 v[210:213], v153 offset:6144
	ds_read_b128 v[214:217], v153 offset:7168
	global_load_lds_dwordx4 v[218:219], off
	v_lshl_add_u64 v[218:219], s[44:45], 0, v[138:139]
	s_add_i32 m0, s33, 0xe000
	s_nop 0
	global_load_lds_dwordx4 v[218:219], off
	s_waitcnt vmcnt(8)
	s_waitcnt lgkmcnt(0)
	s_barrier
	s_setprio 1
	s_waitcnt lgkmcnt(0)
	v_mfma_f32_16x16x32_bf16 v[124:127], v[144:147], v[184:187], 0
	v_mfma_f32_16x16x32_bf16 v[120:123], v[160:163], v[184:187], 0
	v_mfma_f32_16x16x32_bf16 v[108:111], v[144:147], v[192:195], 0
	v_mfma_f32_16x16x32_bf16 v[104:107], v[160:163], v[192:195], 0
	v_mfma_f32_16x16x32_bf16 v[92:95], v[144:147], v[200:203], 0
	v_mfma_f32_16x16x32_bf16 v[88:91], v[160:163], v[200:203], 0
	v_mfma_f32_16x16x32_bf16 v[76:79], v[144:147], v[210:213], 0
	v_mfma_f32_16x16x32_bf16 v[72:75], v[160:163], v[210:213], 0
	v_mfma_f32_16x16x32_bf16 v[124:127], v[156:159], v[188:191], v[124:127]
	v_mfma_f32_16x16x32_bf16 v[120:123], v[164:167], v[188:191], v[120:123]
	v_mfma_f32_16x16x32_bf16 v[108:111], v[156:159], v[196:199], v[108:111]
	v_mfma_f32_16x16x32_bf16 v[104:107], v[164:167], v[196:199], v[104:107]
	v_mfma_f32_16x16x32_bf16 v[92:95], v[156:159], v[206:209], v[92:95]
	v_mfma_f32_16x16x32_bf16 v[88:91], v[164:167], v[206:209], v[88:91]
	v_mfma_f32_16x16x32_bf16 v[76:79], v[156:159], v[214:217], v[76:79]
	v_mfma_f32_16x16x32_bf16 v[72:75], v[164:167], v[214:217], v[72:75]
	s_setprio 0
	s_setprio 1
	v_mfma_f32_16x16x32_bf16 v[116:119], v[168:171], v[184:187], 0
	v_mfma_f32_16x16x32_bf16 v[112:115], v[176:179], v[184:187], 0
	v_mfma_f32_16x16x32_bf16 v[100:103], v[168:171], v[192:195], 0
	v_mfma_f32_16x16x32_bf16 v[96:99], v[176:179], v[192:195], 0
	v_mfma_f32_16x16x32_bf16 v[84:87], v[168:171], v[200:203], 0
	v_mfma_f32_16x16x32_bf16 v[80:83], v[176:179], v[200:203], 0
	v_mfma_f32_16x16x32_bf16 v[68:71], v[168:171], v[210:213], 0
	v_mfma_f32_16x16x32_bf16 v[64:67], v[176:179], v[210:213], 0
	v_mfma_f32_16x16x32_bf16 v[116:119], v[172:175], v[188:191], v[116:119]
	v_mfma_f32_16x16x32_bf16 v[112:115], v[180:183], v[188:191], v[112:115]
	v_mfma_f32_16x16x32_bf16 v[100:103], v[172:175], v[196:199], v[100:103]
	v_mfma_f32_16x16x32_bf16 v[96:99], v[180:183], v[196:199], v[96:99]
	v_mfma_f32_16x16x32_bf16 v[84:87], v[172:175], v[206:209], v[84:87]
	v_mfma_f32_16x16x32_bf16 v[80:83], v[180:183], v[206:209], v[80:83]
	v_mfma_f32_16x16x32_bf16 v[68:71], v[172:175], v[214:217], v[68:71]
	v_mfma_f32_16x16x32_bf16 v[64:67], v[180:183], v[214:217], v[64:67]
	s_setprio 0
	s_barrier
	s_add_i32 s62, s54, s15
	v_lshl_add_u64 v[218:219], s[46:47], 0, v[130:131]
	s_mov_b32 m0, s62
	ds_read_b128 v[184:187], v153 offset:16384
	ds_read_b128 v[188:191], v153 offset:17408
	ds_read_b128 v[192:195], v153 offset:18432
	ds_read_b128 v[196:199], v153 offset:19456
	ds_read_b128 v[200:203], v153 offset:20480
	ds_read_b128 v[206:209], v153 offset:21504
	ds_read_b128 v[210:213], v153 offset:22528
	ds_read_b128 v[214:217], v153 offset:23552
	global_load_lds_dwordx4 v[218:219], off
	s_add_i32 m0, s62, 0x2000
	s_add_u32 s62, s46, 0x20000
	v_lshl_add_u64 v[220:221], s[46:47], 0, v[134:135]
	s_addc_u32 s63, s47, 0
	s_add_i32 s64, s55, s15
	global_load_lds_dwordx4 v[220:221], off
	v_lshl_add_u64 v[222:223], s[62:63], 0, v[130:131]
	s_mov_b32 m0, s64
	global_load_lds_dwordx4 v[222:223], off
	v_lshl_add_u64 v[222:223], s[62:63], 0, v[134:135]
	s_add_i32 m0, s64, 0x2000
	s_nop 0
	global_load_lds_dwordx4 v[222:223], off
	s_waitcnt vmcnt(6)
	s_waitcnt lgkmcnt(0)
	s_barrier
; #define PG8_STAGE(bufoff, gbase, voff) do { _Pragma("unroll") for (int _i = 0; _i < 2; ++_i) \
;         __builtin_amdgcn_global_load_lds((const unsigned*)((const char*)(gbase) + (voff)[_i]), (PG8_LAS unsigned*)(lds + (bufoff) + ldsw + _i * 8192), 16, 0, 0); } while (0)
; #define PG8_LDA(dst, b, h) do { _Pragma("unroll") for (int m = 0; m < 4; ++m) _Pragma("unroll") for (int k = 0; k < 2; ++k) dst[m][k] = *(const PG8_LAS bf16x8*)(lds + PG8_SA(b, h) + aoff + m * 2048 + k * 1024); } while (0)
; #define PG8_LDB(dst, b, h) do { _Pragma("unroll") for (int n = 0; n < 2; ++n) _Pragma("unroll") for (int k = 0; k < 2; ++k) dst[n][k] = *(const PG8_LAS bf16x8*)(lds + PG8_SB(b, h) + boff + n * 2048 + k * 1024); } while (0)
; #define PG8_MMA(ai, bj, At, Bt) do { __builtin_amdgcn_s_setprio(1); _Pragma("unroll") for (int m = 0; m < 4; ++m) _Pragma("unroll") for (int n = 0; n < 2; ++n) _Pragma("unroll") for (int k = 0; k < 2; ++k) \
;         acc[ai][bj][m][n] = __builtin_amdgcn_mfma_f32_16x16x32_bf16(Bt[n][k], At[m][k], acc[ai][bj][m][n], 0, 0, 0); __builtin_amdgcn_s_setprio(0); } while (0)
; #define PG8_WAIT_V(n) asm volatile("s_waitcnt vmcnt(" #n ")" ::: "memory")
; #define PG8_WAIT_L(n) asm volatile("s_waitcnt lgkmcnt(" #n ")" ::: "memory")
; #define PG8_BAR __builtin_amdgcn_s_barrier()
; #define PG8_SCHED __builtin_amdgcn_sched_barrier(0)
; template <class Epi, class Sched, bool ALIGN_EPI = false, bool SP2 = false>
; __device__ __forceinline__ void gemm_phase(PG8_LAS unsigned char* lds, const Gemm g, const Sched& S, const Epi& E) {
;     ...
;             PG8_WAIT_V(8); PG8_WAIT_L(0); PG8_BAR; PG8_MMA(1, 0, At, B0); PG8_MMA(1, 1, At, B1); PG8_BAR; PG8_SCHED;
;             PG8_LDB(B0, 1, 0); PG8_LDB(B1, 1, 1); PG8_SCHED; PG8_LDA(At, 1, 0); PG8_STAGE(PG8_SA(0, 1), a2 + hstep, voffA);
;             PG8_WAIT_V(8); PG8_WAIT_L(0); PG8_BAR; PG8_MMA(0, 0, At, B0); PG8_MMA(0, 1, At, B1); PG8_BAR; PG8_SCHED;
	s_setprio 1
	s_waitcnt lgkmcnt(0)
	v_mfma_f32_16x16x32_bf16 v[60:63], v[144:147], v[184:187], 0
	v_mfma_f32_16x16x32_bf16 v[56:59], v[160:163], v[184:187], 0
	v_mfma_f32_16x16x32_bf16 v[44:47], v[144:147], v[192:195], 0
	v_mfma_f32_16x16x32_bf16 v[40:43], v[160:163], v[192:195], 0
	v_mfma_f32_16x16x32_bf16 v[28:31], v[144:147], v[200:203], 0
	v_mfma_f32_16x16x32_bf16 v[24:27], v[160:163], v[200:203], 0
	v_mfma_f32_16x16x32_bf16 v[12:15], v[144:147], v[210:213], 0
	v_mfma_f32_16x16x32_bf16 v[8:11], v[160:163], v[210:213], 0
	v_mfma_f32_16x16x32_bf16 v[60:63], v[156:159], v[188:191], v[60:63]
	v_mfma_f32_16x16x32_bf16 v[56:59], v[164:167], v[188:191], v[56:59]
	v_mfma_f32_16x16x32_bf16 v[44:47], v[156:159], v[196:199], v[44:47]
	v_mfma_f32_16x16x32_bf16 v[40:43], v[164:167], v[196:199], v[40:43]
	v_mfma_f32_16x16x32_bf16 v[28:31], v[156:159], v[206:209], v[28:31]
	v_mfma_f32_16x16x32_bf16 v[24:27], v[164:167], v[206:209], v[24:27]
	v_lshl_add_u64 v[222:223], s[48:49], 0, v[128:129]
	s_mov_b32 m0, s33
	s_nop 0
	global_load_lds_dwordx4 v[222:223], off
	v_mfma_f32_16x16x32_bf16 v[12:15], v[156:159], v[214:217], v[12:15]
	v_mfma_f32_16x16x32_bf16 v[8:11], v[164:167], v[214:217], v[8:11]
	s_setprio 0
	s_setprio 1
	v_mfma_f32_16x16x32_bf16 v[52:55], v[168:171], v[184:187], 0
	v_mfma_f32_16x16x32_bf16 v[48:51], v[176:179], v[184:187], 0
	v_mfma_f32_16x16x32_bf16 v[36:39], v[168:171], v[192:195], 0
	v_mfma_f32_16x16x32_bf16 v[32:35], v[176:179], v[192:195], 0
	v_mfma_f32_16x16x32_bf16 v[20:23], v[168:171], v[200:203], 0
	v_mfma_f32_16x16x32_bf16 v[16:19], v[176:179], v[200:203], 0
	v_mfma_f32_16x16x32_bf16 v[4:7], v[168:171], v[210:213], 0
	v_mfma_f32_16x16x32_bf16 v[0:3], v[176:179], v[210:213], 0
	v_mfma_f32_16x16x32_bf16 v[52:55], v[172:175], v[188:191], v[52:55]
	v_mfma_f32_16x16x32_bf16 v[48:51], v[180:183], v[188:191], v[48:51]
	v_mfma_f32_16x16x32_bf16 v[36:39], v[172:175], v[196:199], v[36:39]
	v_mfma_f32_16x16x32_bf16 v[32:35], v[180:183], v[196:199], v[32:35]
	v_mfma_f32_16x16x32_bf16 v[20:23], v[172:175], v[206:209], v[20:23]
	v_mfma_f32_16x16x32_bf16 v[16:19], v[180:183], v[206:209], v[16:19]
	v_lshl_add_u64 v[224:225], s[48:49], 0, v[132:133]
	s_mov_b32 m0, s34
	s_nop 0
	global_load_lds_dwordx4 v[224:225], off
	v_mfma_f32_16x16x32_bf16 v[4:7], v[172:175], v[214:217], v[4:7]
	v_mfma_f32_16x16x32_bf16 v[0:3], v[180:183], v[214:217], v[0:3]
	s_setprio 0
	s_barrier
	s_add_i32 s62, 0, 0x18000
	v_add_u32_e32 v155, s62, v149
	s_add_i32 s63, 0, 0x1c000
	ds_read_b128 v[144:147], v155
	ds_read_b128 v[156:159], v155 offset:1024
	ds_read_b128 v[160:163], v155 offset:2048
	ds_read_b128 v[164:167], v155 offset:3072
	v_add_u32_e32 v155, s63, v149
	ds_read_b128 v[168:171], v155
	ds_read_b128 v[172:175], v155 offset:1024
	ds_read_b128 v[176:179], v155 offset:2048
	ds_read_b128 v[180:183], v155 offset:3072
	s_add_u32 s48, s48, 0x20000
	s_addc_u32 s49, s49, 0
	s_mov_b32 m0, s43
	v_lshl_add_u64 v[226:227], s[48:49], 0, v[128:129]
	ds_read_b128 v[184:187], v153 offset:32768
	ds_read_b128 v[188:191], v153 offset:33792
	ds_read_b128 v[192:195], v153 offset:34816
	ds_read_b128 v[196:199], v153 offset:35840
	ds_read_b128 v[200:203], v153 offset:36864
	ds_read_b128 v[206:209], v153 offset:37888
	ds_read_b128 v[210:213], v153 offset:38912
	ds_read_b128 v[214:217], v153 offset:39936
	global_load_lds_dwordx4 v[226:227], off
	v_lshl_add_u64 v[226:227], s[48:49], 0, v[132:133]
	s_mov_b32 m0, s50
	s_nop 0
	global_load_lds_dwordx4 v[226:227], off
	s_waitcnt vmcnt(8)
	s_waitcnt lgkmcnt(0)
	s_barrier
	s_setprio 1
	s_waitcnt lgkmcnt(0)
	v_mfma_f32_16x16x32_bf16 v[124:127], v[144:147], v[184:187], v[124:127]
	v_mfma_f32_16x16x32_bf16 v[120:123], v[160:163], v[184:187], v[120:123]
	v_mfma_f32_16x16x32_bf16 v[108:111], v[144:147], v[192:195], v[108:111]
	v_mfma_f32_16x16x32_bf16 v[104:107], v[160:163], v[192:195], v[104:107]
	v_mfma_f32_16x16x32_bf16 v[92:95], v[144:147], v[200:203], v[92:95]
	v_mfma_f32_16x16x32_bf16 v[88:91], v[160:163], v[200:203], v[88:91]
	v_mfma_f32_16x16x32_bf16 v[76:79], v[144:147], v[210:213], v[76:79]
	v_mfma_f32_16x16x32_bf16 v[72:75], v[160:163], v[210:213], v[72:75]
	v_mfma_f32_16x16x32_bf16 v[124:127], v[156:159], v[188:191], v[124:127]
	v_mfma_f32_16x16x32_bf16 v[120:123], v[164:167], v[188:191], v[120:123]
	v_mfma_f32_16x16x32_bf16 v[108:111], v[156:159], v[196:199], v[108:111]
	v_mfma_f32_16x16x32_bf16 v[104:107], v[164:167], v[196:199], v[104:107]
	v_mfma_f32_16x16x32_bf16 v[92:95], v[156:159], v[206:209], v[92:95]
	v_mfma_f32_16x16x32_bf16 v[88:91], v[164:167], v[206:209], v[88:91]
	v_mfma_f32_16x16x32_bf16 v[76:79], v[156:159], v[214:217], v[76:79]
	v_mfma_f32_16x16x32_bf16 v[72:75], v[164:167], v[214:217], v[72:75]
	s_setprio 0
	s_setprio 1
	v_mfma_f32_16x16x32_bf16 v[116:119], v[168:171], v[184:187], v[116:119]
	v_mfma_f32_16x16x32_bf16 v[112:115], v[176:179], v[184:187], v[112:115]
	v_mfma_f32_16x16x32_bf16 v[100:103], v[168:171], v[192:195], v[100:103]
	v_mfma_f32_16x16x32_bf16 v[96:99], v[176:179], v[192:195], v[96:99]
	v_mfma_f32_16x16x32_bf16 v[84:87], v[168:171], v[200:203], v[84:87]
	v_mfma_f32_16x16x32_bf16 v[80:83], v[176:179], v[200:203], v[80:83]
	v_mfma_f32_16x16x32_bf16 v[68:71], v[168:171], v[210:213], v[68:71]
	v_mfma_f32_16x16x32_bf16 v[64:67], v[176:179], v[210:213], v[64:67]
	v_mfma_f32_16x16x32_bf16 v[116:119], v[172:175], v[188:191], v[116:119]
	v_mfma_f32_16x16x32_bf16 v[112:115], v[180:183], v[188:191], v[112:115]
	v_mfma_f32_16x16x32_bf16 v[100:103], v[172:175], v[196:199], v[100:103]
	v_mfma_f32_16x16x32_bf16 v[96:99], v[180:183], v[196:199], v[96:99]
	v_mfma_f32_16x16x32_bf16 v[84:87], v[172:175], v[206:209], v[84:87]
	v_mfma_f32_16x16x32_bf16 v[80:83], v[180:183], v[206:209], v[80:83]
	v_mfma_f32_16x16x32_bf16 v[68:71], v[172:175], v[214:217], v[68:71]
	v_mfma_f32_16x16x32_bf16 v[64:67], v[180:183], v[214:217], v[64:67]
	s_setprio 0
	s_barrier
; #define PG8_STAGE(bufoff, gbase, voff) do { _Pragma("unroll") for (int _i = 0; _i < 2; ++_i) \
;         __builtin_amdgcn_global_load_lds((const unsigned*)((const char*)(gbase) + (voff)[_i]), (PG8_LAS unsigned*)(lds + (bufoff) + ldsw + _i * 8192), 16, 0, 0); } while (0)
; #define PG8_LDA(dst, b, h) do { _Pragma("unroll") for (int m = 0; m < 4; ++m) _Pragma("unroll") for (int k = 0; k < 2; ++k) dst[m][k] = *(const PG8_LAS bf16x8*)(lds + PG8_SA(b, h) + aoff + m * 2048 + k * 1024); } while (0)
; #define PG8_MMA(ai, bj, At, Bt) do { __builtin_amdgcn_s_setprio(1); _Pragma("unroll") for (int m = 0; m < 4; ++m) _Pragma("unroll") for (int n = 0; n < 2; ++n) _Pragma("unroll") for (int k = 0; k < 2; ++k) \
;         acc[ai][bj][m][n] = __builtin_amdgcn_mfma_f32_16x16x32_bf16(Bt[n][k], At[m][k], acc[ai][bj][m][n], 0, 0, 0); __builtin_amdgcn_s_setprio(0); } while (0)
; #define PG8_WAIT_V(n) asm volatile("s_waitcnt vmcnt(" #n ")" ::: "memory")
; #define PG8_WAIT_L(n) asm volatile("s_waitcnt lgkmcnt(" #n ")" ::: "memory")
; #define PG8_BAR __builtin_amdgcn_s_barrier()
; #define PG8_SCHED __builtin_amdgcn_sched_barrier(0)
; template <class Epi, class Sched, bool ALIGN_EPI = false, bool SP2 = false>
; __device__ __forceinline__ void gemm_phase(PG8_LAS unsigned char* lds, const Gemm g, const Sched& S, const Epi& E) {
;     ...
;         for (int t = 0; t < nt; t += 2) {
;             const bool last = (t == nt - 2);
;             const char* a1 = cA + (size_t)(t + 1) * kstep;
;             const char* a2 = last ? nA : cA + (size_t)(t + 2) * kstep; const char* b2 = last ? nB : cB + (size_t)(t + 2) * kstep;
;             const char* a3 = a2 + kstep; const char* b3 = b2 + kstep;
;     ...
;             PG8_LDA(At, 1, 1); PG8_STAGE(PG8_SB(1, 0), b3, voffB); PG8_STAGE(PG8_SB(1, 1), b3 + hstep, voffB); PG8_STAGE(PG8_SA(1, 0), a3, voffA);
;             PG8_WAIT_V(8); PG8_WAIT_L(0); PG8_BAR; PG8_MMA(1, 0, At, B0); PG8_MMA(1, 1, At, B1); PG8_BAR; PG8_SCHED;
	s_add_i32 s48, s62, s15
	v_lshl_add_u64 v[218:219], v[218:219], 0, s[12:13]
	s_mov_b32 m0, s48
	ds_read_b128 v[184:187], v153 offset:49152
	ds_read_b128 v[188:191], v153 offset:50176
	ds_read_b128 v[192:195], v153 offset:51200
	ds_read_b128 v[196:199], v153 offset:52224
	ds_read_b128 v[200:203], v153 offset:53248
	ds_read_b128 v[206:209], v153 offset:54272
	ds_read_b128 v[210:213], v153 offset:55296
	ds_read_b128 v[214:217], v153 offset:56320
	global_load_lds_dwordx4 v[218:219], off
	s_add_i32 m0, s48, 0x2000
	s_add_u32 s46, s46, 0x20080
	v_lshl_add_u64 v[218:219], v[220:221], 0, s[12:13]
	s_addc_u32 s47, s47, 0
	s_add_i32 s48, s63, s15
	global_load_lds_dwordx4 v[218:219], off
	v_lshl_add_u64 v[218:219], s[46:47], 0, v[130:131]
	s_mov_b32 m0, s48
	s_nop 0
	global_load_lds_dwordx4 v[218:219], off
	v_lshl_add_u64 v[218:219], s[46:47], 0, v[134:135]
	s_add_i32 m0, s48, 0x2000
	s_nop 0
	global_load_lds_dwordx4 v[218:219], off
	s_waitcnt vmcnt(6)
	s_waitcnt lgkmcnt(0)
	s_barrier
	s_setprio 1
	s_waitcnt lgkmcnt(0)
	v_mfma_f32_16x16x32_bf16 v[60:63], v[144:147], v[184:187], v[60:63]
	v_mfma_f32_16x16x32_bf16 v[56:59], v[160:163], v[184:187], v[56:59]
	v_mfma_f32_16x16x32_bf16 v[44:47], v[144:147], v[192:195], v[44:47]
	v_mfma_f32_16x16x32_bf16 v[40:43], v[160:163], v[192:195], v[40:43]
	v_mfma_f32_16x16x32_bf16 v[28:31], v[144:147], v[200:203], v[28:31]
	v_mfma_f32_16x16x32_bf16 v[24:27], v[160:163], v[200:203], v[24:27]
	v_mfma_f32_16x16x32_bf16 v[12:15], v[144:147], v[210:213], v[12:15]
	v_mfma_f32_16x16x32_bf16 v[8:11], v[160:163], v[210:213], v[8:11]
	v_mfma_f32_16x16x32_bf16 v[60:63], v[156:159], v[188:191], v[60:63]
	v_mfma_f32_16x16x32_bf16 v[56:59], v[164:167], v[188:191], v[56:59]
	v_mfma_f32_16x16x32_bf16 v[44:47], v[156:159], v[196:199], v[44:47]
	v_mfma_f32_16x16x32_bf16 v[40:43], v[164:167], v[196:199], v[40:43]
	v_mfma_f32_16x16x32_bf16 v[28:31], v[156:159], v[206:209], v[28:31]
	v_mfma_f32_16x16x32_bf16 v[24:27], v[164:167], v[206:209], v[24:27]
	v_lshl_add_u64 v[218:219], v[222:223], 0, s[12:13]
	s_mov_b32 m0, s52
	s_nop 0
	global_load_lds_dwordx4 v[218:219], off
	v_mfma_f32_16x16x32_bf16 v[12:15], v[156:159], v[214:217], v[12:15]
	v_mfma_f32_16x16x32_bf16 v[8:11], v[164:167], v[214:217], v[8:11]
	s_setprio 0
	s_setprio 1
	v_mfma_f32_16x16x32_bf16 v[52:55], v[168:171], v[184:187], v[52:55]
	v_mfma_f32_16x16x32_bf16 v[48:51], v[176:179], v[184:187], v[48:51]
	v_mfma_f32_16x16x32_bf16 v[36:39], v[168:171], v[192:195], v[36:39]
	v_mfma_f32_16x16x32_bf16 v[32:35], v[176:179], v[192:195], v[32:35]
	v_mfma_f32_16x16x32_bf16 v[20:23], v[168:171], v[200:203], v[20:23]
	v_mfma_f32_16x16x32_bf16 v[16:19], v[176:179], v[200:203], v[16:19]
	v_mfma_f32_16x16x32_bf16 v[4:7], v[168:171], v[210:213], v[4:7]
	v_mfma_f32_16x16x32_bf16 v[0:3], v[176:179], v[210:213], v[0:3]
	v_mfma_f32_16x16x32_bf16 v[52:55], v[172:175], v[188:191], v[52:55]
	v_mfma_f32_16x16x32_bf16 v[48:51], v[180:183], v[188:191], v[48:51]
	v_mfma_f32_16x16x32_bf16 v[36:39], v[172:175], v[196:199], v[36:39]
	v_mfma_f32_16x16x32_bf16 v[32:35], v[180:183], v[196:199], v[32:35]
	v_mfma_f32_16x16x32_bf16 v[20:23], v[172:175], v[206:209], v[20:23]
	v_mfma_f32_16x16x32_bf16 v[16:19], v[180:183], v[206:209], v[16:19]
	v_lshl_add_u64 v[218:219], v[224:225], 0, s[12:13]
	s_mov_b32 m0, s53
	s_nop 0
	global_load_lds_dwordx4 v[218:219], off
	v_mfma_f32_16x16x32_bf16 v[4:7], v[172:175], v[214:217], v[4:7]
	v_mfma_f32_16x16x32_bf16 v[0:3], v[180:183], v[214:217], v[0:3]
	s_setprio 0
	s_barrier
	s_add_i32 s61, s61, 2
	s_add_u32 s44, s44, 0x100
	s_addc_u32 s45, s45, 0
	s_add_u32 s59, s59, 0x100
	s_addc_u32 s60, s60, 0
	.p2align 6

; #define PG8_STAGE(bufoff, gbase, voff) do { _Pragma("unroll") for (int _i = 0; _i < 2; ++_i) \
;         __builtin_amdgcn_global_load_lds((const unsigned*)((const char*)(gbase) + (voff)[_i]), (PG8_LAS unsigned*)(lds + (bufoff) + ldsw + _i * 8192), 16, 0, 0); } while (0)
; #define PG8_LDA(dst, b, h) do { _Pragma("unroll") for (int m = 0; m < 4; ++m) _Pragma("unroll") for (int k = 0; k < 2; ++k) dst[m][k] = *(const PG8_LAS bf16x8*)(lds + PG8_SA(b, h) + aoff + m * 2048 + k * 1024); } while (0)
; #define PG8_LDB(dst, b, h) do { _Pragma("unroll") for (int n = 0; n < 2; ++n) _Pragma("unroll") for (int k = 0; k < 2; ++k) dst[n][k] = *(const PG8_LAS bf16x8*)(lds + PG8_SB(b, h) + boff + n * 2048 + k * 1024); } while (0)
; #define PG8_WAIT_V(n) asm volatile("s_waitcnt vmcnt(" #n ")" ::: "memory")
; #define PG8_WAIT_L(n) asm volatile("s_waitcnt lgkmcnt(" #n ")" ::: "memory")
; #define PG8_BAR __builtin_amdgcn_s_barrier()
; #define PG8_SCHED __builtin_amdgcn_sched_barrier(0)
; template <class Epi, class Sched, bool ALIGN_EPI = false, bool SP2 = false>
; __device__ __forceinline__ void gemm_phase(PG8_LAS unsigned char* lds, const Gemm g, const Sched& S, const Epi& E) {
;     ...
;         const bool has_next = S.next(ui + 1, nxt);
;         const char* nA = has_next ? (const char*)g.A + (size_t)nxt.pm * tstep : cA; const char* nB = has_next ? (const char*)g.Bt + (size_t)nxt.pn * tstep : cB;
;         for (int t = 0; t < nt; t += 2) {
;             const bool last = (t == nt - 2);
;             const char* a1 = cA + (size_t)(t + 1) * kstep;
;             const char* a2 = last ? nA : cA + (size_t)(t + 2) * kstep; const char* b2 = last ? nB : cB + (size_t)(t + 2) * kstep;
;             const char* a3 = a2 + kstep; const char* b3 = b2 + kstep;
;             if (last && has_next) S.a_ready(nxt);
;             if constexpr (SP2) {
;             PG8_LDB(B0, 0, 0); PG8_LDB(B1, 0, 1); PG8_SCHED; PG8_LDA(At, 0, 0); PG8_STAGE(PG8_SA(1, 1), a1 + hstep, voffA);
;             PG8_WAIT_V(8); PG8_WAIT_L(0); PG8_BAR; PG8_MMA(0, 0, At, B0); PG8_MMA(0, 1, At, B1); PG8_BAR; PG8_SCHED;
;             PG8_LDA(At, 0, 1); PG8_STAGE(PG8_SB(0, 0), b2, voffB); PG8_STAGE(PG8_SB(0, 1), b2 + hstep, voffB); PG8_STAGE(PG8_SA(0, 0), a2, voffA);
;             PG8_WAIT_V(8); PG8_WAIT_L(0); PG8_BAR; PG8_MMA(1, 0, At, B0); PG8_MMA(1, 1, At, B1); PG8_BAR; PG8_SCHED;
.LBB0_1899:
	s_ashr_i32 s25, s24, 31
	s_lshl_b64 s[26:27], s[24:25], 19
	s_add_u32 s26, s22, s26
	s_addc_u32 s27, s23, s27
	s_and_b64 s[28:29], s[4:5], exec
	s_cselect_b32 s25, s27, s39
	s_cselect_b32 s53, s26, s38
	s_ashr_i32 s13, s12, 31
	s_lshl_b64 s[28:29], s[12:13], 19
	s_add_u32 s28, s3, s28
	s_addc_u32 s29, s14, s29
	s_and_b64 s[42:43], s[4:5], exec
	s_cselect_b32 s13, s29, s41
	s_cselect_b32 s54, s28, s40
	s_add_u32 s38, s38, 0x40080
	s_addc_u32 s39, s39, 0
	s_add_u32 s55, s40, 0x100
	s_addc_u32 s56, s41, 0
	s_mov_b32 s57, -2
	ds_read_b128 v[144:147], v155
	ds_read_b128 v[148:151], v155 offset:1024
	ds_read_b128 v[160:163], v155 offset:2048
	ds_read_b128 v[164:167], v155 offset:3072
	ds_read_b128 v[168:171], v156
	ds_read_b128 v[172:175], v156 offset:1024
	ds_read_b128 v[176:179], v156 offset:2048
	ds_read_b128 v[180:183], v156 offset:3072
	s_add_u32 s40, s38, 0xfffc0080
	s_addc_u32 s41, s39, -1
	s_cmp_eq_u32 s57, 12
	s_cselect_b32 s43, s25, s41
	s_cselect_b32 s42, s53, s40
	s_cselect_b32 s41, s13, s56
	s_cselect_b32 s40, s54, s55
	v_lshl_add_u64 v[218:219], s[38:39], 0, v[136:137]
	s_add_i32 m0, s34, 0xc000
	ds_read_b128 v[184:187], v157
	ds_read_b128 v[188:191], v157 offset:1024
	ds_read_b128 v[192:195], v157 offset:2048
	ds_read_b128 v[196:199], v157 offset:3072
	ds_read_b128 v[200:203], v157 offset:4096
	ds_read_b128 v[206:209], v157 offset:5120
	ds_read_b128 v[210:213], v157 offset:6144
	ds_read_b128 v[214:217], v157 offset:7168
	global_load_lds_dwordx4 v[218:219], off
	v_lshl_add_u64 v[218:219], s[38:39], 0, v[138:139]
	s_add_i32 m0, s34, 0xe000
	s_nop 0
	global_load_lds_dwordx4 v[218:219], off
	s_waitcnt vmcnt(8)
	s_waitcnt lgkmcnt(0)
	s_barrier
	s_setprio 1
	s_waitcnt lgkmcnt(0)
	v_mfma_f32_16x16x32_bf16 v[124:127], v[144:147], v[184:187], 0
	v_mfma_f32_16x16x32_bf16 v[120:123], v[160:163], v[184:187], 0
	v_mfma_f32_16x16x32_bf16 v[108:111], v[144:147], v[192:195], 0
	v_mfma_f32_16x16x32_bf16 v[104:107], v[160:163], v[192:195], 0
	v_mfma_f32_16x16x32_bf16 v[92:95], v[144:147], v[200:203], 0
	v_mfma_f32_16x16x32_bf16 v[88:91], v[160:163], v[200:203], 0
	v_mfma_f32_16x16x32_bf16 v[76:79], v[144:147], v[210:213], 0
	v_mfma_f32_16x16x32_bf16 v[72:75], v[160:163], v[210:213], 0
	v_mfma_f32_16x16x32_bf16 v[124:127], v[148:151], v[188:191], v[124:127]
	v_mfma_f32_16x16x32_bf16 v[120:123], v[164:167], v[188:191], v[120:123]
	v_mfma_f32_16x16x32_bf16 v[108:111], v[148:151], v[196:199], v[108:111]
	v_mfma_f32_16x16x32_bf16 v[104:107], v[164:167], v[196:199], v[104:107]
	v_mfma_f32_16x16x32_bf16 v[92:95], v[148:151], v[206:209], v[92:95]
	v_mfma_f32_16x16x32_bf16 v[88:91], v[164:167], v[206:209], v[88:91]
	v_mfma_f32_16x16x32_bf16 v[76:79], v[148:151], v[214:217], v[76:79]
	v_mfma_f32_16x16x32_bf16 v[72:75], v[164:167], v[214:217], v[72:75]
	s_setprio 0
	s_setprio 1
	v_mfma_f32_16x16x32_bf16 v[116:119], v[168:171], v[184:187], 0
	v_mfma_f32_16x16x32_bf16 v[112:115], v[176:179], v[184:187], 0
	v_mfma_f32_16x16x32_bf16 v[100:103], v[168:171], v[192:195], 0
	v_mfma_f32_16x16x32_bf16 v[96:99], v[176:179], v[192:195], 0
	v_mfma_f32_16x16x32_bf16 v[84:87], v[168:171], v[200:203], 0
	v_mfma_f32_16x16x32_bf16 v[80:83], v[176:179], v[200:203], 0
	v_mfma_f32_16x16x32_bf16 v[68:71], v[168:171], v[210:213], 0
	v_mfma_f32_16x16x32_bf16 v[64:67], v[176:179], v[210:213], 0
	v_mfma_f32_16x16x32_bf16 v[116:119], v[172:175], v[188:191], v[116:119]
	v_mfma_f32_16x16x32_bf16 v[112:115], v[180:183], v[188:191], v[112:115]
	v_mfma_f32_16x16x32_bf16 v[100:103], v[172:175], v[196:199], v[100:103]
	v_mfma_f32_16x16x32_bf16 v[96:99], v[180:183], v[196:199], v[96:99]
	v_mfma_f32_16x16x32_bf16 v[84:87], v[172:175], v[206:209], v[84:87]
	v_mfma_f32_16x16x32_bf16 v[80:83], v[180:183], v[206:209], v[80:83]
	v_mfma_f32_16x16x32_bf16 v[68:71], v[172:175], v[214:217], v[68:71]
	v_mfma_f32_16x16x32_bf16 v[64:67], v[180:183], v[214:217], v[64:67]
	s_setprio 0
	s_barrier
	s_add_i32 s58, s49, s15
	v_lshl_add_u64 v[218:219], s[40:41], 0, v[132:133]
	s_mov_b32 m0, s58
	ds_read_b128 v[184:187], v157 offset:16384
	ds_read_b128 v[188:191], v157 offset:17408
	ds_read_b128 v[192:195], v157 offset:18432
	ds_read_b128 v[196:199], v157 offset:19456
	ds_read_b128 v[200:203], v157 offset:20480
	ds_read_b128 v[206:209], v157 offset:21504
	ds_read_b128 v[210:213], v157 offset:22528
	ds_read_b128 v[214:217], v157 offset:23552
	global_load_lds_dwordx4 v[218:219], off
	s_add_i32 m0, s58, 0x2000
	s_add_u32 s58, s40, 0x40000
	v_lshl_add_u64 v[220:221], s[40:41], 0, v[128:129]
	s_addc_u32 s59, s41, 0
	s_add_i32 s60, s50, s15
	global_load_lds_dwordx4 v[220:221], off
	v_lshl_add_u64 v[222:223], s[58:59], 0, v[132:133]
	s_mov_b32 m0, s60
	global_load_lds_dwordx4 v[222:223], off
	v_lshl_add_u64 v[222:223], s[58:59], 0, v[128:129]
	s_add_i32 m0, s60, 0x2000
	s_nop 0
	global_load_lds_dwordx4 v[222:223], off
	s_waitcnt vmcnt(6)
	s_waitcnt lgkmcnt(0)
	s_barrier
; #define PG8_STAGE(bufoff, gbase, voff) do { _Pragma("unroll") for (int _i = 0; _i < 2; ++_i) \
;         __builtin_amdgcn_global_load_lds((const unsigned*)((const char*)(gbase) + (voff)[_i]), (PG8_LAS unsigned*)(lds + (bufoff) + ldsw + _i * 8192), 16, 0, 0); } while (0)
; #define PG8_LDA(dst, b, h) do { _Pragma("unroll") for (int m = 0; m < 4; ++m) _Pragma("unroll") for (int k = 0; k < 2; ++k) dst[m][k] = *(const PG8_LAS bf16x8*)(lds + PG8_SA(b, h) + aoff + m * 2048 + k * 1024); } while (0)
; #define PG8_LDB(dst, b, h) do { _Pragma("unroll") for (int n = 0; n < 2; ++n) _Pragma("unroll") for (int k = 0; k < 2; ++k) dst[n][k] = *(const PG8_LAS bf16x8*)(lds + PG8_SB(b, h) + boff + n * 2048 + k * 1024); } while (0)
; #define PG8_MMA(ai, bj, At, Bt) do { __builtin_amdgcn_s_setprio(1); _Pragma("unroll") for (int m = 0; m < 4; ++m) _Pragma("unroll") for (int n = 0; n < 2; ++n) _Pragma("unroll") for (int k = 0; k < 2; ++k) \
;         acc[ai][bj][m][n] = __builtin_amdgcn_mfma_f32_16x16x32_bf16(Bt[n][k], At[m][k], acc[ai][bj][m][n], 0, 0, 0); __builtin_amdgcn_s_setprio(0); } while (0)
; #define PG8_WAIT_V(n) asm volatile("s_waitcnt vmcnt(" #n ")" ::: "memory")
; #define PG8_WAIT_L(n) asm volatile("s_waitcnt lgkmcnt(" #n ")" ::: "memory")
; #define PG8_BAR __builtin_amdgcn_s_barrier()
; #define PG8_SCHED __builtin_amdgcn_sched_barrier(0)
; template <class Epi, class Sched, bool ALIGN_EPI = false, bool SP2 = false>
; __device__ __forceinline__ void gemm_phase(PG8_LAS unsigned char* lds, const Gemm g, const Sched& S, const Epi& E) {
;     ...
;             PG8_LDA(At, 0, 1); PG8_STAGE(PG8_SB(0, 0), b2, voffB); PG8_STAGE(PG8_SB(0, 1), b2 + hstep, voffB); PG8_STAGE(PG8_SA(0, 0), a2, voffA);
;             PG8_WAIT_V(8); PG8_WAIT_L(0); PG8_BAR; PG8_MMA(1, 0, At, B0); PG8_MMA(1, 1, At, B1); PG8_BAR; PG8_SCHED;
;             PG8_LDB(B0, 1, 0); PG8_LDB(B1, 1, 1); PG8_SCHED; PG8_LDA(At, 1, 0); PG8_STAGE(PG8_SA(0, 1), a2 + hstep, voffA);
;             PG8_WAIT_V(8); PG8_WAIT_L(0); PG8_BAR; PG8_MMA(0, 0, At, B0); PG8_MMA(0, 1, At, B1); PG8_BAR; PG8_SCHED;
	s_setprio 1
	s_waitcnt lgkmcnt(0)
	v_mfma_f32_16x16x32_bf16 v[60:63], v[144:147], v[184:187], 0
	v_mfma_f32_16x16x32_bf16 v[56:59], v[160:163], v[184:187], 0
	v_mfma_f32_16x16x32_bf16 v[44:47], v[144:147], v[192:195], 0
	v_mfma_f32_16x16x32_bf16 v[40:43], v[160:163], v[192:195], 0
	v_mfma_f32_16x16x32_bf16 v[28:31], v[144:147], v[200:203], 0
	v_mfma_f32_16x16x32_bf16 v[24:27], v[160:163], v[200:203], 0
	v_mfma_f32_16x16x32_bf16 v[12:15], v[144:147], v[210:213], 0
	v_mfma_f32_16x16x32_bf16 v[8:11], v[160:163], v[210:213], 0
	v_mfma_f32_16x16x32_bf16 v[60:63], v[148:151], v[188:191], v[60:63]
	v_mfma_f32_16x16x32_bf16 v[56:59], v[164:167], v[188:191], v[56:59]
	v_mfma_f32_16x16x32_bf16 v[44:47], v[148:151], v[196:199], v[44:47]
	v_mfma_f32_16x16x32_bf16 v[40:43], v[164:167], v[196:199], v[40:43]
	v_mfma_f32_16x16x32_bf16 v[28:31], v[148:151], v[206:209], v[28:31]
	v_mfma_f32_16x16x32_bf16 v[24:27], v[164:167], v[206:209], v[24:27]
	v_lshl_add_u64 v[222:223], s[42:43], 0, v[134:135]
	s_mov_b32 m0, s34
	s_nop 0
	global_load_lds_dwordx4 v[222:223], off
	v_mfma_f32_16x16x32_bf16 v[12:15], v[148:151], v[214:217], v[12:15]
	v_mfma_f32_16x16x32_bf16 v[8:11], v[164:167], v[214:217], v[8:11]
	s_setprio 0
	s_setprio 1
	v_mfma_f32_16x16x32_bf16 v[52:55], v[168:171], v[184:187], 0
	v_mfma_f32_16x16x32_bf16 v[48:51], v[176:179], v[184:187], 0
	v_mfma_f32_16x16x32_bf16 v[36:39], v[168:171], v[192:195], 0
	v_mfma_f32_16x16x32_bf16 v[32:35], v[176:179], v[192:195], 0
	v_mfma_f32_16x16x32_bf16 v[20:23], v[168:171], v[200:203], 0
	v_mfma_f32_16x16x32_bf16 v[16:19], v[176:179], v[200:203], 0
	v_mfma_f32_16x16x32_bf16 v[4:7], v[168:171], v[210:213], 0
	v_mfma_f32_16x16x32_bf16 v[0:3], v[176:179], v[210:213], 0
	v_mfma_f32_16x16x32_bf16 v[52:55], v[172:175], v[188:191], v[52:55]
	v_mfma_f32_16x16x32_bf16 v[48:51], v[180:183], v[188:191], v[48:51]
	v_mfma_f32_16x16x32_bf16 v[36:39], v[172:175], v[196:199], v[36:39]
	v_mfma_f32_16x16x32_bf16 v[32:35], v[180:183], v[196:199], v[32:35]
	v_mfma_f32_16x16x32_bf16 v[20:23], v[172:175], v[206:209], v[20:23]
	v_mfma_f32_16x16x32_bf16 v[16:19], v[180:183], v[206:209], v[16:19]
	v_lshl_add_u64 v[224:225], s[42:43], 0, v[130:131]
	s_mov_b32 m0, s37
	s_nop 0
	global_load_lds_dwordx4 v[224:225], off
	v_mfma_f32_16x16x32_bf16 v[4:7], v[172:175], v[214:217], v[4:7]
	v_mfma_f32_16x16x32_bf16 v[0:3], v[180:183], v[214:217], v[0:3]
	s_setprio 0
	s_barrier
	s_add_i32 s58, 0, 0x18000
	v_add_u32_e32 v159, s58, v153
	s_add_i32 s59, 0, 0x1c000
	ds_read_b128 v[144:147], v159
	ds_read_b128 v[148:151], v159 offset:1024
	ds_read_b128 v[160:163], v159 offset:2048
	ds_read_b128 v[164:167], v159 offset:3072
	v_add_u32_e32 v159, s59, v153
	ds_read_b128 v[168:171], v159
	ds_read_b128 v[172:175], v159 offset:1024
	ds_read_b128 v[176:179], v159 offset:2048
	ds_read_b128 v[180:183], v159 offset:3072
	s_add_u32 s42, s42, 0x40000
	s_addc_u32 s43, s43, 0
	s_mov_b32 m0, s44
	v_lshl_add_u64 v[226:227], s[42:43], 0, v[134:135]
	ds_read_b128 v[184:187], v157 offset:32768
	ds_read_b128 v[188:191], v157 offset:33792
	ds_read_b128 v[192:195], v157 offset:34816
	ds_read_b128 v[196:199], v157 offset:35840
	ds_read_b128 v[200:203], v157 offset:36864
	ds_read_b128 v[206:209], v157 offset:37888
	ds_read_b128 v[210:213], v157 offset:38912
	ds_read_b128 v[214:217], v157 offset:39936
	global_load_lds_dwordx4 v[226:227], off
	v_lshl_add_u64 v[226:227], s[42:43], 0, v[130:131]
	s_mov_b32 m0, s45
	s_nop 0
	global_load_lds_dwordx4 v[226:227], off
	s_waitcnt vmcnt(8)
	s_waitcnt lgkmcnt(0)
	s_barrier
	s_setprio 1
	s_waitcnt lgkmcnt(0)
	v_mfma_f32_16x16x32_bf16 v[124:127], v[144:147], v[184:187], v[124:127]
	v_mfma_f32_16x16x32_bf16 v[120:123], v[160:163], v[184:187], v[120:123]
	v_mfma_f32_16x16x32_bf16 v[108:111], v[144:147], v[192:195], v[108:111]
	v_mfma_f32_16x16x32_bf16 v[104:107], v[160:163], v[192:195], v[104:107]
	v_mfma_f32_16x16x32_bf16 v[92:95], v[144:147], v[200:203], v[92:95]
	v_mfma_f32_16x16x32_bf16 v[88:91], v[160:163], v[200:203], v[88:91]
	v_mfma_f32_16x16x32_bf16 v[76:79], v[144:147], v[210:213], v[76:79]
	v_mfma_f32_16x16x32_bf16 v[72:75], v[160:163], v[210:213], v[72:75]
	v_mfma_f32_16x16x32_bf16 v[124:127], v[148:151], v[188:191], v[124:127]
	v_mfma_f32_16x16x32_bf16 v[120:123], v[164:167], v[188:191], v[120:123]
	v_mfma_f32_16x16x32_bf16 v[108:111], v[148:151], v[196:199], v[108:111]
	v_mfma_f32_16x16x32_bf16 v[104:107], v[164:167], v[196:199], v[104:107]
	v_mfma_f32_16x16x32_bf16 v[92:95], v[148:151], v[206:209], v[92:95]
	v_mfma_f32_16x16x32_bf16 v[88:91], v[164:167], v[206:209], v[88:91]
	v_mfma_f32_16x16x32_bf16 v[76:79], v[148:151], v[214:217], v[76:79]
	v_mfma_f32_16x16x32_bf16 v[72:75], v[164:167], v[214:217], v[72:75]
	s_setprio 0
	s_setprio 1
	v_mfma_f32_16x16x32_bf16 v[116:119], v[168:171], v[184:187], v[116:119]
	v_mfma_f32_16x16x32_bf16 v[112:115], v[176:179], v[184:187], v[112:115]
	v_mfma_f32_16x16x32_bf16 v[100:103], v[168:171], v[192:195], v[100:103]
	v_mfma_f32_16x16x32_bf16 v[96:99], v[176:179], v[192:195], v[96:99]
	v_mfma_f32_16x16x32_bf16 v[84:87], v[168:171], v[200:203], v[84:87]
	v_mfma_f32_16x16x32_bf16 v[80:83], v[176:179], v[200:203], v[80:83]
	v_mfma_f32_16x16x32_bf16 v[68:71], v[168:171], v[210:213], v[68:71]
	v_mfma_f32_16x16x32_bf16 v[64:67], v[176:179], v[210:213], v[64:67]
	v_mfma_f32_16x16x32_bf16 v[116:119], v[172:175], v[188:191], v[116:119]
	v_mfma_f32_16x16x32_bf16 v[112:115], v[180:183], v[188:191], v[112:115]
	v_mfma_f32_16x16x32_bf16 v[100:103], v[172:175], v[196:199], v[100:103]
	v_mfma_f32_16x16x32_bf16 v[96:99], v[180:183], v[196:199], v[96:99]
	v_mfma_f32_16x16x32_bf16 v[84:87], v[172:175], v[206:209], v[84:87]
	v_mfma_f32_16x16x32_bf16 v[80:83], v[180:183], v[206:209], v[80:83]
	v_mfma_f32_16x16x32_bf16 v[68:71], v[172:175], v[214:217], v[68:71]
	v_mfma_f32_16x16x32_bf16 v[64:67], v[180:183], v[214:217], v[64:67]
	s_setprio 0
	s_barrier
; #define PG8_STAGE(bufoff, gbase, voff) do { _Pragma("unroll") for (int _i = 0; _i < 2; ++_i) \
;         __builtin_amdgcn_global_load_lds((const unsigned*)((const char*)(gbase) + (voff)[_i]), (PG8_LAS unsigned*)(lds + (bufoff) + ldsw + _i * 8192), 16, 0, 0); } while (0)
; #define PG8_LDA(dst, b, h) do { _Pragma("unroll") for (int m = 0; m < 4; ++m) _Pragma("unroll") for (int k = 0; k < 2; ++k) dst[m][k] = *(const PG8_LAS bf16x8*)(lds + PG8_SA(b, h) + aoff + m * 2048 + k * 1024); } while (0)
; #define PG8_LDB(dst, b, h) do { _Pragma("unroll") for (int n = 0; n < 2; ++n) _Pragma("unroll") for (int k = 0; k < 2; ++k) dst[n][k] = *(const PG8_LAS bf16x8*)(lds + PG8_SB(b, h) + boff + n * 2048 + k * 1024); } while (0)
; #define PG8_MMA(ai, bj, At, Bt) do { __builtin_amdgcn_s_setprio(1); _Pragma("unroll") for (int m = 0; m < 4; ++m) _Pragma("unroll") for (int n = 0; n < 2; ++n) _Pragma("unroll") for (int k = 0; k < 2; ++k) \
;         acc[ai][bj][m][n] = __builtin_amdgcn_mfma_f32_16x16x32_bf16(Bt[n][k], At[m][k], acc[ai][bj][m][n], 0, 0, 0); __builtin_amdgcn_s_setprio(0); } while (0)
; #define PG8_WAIT_V(n) asm volatile("s_waitcnt vmcnt(" #n ")" ::: "memory")
; #define PG8_WAIT_L(n) asm volatile("s_waitcnt lgkmcnt(" #n ")" ::: "memory")
; #define PG8_BAR __builtin_amdgcn_s_barrier()
; #define PG8_SCHED __builtin_amdgcn_sched_barrier(0)
; template <class Epi, class Sched, bool ALIGN_EPI = false, bool SP2 = false>
; __device__ __forceinline__ void gemm_phase(PG8_LAS unsigned char* lds, const Gemm g, const Sched& S, const Epi& E) {
;     ...
;             PG8_LDB(B0, 1, 0); PG8_LDB(B1, 1, 1); PG8_SCHED; PG8_LDA(At, 1, 0); PG8_STAGE(PG8_SA(0, 1), a2 + hstep, voffA);
;             PG8_WAIT_V(8); PG8_WAIT_L(0); PG8_BAR; PG8_MMA(0, 0, At, B0); PG8_MMA(0, 1, At, B1); PG8_BAR; PG8_SCHED;
;             PG8_LDA(At, 1, 1); PG8_STAGE(PG8_SB(1, 0), b3, voffB); PG8_STAGE(PG8_SB(1, 1), b3 + hstep, voffB); PG8_STAGE(PG8_SA(1, 0), a3, voffA);
;             PG8_WAIT_V(8); PG8_WAIT_L(0); PG8_BAR; PG8_MMA(1, 0, At, B0); PG8_MMA(1, 1, At, B1); PG8_BAR; PG8_SCHED;
	s_add_i32 s42, s58, s15
	v_lshl_add_u64 v[218:219], v[218:219], 0, s[8:9]
	s_mov_b32 m0, s42
	ds_read_b128 v[184:187], v157 offset:49152
	ds_read_b128 v[188:191], v157 offset:50176
	ds_read_b128 v[192:195], v157 offset:51200
	ds_read_b128 v[196:199], v157 offset:52224
	ds_read_b128 v[200:203], v157 offset:53248
	ds_read_b128 v[206:209], v157 offset:54272
	ds_read_b128 v[210:213], v157 offset:55296
	ds_read_b128 v[214:217], v157 offset:56320
	global_load_lds_dwordx4 v[218:219], off
	s_add_i32 m0, s42, 0x2000
	s_add_u32 s40, s40, 0x40080
	v_lshl_add_u64 v[218:219], v[220:221], 0, s[8:9]
	s_addc_u32 s41, s41, 0
	s_add_i32 s42, s59, s15
	global_load_lds_dwordx4 v[218:219], off
	v_lshl_add_u64 v[218:219], s[40:41], 0, v[132:133]
	s_mov_b32 m0, s42
	s_nop 0
	global_load_lds_dwordx4 v[218:219], off
	v_lshl_add_u64 v[218:219], s[40:41], 0, v[128:129]
	s_add_i32 m0, s42, 0x2000
	s_nop 0
	global_load_lds_dwordx4 v[218:219], off
	s_waitcnt vmcnt(6)
	s_waitcnt lgkmcnt(0)
	s_barrier
	s_setprio 1
	s_waitcnt lgkmcnt(0)
	v_mfma_f32_16x16x32_bf16 v[60:63], v[144:147], v[184:187], v[60:63]
	v_mfma_f32_16x16x32_bf16 v[56:59], v[160:163], v[184:187], v[56:59]
	v_mfma_f32_16x16x32_bf16 v[44:47], v[144:147], v[192:195], v[44:47]
	v_mfma_f32_16x16x32_bf16 v[40:43], v[160:163], v[192:195], v[40:43]
	v_mfma_f32_16x16x32_bf16 v[28:31], v[144:147], v[200:203], v[28:31]
	v_mfma_f32_16x16x32_bf16 v[24:27], v[160:163], v[200:203], v[24:27]
	v_mfma_f32_16x16x32_bf16 v[12:15], v[144:147], v[210:213], v[12:15]
	v_mfma_f32_16x16x32_bf16 v[8:11], v[160:163], v[210:213], v[8:11]
	v_mfma_f32_16x16x32_bf16 v[60:63], v[148:151], v[188:191], v[60:63]
	v_mfma_f32_16x16x32_bf16 v[56:59], v[164:167], v[188:191], v[56:59]
	v_mfma_f32_16x16x32_bf16 v[44:47], v[148:151], v[196:199], v[44:47]
	v_mfma_f32_16x16x32_bf16 v[40:43], v[164:167], v[196:199], v[40:43]
	v_mfma_f32_16x16x32_bf16 v[28:31], v[148:151], v[206:209], v[28:31]
	v_mfma_f32_16x16x32_bf16 v[24:27], v[164:167], v[206:209], v[24:27]
	v_lshl_add_u64 v[218:219], v[222:223], 0, s[8:9]
	s_mov_b32 m0, s47
	s_nop 0
	global_load_lds_dwordx4 v[218:219], off
	v_mfma_f32_16x16x32_bf16 v[12:15], v[148:151], v[214:217], v[12:15]
	v_mfma_f32_16x16x32_bf16 v[8:11], v[164:167], v[214:217], v[8:11]
	s_setprio 0
	s_setprio 1
	v_mfma_f32_16x16x32_bf16 v[52:55], v[168:171], v[184:187], v[52:55]
	v_mfma_f32_16x16x32_bf16 v[48:51], v[176:179], v[184:187], v[48:51]
	v_mfma_f32_16x16x32_bf16 v[36:39], v[168:171], v[192:195], v[36:39]
	v_mfma_f32_16x16x32_bf16 v[32:35], v[176:179], v[192:195], v[32:35]
	v_mfma_f32_16x16x32_bf16 v[20:23], v[168:171], v[200:203], v[20:23]
	v_mfma_f32_16x16x32_bf16 v[16:19], v[176:179], v[200:203], v[16:19]
	v_mfma_f32_16x16x32_bf16 v[4:7], v[168:171], v[210:213], v[4:7]
	v_mfma_f32_16x16x32_bf16 v[0:3], v[176:179], v[210:213], v[0:3]
	v_mfma_f32_16x16x32_bf16 v[52:55], v[172:175], v[188:191], v[52:55]
	v_mfma_f32_16x16x32_bf16 v[48:51], v[180:183], v[188:191], v[48:51]
	v_mfma_f32_16x16x32_bf16 v[36:39], v[172:175], v[196:199], v[36:39]
	v_mfma_f32_16x16x32_bf16 v[32:35], v[180:183], v[196:199], v[32:35]
	v_mfma_f32_16x16x32_bf16 v[20:23], v[172:175], v[206:209], v[20:23]
	v_mfma_f32_16x16x32_bf16 v[16:19], v[180:183], v[206:209], v[16:19]
	v_lshl_add_u64 v[218:219], v[224:225], 0, s[8:9]
	s_mov_b32 m0, s48
	s_nop 0
	global_load_lds_dwordx4 v[218:219], off
	v_mfma_f32_16x16x32_bf16 v[4:7], v[172:175], v[214:217], v[4:7]
	v_mfma_f32_16x16x32_bf16 v[0:3], v[180:183], v[214:217], v[0:3]
	s_setprio 0
	s_barrier
	s_add_i32 s57, s57, 2
	s_add_u32 s38, s38, 0x100
	s_addc_u32 s39, s39, 0
	s_add_u32 s55, s55, 0x100
	s_addc_u32 s56, s56, 0
	.p2align 6

; #define PG8_STAGE(bufoff, gbase, voff) do { _Pragma("unroll") for (int _i = 0; _i < 2; ++_i) \
;         __builtin_amdgcn_global_load_lds((const unsigned*)((const char*)(gbase) + (voff)[_i]), (PG8_LAS unsigned*)(lds + (bufoff) + ldsw + _i * 8192), 16, 0, 0); } while (0)
; #define PG8_LDA(dst, b, h) do { _Pragma("unroll") for (int m = 0; m < 4; ++m) _Pragma("unroll") for (int k = 0; k < 2; ++k) dst[m][k] = *(const PG8_LAS bf16x8*)(lds + PG8_SA(b, h) + aoff + m * 2048 + k * 1024); } while (0)
; #define PG8_LDB(dst, b, h) do { _Pragma("unroll") for (int n = 0; n < 2; ++n) _Pragma("unroll") for (int k = 0; k < 2; ++k) dst[n][k] = *(const PG8_LAS bf16x8*)(lds + PG8_SB(b, h) + boff + n * 2048 + k * 1024); } while (0)
; #define PG8_WAIT_V(n) asm volatile("s_waitcnt vmcnt(" #n ")" ::: "memory")
; #define PG8_WAIT_L(n) asm volatile("s_waitcnt lgkmcnt(" #n ")" ::: "memory")
; #define PG8_BAR __builtin_amdgcn_s_barrier()
; #define PG8_SCHED __builtin_amdgcn_sched_barrier(0)
; template <class Epi, class Sched, bool ALIGN_EPI = false, bool SP2 = false>
; __device__ __forceinline__ void gemm_phase(PG8_LAS unsigned char* lds, const Gemm g, const Sched& S, const Epi& E) {
;     ...
;         const bool has_next = S.next(ui + 1, nxt);
;         const char* nA = has_next ? (const char*)g.A + (size_t)nxt.pm * tstep : cA; const char* nB = has_next ? (const char*)g.Bt + (size_t)nxt.pn * tstep : cB;
;         for (int t = 0; t < nt; t += 2) {
;             const bool last = (t == nt - 2);
;             const char* a1 = cA + (size_t)(t + 1) * kstep;
;             const char* a2 = last ? nA : cA + (size_t)(t + 2) * kstep; const char* b2 = last ? nB : cB + (size_t)(t + 2) * kstep;
;             const char* a3 = a2 + kstep; const char* b3 = b2 + kstep;
;             if (last && has_next) S.a_ready(nxt);
;             if constexpr (SP2) {
;             PG8_LDB(B0, 0, 0); PG8_LDB(B1, 0, 1); PG8_SCHED; PG8_LDA(At, 0, 0); PG8_STAGE(PG8_SA(1, 1), a1 + hstep, voffA);
;             PG8_WAIT_V(8); PG8_WAIT_L(0); PG8_BAR; PG8_MMA(0, 0, At, B0); PG8_MMA(0, 1, At, B1); PG8_BAR; PG8_SCHED;
;             PG8_LDA(At, 0, 1); PG8_STAGE(PG8_SB(0, 0), b2, voffB); PG8_STAGE(PG8_SB(0, 1), b2 + hstep, voffB); PG8_STAGE(PG8_SA(0, 0), a2, voffA);
;             PG8_WAIT_V(8); PG8_WAIT_L(0); PG8_BAR; PG8_MMA(1, 0, At, B0); PG8_MMA(1, 1, At, B1); PG8_BAR; PG8_SCHED;
.LBB0_1977:
	s_add_u32 s53, s28, 0x100
	s_addc_u32 s54, s29, 0
	s_mov_b32 s55, -2
	s_waitcnt lgkmcnt(0)
	ds_read_b128 v[144:147], v151
	ds_read_b128 v[156:159], v151 offset:1024
	ds_read_b128 v[160:163], v151 offset:2048
	ds_read_b128 v[164:167], v151 offset:3072
	ds_read_b128 v[168:171], v152
	ds_read_b128 v[172:175], v152 offset:1024
	ds_read_b128 v[176:179], v152 offset:2048
	ds_read_b128 v[180:183], v152 offset:3072
	s_add_u32 s28, s26, 0x100
	s_addc_u32 s29, s27, 0
	s_cmp_eq_u32 s55, 40
	s_cselect_b32 s39, s1, s29
	s_cselect_b32 s38, s0, s28
	s_cselect_b32 s37, s25, s54
	s_cselect_b32 s36, s24, s53
	v_lshl_add_u64 v[218:219], s[26:27], 0, v[136:137]
	s_add_i32 m0, s33, 0xc000
	ds_read_b128 v[184:187], v153
	ds_read_b128 v[188:191], v153 offset:1024
	ds_read_b128 v[192:195], v153 offset:2048
	ds_read_b128 v[196:199], v153 offset:3072
	ds_read_b128 v[200:203], v153 offset:4096
	ds_read_b128 v[206:209], v153 offset:5120
	ds_read_b128 v[210:213], v153 offset:6144
	ds_read_b128 v[214:217], v153 offset:7168
	global_load_lds_dwordx4 v[218:219], off
	v_lshl_add_u64 v[218:219], s[26:27], 0, v[138:139]
	s_add_i32 m0, s33, 0xe000
	s_nop 0
	global_load_lds_dwordx4 v[218:219], off
	s_waitcnt vmcnt(8)
	s_waitcnt lgkmcnt(0)
	s_barrier
	s_setprio 1
	s_waitcnt lgkmcnt(0)
	v_mfma_f32_16x16x32_bf16 v[124:127], v[144:147], v[184:187], 0
	v_mfma_f32_16x16x32_bf16 v[120:123], v[160:163], v[184:187], 0
	v_mfma_f32_16x16x32_bf16 v[108:111], v[144:147], v[192:195], 0
	v_mfma_f32_16x16x32_bf16 v[104:107], v[160:163], v[192:195], 0
	v_mfma_f32_16x16x32_bf16 v[92:95], v[144:147], v[200:203], 0
	v_mfma_f32_16x16x32_bf16 v[88:91], v[160:163], v[200:203], 0
	v_mfma_f32_16x16x32_bf16 v[76:79], v[144:147], v[210:213], 0
	v_mfma_f32_16x16x32_bf16 v[72:75], v[160:163], v[210:213], 0
	v_mfma_f32_16x16x32_bf16 v[124:127], v[156:159], v[188:191], v[124:127]
	v_mfma_f32_16x16x32_bf16 v[120:123], v[164:167], v[188:191], v[120:123]
	v_mfma_f32_16x16x32_bf16 v[108:111], v[156:159], v[196:199], v[108:111]
	v_mfma_f32_16x16x32_bf16 v[104:107], v[164:167], v[196:199], v[104:107]
	v_mfma_f32_16x16x32_bf16 v[92:95], v[156:159], v[206:209], v[92:95]
	v_mfma_f32_16x16x32_bf16 v[88:91], v[164:167], v[206:209], v[88:91]
	v_mfma_f32_16x16x32_bf16 v[76:79], v[156:159], v[214:217], v[76:79]
	v_mfma_f32_16x16x32_bf16 v[72:75], v[164:167], v[214:217], v[72:75]
	s_setprio 0
	s_setprio 1
	v_mfma_f32_16x16x32_bf16 v[116:119], v[168:171], v[184:187], 0
	v_mfma_f32_16x16x32_bf16 v[112:115], v[176:179], v[184:187], 0
	v_mfma_f32_16x16x32_bf16 v[100:103], v[168:171], v[192:195], 0
	v_mfma_f32_16x16x32_bf16 v[96:99], v[176:179], v[192:195], 0
	v_mfma_f32_16x16x32_bf16 v[84:87], v[168:171], v[200:203], 0
	v_mfma_f32_16x16x32_bf16 v[80:83], v[176:179], v[200:203], 0
	v_mfma_f32_16x16x32_bf16 v[68:71], v[168:171], v[210:213], 0
	v_mfma_f32_16x16x32_bf16 v[64:67], v[176:179], v[210:213], 0
	v_mfma_f32_16x16x32_bf16 v[116:119], v[172:175], v[188:191], v[116:119]
	v_mfma_f32_16x16x32_bf16 v[112:115], v[180:183], v[188:191], v[112:115]
	v_mfma_f32_16x16x32_bf16 v[100:103], v[172:175], v[196:199], v[100:103]
	v_mfma_f32_16x16x32_bf16 v[96:99], v[180:183], v[196:199], v[96:99]
	v_mfma_f32_16x16x32_bf16 v[84:87], v[172:175], v[206:209], v[84:87]
	v_mfma_f32_16x16x32_bf16 v[80:83], v[180:183], v[206:209], v[80:83]
	v_mfma_f32_16x16x32_bf16 v[68:71], v[172:175], v[214:217], v[68:71]
	v_mfma_f32_16x16x32_bf16 v[64:67], v[180:183], v[214:217], v[64:67]
	s_setprio 0
	s_barrier
	s_add_i32 s26, s45, s15
	v_lshl_add_u64 v[218:219], s[36:37], 0, v[130:131]
	s_mov_b32 m0, s26
	ds_read_b128 v[184:187], v153 offset:16384
	ds_read_b128 v[188:191], v153 offset:17408
	ds_read_b128 v[192:195], v153 offset:18432
	ds_read_b128 v[196:199], v153 offset:19456
	ds_read_b128 v[200:203], v153 offset:20480
	ds_read_b128 v[206:209], v153 offset:21504
	ds_read_b128 v[210:213], v153 offset:22528
	ds_read_b128 v[214:217], v153 offset:23552
	global_load_lds_dwordx4 v[218:219], off
	s_add_i32 m0, s26, 0x2000
	s_add_u32 s26, s36, 0xb0000
	v_lshl_add_u64 v[220:221], s[36:37], 0, v[134:135]
	s_addc_u32 s27, s37, 0
	s_add_i32 s56, s46, s15
	global_load_lds_dwordx4 v[220:221], off
	v_lshl_add_u64 v[222:223], s[26:27], 0, v[130:131]
	s_mov_b32 m0, s56
	global_load_lds_dwordx4 v[222:223], off
	v_lshl_add_u64 v[222:223], s[26:27], 0, v[134:135]
	s_add_i32 m0, s56, 0x2000
	s_nop 0
	global_load_lds_dwordx4 v[222:223], off
	s_waitcnt vmcnt(6)
	s_waitcnt lgkmcnt(0)
	s_barrier
; #define PG8_STAGE(bufoff, gbase, voff) do { _Pragma("unroll") for (int _i = 0; _i < 2; ++_i) \
;         __builtin_amdgcn_global_load_lds((const unsigned*)((const char*)(gbase) + (voff)[_i]), (PG8_LAS unsigned*)(lds + (bufoff) + ldsw + _i * 8192), 16, 0, 0); } while (0)
; #define PG8_LDA(dst, b, h) do { _Pragma("unroll") for (int m = 0; m < 4; ++m) _Pragma("unroll") for (int k = 0; k < 2; ++k) dst[m][k] = *(const PG8_LAS bf16x8*)(lds + PG8_SA(b, h) + aoff + m * 2048 + k * 1024); } while (0)
; #define PG8_LDB(dst, b, h) do { _Pragma("unroll") for (int n = 0; n < 2; ++n) _Pragma("unroll") for (int k = 0; k < 2; ++k) dst[n][k] = *(const PG8_LAS bf16x8*)(lds + PG8_SB(b, h) + boff + n * 2048 + k * 1024); } while (0)
; #define PG8_MMA(ai, bj, At, Bt) do { __builtin_amdgcn_s_setprio(1); _Pragma("unroll") for (int m = 0; m < 4; ++m) _Pragma("unroll") for (int n = 0; n < 2; ++n) _Pragma("unroll") for (int k = 0; k < 2; ++k) \
;         acc[ai][bj][m][n] = __builtin_amdgcn_mfma_f32_16x16x32_bf16(Bt[n][k], At[m][k], acc[ai][bj][m][n], 0, 0, 0); __builtin_amdgcn_s_setprio(0); } while (0)
; #define PG8_WAIT_V(n) asm volatile("s_waitcnt vmcnt(" #n ")" ::: "memory")
; #define PG8_WAIT_L(n) asm volatile("s_waitcnt lgkmcnt(" #n ")" ::: "memory")
; #define PG8_BAR __builtin_amdgcn_s_barrier()
; #define PG8_SCHED __builtin_amdgcn_sched_barrier(0)
; template <class Epi, class Sched, bool ALIGN_EPI = false, bool SP2 = false>
; __device__ __forceinline__ void gemm_phase(PG8_LAS unsigned char* lds, const Gemm g, const Sched& S, const Epi& E) {
;     ...
;             PG8_LDA(At, 0, 1); PG8_STAGE(PG8_SB(0, 0), b2, voffB); PG8_STAGE(PG8_SB(0, 1), b2 + hstep, voffB); PG8_STAGE(PG8_SA(0, 0), a2, voffA);
;             PG8_WAIT_V(8); PG8_WAIT_L(0); PG8_BAR; PG8_MMA(1, 0, At, B0); PG8_MMA(1, 1, At, B1); PG8_BAR; PG8_SCHED;
;             PG8_LDB(B0, 1, 0); PG8_LDB(B1, 1, 1); PG8_SCHED; PG8_LDA(At, 1, 0); PG8_STAGE(PG8_SA(0, 1), a2 + hstep, voffA);
;             PG8_WAIT_V(8); PG8_WAIT_L(0); PG8_BAR; PG8_MMA(0, 0, At, B0); PG8_MMA(0, 1, At, B1); PG8_BAR; PG8_SCHED;
	s_setprio 1
	s_waitcnt lgkmcnt(0)
	v_mfma_f32_16x16x32_bf16 v[60:63], v[144:147], v[184:187], 0
	v_mfma_f32_16x16x32_bf16 v[56:59], v[160:163], v[184:187], 0
	v_mfma_f32_16x16x32_bf16 v[44:47], v[144:147], v[192:195], 0
	v_mfma_f32_16x16x32_bf16 v[40:43], v[160:163], v[192:195], 0
	v_mfma_f32_16x16x32_bf16 v[28:31], v[144:147], v[200:203], 0
	v_mfma_f32_16x16x32_bf16 v[24:27], v[160:163], v[200:203], 0
	v_mfma_f32_16x16x32_bf16 v[12:15], v[144:147], v[210:213], 0
	v_mfma_f32_16x16x32_bf16 v[8:11], v[160:163], v[210:213], 0
	v_mfma_f32_16x16x32_bf16 v[60:63], v[156:159], v[188:191], v[60:63]
	v_mfma_f32_16x16x32_bf16 v[56:59], v[164:167], v[188:191], v[56:59]
	v_mfma_f32_16x16x32_bf16 v[44:47], v[156:159], v[196:199], v[44:47]
	v_mfma_f32_16x16x32_bf16 v[40:43], v[164:167], v[196:199], v[40:43]
	v_mfma_f32_16x16x32_bf16 v[28:31], v[156:159], v[206:209], v[28:31]
	v_mfma_f32_16x16x32_bf16 v[24:27], v[164:167], v[206:209], v[24:27]
	v_lshl_add_u64 v[222:223], s[38:39], 0, v[128:129]
	s_mov_b32 m0, s33
	s_nop 0
	global_load_lds_dwordx4 v[222:223], off
	v_mfma_f32_16x16x32_bf16 v[12:15], v[156:159], v[214:217], v[12:15]
	v_mfma_f32_16x16x32_bf16 v[8:11], v[164:167], v[214:217], v[8:11]
	s_setprio 0
	s_setprio 1
	v_mfma_f32_16x16x32_bf16 v[52:55], v[168:171], v[184:187], 0
	v_mfma_f32_16x16x32_bf16 v[48:51], v[176:179], v[184:187], 0
	v_mfma_f32_16x16x32_bf16 v[36:39], v[168:171], v[192:195], 0
	v_mfma_f32_16x16x32_bf16 v[32:35], v[176:179], v[192:195], 0
	v_mfma_f32_16x16x32_bf16 v[20:23], v[168:171], v[200:203], 0
	v_mfma_f32_16x16x32_bf16 v[16:19], v[176:179], v[200:203], 0
	v_mfma_f32_16x16x32_bf16 v[4:7], v[168:171], v[210:213], 0
	v_mfma_f32_16x16x32_bf16 v[0:3], v[176:179], v[210:213], 0
	v_mfma_f32_16x16x32_bf16 v[52:55], v[172:175], v[188:191], v[52:55]
	v_mfma_f32_16x16x32_bf16 v[48:51], v[180:183], v[188:191], v[48:51]
	v_mfma_f32_16x16x32_bf16 v[36:39], v[172:175], v[196:199], v[36:39]
	v_mfma_f32_16x16x32_bf16 v[32:35], v[180:183], v[196:199], v[32:35]
	v_mfma_f32_16x16x32_bf16 v[20:23], v[172:175], v[206:209], v[20:23]
	v_mfma_f32_16x16x32_bf16 v[16:19], v[180:183], v[206:209], v[16:19]
	v_lshl_add_u64 v[224:225], s[38:39], 0, v[132:133]
	s_mov_b32 m0, s34
	s_nop 0
	global_load_lds_dwordx4 v[224:225], off
	v_mfma_f32_16x16x32_bf16 v[4:7], v[172:175], v[214:217], v[4:7]
	v_mfma_f32_16x16x32_bf16 v[0:3], v[180:183], v[214:217], v[0:3]
	s_setprio 0
	s_barrier
	s_add_i32 s56, 0, 0x18000
	v_add_u32_e32 v155, s56, v149
	s_add_i32 s57, 0, 0x1c000
	ds_read_b128 v[144:147], v155
	ds_read_b128 v[156:159], v155 offset:1024
	ds_read_b128 v[160:163], v155 offset:2048
	ds_read_b128 v[164:167], v155 offset:3072
	v_add_u32_e32 v155, s57, v149
	ds_read_b128 v[168:171], v155
	ds_read_b128 v[172:175], v155 offset:1024
	ds_read_b128 v[176:179], v155 offset:2048
	ds_read_b128 v[180:183], v155 offset:3072
	s_add_u32 s26, s38, 0xb0000
	s_addc_u32 s27, s39, 0
	s_mov_b32 m0, s40
	v_lshl_add_u64 v[226:227], s[26:27], 0, v[128:129]
	ds_read_b128 v[184:187], v153 offset:32768
	ds_read_b128 v[188:191], v153 offset:33792
	ds_read_b128 v[192:195], v153 offset:34816
	ds_read_b128 v[196:199], v153 offset:35840
	ds_read_b128 v[200:203], v153 offset:36864
	ds_read_b128 v[206:209], v153 offset:37888
	ds_read_b128 v[210:213], v153 offset:38912
	ds_read_b128 v[214:217], v153 offset:39936
	global_load_lds_dwordx4 v[226:227], off
	v_lshl_add_u64 v[226:227], s[26:27], 0, v[132:133]
	s_mov_b32 m0, s41
	s_nop 0
	global_load_lds_dwordx4 v[226:227], off
	s_waitcnt vmcnt(8)
	s_waitcnt lgkmcnt(0)
	s_barrier
	s_setprio 1
	s_waitcnt lgkmcnt(0)
	v_mfma_f32_16x16x32_bf16 v[124:127], v[144:147], v[184:187], v[124:127]
	v_mfma_f32_16x16x32_bf16 v[120:123], v[160:163], v[184:187], v[120:123]
	v_mfma_f32_16x16x32_bf16 v[108:111], v[144:147], v[192:195], v[108:111]
	v_mfma_f32_16x16x32_bf16 v[104:107], v[160:163], v[192:195], v[104:107]
	v_mfma_f32_16x16x32_bf16 v[92:95], v[144:147], v[200:203], v[92:95]
	v_mfma_f32_16x16x32_bf16 v[88:91], v[160:163], v[200:203], v[88:91]
	v_mfma_f32_16x16x32_bf16 v[76:79], v[144:147], v[210:213], v[76:79]
	v_mfma_f32_16x16x32_bf16 v[72:75], v[160:163], v[210:213], v[72:75]
	v_mfma_f32_16x16x32_bf16 v[124:127], v[156:159], v[188:191], v[124:127]
	v_mfma_f32_16x16x32_bf16 v[120:123], v[164:167], v[188:191], v[120:123]
	v_mfma_f32_16x16x32_bf16 v[108:111], v[156:159], v[196:199], v[108:111]
	v_mfma_f32_16x16x32_bf16 v[104:107], v[164:167], v[196:199], v[104:107]
	v_mfma_f32_16x16x32_bf16 v[92:95], v[156:159], v[206:209], v[92:95]
	v_mfma_f32_16x16x32_bf16 v[88:91], v[164:167], v[206:209], v[88:91]
	v_mfma_f32_16x16x32_bf16 v[76:79], v[156:159], v[214:217], v[76:79]
	v_mfma_f32_16x16x32_bf16 v[72:75], v[164:167], v[214:217], v[72:75]
	s_setprio 0
	s_setprio 1
	v_mfma_f32_16x16x32_bf16 v[116:119], v[168:171], v[184:187], v[116:119]
	v_mfma_f32_16x16x32_bf16 v[112:115], v[176:179], v[184:187], v[112:115]
	v_mfma_f32_16x16x32_bf16 v[100:103], v[168:171], v[192:195], v[100:103]
	v_mfma_f32_16x16x32_bf16 v[96:99], v[176:179], v[192:195], v[96:99]
	v_mfma_f32_16x16x32_bf16 v[84:87], v[168:171], v[200:203], v[84:87]
	v_mfma_f32_16x16x32_bf16 v[80:83], v[176:179], v[200:203], v[80:83]
	v_mfma_f32_16x16x32_bf16 v[68:71], v[168:171], v[210:213], v[68:71]
	v_mfma_f32_16x16x32_bf16 v[64:67], v[176:179], v[210:213], v[64:67]
	v_mfma_f32_16x16x32_bf16 v[116:119], v[172:175], v[188:191], v[116:119]
	v_mfma_f32_16x16x32_bf16 v[112:115], v[180:183], v[188:191], v[112:115]
	v_mfma_f32_16x16x32_bf16 v[100:103], v[172:175], v[196:199], v[100:103]
	v_mfma_f32_16x16x32_bf16 v[96:99], v[180:183], v[196:199], v[96:99]
	v_mfma_f32_16x16x32_bf16 v[84:87], v[172:175], v[206:209], v[84:87]
	v_mfma_f32_16x16x32_bf16 v[80:83], v[180:183], v[206:209], v[80:83]
	v_mfma_f32_16x16x32_bf16 v[68:71], v[172:175], v[214:217], v[68:71]
	v_mfma_f32_16x16x32_bf16 v[64:67], v[180:183], v[214:217], v[64:67]
	s_setprio 0
	s_barrier
; #define PG8_STAGE(bufoff, gbase, voff) do { _Pragma("unroll") for (int _i = 0; _i < 2; ++_i) \
;         __builtin_amdgcn_global_load_lds((const unsigned*)((const char*)(gbase) + (voff)[_i]), (PG8_LAS unsigned*)(lds + (bufoff) + ldsw + _i * 8192), 16, 0, 0); } while (0)
; #define PG8_LDA(dst, b, h) do { _Pragma("unroll") for (int m = 0; m < 4; ++m) _Pragma("unroll") for (int k = 0; k < 2; ++k) dst[m][k] = *(const PG8_LAS bf16x8*)(lds + PG8_SA(b, h) + aoff + m * 2048 + k * 1024); } while (0)
; #define PG8_LDB(dst, b, h) do { _Pragma("unroll") for (int n = 0; n < 2; ++n) _Pragma("unroll") for (int k = 0; k < 2; ++k) dst[n][k] = *(const PG8_LAS bf16x8*)(lds + PG8_SB(b, h) + boff + n * 2048 + k * 1024); } while (0)
; #define PG8_MMA(ai, bj, At, Bt) do { __builtin_amdgcn_s_setprio(1); _Pragma("unroll") for (int m = 0; m < 4; ++m) _Pragma("unroll") for (int n = 0; n < 2; ++n) _Pragma("unroll") for (int k = 0; k < 2; ++k) \
;         acc[ai][bj][m][n] = __builtin_amdgcn_mfma_f32_16x16x32_bf16(Bt[n][k], At[m][k], acc[ai][bj][m][n], 0, 0, 0); __builtin_amdgcn_s_setprio(0); } while (0)
; #define PG8_WAIT_V(n) asm volatile("s_waitcnt vmcnt(" #n ")" ::: "memory")
; #define PG8_WAIT_L(n) asm volatile("s_waitcnt lgkmcnt(" #n ")" ::: "memory")
; #define PG8_BAR __builtin_amdgcn_s_barrier()
; #define PG8_SCHED __builtin_amdgcn_sched_barrier(0)
; template <class Epi, class Sched, bool ALIGN_EPI = false, bool SP2 = false>
; __device__ __forceinline__ void gemm_phase(PG8_LAS unsigned char* lds, const Gemm g, const Sched& S, const Epi& E) {
;     ...
;             PG8_LDB(B0, 1, 0); PG8_LDB(B1, 1, 1); PG8_SCHED; PG8_LDA(At, 1, 0); PG8_STAGE(PG8_SA(0, 1), a2 + hstep, voffA);
;             PG8_WAIT_V(8); PG8_WAIT_L(0); PG8_BAR; PG8_MMA(0, 0, At, B0); PG8_MMA(0, 1, At, B1); PG8_BAR; PG8_SCHED;
;             PG8_LDA(At, 1, 1); PG8_STAGE(PG8_SB(1, 0), b3, voffB); PG8_STAGE(PG8_SB(1, 1), b3 + hstep, voffB); PG8_STAGE(PG8_SA(1, 0), a3, voffA);
;             PG8_WAIT_V(8); PG8_WAIT_L(0); PG8_BAR; PG8_MMA(1, 0, At, B0); PG8_MMA(1, 1, At, B1); PG8_BAR; PG8_SCHED;
	s_add_i32 s26, s56, s15
	v_lshl_add_u64 v[218:219], v[218:219], 0, s[12:13]
	s_mov_b32 m0, s26
	ds_read_b128 v[184:187], v153 offset:49152
	ds_read_b128 v[188:191], v153 offset:50176
	ds_read_b128 v[192:195], v153 offset:51200
	ds_read_b128 v[196:199], v153 offset:52224
	ds_read_b128 v[200:203], v153 offset:53248
	ds_read_b128 v[206:209], v153 offset:54272
	ds_read_b128 v[210:213], v153 offset:55296
	ds_read_b128 v[214:217], v153 offset:56320
	global_load_lds_dwordx4 v[218:219], off
	s_add_i32 m0, s26, 0x2000
	s_add_u32 s26, s36, 0xb0080
	v_lshl_add_u64 v[218:219], v[220:221], 0, s[12:13]
	s_addc_u32 s27, s37, 0
	s_add_i32 s36, s57, s15
	global_load_lds_dwordx4 v[218:219], off
	v_lshl_add_u64 v[218:219], s[26:27], 0, v[130:131]
	s_mov_b32 m0, s36
	s_nop 0
	global_load_lds_dwordx4 v[218:219], off
	v_lshl_add_u64 v[218:219], s[26:27], 0, v[134:135]
	s_add_i32 m0, s36, 0x2000
	s_nop 0
	global_load_lds_dwordx4 v[218:219], off
	s_waitcnt vmcnt(6)
	s_waitcnt lgkmcnt(0)
	s_barrier
	s_setprio 1
	s_waitcnt lgkmcnt(0)
	v_mfma_f32_16x16x32_bf16 v[60:63], v[144:147], v[184:187], v[60:63]
	v_mfma_f32_16x16x32_bf16 v[56:59], v[160:163], v[184:187], v[56:59]
	v_mfma_f32_16x16x32_bf16 v[44:47], v[144:147], v[192:195], v[44:47]
	v_mfma_f32_16x16x32_bf16 v[40:43], v[160:163], v[192:195], v[40:43]
	v_mfma_f32_16x16x32_bf16 v[28:31], v[144:147], v[200:203], v[28:31]
	v_mfma_f32_16x16x32_bf16 v[24:27], v[160:163], v[200:203], v[24:27]
	v_mfma_f32_16x16x32_bf16 v[12:15], v[144:147], v[210:213], v[12:15]
	v_mfma_f32_16x16x32_bf16 v[8:11], v[160:163], v[210:213], v[8:11]
	v_mfma_f32_16x16x32_bf16 v[60:63], v[156:159], v[188:191], v[60:63]
	v_mfma_f32_16x16x32_bf16 v[56:59], v[164:167], v[188:191], v[56:59]
	v_mfma_f32_16x16x32_bf16 v[44:47], v[156:159], v[196:199], v[44:47]
	v_mfma_f32_16x16x32_bf16 v[40:43], v[164:167], v[196:199], v[40:43]
	v_mfma_f32_16x16x32_bf16 v[28:31], v[156:159], v[206:209], v[28:31]
	v_mfma_f32_16x16x32_bf16 v[24:27], v[164:167], v[206:209], v[24:27]
	v_lshl_add_u64 v[218:219], v[222:223], 0, s[12:13]
	s_mov_b32 m0, s43
	s_nop 0
	global_load_lds_dwordx4 v[218:219], off
	v_mfma_f32_16x16x32_bf16 v[12:15], v[156:159], v[214:217], v[12:15]
	v_mfma_f32_16x16x32_bf16 v[8:11], v[164:167], v[214:217], v[8:11]
	s_setprio 0
	s_setprio 1
	v_mfma_f32_16x16x32_bf16 v[52:55], v[168:171], v[184:187], v[52:55]
	v_mfma_f32_16x16x32_bf16 v[48:51], v[176:179], v[184:187], v[48:51]
	v_mfma_f32_16x16x32_bf16 v[36:39], v[168:171], v[192:195], v[36:39]
	v_mfma_f32_16x16x32_bf16 v[32:35], v[176:179], v[192:195], v[32:35]
	v_mfma_f32_16x16x32_bf16 v[20:23], v[168:171], v[200:203], v[20:23]
	v_mfma_f32_16x16x32_bf16 v[16:19], v[176:179], v[200:203], v[16:19]
	v_mfma_f32_16x16x32_bf16 v[4:7], v[168:171], v[210:213], v[4:7]
	v_mfma_f32_16x16x32_bf16 v[0:3], v[176:179], v[210:213], v[0:3]
	v_mfma_f32_16x16x32_bf16 v[52:55], v[172:175], v[188:191], v[52:55]
	v_mfma_f32_16x16x32_bf16 v[48:51], v[180:183], v[188:191], v[48:51]
	v_mfma_f32_16x16x32_bf16 v[36:39], v[172:175], v[196:199], v[36:39]
	v_mfma_f32_16x16x32_bf16 v[32:35], v[180:183], v[196:199], v[32:35]
	v_mfma_f32_16x16x32_bf16 v[20:23], v[172:175], v[206:209], v[20:23]
	v_mfma_f32_16x16x32_bf16 v[16:19], v[180:183], v[206:209], v[16:19]
	v_lshl_add_u64 v[218:219], v[224:225], 0, s[12:13]
	s_mov_b32 m0, s44
	s_nop 0
	global_load_lds_dwordx4 v[218:219], off
	v_mfma_f32_16x16x32_bf16 v[4:7], v[172:175], v[214:217], v[4:7]
	v_mfma_f32_16x16x32_bf16 v[0:3], v[180:183], v[214:217], v[0:3]
	s_setprio 0
	s_barrier
	s_add_i32 s55, s55, 2
	s_add_u32 s53, s53, 0x100
	s_addc_u32 s54, s54, 0
	s_mov_b64 s[26:27], s[28:29]
	.p2align 6
